# GEMM loops: removed back-to-back s_setprio 0 / s_setprio 3 pairs inside the 32-MFMA bursts
# speedup vs baseline: 1.0068x; 1.0068x over previous
; #define PG8_STAGE(bufoff, gbase, voff) do { _Pragma("unroll") for (int _i = 0; _i < 2; ++_i) \
;         __builtin_amdgcn_global_load_lds((const unsigned*)((const char*)(gbase) + (voff)[_i]), (LAS unsigned*)(lds + (bufoff) + ldsw + _i * 8192), 16, 0, 0); } while (0)
; #define PG8_LDA(dst, b, h) do { _Pragma("unroll") for (int m = 0; m < 4; ++m) _Pragma("unroll") for (int k = 0; k < 2; ++k) dst[m][k] = *(const LAS bf16x8*)(lds + PG8_SA(b, h) + aoff + m * 2048 + k * 1024); } while (0)
; #define PG8_LDB(dst, b, h) do { _Pragma("unroll") for (int n = 0; n < 2; ++n) _Pragma("unroll") for (int k = 0; k < 2; ++k) dst[n][k] = *(const LAS bf16x8*)(lds + PG8_SB(b, h) + boff + n * 2048 + k * 1024); } while (0)
; #define PG8_MMA(ai, bj, At, Bt) do { __builtin_amdgcn_s_setprio(3); _Pragma("unroll") for (int m = 0; m < 4; ++m) _Pragma("unroll") for (int n = 0; n < 2; ++n) _Pragma("unroll") for (int k = 0; k < 2; ++k) \
;         acc[ai][bj][m][n] = __builtin_amdgcn_mfma_f32_16x16x32_bf16(Bt[n][k], At[m][k], acc[ai][bj][m][n], 0, 0, 0); __builtin_amdgcn_s_setprio(0); } while (0)
; #define PG8_WAIT_V(n) asm volatile("s_waitcnt vmcnt(" #n ")" ::: "memory")
; #define PG8_BAR __builtin_amdgcn_s_barrier()
; template <class Epi, bool ALIGN_EPI>
; __device__ __forceinline__ void gemm_phase(LAS unsigned char* lds, const Gemm g, const StaticOrder& S, const Epi& E) {
;     ...
;         const char* nA = has_next ? (const char*)g.A + (size_t)nxt.pm * tstep : cA; const char* nB = has_next ? (const char*)g.Bt + (size_t)nxt.pn * tstep : cB;
;         for (int t = 0; t < nt; t += 2) {
;             const bool last = (t == nt - 2);
;             const char* a1 = cA + (size_t)(t + 1) * kstep;
;             const char* a2 = last ? nA : cA + (size_t)(t + 2) * kstep; const char* b2 = last ? nB : cB + (size_t)(t + 2) * kstep;
;             const char* a3 = a2 + kstep; const char* b3 = b2 + kstep;
;             PG8_LDB(B0, 0, 0); PG8_LDB(B1, 0, 1); PG8_SCHED; PG8_LDA(At, 0, 0); PG8_STAGE(PG8_SA(1, 1), a1 + hstep, voffA);
;             PG8_WAIT_V(8); PG8_WAIT_L(0); PG8_BAR; PG8_MMA(0, 0, At, B0); PG8_MMA(0, 1, At, B1); PG8_BAR; PG8_SCHED;
;             PG8_LDA(At, 0, 1); PG8_STAGE(PG8_SB(0, 0), b2, voffB); PG8_STAGE(PG8_SB(0, 1), b2 + hstep, voffB); PG8_STAGE(PG8_SA(0, 0), a2, voffA);
;             PG8_WAIT_V(8); PG8_WAIT_L(0); PG8_BAR; PG8_MMA(1, 0, At, B0); PG8_MMA(1, 1, At, B1); PG8_BAR; PG8_SCHED;
.LBB0_292:
	s_ashr_i32 s69, s68, 31
	s_lshl_b64 s[8:9], s[68:69], 19
	s_add_u32 s70, s34, s8
	s_addc_u32 s71, s35, s9
	s_and_b64 s[8:9], s[0:1], exec
	s_cselect_b32 s5, s71, s81
	s_cselect_b32 s69, s70, s80
	s_ashr_i32 s67, s66, 31
	s_lshl_b64 s[8:9], s[66:67], 19
	s_add_u32 s72, s26, s8
	s_addc_u32 s73, s27, s9
	s_and_b64 s[8:9], s[0:1], exec
	s_cselect_b32 s67, s73, s83
	s_cselect_b32 s79, s72, s82
	s_add_u32 s80, s80, 0x40080
	s_addc_u32 s81, s81, 0
	s_add_u32 vcc_lo, s82, 0x100
	s_addc_u32 vcc_hi, s83, 0
	s_mov_b32 s8, -2
	ds_read_b128 v[148:151], v192
	ds_read_b128 v[152:155], v192 offset:1024
	ds_read_b128 v[156:159], v192 offset:2048
	ds_read_b128 v[160:163], v192 offset:3072
	ds_read_b128 v[164:167], v193
	ds_read_b128 v[168:171], v193 offset:1024
	ds_read_b128 v[172:175], v193 offset:2048
	ds_read_b128 v[176:179], v193 offset:3072
	s_add_u32 s9, s80, 0xfffc0080
	s_addc_u32 s50, s81, -1
	s_cmp_eq_u32 s8, 12
	s_cselect_b32 s85, s5, s50
	s_cselect_b32 s84, s69, s9
	s_cselect_b32 s83, s67, vcc_hi
	s_cselect_b32 s82, s79, vcc_lo
	v_lshl_add_u64 v[224:225], s[80:81], 0, v[140:141]
	s_add_i32 m0, s76, 0xc000
	ds_read_b128 v[180:183], v194
	ds_read_b128 v[196:199], v194 offset:1024
	ds_read_b128 v[200:203], v194 offset:2048
	ds_read_b128 v[204:207], v194 offset:3072
	ds_read_b128 v[208:211], v194 offset:4096
	ds_read_b128 v[212:215], v194 offset:5120
	ds_read_b128 v[216:219], v194 offset:6144
	ds_read_b128 v[220:223], v194 offset:7168
	global_load_lds_dwordx4 v[224:225], off
	v_lshl_add_u64 v[224:225], s[80:81], 0, v[142:143]
	s_add_i32 m0, s76, 0xe000
	s_nop 0
	global_load_lds_dwordx4 v[224:225], off
	s_waitcnt vmcnt(8)
	s_waitcnt lgkmcnt(0)
	s_barrier
	s_setprio 3
	s_waitcnt lgkmcnt(0)
	v_mfma_f32_16x16x32_bf16 v[118:121], v[148:151], v[180:183], 0
	v_mfma_f32_16x16x32_bf16 v[114:117], v[156:159], v[180:183], 0
	v_mfma_f32_16x16x32_bf16 v[102:105], v[148:151], v[200:203], 0
	v_mfma_f32_16x16x32_bf16 v[98:101], v[156:159], v[200:203], 0
	v_mfma_f32_16x16x32_bf16 v[86:89], v[148:151], v[208:211], 0
	v_mfma_f32_16x16x32_bf16 v[82:85], v[156:159], v[208:211], 0
	v_mfma_f32_16x16x32_bf16 v[70:73], v[148:151], v[216:219], 0
	v_mfma_f32_16x16x32_bf16 v[66:69], v[156:159], v[216:219], 0
	v_mfma_f32_16x16x32_bf16 v[118:121], v[152:155], v[196:199], v[118:121]
	v_mfma_f32_16x16x32_bf16 v[114:117], v[160:163], v[196:199], v[114:117]
	v_mfma_f32_16x16x32_bf16 v[102:105], v[152:155], v[204:207], v[102:105]
	v_mfma_f32_16x16x32_bf16 v[98:101], v[160:163], v[204:207], v[98:101]
	v_mfma_f32_16x16x32_bf16 v[86:89], v[152:155], v[212:215], v[86:89]
	v_mfma_f32_16x16x32_bf16 v[82:85], v[160:163], v[212:215], v[82:85]
	v_mfma_f32_16x16x32_bf16 v[70:73], v[152:155], v[220:223], v[70:73]
	v_mfma_f32_16x16x32_bf16 v[66:69], v[160:163], v[220:223], v[66:69]
	v_mfma_f32_16x16x32_bf16 v[126:129], v[164:167], v[180:183], 0
	v_mfma_f32_16x16x32_bf16 v[122:125], v[172:175], v[180:183], 0
	v_mfma_f32_16x16x32_bf16 v[110:113], v[164:167], v[200:203], 0
	v_mfma_f32_16x16x32_bf16 v[106:109], v[172:175], v[200:203], 0
	v_mfma_f32_16x16x32_bf16 v[94:97], v[164:167], v[208:211], 0
	v_mfma_f32_16x16x32_bf16 v[90:93], v[172:175], v[208:211], 0
	v_mfma_f32_16x16x32_bf16 v[78:81], v[164:167], v[216:219], 0
	v_mfma_f32_16x16x32_bf16 v[74:77], v[172:175], v[216:219], 0
	v_mfma_f32_16x16x32_bf16 v[126:129], v[168:171], v[196:199], v[126:129]
	v_mfma_f32_16x16x32_bf16 v[122:125], v[176:179], v[196:199], v[122:125]
	v_mfma_f32_16x16x32_bf16 v[110:113], v[168:171], v[204:207], v[110:113]
	v_mfma_f32_16x16x32_bf16 v[106:109], v[176:179], v[204:207], v[106:109]
	v_mfma_f32_16x16x32_bf16 v[94:97], v[168:171], v[212:215], v[94:97]
	v_mfma_f32_16x16x32_bf16 v[90:93], v[176:179], v[212:215], v[90:93]
	v_mfma_f32_16x16x32_bf16 v[78:81], v[168:171], v[220:223], v[78:81]
	v_mfma_f32_16x16x32_bf16 v[74:77], v[176:179], v[220:223], v[74:77]
	s_setprio 0
	s_barrier
	s_add_i32 s9, s95, s33
	v_lshl_add_u64 v[224:225], s[82:83], 0, v[132:133]
	s_mov_b32 m0, s9
	ds_read_b128 v[180:183], v194 offset:16384
	ds_read_b128 v[196:199], v194 offset:17408
	ds_read_b128 v[200:203], v194 offset:18432
	ds_read_b128 v[204:207], v194 offset:19456
	ds_read_b128 v[208:211], v194 offset:20480
	ds_read_b128 v[212:215], v194 offset:21504
	ds_read_b128 v[216:219], v194 offset:22528
	ds_read_b128 v[220:223], v194 offset:23552
	global_load_lds_dwordx4 v[224:225], off
	s_add_i32 m0, s9, 0x2000
	s_add_u32 s50, s82, 0x40000
	v_lshl_add_u64 v[226:227], s[82:83], 0, v[136:137]
	s_addc_u32 s51, s83, 0
	s_add_i32 s9, s96, s33
	global_load_lds_dwordx4 v[226:227], off
	v_lshl_add_u64 v[228:229], s[50:51], 0, v[132:133]
	s_mov_b32 m0, s9
	v_lshl_add_u64 v[230:231], s[84:85], 0, v[134:135]
	global_load_lds_dwordx4 v[228:229], off
	v_lshl_add_u64 v[228:229], s[50:51], 0, v[136:137]
	s_add_i32 m0, s9, 0x2000
	s_nop 0
	global_load_lds_dwordx4 v[228:229], off
	v_lshl_add_u64 v[228:229], s[84:85], 0, v[130:131]
	s_mov_b32 m0, s76
	s_nop 0
	global_load_lds_dwordx4 v[228:229], off
	s_mov_b32 m0, s77
	s_nop 0
	global_load_lds_dwordx4 v[230:231], off
	s_waitcnt vmcnt(8)
	s_waitcnt lgkmcnt(0)
	s_barrier
; #define PG8_STAGE(bufoff, gbase, voff) do { _Pragma("unroll") for (int _i = 0; _i < 2; ++_i) \
;         __builtin_amdgcn_global_load_lds((const unsigned*)((const char*)(gbase) + (voff)[_i]), (LAS unsigned*)(lds + (bufoff) + ldsw + _i * 8192), 16, 0, 0); } while (0)
; #define PG8_LDA(dst, b, h) do { _Pragma("unroll") for (int m = 0; m < 4; ++m) _Pragma("unroll") for (int k = 0; k < 2; ++k) dst[m][k] = *(const LAS bf16x8*)(lds + PG8_SA(b, h) + aoff + m * 2048 + k * 1024); } while (0)
; #define PG8_LDB(dst, b, h) do { _Pragma("unroll") for (int n = 0; n < 2; ++n) _Pragma("unroll") for (int k = 0; k < 2; ++k) dst[n][k] = *(const LAS bf16x8*)(lds + PG8_SB(b, h) + boff + n * 2048 + k * 1024); } while (0)
; #define PG8_MMA(ai, bj, At, Bt) do { __builtin_amdgcn_s_setprio(3); _Pragma("unroll") for (int m = 0; m < 4; ++m) _Pragma("unroll") for (int n = 0; n < 2; ++n) _Pragma("unroll") for (int k = 0; k < 2; ++k) \
;         acc[ai][bj][m][n] = __builtin_amdgcn_mfma_f32_16x16x32_bf16(Bt[n][k], At[m][k], acc[ai][bj][m][n], 0, 0, 0); __builtin_amdgcn_s_setprio(0); } while (0)
; #define PG8_WAIT_V(n) asm volatile("s_waitcnt vmcnt(" #n ")" ::: "memory")
; #define PG8_WAIT_L(n) asm volatile("s_waitcnt lgkmcnt(" #n ")" ::: "memory")
; #define PG8_BAR __builtin_amdgcn_s_barrier()
; #define PG8_SCHED __builtin_amdgcn_sched_barrier(0)
; template <class Epi, bool ALIGN_EPI>
; __device__ __forceinline__ void gemm_phase(LAS unsigned char* lds, const Gemm g, const StaticOrder& S, const Epi& E) {
;     ...
;             PG8_LDA(At, 0, 1); PG8_STAGE(PG8_SB(0, 0), b2, voffB); PG8_STAGE(PG8_SB(0, 1), b2 + hstep, voffB); PG8_STAGE(PG8_SA(0, 0), a2, voffA);
;             PG8_WAIT_V(8); PG8_WAIT_L(0); PG8_BAR; PG8_MMA(1, 0, At, B0); PG8_MMA(1, 1, At, B1); PG8_BAR; PG8_SCHED;
;             PG8_LDB(B0, 1, 0); PG8_LDB(B1, 1, 1); PG8_SCHED; PG8_LDA(At, 1, 0); PG8_STAGE(PG8_SA(0, 1), a2 + hstep, voffA);
;             PG8_WAIT_V(8); PG8_WAIT_L(0); PG8_BAR; PG8_MMA(0, 0, At, B0); PG8_MMA(0, 1, At, B1); PG8_BAR; PG8_SCHED;
	s_setprio 3
	s_waitcnt lgkmcnt(0)
	v_mfma_f32_16x16x32_bf16 v[54:57], v[148:151], v[180:183], 0
	v_mfma_f32_16x16x32_bf16 v[50:53], v[156:159], v[180:183], 0
	v_mfma_f32_16x16x32_bf16 v[38:41], v[148:151], v[200:203], 0
	v_mfma_f32_16x16x32_bf16 v[34:37], v[156:159], v[200:203], 0
	v_mfma_f32_16x16x32_bf16 v[22:25], v[148:151], v[208:211], 0
	v_mfma_f32_16x16x32_bf16 v[18:21], v[156:159], v[208:211], 0
	v_mfma_f32_16x16x32_bf16 v[6:9], v[148:151], v[216:219], 0
	v_mfma_f32_16x16x32_bf16 v[2:5], v[156:159], v[216:219], 0
	v_mfma_f32_16x16x32_bf16 v[54:57], v[152:155], v[196:199], v[54:57]
	v_mfma_f32_16x16x32_bf16 v[50:53], v[160:163], v[196:199], v[50:53]
	v_mfma_f32_16x16x32_bf16 v[38:41], v[152:155], v[204:207], v[38:41]
	v_mfma_f32_16x16x32_bf16 v[34:37], v[160:163], v[204:207], v[34:37]
	v_mfma_f32_16x16x32_bf16 v[22:25], v[152:155], v[212:215], v[22:25]
	v_mfma_f32_16x16x32_bf16 v[18:21], v[160:163], v[212:215], v[18:21]
	v_mfma_f32_16x16x32_bf16 v[6:9], v[152:155], v[220:223], v[6:9]
	v_mfma_f32_16x16x32_bf16 v[2:5], v[160:163], v[220:223], v[2:5]
	v_mfma_f32_16x16x32_bf16 v[62:65], v[164:167], v[180:183], 0
	v_mfma_f32_16x16x32_bf16 v[58:61], v[172:175], v[180:183], 0
	v_mfma_f32_16x16x32_bf16 v[46:49], v[164:167], v[200:203], 0
	v_mfma_f32_16x16x32_bf16 v[42:45], v[172:175], v[200:203], 0
	v_mfma_f32_16x16x32_bf16 v[30:33], v[164:167], v[208:211], 0
	v_mfma_f32_16x16x32_bf16 v[26:29], v[172:175], v[208:211], 0
	v_mfma_f32_16x16x32_bf16 v[14:17], v[164:167], v[216:219], 0
	v_mfma_f32_16x16x32_bf16 v[10:13], v[172:175], v[216:219], 0
	v_mfma_f32_16x16x32_bf16 v[62:65], v[168:171], v[196:199], v[62:65]
	v_mfma_f32_16x16x32_bf16 v[58:61], v[176:179], v[196:199], v[58:61]
	v_mfma_f32_16x16x32_bf16 v[46:49], v[168:171], v[204:207], v[46:49]
	v_mfma_f32_16x16x32_bf16 v[42:45], v[176:179], v[204:207], v[42:45]
	v_mfma_f32_16x16x32_bf16 v[30:33], v[168:171], v[212:215], v[30:33]
	v_mfma_f32_16x16x32_bf16 v[26:29], v[176:179], v[212:215], v[26:29]
	v_mfma_f32_16x16x32_bf16 v[14:17], v[168:171], v[220:223], v[14:17]
	v_mfma_f32_16x16x32_bf16 v[10:13], v[176:179], v[220:223], v[10:13]
	s_setprio 0
	s_barrier
	s_add_i32 s9, 0, 0x18000
	v_add_u32_e32 v138, s9, v189
	s_add_i32 s89, 0, 0x1c000
	ds_read_b128 v[148:151], v138
	ds_read_b128 v[152:155], v138 offset:1024
	ds_read_b128 v[156:159], v138 offset:2048
	ds_read_b128 v[160:163], v138 offset:3072
	v_add_u32_e32 v138, s89, v189
	ds_read_b128 v[164:167], v138
	ds_read_b128 v[168:171], v138 offset:1024
	ds_read_b128 v[172:175], v138 offset:2048
	ds_read_b128 v[176:179], v138 offset:3072
	s_add_u32 s50, s84, 0x40000
	s_addc_u32 s51, s85, 0
	s_mov_b32 m0, s86
	v_lshl_add_u64 v[232:233], s[50:51], 0, v[130:131]
	ds_read_b128 v[180:183], v194 offset:32768
	ds_read_b128 v[196:199], v194 offset:33792
	ds_read_b128 v[200:203], v194 offset:34816
	ds_read_b128 v[204:207], v194 offset:35840
	ds_read_b128 v[208:211], v194 offset:36864
	ds_read_b128 v[212:215], v194 offset:37888
	ds_read_b128 v[216:219], v194 offset:38912
	ds_read_b128 v[220:223], v194 offset:39936
	global_load_lds_dwordx4 v[232:233], off
	v_lshl_add_u64 v[232:233], s[50:51], 0, v[134:135]
	s_mov_b32 m0, s87
	s_nop 0
	global_load_lds_dwordx4 v[232:233], off
	s_waitcnt vmcnt(8)
	s_waitcnt lgkmcnt(0)
	s_barrier
	s_setprio 3
	s_waitcnt lgkmcnt(0)
	v_mfma_f32_16x16x32_bf16 v[118:121], v[148:151], v[180:183], v[118:121]
	v_mfma_f32_16x16x32_bf16 v[114:117], v[156:159], v[180:183], v[114:117]
	v_mfma_f32_16x16x32_bf16 v[102:105], v[148:151], v[200:203], v[102:105]
	v_mfma_f32_16x16x32_bf16 v[98:101], v[156:159], v[200:203], v[98:101]
	v_mfma_f32_16x16x32_bf16 v[86:89], v[148:151], v[208:211], v[86:89]
	v_mfma_f32_16x16x32_bf16 v[82:85], v[156:159], v[208:211], v[82:85]
	v_mfma_f32_16x16x32_bf16 v[70:73], v[148:151], v[216:219], v[70:73]
	v_mfma_f32_16x16x32_bf16 v[66:69], v[156:159], v[216:219], v[66:69]
	v_mfma_f32_16x16x32_bf16 v[118:121], v[152:155], v[196:199], v[118:121]
	v_mfma_f32_16x16x32_bf16 v[114:117], v[160:163], v[196:199], v[114:117]
	v_mfma_f32_16x16x32_bf16 v[102:105], v[152:155], v[204:207], v[102:105]
	v_mfma_f32_16x16x32_bf16 v[98:101], v[160:163], v[204:207], v[98:101]
	v_mfma_f32_16x16x32_bf16 v[86:89], v[152:155], v[212:215], v[86:89]
	v_mfma_f32_16x16x32_bf16 v[82:85], v[160:163], v[212:215], v[82:85]
	v_mfma_f32_16x16x32_bf16 v[70:73], v[152:155], v[220:223], v[70:73]
	v_mfma_f32_16x16x32_bf16 v[66:69], v[160:163], v[220:223], v[66:69]
	v_mfma_f32_16x16x32_bf16 v[126:129], v[164:167], v[180:183], v[126:129]
	v_mfma_f32_16x16x32_bf16 v[122:125], v[172:175], v[180:183], v[122:125]
	v_mfma_f32_16x16x32_bf16 v[110:113], v[164:167], v[200:203], v[110:113]
	v_mfma_f32_16x16x32_bf16 v[106:109], v[172:175], v[200:203], v[106:109]
	v_mfma_f32_16x16x32_bf16 v[94:97], v[164:167], v[208:211], v[94:97]
	v_mfma_f32_16x16x32_bf16 v[90:93], v[172:175], v[208:211], v[90:93]
	v_mfma_f32_16x16x32_bf16 v[78:81], v[164:167], v[216:219], v[78:81]
	v_mfma_f32_16x16x32_bf16 v[74:77], v[172:175], v[216:219], v[74:77]
	v_mfma_f32_16x16x32_bf16 v[126:129], v[168:171], v[196:199], v[126:129]
	v_mfma_f32_16x16x32_bf16 v[122:125], v[176:179], v[196:199], v[122:125]
	v_mfma_f32_16x16x32_bf16 v[110:113], v[168:171], v[204:207], v[110:113]
	v_mfma_f32_16x16x32_bf16 v[106:109], v[176:179], v[204:207], v[106:109]
	v_mfma_f32_16x16x32_bf16 v[94:97], v[168:171], v[212:215], v[94:97]
	v_mfma_f32_16x16x32_bf16 v[90:93], v[176:179], v[212:215], v[90:93]
	v_mfma_f32_16x16x32_bf16 v[78:81], v[168:171], v[220:223], v[78:81]
	v_mfma_f32_16x16x32_bf16 v[74:77], v[176:179], v[220:223], v[74:77]
	s_setprio 0
	s_barrier
; #define PG8_STAGE(bufoff, gbase, voff) do { _Pragma("unroll") for (int _i = 0; _i < 2; ++_i) \
;         __builtin_amdgcn_global_load_lds((const unsigned*)((const char*)(gbase) + (voff)[_i]), (LAS unsigned*)(lds + (bufoff) + ldsw + _i * 8192), 16, 0, 0); } while (0)
; #define PG8_LDA(dst, b, h) do { _Pragma("unroll") for (int m = 0; m < 4; ++m) _Pragma("unroll") for (int k = 0; k < 2; ++k) dst[m][k] = *(const LAS bf16x8*)(lds + PG8_SA(b, h) + aoff + m * 2048 + k * 1024); } while (0)
; #define PG8_LDB(dst, b, h) do { _Pragma("unroll") for (int n = 0; n < 2; ++n) _Pragma("unroll") for (int k = 0; k < 2; ++k) dst[n][k] = *(const LAS bf16x8*)(lds + PG8_SB(b, h) + boff + n * 2048 + k * 1024); } while (0)
; #define PG8_WAIT_V(n) asm volatile("s_waitcnt vmcnt(" #n ")" ::: "memory")
; #define PG8_BAR __builtin_amdgcn_s_barrier()
; template <class Epi, bool ALIGN_EPI>
; __device__ __forceinline__ void gemm_phase(LAS unsigned char* lds, const Gemm g, const StaticOrder& S, const Epi& E) {
;     ...
;         for (int t = 0; t < nt; t += 2) {
;             const bool last = (t == nt - 2);
;             const char* a1 = cA + (size_t)(t + 1) * kstep;
;             const char* a2 = last ? nA : cA + (size_t)(t + 2) * kstep; const char* b2 = last ? nB : cB + (size_t)(t + 2) * kstep;
;             const char* a3 = a2 + kstep; const char* b3 = b2 + kstep;
;             PG8_LDB(B0, 0, 0); PG8_LDB(B1, 0, 1); PG8_SCHED; PG8_LDA(At, 0, 0); PG8_STAGE(PG8_SA(1, 1), a1 + hstep, voffA);
;             PG8_WAIT_V(8); PG8_WAIT_L(0); PG8_BAR; PG8_MMA(0, 0, At, B0); PG8_MMA(0, 1, At, B1); PG8_BAR; PG8_SCHED;
;             PG8_LDA(At, 0, 1); PG8_STAGE(PG8_SB(0, 0), b2, voffB); PG8_STAGE(PG8_SB(0, 1), b2 + hstep, voffB); PG8_STAGE(PG8_SA(0, 0), a2, voffA);
;             PG8_WAIT_V(8); PG8_WAIT_L(0); PG8_BAR; PG8_MMA(1, 0, At, B0); PG8_MMA(1, 1, At, B1); PG8_BAR; PG8_SCHED;
;             PG8_LDB(B0, 1, 0); PG8_LDB(B1, 1, 1); PG8_SCHED; PG8_LDA(At, 1, 0); PG8_STAGE(PG8_SA(0, 1), a2 + hstep, voffA);
;             PG8_WAIT_V(8); PG8_WAIT_L(0); PG8_BAR; PG8_MMA(0, 0, At, B0); PG8_MMA(0, 1, At, B1); PG8_BAR; PG8_SCHED;
;             PG8_LDA(At, 1, 1); PG8_STAGE(PG8_SB(1, 0), b3, voffB); PG8_STAGE(PG8_SB(1, 1), b3 + hstep, voffB); PG8_STAGE(PG8_SA(1, 0), a3, voffA);
;             PG8_WAIT_V(8); PG8_WAIT_L(0); PG8_BAR; PG8_MMA(1, 0, At, B0); PG8_MMA(1, 1, At, B1); PG8_BAR; PG8_SCHED;
	s_add_i32 s9, s9, s33
	v_lshl_add_u64 v[224:225], v[224:225], 0, s[62:63]
	s_mov_b32 m0, s9
	ds_read_b128 v[180:183], v194 offset:49152
	ds_read_b128 v[196:199], v194 offset:50176
	ds_read_b128 v[200:203], v194 offset:51200
	ds_read_b128 v[204:207], v194 offset:52224
	ds_read_b128 v[208:211], v194 offset:53248
	ds_read_b128 v[212:215], v194 offset:54272
	ds_read_b128 v[216:219], v194 offset:55296
	ds_read_b128 v[220:223], v194 offset:56320
	global_load_lds_dwordx4 v[224:225], off
	s_add_i32 m0, s9, 0x2000
	s_add_u32 s50, s82, 0x40080
	v_lshl_add_u64 v[224:225], v[226:227], 0, s[62:63]
	s_addc_u32 s51, s83, 0
	s_add_i32 s9, s89, s33
	global_load_lds_dwordx4 v[224:225], off
	v_lshl_add_u64 v[224:225], s[50:51], 0, v[132:133]
	s_mov_b32 m0, s9
	s_nop 0
	global_load_lds_dwordx4 v[224:225], off
	v_lshl_add_u64 v[224:225], s[50:51], 0, v[136:137]
	s_add_i32 m0, s9, 0x2000
	s_nop 0
	global_load_lds_dwordx4 v[224:225], off
	v_lshl_add_u64 v[224:225], v[228:229], 0, s[62:63]
	s_mov_b32 m0, s93
	s_nop 0
	global_load_lds_dwordx4 v[224:225], off
	v_lshl_add_u64 v[224:225], v[230:231], 0, s[62:63]
	s_mov_b32 m0, s94
	s_nop 0
	global_load_lds_dwordx4 v[224:225], off
	s_waitcnt vmcnt(8)
	s_waitcnt lgkmcnt(0)
	s_barrier
	s_setprio 3
	s_waitcnt lgkmcnt(0)
	v_mfma_f32_16x16x32_bf16 v[54:57], v[148:151], v[180:183], v[54:57]
	v_mfma_f32_16x16x32_bf16 v[50:53], v[156:159], v[180:183], v[50:53]
	v_mfma_f32_16x16x32_bf16 v[38:41], v[148:151], v[200:203], v[38:41]
	v_mfma_f32_16x16x32_bf16 v[34:37], v[156:159], v[200:203], v[34:37]
	v_mfma_f32_16x16x32_bf16 v[22:25], v[148:151], v[208:211], v[22:25]
	v_mfma_f32_16x16x32_bf16 v[18:21], v[156:159], v[208:211], v[18:21]
	v_mfma_f32_16x16x32_bf16 v[6:9], v[148:151], v[216:219], v[6:9]
	v_mfma_f32_16x16x32_bf16 v[2:5], v[156:159], v[216:219], v[2:5]
	v_mfma_f32_16x16x32_bf16 v[54:57], v[152:155], v[196:199], v[54:57]
	v_mfma_f32_16x16x32_bf16 v[50:53], v[160:163], v[196:199], v[50:53]
	v_mfma_f32_16x16x32_bf16 v[38:41], v[152:155], v[204:207], v[38:41]
	v_mfma_f32_16x16x32_bf16 v[34:37], v[160:163], v[204:207], v[34:37]
	v_mfma_f32_16x16x32_bf16 v[22:25], v[152:155], v[212:215], v[22:25]
	v_mfma_f32_16x16x32_bf16 v[18:21], v[160:163], v[212:215], v[18:21]
	v_mfma_f32_16x16x32_bf16 v[6:9], v[152:155], v[220:223], v[6:9]
	v_mfma_f32_16x16x32_bf16 v[2:5], v[160:163], v[220:223], v[2:5]
	v_mfma_f32_16x16x32_bf16 v[62:65], v[164:167], v[180:183], v[62:65]
	v_mfma_f32_16x16x32_bf16 v[58:61], v[172:175], v[180:183], v[58:61]
	v_mfma_f32_16x16x32_bf16 v[46:49], v[164:167], v[200:203], v[46:49]
	v_mfma_f32_16x16x32_bf16 v[42:45], v[172:175], v[200:203], v[42:45]
	v_mfma_f32_16x16x32_bf16 v[30:33], v[164:167], v[208:211], v[30:33]
	v_mfma_f32_16x16x32_bf16 v[26:29], v[172:175], v[208:211], v[26:29]
	v_mfma_f32_16x16x32_bf16 v[14:17], v[164:167], v[216:219], v[14:17]
	v_mfma_f32_16x16x32_bf16 v[10:13], v[172:175], v[216:219], v[10:13]
	v_mfma_f32_16x16x32_bf16 v[62:65], v[168:171], v[196:199], v[62:65]
	v_mfma_f32_16x16x32_bf16 v[58:61], v[176:179], v[196:199], v[58:61]
	v_mfma_f32_16x16x32_bf16 v[46:49], v[168:171], v[204:207], v[46:49]
	v_mfma_f32_16x16x32_bf16 v[42:45], v[176:179], v[204:207], v[42:45]
	v_mfma_f32_16x16x32_bf16 v[30:33], v[168:171], v[212:215], v[30:33]
	v_mfma_f32_16x16x32_bf16 v[26:29], v[176:179], v[212:215], v[26:29]
	v_mfma_f32_16x16x32_bf16 v[14:17], v[168:171], v[220:223], v[14:17]
	v_mfma_f32_16x16x32_bf16 v[10:13], v[176:179], v[220:223], v[10:13]
	s_setprio 0
	s_barrier
	s_add_i32 s8, s8, 2
	s_add_u32 s80, s80, 0x100
	s_addc_u32 s81, s81, 0
	s_add_u32 vcc_lo, vcc_lo, 0x100
	s_addc_u32 vcc_hi, vcc_hi, 0
.LBB0_293:
	ds_read_b128 v[148:151], v192
	ds_read_b128 v[152:155], v192 offset:1024
	ds_read_b128 v[156:159], v192 offset:2048
	ds_read_b128 v[160:163], v192 offset:3072
	ds_read_b128 v[164:167], v193
	ds_read_b128 v[168:171], v193 offset:1024
	ds_read_b128 v[172:175], v193 offset:2048
	ds_read_b128 v[176:179], v193 offset:3072
	s_add_u32 s9, s80, 0xfffc0080
	s_addc_u32 s50, s81, -1
	s_cmp_eq_u32 s8, 12
	s_cselect_b32 s85, s5, s50
	s_cselect_b32 s84, s69, s9
	s_cselect_b32 s83, s67, vcc_hi
	s_cselect_b32 s82, s79, vcc_lo
	v_lshl_add_u64 v[224:225], s[80:81], 0, v[140:141]
	s_add_i32 m0, s76, 0xc000
	ds_read_b128 v[180:183], v194
	ds_read_b128 v[196:199], v194 offset:1024
	ds_read_b128 v[200:203], v194 offset:2048
	ds_read_b128 v[204:207], v194 offset:3072
	ds_read_b128 v[208:211], v194 offset:4096
	ds_read_b128 v[212:215], v194 offset:5120
	ds_read_b128 v[216:219], v194 offset:6144
	ds_read_b128 v[220:223], v194 offset:7168
	global_load_lds_dwordx4 v[224:225], off
	v_lshl_add_u64 v[224:225], s[80:81], 0, v[142:143]
	s_add_i32 m0, s76, 0xe000
	s_nop 0
	global_load_lds_dwordx4 v[224:225], off
	s_waitcnt vmcnt(8)
	s_waitcnt lgkmcnt(0)
	s_barrier
; #define PG8_STAGE(bufoff, gbase, voff) do { _Pragma("unroll") for (int _i = 0; _i < 2; ++_i) \
;         __builtin_amdgcn_global_load_lds((const unsigned*)((const char*)(gbase) + (voff)[_i]), (LAS unsigned*)(lds + (bufoff) + ldsw + _i * 8192), 16, 0, 0); } while (0)
; #define PG8_LDA(dst, b, h) do { _Pragma("unroll") for (int m = 0; m < 4; ++m) _Pragma("unroll") for (int k = 0; k < 2; ++k) dst[m][k] = *(const LAS bf16x8*)(lds + PG8_SA(b, h) + aoff + m * 2048 + k * 1024); } while (0)
; #define PG8_LDB(dst, b, h) do { _Pragma("unroll") for (int n = 0; n < 2; ++n) _Pragma("unroll") for (int k = 0; k < 2; ++k) dst[n][k] = *(const LAS bf16x8*)(lds + PG8_SB(b, h) + boff + n * 2048 + k * 1024); } while (0)
; #define PG8_MMA(ai, bj, At, Bt) do { __builtin_amdgcn_s_setprio(3); _Pragma("unroll") for (int m = 0; m < 4; ++m) _Pragma("unroll") for (int n = 0; n < 2; ++n) _Pragma("unroll") for (int k = 0; k < 2; ++k) \
;         acc[ai][bj][m][n] = __builtin_amdgcn_mfma_f32_16x16x32_bf16(Bt[n][k], At[m][k], acc[ai][bj][m][n], 0, 0, 0); __builtin_amdgcn_s_setprio(0); } while (0)
; #define PG8_WAIT_V(n) asm volatile("s_waitcnt vmcnt(" #n ")" ::: "memory")
; #define PG8_WAIT_L(n) asm volatile("s_waitcnt lgkmcnt(" #n ")" ::: "memory")
; #define PG8_BAR __builtin_amdgcn_s_barrier()
; #define PG8_SCHED __builtin_amdgcn_sched_barrier(0)
; template <class Epi, bool ALIGN_EPI>
; __device__ __forceinline__ void gemm_phase(LAS unsigned char* lds, const Gemm g, const StaticOrder& S, const Epi& E) {
;     ...
;             PG8_LDB(B0, 0, 0); PG8_LDB(B1, 0, 1); PG8_SCHED; PG8_LDA(At, 0, 0); PG8_STAGE(PG8_SA(1, 1), a1 + hstep, voffA);
;             PG8_WAIT_V(8); PG8_WAIT_L(0); PG8_BAR; PG8_MMA(0, 0, At, B0); PG8_MMA(0, 1, At, B1); PG8_BAR; PG8_SCHED;
;             PG8_LDA(At, 0, 1); PG8_STAGE(PG8_SB(0, 0), b2, voffB); PG8_STAGE(PG8_SB(0, 1), b2 + hstep, voffB); PG8_STAGE(PG8_SA(0, 0), a2, voffA);
;             PG8_WAIT_V(8); PG8_WAIT_L(0); PG8_BAR; PG8_MMA(1, 0, At, B0); PG8_MMA(1, 1, At, B1); PG8_BAR; PG8_SCHED;
	s_setprio 3
	s_waitcnt lgkmcnt(0)
	v_mfma_f32_16x16x32_bf16 v[118:121], v[148:151], v[180:183], v[118:121]
	v_mfma_f32_16x16x32_bf16 v[114:117], v[156:159], v[180:183], v[114:117]
	v_mfma_f32_16x16x32_bf16 v[102:105], v[148:151], v[200:203], v[102:105]
	v_mfma_f32_16x16x32_bf16 v[98:101], v[156:159], v[200:203], v[98:101]
	v_mfma_f32_16x16x32_bf16 v[86:89], v[148:151], v[208:211], v[86:89]
	v_mfma_f32_16x16x32_bf16 v[82:85], v[156:159], v[208:211], v[82:85]
	v_mfma_f32_16x16x32_bf16 v[70:73], v[148:151], v[216:219], v[70:73]
	v_mfma_f32_16x16x32_bf16 v[66:69], v[156:159], v[216:219], v[66:69]
	v_mfma_f32_16x16x32_bf16 v[118:121], v[152:155], v[196:199], v[118:121]
	v_mfma_f32_16x16x32_bf16 v[114:117], v[160:163], v[196:199], v[114:117]
	v_mfma_f32_16x16x32_bf16 v[102:105], v[152:155], v[204:207], v[102:105]
	v_mfma_f32_16x16x32_bf16 v[98:101], v[160:163], v[204:207], v[98:101]
	v_mfma_f32_16x16x32_bf16 v[86:89], v[152:155], v[212:215], v[86:89]
	v_mfma_f32_16x16x32_bf16 v[82:85], v[160:163], v[212:215], v[82:85]
	v_mfma_f32_16x16x32_bf16 v[70:73], v[152:155], v[220:223], v[70:73]
	v_mfma_f32_16x16x32_bf16 v[66:69], v[160:163], v[220:223], v[66:69]
	v_mfma_f32_16x16x32_bf16 v[126:129], v[164:167], v[180:183], v[126:129]
	v_mfma_f32_16x16x32_bf16 v[122:125], v[172:175], v[180:183], v[122:125]
	v_mfma_f32_16x16x32_bf16 v[110:113], v[164:167], v[200:203], v[110:113]
	v_mfma_f32_16x16x32_bf16 v[106:109], v[172:175], v[200:203], v[106:109]
	v_mfma_f32_16x16x32_bf16 v[94:97], v[164:167], v[208:211], v[94:97]
	v_mfma_f32_16x16x32_bf16 v[90:93], v[172:175], v[208:211], v[90:93]
	v_mfma_f32_16x16x32_bf16 v[78:81], v[164:167], v[216:219], v[78:81]
	v_mfma_f32_16x16x32_bf16 v[74:77], v[172:175], v[216:219], v[74:77]
	v_mfma_f32_16x16x32_bf16 v[126:129], v[168:171], v[196:199], v[126:129]
	v_mfma_f32_16x16x32_bf16 v[122:125], v[176:179], v[196:199], v[122:125]
	v_mfma_f32_16x16x32_bf16 v[110:113], v[168:171], v[204:207], v[110:113]
	v_mfma_f32_16x16x32_bf16 v[106:109], v[176:179], v[204:207], v[106:109]
	v_mfma_f32_16x16x32_bf16 v[94:97], v[168:171], v[212:215], v[94:97]
	v_mfma_f32_16x16x32_bf16 v[90:93], v[176:179], v[212:215], v[90:93]
	v_mfma_f32_16x16x32_bf16 v[78:81], v[168:171], v[220:223], v[78:81]
	v_mfma_f32_16x16x32_bf16 v[74:77], v[176:179], v[220:223], v[74:77]
	s_setprio 0
	s_barrier
	s_add_i32 s9, s95, s33
	v_lshl_add_u64 v[224:225], s[82:83], 0, v[132:133]
	s_mov_b32 m0, s9
	ds_read_b128 v[180:183], v194 offset:16384
	ds_read_b128 v[196:199], v194 offset:17408
	ds_read_b128 v[200:203], v194 offset:18432
	ds_read_b128 v[204:207], v194 offset:19456
	ds_read_b128 v[208:211], v194 offset:20480
	ds_read_b128 v[212:215], v194 offset:21504
	ds_read_b128 v[216:219], v194 offset:22528
	ds_read_b128 v[220:223], v194 offset:23552
	global_load_lds_dwordx4 v[224:225], off
	s_add_i32 m0, s9, 0x2000
	s_add_u32 s50, s82, 0x40000
	v_lshl_add_u64 v[226:227], s[82:83], 0, v[136:137]
	s_addc_u32 s51, s83, 0
	s_add_i32 s9, s96, s33
	global_load_lds_dwordx4 v[226:227], off
	v_lshl_add_u64 v[228:229], s[50:51], 0, v[132:133]
	s_mov_b32 m0, s9
	v_lshl_add_u64 v[230:231], s[84:85], 0, v[134:135]
	global_load_lds_dwordx4 v[228:229], off
	v_lshl_add_u64 v[228:229], s[50:51], 0, v[136:137]
	s_add_i32 m0, s9, 0x2000
	s_nop 0
	global_load_lds_dwordx4 v[228:229], off
	v_lshl_add_u64 v[228:229], s[84:85], 0, v[130:131]
	s_mov_b32 m0, s76
	s_nop 0
	global_load_lds_dwordx4 v[228:229], off
	s_mov_b32 m0, s77
	s_nop 0
	global_load_lds_dwordx4 v[230:231], off
	s_waitcnt vmcnt(8)
	s_waitcnt lgkmcnt(0)
	s_barrier
	s_setprio 3
	s_waitcnt lgkmcnt(0)
	v_mfma_f32_16x16x32_bf16 v[54:57], v[148:151], v[180:183], v[54:57]
	v_mfma_f32_16x16x32_bf16 v[50:53], v[156:159], v[180:183], v[50:53]
	v_mfma_f32_16x16x32_bf16 v[38:41], v[148:151], v[200:203], v[38:41]
	v_mfma_f32_16x16x32_bf16 v[34:37], v[156:159], v[200:203], v[34:37]
	v_mfma_f32_16x16x32_bf16 v[22:25], v[148:151], v[208:211], v[22:25]
	v_mfma_f32_16x16x32_bf16 v[18:21], v[156:159], v[208:211], v[18:21]
	v_mfma_f32_16x16x32_bf16 v[6:9], v[148:151], v[216:219], v[6:9]
	v_mfma_f32_16x16x32_bf16 v[2:5], v[156:159], v[216:219], v[2:5]
	v_mfma_f32_16x16x32_bf16 v[54:57], v[152:155], v[196:199], v[54:57]
	v_mfma_f32_16x16x32_bf16 v[50:53], v[160:163], v[196:199], v[50:53]
	v_mfma_f32_16x16x32_bf16 v[38:41], v[152:155], v[204:207], v[38:41]
	v_mfma_f32_16x16x32_bf16 v[34:37], v[160:163], v[204:207], v[34:37]
	v_mfma_f32_16x16x32_bf16 v[22:25], v[152:155], v[212:215], v[22:25]
	v_mfma_f32_16x16x32_bf16 v[18:21], v[160:163], v[212:215], v[18:21]
	v_mfma_f32_16x16x32_bf16 v[6:9], v[152:155], v[220:223], v[6:9]
	v_mfma_f32_16x16x32_bf16 v[2:5], v[160:163], v[220:223], v[2:5]
	v_mfma_f32_16x16x32_bf16 v[62:65], v[164:167], v[180:183], v[62:65]
	v_mfma_f32_16x16x32_bf16 v[58:61], v[172:175], v[180:183], v[58:61]
	v_mfma_f32_16x16x32_bf16 v[46:49], v[164:167], v[200:203], v[46:49]
	v_mfma_f32_16x16x32_bf16 v[42:45], v[172:175], v[200:203], v[42:45]
	v_mfma_f32_16x16x32_bf16 v[30:33], v[164:167], v[208:211], v[30:33]
	v_mfma_f32_16x16x32_bf16 v[26:29], v[172:175], v[208:211], v[26:29]
	v_mfma_f32_16x16x32_bf16 v[14:17], v[164:167], v[216:219], v[14:17]
	v_mfma_f32_16x16x32_bf16 v[10:13], v[172:175], v[216:219], v[10:13]
	v_mfma_f32_16x16x32_bf16 v[62:65], v[168:171], v[196:199], v[62:65]
	v_mfma_f32_16x16x32_bf16 v[58:61], v[176:179], v[196:199], v[58:61]
	v_mfma_f32_16x16x32_bf16 v[46:49], v[168:171], v[204:207], v[46:49]
	v_mfma_f32_16x16x32_bf16 v[42:45], v[176:179], v[204:207], v[42:45]
	v_mfma_f32_16x16x32_bf16 v[30:33], v[168:171], v[212:215], v[30:33]
	v_mfma_f32_16x16x32_bf16 v[26:29], v[176:179], v[212:215], v[26:29]
	v_mfma_f32_16x16x32_bf16 v[14:17], v[168:171], v[220:223], v[14:17]
	v_mfma_f32_16x16x32_bf16 v[10:13], v[176:179], v[220:223], v[10:13]
	s_setprio 0
	s_barrier
; #define PG8_STAGE(bufoff, gbase, voff) do { _Pragma("unroll") for (int _i = 0; _i < 2; ++_i) \
;         __builtin_amdgcn_global_load_lds((const unsigned*)((const char*)(gbase) + (voff)[_i]), (LAS unsigned*)(lds + (bufoff) + ldsw + _i * 8192), 16, 0, 0); } while (0)
; #define PG8_LDA(dst, b, h) do { _Pragma("unroll") for (int m = 0; m < 4; ++m) _Pragma("unroll") for (int k = 0; k < 2; ++k) dst[m][k] = *(const LAS bf16x8*)(lds + PG8_SA(b, h) + aoff + m * 2048 + k * 1024); } while (0)
; #define PG8_LDB(dst, b, h) do { _Pragma("unroll") for (int n = 0; n < 2; ++n) _Pragma("unroll") for (int k = 0; k < 2; ++k) dst[n][k] = *(const LAS bf16x8*)(lds + PG8_SB(b, h) + boff + n * 2048 + k * 1024); } while (0)
; #define PG8_MMA(ai, bj, At, Bt) do { __builtin_amdgcn_s_setprio(3); _Pragma("unroll") for (int m = 0; m < 4; ++m) _Pragma("unroll") for (int n = 0; n < 2; ++n) _Pragma("unroll") for (int k = 0; k < 2; ++k) \
;         acc[ai][bj][m][n] = __builtin_amdgcn_mfma_f32_16x16x32_bf16(Bt[n][k], At[m][k], acc[ai][bj][m][n], 0, 0, 0); __builtin_amdgcn_s_setprio(0); } while (0)
; #define PG8_WAIT_V(n) asm volatile("s_waitcnt vmcnt(" #n ")" ::: "memory")
; #define PG8_WAIT_L(n) asm volatile("s_waitcnt lgkmcnt(" #n ")" ::: "memory")
; #define PG8_BAR __builtin_amdgcn_s_barrier()
; #define PG8_SCHED __builtin_amdgcn_sched_barrier(0)
; template <class Epi, bool ALIGN_EPI>
; __device__ __forceinline__ void gemm_phase(LAS unsigned char* lds, const Gemm g, const StaticOrder& S, const Epi& E) {
;     ...
;             PG8_LDB(B0, 1, 0); PG8_LDB(B1, 1, 1); PG8_SCHED; PG8_LDA(At, 1, 0); PG8_STAGE(PG8_SA(0, 1), a2 + hstep, voffA);
;             PG8_WAIT_V(8); PG8_WAIT_L(0); PG8_BAR; PG8_MMA(0, 0, At, B0); PG8_MMA(0, 1, At, B1); PG8_BAR; PG8_SCHED;
	s_add_i32 s9, 0, 0x18000
	v_add_u32_e32 v138, s9, v189
	s_add_i32 s89, 0, 0x1c000
	ds_read_b128 v[148:151], v138
	ds_read_b128 v[152:155], v138 offset:1024
	ds_read_b128 v[156:159], v138 offset:2048
	ds_read_b128 v[160:163], v138 offset:3072
	v_add_u32_e32 v138, s89, v189
	ds_read_b128 v[164:167], v138
	ds_read_b128 v[168:171], v138 offset:1024
	ds_read_b128 v[172:175], v138 offset:2048
	ds_read_b128 v[176:179], v138 offset:3072
	s_add_u32 s50, s84, 0x40000
	s_addc_u32 s51, s85, 0
	s_mov_b32 m0, s86
	v_lshl_add_u64 v[232:233], s[50:51], 0, v[130:131]
	ds_read_b128 v[180:183], v194 offset:32768
	ds_read_b128 v[196:199], v194 offset:33792
	ds_read_b128 v[200:203], v194 offset:34816
	ds_read_b128 v[204:207], v194 offset:35840
	ds_read_b128 v[208:211], v194 offset:36864
	ds_read_b128 v[212:215], v194 offset:37888
	ds_read_b128 v[216:219], v194 offset:38912
	ds_read_b128 v[220:223], v194 offset:39936
	global_load_lds_dwordx4 v[232:233], off
	v_lshl_add_u64 v[232:233], s[50:51], 0, v[134:135]
	s_mov_b32 m0, s87
	s_nop 0
	global_load_lds_dwordx4 v[232:233], off
	s_waitcnt vmcnt(8)
	s_waitcnt lgkmcnt(0)
	s_barrier
	s_setprio 3
	s_waitcnt lgkmcnt(0)
	v_mfma_f32_16x16x32_bf16 v[118:121], v[148:151], v[180:183], v[118:121]
	v_mfma_f32_16x16x32_bf16 v[114:117], v[156:159], v[180:183], v[114:117]
	v_mfma_f32_16x16x32_bf16 v[102:105], v[148:151], v[200:203], v[102:105]
	v_mfma_f32_16x16x32_bf16 v[98:101], v[156:159], v[200:203], v[98:101]
	v_mfma_f32_16x16x32_bf16 v[86:89], v[148:151], v[208:211], v[86:89]
	v_mfma_f32_16x16x32_bf16 v[82:85], v[156:159], v[208:211], v[82:85]
	v_mfma_f32_16x16x32_bf16 v[70:73], v[148:151], v[216:219], v[70:73]
	v_mfma_f32_16x16x32_bf16 v[66:69], v[156:159], v[216:219], v[66:69]
	v_mfma_f32_16x16x32_bf16 v[118:121], v[152:155], v[196:199], v[118:121]
	v_mfma_f32_16x16x32_bf16 v[114:117], v[160:163], v[196:199], v[114:117]
	v_mfma_f32_16x16x32_bf16 v[102:105], v[152:155], v[204:207], v[102:105]
	v_mfma_f32_16x16x32_bf16 v[98:101], v[160:163], v[204:207], v[98:101]
	v_mfma_f32_16x16x32_bf16 v[86:89], v[152:155], v[212:215], v[86:89]
	v_mfma_f32_16x16x32_bf16 v[82:85], v[160:163], v[212:215], v[82:85]
	v_mfma_f32_16x16x32_bf16 v[70:73], v[152:155], v[220:223], v[70:73]
	v_mfma_f32_16x16x32_bf16 v[66:69], v[160:163], v[220:223], v[66:69]
	v_mfma_f32_16x16x32_bf16 v[126:129], v[164:167], v[180:183], v[126:129]
	v_mfma_f32_16x16x32_bf16 v[122:125], v[172:175], v[180:183], v[122:125]
	v_mfma_f32_16x16x32_bf16 v[110:113], v[164:167], v[200:203], v[110:113]
	v_mfma_f32_16x16x32_bf16 v[106:109], v[172:175], v[200:203], v[106:109]
	v_mfma_f32_16x16x32_bf16 v[94:97], v[164:167], v[208:211], v[94:97]
	v_mfma_f32_16x16x32_bf16 v[90:93], v[172:175], v[208:211], v[90:93]
	v_mfma_f32_16x16x32_bf16 v[78:81], v[164:167], v[216:219], v[78:81]
	v_mfma_f32_16x16x32_bf16 v[74:77], v[172:175], v[216:219], v[74:77]
	v_mfma_f32_16x16x32_bf16 v[126:129], v[168:171], v[196:199], v[126:129]
	v_mfma_f32_16x16x32_bf16 v[122:125], v[176:179], v[196:199], v[122:125]
	v_mfma_f32_16x16x32_bf16 v[110:113], v[168:171], v[204:207], v[110:113]
	v_mfma_f32_16x16x32_bf16 v[106:109], v[176:179], v[204:207], v[106:109]
	v_mfma_f32_16x16x32_bf16 v[94:97], v[168:171], v[212:215], v[94:97]
	v_mfma_f32_16x16x32_bf16 v[90:93], v[176:179], v[212:215], v[90:93]
	v_mfma_f32_16x16x32_bf16 v[78:81], v[168:171], v[220:223], v[78:81]
	v_mfma_f32_16x16x32_bf16 v[74:77], v[176:179], v[220:223], v[74:77]
	s_setprio 0
	s_barrier
; #define PG8_STAGE(bufoff, gbase, voff) do { _Pragma("unroll") for (int _i = 0; _i < 2; ++_i) \
;         __builtin_amdgcn_global_load_lds((const unsigned*)((const char*)(gbase) + (voff)[_i]), (LAS unsigned*)(lds + (bufoff) + ldsw + _i * 8192), 16, 0, 0); } while (0)
; #define PG8_LDA(dst, b, h) do { _Pragma("unroll") for (int m = 0; m < 4; ++m) _Pragma("unroll") for (int k = 0; k < 2; ++k) dst[m][k] = *(const LAS bf16x8*)(lds + PG8_SA(b, h) + aoff + m * 2048 + k * 1024); } while (0)
; #define PG8_MMA(ai, bj, At, Bt) do { __builtin_amdgcn_s_setprio(3); _Pragma("unroll") for (int m = 0; m < 4; ++m) _Pragma("unroll") for (int n = 0; n < 2; ++n) _Pragma("unroll") for (int k = 0; k < 2; ++k) \
;         acc[ai][bj][m][n] = __builtin_amdgcn_mfma_f32_16x16x32_bf16(Bt[n][k], At[m][k], acc[ai][bj][m][n], 0, 0, 0); __builtin_amdgcn_s_setprio(0); } while (0)
; #define PG8_WAIT_V(n) asm volatile("s_waitcnt vmcnt(" #n ")" ::: "memory")
; #define PG8_WAIT_L(n) asm volatile("s_waitcnt lgkmcnt(" #n ")" ::: "memory")
; #define PG8_BAR __builtin_amdgcn_s_barrier()
; #define PG8_SCHED __builtin_amdgcn_sched_barrier(0)
; template <class Epi, bool ALIGN_EPI>
; __device__ __forceinline__ void gemm_phase(LAS unsigned char* lds, const Gemm g, const StaticOrder& S, const Epi& E) {
;     ...
;             PG8_LDA(At, 1, 1); PG8_STAGE(PG8_SB(1, 0), b3, voffB); PG8_STAGE(PG8_SB(1, 1), b3 + hstep, voffB); PG8_STAGE(PG8_SA(1, 0), a3, voffA);
;             PG8_WAIT_V(8); PG8_WAIT_L(0); PG8_BAR; PG8_MMA(1, 0, At, B0); PG8_MMA(1, 1, At, B1); PG8_BAR; PG8_SCHED;
;         }
;         if constexpr (ALIGN_EPI) { if (wr == 0) PG8_BAR; }
	s_add_i32 s9, s9, s33
	v_lshl_add_u64 v[224:225], v[224:225], 0, s[62:63]
	s_mov_b32 m0, s9
	ds_read_b128 v[180:183], v194 offset:49152
	ds_read_b128 v[196:199], v194 offset:50176
	ds_read_b128 v[200:203], v194 offset:51200
	ds_read_b128 v[204:207], v194 offset:52224
	ds_read_b128 v[208:211], v194 offset:53248
	ds_read_b128 v[212:215], v194 offset:54272
	ds_read_b128 v[216:219], v194 offset:55296
	ds_read_b128 v[220:223], v194 offset:56320
	global_load_lds_dwordx4 v[224:225], off
	s_add_i32 m0, s9, 0x2000
	s_add_u32 s50, s82, 0x40080
	v_lshl_add_u64 v[224:225], v[226:227], 0, s[62:63]
	s_addc_u32 s51, s83, 0
	s_add_i32 s9, s89, s33
	global_load_lds_dwordx4 v[224:225], off
	v_lshl_add_u64 v[224:225], s[50:51], 0, v[132:133]
	s_mov_b32 m0, s9
	s_nop 0
	global_load_lds_dwordx4 v[224:225], off
	v_lshl_add_u64 v[224:225], s[50:51], 0, v[136:137]
	s_add_i32 m0, s9, 0x2000
	s_nop 0
	global_load_lds_dwordx4 v[224:225], off
	v_lshl_add_u64 v[224:225], v[228:229], 0, s[62:63]
	s_mov_b32 m0, s93
	s_nop 0
	global_load_lds_dwordx4 v[224:225], off
	v_lshl_add_u64 v[224:225], v[230:231], 0, s[62:63]
	s_mov_b32 m0, s94
	s_nop 0
	global_load_lds_dwordx4 v[224:225], off
	s_waitcnt vmcnt(8)
	s_waitcnt lgkmcnt(0)
	s_barrier
	s_setprio 3
	s_waitcnt lgkmcnt(0)
	v_mfma_f32_16x16x32_bf16 v[54:57], v[148:151], v[180:183], v[54:57]
	v_mfma_f32_16x16x32_bf16 v[50:53], v[156:159], v[180:183], v[50:53]
	v_mfma_f32_16x16x32_bf16 v[38:41], v[148:151], v[200:203], v[38:41]
	v_mfma_f32_16x16x32_bf16 v[34:37], v[156:159], v[200:203], v[34:37]
	v_mfma_f32_16x16x32_bf16 v[22:25], v[148:151], v[208:211], v[22:25]
	v_mfma_f32_16x16x32_bf16 v[18:21], v[156:159], v[208:211], v[18:21]
	v_mfma_f32_16x16x32_bf16 v[6:9], v[148:151], v[216:219], v[6:9]
	v_mfma_f32_16x16x32_bf16 v[2:5], v[156:159], v[216:219], v[2:5]
	v_mfma_f32_16x16x32_bf16 v[54:57], v[152:155], v[196:199], v[54:57]
	v_mfma_f32_16x16x32_bf16 v[50:53], v[160:163], v[196:199], v[50:53]
	v_mfma_f32_16x16x32_bf16 v[38:41], v[152:155], v[204:207], v[38:41]
	v_mfma_f32_16x16x32_bf16 v[34:37], v[160:163], v[204:207], v[34:37]
	v_mfma_f32_16x16x32_bf16 v[22:25], v[152:155], v[212:215], v[22:25]
	v_mfma_f32_16x16x32_bf16 v[18:21], v[160:163], v[212:215], v[18:21]
	v_mfma_f32_16x16x32_bf16 v[6:9], v[152:155], v[220:223], v[6:9]
	v_mfma_f32_16x16x32_bf16 v[2:5], v[160:163], v[220:223], v[2:5]
	v_mfma_f32_16x16x32_bf16 v[62:65], v[164:167], v[180:183], v[62:65]
	v_mfma_f32_16x16x32_bf16 v[58:61], v[172:175], v[180:183], v[58:61]
	v_mfma_f32_16x16x32_bf16 v[46:49], v[164:167], v[200:203], v[46:49]
	v_mfma_f32_16x16x32_bf16 v[42:45], v[172:175], v[200:203], v[42:45]
	v_mfma_f32_16x16x32_bf16 v[30:33], v[164:167], v[208:211], v[30:33]
	v_mfma_f32_16x16x32_bf16 v[26:29], v[172:175], v[208:211], v[26:29]
	v_mfma_f32_16x16x32_bf16 v[14:17], v[164:167], v[216:219], v[14:17]
	v_mfma_f32_16x16x32_bf16 v[10:13], v[172:175], v[216:219], v[10:13]
	v_mfma_f32_16x16x32_bf16 v[62:65], v[168:171], v[196:199], v[62:65]
	v_mfma_f32_16x16x32_bf16 v[58:61], v[176:179], v[196:199], v[58:61]
	v_mfma_f32_16x16x32_bf16 v[46:49], v[168:171], v[204:207], v[46:49]
	v_mfma_f32_16x16x32_bf16 v[42:45], v[176:179], v[204:207], v[42:45]
	v_mfma_f32_16x16x32_bf16 v[30:33], v[168:171], v[212:215], v[30:33]
	v_mfma_f32_16x16x32_bf16 v[26:29], v[176:179], v[212:215], v[26:29]
	v_mfma_f32_16x16x32_bf16 v[14:17], v[168:171], v[220:223], v[14:17]
	v_mfma_f32_16x16x32_bf16 v[10:13], v[176:179], v[220:223], v[10:13]
	s_setprio 0
	s_barrier
	s_add_i32 s8, s8, 2
	s_add_u32 s80, s80, 0x100
	s_addc_u32 s81, s81, 0
	s_add_u32 vcc_lo, vcc_lo, 0x100
	s_addc_u32 vcc_hi, vcc_hi, 0
	s_cmp_gt_u32 s8, 13
	s_cbranch_scc0 .LBB0_293
	s_and_b64 vcc, exec, s[64:65]
	s_cbranch_vccz .LBB0_296
	s_barrier

; #define PG8_STAGE(bufoff, gbase, voff) do { _Pragma("unroll") for (int _i = 0; _i < 2; ++_i) \
;         __builtin_amdgcn_global_load_lds((const unsigned*)((const char*)(gbase) + (voff)[_i]), (LAS unsigned*)(lds + (bufoff) + ldsw + _i * 8192), 16, 0, 0); } while (0)
; #define PG8_LDA(dst, b, h) do { _Pragma("unroll") for (int m = 0; m < 4; ++m) _Pragma("unroll") for (int k = 0; k < 2; ++k) dst[m][k] = *(const LAS bf16x8*)(lds + PG8_SA(b, h) + aoff + m * 2048 + k * 1024); } while (0)
; #define PG8_LDB(dst, b, h) do { _Pragma("unroll") for (int n = 0; n < 2; ++n) _Pragma("unroll") for (int k = 0; k < 2; ++k) dst[n][k] = *(const LAS bf16x8*)(lds + PG8_SB(b, h) + boff + n * 2048 + k * 1024); } while (0)
; #define PG8_MMA(ai, bj, At, Bt) do { __builtin_amdgcn_s_setprio(3); _Pragma("unroll") for (int m = 0; m < 4; ++m) _Pragma("unroll") for (int n = 0; n < 2; ++n) _Pragma("unroll") for (int k = 0; k < 2; ++k) \
;         acc[ai][bj][m][n] = __builtin_amdgcn_mfma_f32_16x16x32_bf16(Bt[n][k], At[m][k], acc[ai][bj][m][n], 0, 0, 0); __builtin_amdgcn_s_setprio(0); } while (0)
; #define PG8_BAR __builtin_amdgcn_s_barrier()
; template <class Epi, bool ALIGN_EPI>
; __device__ __forceinline__ void gemm_phase(LAS unsigned char* lds, const Gemm g, const StaticOrder& S, const Epi& E) {
;     ...
;         const bool has_next = S.next(ui + 1, nxt);
;         const char* nA = has_next ? (const char*)g.A + (size_t)nxt.pm * tstep : cA; const char* nB = has_next ? (const char*)g.Bt + (size_t)nxt.pn * tstep : cB;
;         for (int t = 0; t < nt; t += 2) {
;             const bool last = (t == nt - 2);
;             const char* a1 = cA + (size_t)(t + 1) * kstep;
;             const char* a2 = last ? nA : cA + (size_t)(t + 2) * kstep; const char* b2 = last ? nB : cB + (size_t)(t + 2) * kstep;
;             const char* a3 = a2 + kstep; const char* b3 = b2 + kstep;
;             PG8_LDB(B0, 0, 0); PG8_LDB(B1, 0, 1); PG8_SCHED; PG8_LDA(At, 0, 0); PG8_STAGE(PG8_SA(1, 1), a1 + hstep, voffA);
;             PG8_WAIT_V(8); PG8_WAIT_L(0); PG8_BAR; PG8_MMA(0, 0, At, B0); PG8_MMA(0, 1, At, B1); PG8_BAR; PG8_SCHED;
;             PG8_LDA(At, 0, 1); PG8_STAGE(PG8_SB(0, 0), b2, voffB); PG8_STAGE(PG8_SB(0, 1), b2 + hstep, voffB); PG8_STAGE(PG8_SA(0, 0), a2, voffA);
;             PG8_WAIT_V(8); PG8_WAIT_L(0); PG8_BAR; PG8_MMA(1, 0, At, B0); PG8_MMA(1, 1, At, B1); PG8_BAR; PG8_SCHED;
.LBB0_519:
	s_ashr_i32 s55, s54, 31
	s_lshl_b64 s[56:57], s[54:55], 19
	s_add_u32 s56, s26, s56
	s_addc_u32 s57, s27, s57
	s_and_b64 s[58:59], s[4:5], exec
	s_cselect_b32 s55, s57, s65
	s_cselect_b32 s61, s56, s64
	s_ashr_i32 s53, s52, 31
	s_lshl_b64 s[58:59], s[52:53], 19
	s_add_u32 s58, s10, s58
	s_addc_u32 s59, s11, s59
	s_and_b64 s[68:69], s[4:5], exec
	s_cselect_b32 s53, s59, s67
	s_cselect_b32 s82, s58, s66
	s_add_u32 s64, s64, 0x40080
	s_addc_u32 s65, s65, 0
	s_add_u32 s83, s66, 0x100
	s_addc_u32 s84, s67, 0
	s_mov_b32 s85, -2
	s_waitcnt lgkmcnt(0)
	ds_read_b128 v[130:133], v214
	ds_read_b128 v[134:137], v214 offset:1024
	ds_read_b128 v[138:141], v214 offset:2048
	ds_read_b128 v[142:145], v214 offset:3072
	ds_read_b128 v[146:149], v215
	ds_read_b128 v[150:153], v215 offset:1024
	ds_read_b128 v[154:157], v215 offset:2048
	ds_read_b128 v[158:161], v215 offset:3072
	s_add_u32 s66, s64, 0xfffc0080
	s_addc_u32 s67, s65, -1
	s_cmp_eq_u32 s85, 12
	s_cselect_b32 s69, s55, s67
	s_cselect_b32 s68, s61, s66
	s_cselect_b32 s67, s53, s84
	s_cselect_b32 s66, s82, s83
	v_lshl_add_u64 v[222:223], s[64:65], 0, v[186:187]
	s_add_i32 m0, s63, 0xc000
	ds_read_b128 v[162:165], v216
	ds_read_b128 v[166:169], v216 offset:1024
	ds_read_b128 v[170:173], v216 offset:2048
	ds_read_b128 v[174:177], v216 offset:3072
	ds_read_b128 v[194:197], v216 offset:4096
	ds_read_b128 v[198:201], v216 offset:5120
	ds_read_b128 v[202:205], v216 offset:6144
	ds_read_b128 v[218:221], v216 offset:7168
	global_load_lds_dwordx4 v[222:223], off
	v_lshl_add_u64 v[222:223], s[64:65], 0, v[188:189]
	s_add_i32 m0, s63, 0xe000
	s_nop 0
	global_load_lds_dwordx4 v[222:223], off
	s_waitcnt vmcnt(8)
	s_waitcnt lgkmcnt(0)
	s_barrier
	s_setprio 3
	s_waitcnt lgkmcnt(0)
	v_mfma_f32_16x16x32_bf16 v[126:129], v[130:133], v[162:165], 0
	v_mfma_f32_16x16x32_bf16 v[122:125], v[138:141], v[162:165], 0
	v_mfma_f32_16x16x32_bf16 v[110:113], v[130:133], v[170:173], 0
	v_mfma_f32_16x16x32_bf16 v[106:109], v[138:141], v[170:173], 0
	v_mfma_f32_16x16x32_bf16 v[94:97], v[130:133], v[194:197], 0
	v_mfma_f32_16x16x32_bf16 v[90:93], v[138:141], v[194:197], 0
	v_mfma_f32_16x16x32_bf16 v[78:81], v[130:133], v[202:205], 0
	v_mfma_f32_16x16x32_bf16 v[74:77], v[138:141], v[202:205], 0
	v_mfma_f32_16x16x32_bf16 v[126:129], v[134:137], v[166:169], v[126:129]
	v_mfma_f32_16x16x32_bf16 v[122:125], v[142:145], v[166:169], v[122:125]
	v_mfma_f32_16x16x32_bf16 v[110:113], v[134:137], v[174:177], v[110:113]
	v_mfma_f32_16x16x32_bf16 v[106:109], v[142:145], v[174:177], v[106:109]
	v_mfma_f32_16x16x32_bf16 v[94:97], v[134:137], v[198:201], v[94:97]
	v_mfma_f32_16x16x32_bf16 v[90:93], v[142:145], v[198:201], v[90:93]
	v_mfma_f32_16x16x32_bf16 v[78:81], v[134:137], v[218:221], v[78:81]
	v_mfma_f32_16x16x32_bf16 v[74:77], v[142:145], v[218:221], v[74:77]
	v_mfma_f32_16x16x32_bf16 v[118:121], v[146:149], v[162:165], 0
	v_mfma_f32_16x16x32_bf16 v[114:117], v[154:157], v[162:165], 0
	v_mfma_f32_16x16x32_bf16 v[102:105], v[146:149], v[170:173], 0
	v_mfma_f32_16x16x32_bf16 v[98:101], v[154:157], v[170:173], 0
	v_mfma_f32_16x16x32_bf16 v[86:89], v[146:149], v[194:197], 0
	v_mfma_f32_16x16x32_bf16 v[82:85], v[154:157], v[194:197], 0
	v_mfma_f32_16x16x32_bf16 v[70:73], v[146:149], v[202:205], 0
	v_mfma_f32_16x16x32_bf16 v[66:69], v[154:157], v[202:205], 0
	v_mfma_f32_16x16x32_bf16 v[118:121], v[150:153], v[166:169], v[118:121]
	v_mfma_f32_16x16x32_bf16 v[114:117], v[158:161], v[166:169], v[114:117]
	v_mfma_f32_16x16x32_bf16 v[102:105], v[150:153], v[174:177], v[102:105]
	v_mfma_f32_16x16x32_bf16 v[98:101], v[158:161], v[174:177], v[98:101]
	v_mfma_f32_16x16x32_bf16 v[86:89], v[150:153], v[198:201], v[86:89]
	v_mfma_f32_16x16x32_bf16 v[82:85], v[158:161], v[198:201], v[82:85]
	v_mfma_f32_16x16x32_bf16 v[70:73], v[150:153], v[218:221], v[70:73]
	v_mfma_f32_16x16x32_bf16 v[66:69], v[158:161], v[218:221], v[66:69]
	s_setprio 0
	s_barrier
	s_add_i32 s86, s80, s33
	v_lshl_add_u64 v[222:223], s[66:67], 0, v[180:181]
	s_mov_b32 m0, s86
	ds_read_b128 v[162:165], v216 offset:16384
	ds_read_b128 v[166:169], v216 offset:17408
	ds_read_b128 v[170:173], v216 offset:18432
	ds_read_b128 v[174:177], v216 offset:19456
	ds_read_b128 v[194:197], v216 offset:20480
	ds_read_b128 v[198:201], v216 offset:21504
	ds_read_b128 v[202:205], v216 offset:22528
	ds_read_b128 v[218:221], v216 offset:23552
	global_load_lds_dwordx4 v[222:223], off
	s_add_i32 m0, s86, 0x2000
	s_add_u32 s86, s66, 0x40000
	v_lshl_add_u64 v[224:225], s[66:67], 0, v[184:185]
	s_addc_u32 s87, s67, 0
	s_add_i32 s88, s81, s33
	global_load_lds_dwordx4 v[224:225], off
	v_lshl_add_u64 v[226:227], s[86:87], 0, v[180:181]
	s_mov_b32 m0, s88
	v_lshl_add_u64 v[228:229], s[68:69], 0, v[182:183]
	global_load_lds_dwordx4 v[226:227], off
	v_lshl_add_u64 v[226:227], s[86:87], 0, v[184:185]
	s_add_i32 m0, s88, 0x2000
	s_nop 0
	global_load_lds_dwordx4 v[226:227], off
	v_lshl_add_u64 v[226:227], s[68:69], 0, v[178:179]
	s_mov_b32 m0, s63
	s_nop 0
	global_load_lds_dwordx4 v[226:227], off
	s_mov_b32 m0, s70
	s_nop 0
	global_load_lds_dwordx4 v[228:229], off
	s_waitcnt vmcnt(8)
	s_waitcnt lgkmcnt(0)
	s_barrier
; #define PG8_STAGE(bufoff, gbase, voff) do { _Pragma("unroll") for (int _i = 0; _i < 2; ++_i) \
;         __builtin_amdgcn_global_load_lds((const unsigned*)((const char*)(gbase) + (voff)[_i]), (LAS unsigned*)(lds + (bufoff) + ldsw + _i * 8192), 16, 0, 0); } while (0)
; #define PG8_LDA(dst, b, h) do { _Pragma("unroll") for (int m = 0; m < 4; ++m) _Pragma("unroll") for (int k = 0; k < 2; ++k) dst[m][k] = *(const LAS bf16x8*)(lds + PG8_SA(b, h) + aoff + m * 2048 + k * 1024); } while (0)
; #define PG8_LDB(dst, b, h) do { _Pragma("unroll") for (int n = 0; n < 2; ++n) _Pragma("unroll") for (int k = 0; k < 2; ++k) dst[n][k] = *(const LAS bf16x8*)(lds + PG8_SB(b, h) + boff + n * 2048 + k * 1024); } while (0)
; #define PG8_MMA(ai, bj, At, Bt) do { __builtin_amdgcn_s_setprio(3); _Pragma("unroll") for (int m = 0; m < 4; ++m) _Pragma("unroll") for (int n = 0; n < 2; ++n) _Pragma("unroll") for (int k = 0; k < 2; ++k) \
;         acc[ai][bj][m][n] = __builtin_amdgcn_mfma_f32_16x16x32_bf16(Bt[n][k], At[m][k], acc[ai][bj][m][n], 0, 0, 0); __builtin_amdgcn_s_setprio(0); } while (0)
; #define PG8_WAIT_V(n) asm volatile("s_waitcnt vmcnt(" #n ")" ::: "memory")
; #define PG8_WAIT_L(n) asm volatile("s_waitcnt lgkmcnt(" #n ")" ::: "memory")
; #define PG8_BAR __builtin_amdgcn_s_barrier()
; #define PG8_SCHED __builtin_amdgcn_sched_barrier(0)
; template <class Epi, bool ALIGN_EPI>
; __device__ __forceinline__ void gemm_phase(LAS unsigned char* lds, const Gemm g, const StaticOrder& S, const Epi& E) {
;     ...
;             PG8_LDA(At, 0, 1); PG8_STAGE(PG8_SB(0, 0), b2, voffB); PG8_STAGE(PG8_SB(0, 1), b2 + hstep, voffB); PG8_STAGE(PG8_SA(0, 0), a2, voffA);
;             PG8_WAIT_V(8); PG8_WAIT_L(0); PG8_BAR; PG8_MMA(1, 0, At, B0); PG8_MMA(1, 1, At, B1); PG8_BAR; PG8_SCHED;
;             PG8_LDB(B0, 1, 0); PG8_LDB(B1, 1, 1); PG8_SCHED; PG8_LDA(At, 1, 0); PG8_STAGE(PG8_SA(0, 1), a2 + hstep, voffA);
;             PG8_WAIT_V(8); PG8_WAIT_L(0); PG8_BAR; PG8_MMA(0, 0, At, B0); PG8_MMA(0, 1, At, B1); PG8_BAR; PG8_SCHED;
	s_setprio 3
	s_waitcnt lgkmcnt(0)
	v_mfma_f32_16x16x32_bf16 v[62:65], v[130:133], v[162:165], 0
	v_mfma_f32_16x16x32_bf16 v[58:61], v[138:141], v[162:165], 0
	v_mfma_f32_16x16x32_bf16 v[46:49], v[130:133], v[170:173], 0
	v_mfma_f32_16x16x32_bf16 v[42:45], v[138:141], v[170:173], 0
	v_mfma_f32_16x16x32_bf16 v[30:33], v[130:133], v[194:197], 0
	v_mfma_f32_16x16x32_bf16 v[26:29], v[138:141], v[194:197], 0
	v_mfma_f32_16x16x32_bf16 v[14:17], v[130:133], v[202:205], 0
	v_mfma_f32_16x16x32_bf16 v[10:13], v[138:141], v[202:205], 0
	v_mfma_f32_16x16x32_bf16 v[62:65], v[134:137], v[166:169], v[62:65]
	v_mfma_f32_16x16x32_bf16 v[58:61], v[142:145], v[166:169], v[58:61]
	v_mfma_f32_16x16x32_bf16 v[46:49], v[134:137], v[174:177], v[46:49]
	v_mfma_f32_16x16x32_bf16 v[42:45], v[142:145], v[174:177], v[42:45]
	v_mfma_f32_16x16x32_bf16 v[30:33], v[134:137], v[198:201], v[30:33]
	v_mfma_f32_16x16x32_bf16 v[26:29], v[142:145], v[198:201], v[26:29]
	v_mfma_f32_16x16x32_bf16 v[14:17], v[134:137], v[218:221], v[14:17]
	v_mfma_f32_16x16x32_bf16 v[10:13], v[142:145], v[218:221], v[10:13]
	v_mfma_f32_16x16x32_bf16 v[54:57], v[146:149], v[162:165], 0
	v_mfma_f32_16x16x32_bf16 v[50:53], v[154:157], v[162:165], 0
	v_mfma_f32_16x16x32_bf16 v[38:41], v[146:149], v[170:173], 0
	v_mfma_f32_16x16x32_bf16 v[34:37], v[154:157], v[170:173], 0
	v_mfma_f32_16x16x32_bf16 v[22:25], v[146:149], v[194:197], 0
	v_mfma_f32_16x16x32_bf16 v[18:21], v[154:157], v[194:197], 0
	v_mfma_f32_16x16x32_bf16 v[6:9], v[146:149], v[202:205], 0
	v_mfma_f32_16x16x32_bf16 v[2:5], v[154:157], v[202:205], 0
	v_mfma_f32_16x16x32_bf16 v[54:57], v[150:153], v[166:169], v[54:57]
	v_mfma_f32_16x16x32_bf16 v[50:53], v[158:161], v[166:169], v[50:53]
	v_mfma_f32_16x16x32_bf16 v[38:41], v[150:153], v[174:177], v[38:41]
	v_mfma_f32_16x16x32_bf16 v[34:37], v[158:161], v[174:177], v[34:37]
	v_mfma_f32_16x16x32_bf16 v[22:25], v[150:153], v[198:201], v[22:25]
	v_mfma_f32_16x16x32_bf16 v[18:21], v[158:161], v[198:201], v[18:21]
	v_mfma_f32_16x16x32_bf16 v[6:9], v[150:153], v[218:221], v[6:9]
	v_mfma_f32_16x16x32_bf16 v[2:5], v[158:161], v[218:221], v[2:5]
	s_setprio 0
	s_barrier
	s_add_i32 s86, 0, 0x18000
	s_add_i32 s87, 0, 0x1c000
	v_add_u32_e32 v142, s86, v212
	v_add_u32_e32 v158, s87, v212
	ds_read_b128 v[130:133], v142
	ds_read_b128 v[134:137], v142 offset:1024
	ds_read_b128 v[138:141], v142 offset:2048
	ds_read_b128 v[142:145], v142 offset:3072
	ds_read_b128 v[146:149], v158
	ds_read_b128 v[150:153], v158 offset:1024
	ds_read_b128 v[154:157], v158 offset:2048
	ds_read_b128 v[158:161], v158 offset:3072
	s_add_u32 s68, s68, 0x40000
	s_addc_u32 s69, s69, 0
	s_mov_b32 m0, s71
	v_lshl_add_u64 v[230:231], s[68:69], 0, v[178:179]
	ds_read_b128 v[162:165], v216 offset:32768
	ds_read_b128 v[166:169], v216 offset:33792
	ds_read_b128 v[170:173], v216 offset:34816
	ds_read_b128 v[174:177], v216 offset:35840
	ds_read_b128 v[194:197], v216 offset:36864
	ds_read_b128 v[198:201], v216 offset:37888
	ds_read_b128 v[202:205], v216 offset:38912
	ds_read_b128 v[218:221], v216 offset:39936
	global_load_lds_dwordx4 v[230:231], off
	v_lshl_add_u64 v[230:231], s[68:69], 0, v[182:183]
	s_mov_b32 m0, s72
	s_nop 0
	global_load_lds_dwordx4 v[230:231], off
	s_waitcnt vmcnt(8)
	s_waitcnt lgkmcnt(0)
	s_barrier
	s_setprio 3
	s_waitcnt lgkmcnt(0)
	v_mfma_f32_16x16x32_bf16 v[126:129], v[130:133], v[162:165], v[126:129]
	v_mfma_f32_16x16x32_bf16 v[122:125], v[138:141], v[162:165], v[122:125]
	v_mfma_f32_16x16x32_bf16 v[110:113], v[130:133], v[170:173], v[110:113]
	v_mfma_f32_16x16x32_bf16 v[106:109], v[138:141], v[170:173], v[106:109]
	v_mfma_f32_16x16x32_bf16 v[94:97], v[130:133], v[194:197], v[94:97]
	v_mfma_f32_16x16x32_bf16 v[90:93], v[138:141], v[194:197], v[90:93]
	v_mfma_f32_16x16x32_bf16 v[78:81], v[130:133], v[202:205], v[78:81]
	v_mfma_f32_16x16x32_bf16 v[74:77], v[138:141], v[202:205], v[74:77]
	v_mfma_f32_16x16x32_bf16 v[126:129], v[134:137], v[166:169], v[126:129]
	v_mfma_f32_16x16x32_bf16 v[122:125], v[142:145], v[166:169], v[122:125]
	v_mfma_f32_16x16x32_bf16 v[110:113], v[134:137], v[174:177], v[110:113]
	v_mfma_f32_16x16x32_bf16 v[106:109], v[142:145], v[174:177], v[106:109]
	v_mfma_f32_16x16x32_bf16 v[94:97], v[134:137], v[198:201], v[94:97]
	v_mfma_f32_16x16x32_bf16 v[90:93], v[142:145], v[198:201], v[90:93]
	v_mfma_f32_16x16x32_bf16 v[78:81], v[134:137], v[218:221], v[78:81]
	v_mfma_f32_16x16x32_bf16 v[74:77], v[142:145], v[218:221], v[74:77]
	v_mfma_f32_16x16x32_bf16 v[118:121], v[146:149], v[162:165], v[118:121]
	v_mfma_f32_16x16x32_bf16 v[114:117], v[154:157], v[162:165], v[114:117]
	v_mfma_f32_16x16x32_bf16 v[102:105], v[146:149], v[170:173], v[102:105]
	v_mfma_f32_16x16x32_bf16 v[98:101], v[154:157], v[170:173], v[98:101]
	v_mfma_f32_16x16x32_bf16 v[86:89], v[146:149], v[194:197], v[86:89]
	v_mfma_f32_16x16x32_bf16 v[82:85], v[154:157], v[194:197], v[82:85]
	v_mfma_f32_16x16x32_bf16 v[70:73], v[146:149], v[202:205], v[70:73]
	v_mfma_f32_16x16x32_bf16 v[66:69], v[154:157], v[202:205], v[66:69]
	v_mfma_f32_16x16x32_bf16 v[118:121], v[150:153], v[166:169], v[118:121]
	v_mfma_f32_16x16x32_bf16 v[114:117], v[158:161], v[166:169], v[114:117]
	v_mfma_f32_16x16x32_bf16 v[102:105], v[150:153], v[174:177], v[102:105]
	v_mfma_f32_16x16x32_bf16 v[98:101], v[158:161], v[174:177], v[98:101]
	v_mfma_f32_16x16x32_bf16 v[86:89], v[150:153], v[198:201], v[86:89]
	v_mfma_f32_16x16x32_bf16 v[82:85], v[158:161], v[198:201], v[82:85]
	v_mfma_f32_16x16x32_bf16 v[70:73], v[150:153], v[218:221], v[70:73]
	v_mfma_f32_16x16x32_bf16 v[66:69], v[158:161], v[218:221], v[66:69]
	s_setprio 0
	s_barrier
; #define PG8_STAGE(bufoff, gbase, voff) do { _Pragma("unroll") for (int _i = 0; _i < 2; ++_i) \
;         __builtin_amdgcn_global_load_lds((const unsigned*)((const char*)(gbase) + (voff)[_i]), (LAS unsigned*)(lds + (bufoff) + ldsw + _i * 8192), 16, 0, 0); } while (0)
; #define PG8_LDA(dst, b, h) do { _Pragma("unroll") for (int m = 0; m < 4; ++m) _Pragma("unroll") for (int k = 0; k < 2; ++k) dst[m][k] = *(const LAS bf16x8*)(lds + PG8_SA(b, h) + aoff + m * 2048 + k * 1024); } while (0)
; #define PG8_LDB(dst, b, h) do { _Pragma("unroll") for (int n = 0; n < 2; ++n) _Pragma("unroll") for (int k = 0; k < 2; ++k) dst[n][k] = *(const LAS bf16x8*)(lds + PG8_SB(b, h) + boff + n * 2048 + k * 1024); } while (0)
; #define PG8_WAIT_V(n) asm volatile("s_waitcnt vmcnt(" #n ")" ::: "memory")
; #define PG8_BAR __builtin_amdgcn_s_barrier()
; template <class Epi, bool ALIGN_EPI>
; __device__ __forceinline__ void gemm_phase(LAS unsigned char* lds, const Gemm g, const StaticOrder& S, const Epi& E) {
;     ...
;         for (int t = 0; t < nt; t += 2) {
;             const bool last = (t == nt - 2);
;             const char* a1 = cA + (size_t)(t + 1) * kstep;
;             const char* a2 = last ? nA : cA + (size_t)(t + 2) * kstep; const char* b2 = last ? nB : cB + (size_t)(t + 2) * kstep;
;             const char* a3 = a2 + kstep; const char* b3 = b2 + kstep;
;             PG8_LDB(B0, 0, 0); PG8_LDB(B1, 0, 1); PG8_SCHED; PG8_LDA(At, 0, 0); PG8_STAGE(PG8_SA(1, 1), a1 + hstep, voffA);
;             PG8_WAIT_V(8); PG8_WAIT_L(0); PG8_BAR; PG8_MMA(0, 0, At, B0); PG8_MMA(0, 1, At, B1); PG8_BAR; PG8_SCHED;
;             PG8_LDA(At, 0, 1); PG8_STAGE(PG8_SB(0, 0), b2, voffB); PG8_STAGE(PG8_SB(0, 1), b2 + hstep, voffB); PG8_STAGE(PG8_SA(0, 0), a2, voffA);
;             PG8_WAIT_V(8); PG8_WAIT_L(0); PG8_BAR; PG8_MMA(1, 0, At, B0); PG8_MMA(1, 1, At, B1); PG8_BAR; PG8_SCHED;
;             PG8_LDB(B0, 1, 0); PG8_LDB(B1, 1, 1); PG8_SCHED; PG8_LDA(At, 1, 0); PG8_STAGE(PG8_SA(0, 1), a2 + hstep, voffA);
;             PG8_WAIT_V(8); PG8_WAIT_L(0); PG8_BAR; PG8_MMA(0, 0, At, B0); PG8_MMA(0, 1, At, B1); PG8_BAR; PG8_SCHED;
;             PG8_LDA(At, 1, 1); PG8_STAGE(PG8_SB(1, 0), b3, voffB); PG8_STAGE(PG8_SB(1, 1), b3 + hstep, voffB); PG8_STAGE(PG8_SA(1, 0), a3, voffA);
;             PG8_WAIT_V(8); PG8_WAIT_L(0); PG8_BAR; PG8_MMA(1, 0, At, B0); PG8_MMA(1, 1, At, B1); PG8_BAR; PG8_SCHED;
	s_add_i32 s68, s86, s33
	v_lshl_add_u64 v[222:223], v[222:223], 0, s[18:19]
	s_mov_b32 m0, s68
	ds_read_b128 v[162:165], v216 offset:49152
	ds_read_b128 v[166:169], v216 offset:50176
	ds_read_b128 v[170:173], v216 offset:51200
	ds_read_b128 v[174:177], v216 offset:52224
	ds_read_b128 v[194:197], v216 offset:53248
	ds_read_b128 v[198:201], v216 offset:54272
	ds_read_b128 v[202:205], v216 offset:55296
	ds_read_b128 v[218:221], v216 offset:56320
	global_load_lds_dwordx4 v[222:223], off
	s_add_i32 m0, s68, 0x2000
	s_add_u32 s66, s66, 0x40080
	v_lshl_add_u64 v[222:223], v[224:225], 0, s[18:19]
	s_addc_u32 s67, s67, 0
	s_add_i32 s68, s87, s33
	global_load_lds_dwordx4 v[222:223], off
	v_lshl_add_u64 v[222:223], s[66:67], 0, v[180:181]
	s_mov_b32 m0, s68
	s_nop 0
	global_load_lds_dwordx4 v[222:223], off
	v_lshl_add_u64 v[222:223], s[66:67], 0, v[184:185]
	s_add_i32 m0, s68, 0x2000
	s_nop 0
	global_load_lds_dwordx4 v[222:223], off
	v_lshl_add_u64 v[222:223], v[226:227], 0, s[18:19]
	s_mov_b32 m0, s78
	s_nop 0
	global_load_lds_dwordx4 v[222:223], off
	v_lshl_add_u64 v[222:223], v[228:229], 0, s[18:19]
	s_mov_b32 m0, s79
	s_nop 0
	global_load_lds_dwordx4 v[222:223], off
	s_waitcnt vmcnt(8)
	s_waitcnt lgkmcnt(0)
	s_barrier
	s_setprio 3
	s_waitcnt lgkmcnt(0)
	v_mfma_f32_16x16x32_bf16 v[62:65], v[130:133], v[162:165], v[62:65]
	v_mfma_f32_16x16x32_bf16 v[58:61], v[138:141], v[162:165], v[58:61]
	v_mfma_f32_16x16x32_bf16 v[46:49], v[130:133], v[170:173], v[46:49]
	v_mfma_f32_16x16x32_bf16 v[42:45], v[138:141], v[170:173], v[42:45]
	v_mfma_f32_16x16x32_bf16 v[30:33], v[130:133], v[194:197], v[30:33]
	v_mfma_f32_16x16x32_bf16 v[26:29], v[138:141], v[194:197], v[26:29]
	v_mfma_f32_16x16x32_bf16 v[14:17], v[130:133], v[202:205], v[14:17]
	v_mfma_f32_16x16x32_bf16 v[10:13], v[138:141], v[202:205], v[10:13]
	v_mfma_f32_16x16x32_bf16 v[62:65], v[134:137], v[166:169], v[62:65]
	v_mfma_f32_16x16x32_bf16 v[58:61], v[142:145], v[166:169], v[58:61]
	v_mfma_f32_16x16x32_bf16 v[46:49], v[134:137], v[174:177], v[46:49]
	v_mfma_f32_16x16x32_bf16 v[42:45], v[142:145], v[174:177], v[42:45]
	v_mfma_f32_16x16x32_bf16 v[30:33], v[134:137], v[198:201], v[30:33]
	v_mfma_f32_16x16x32_bf16 v[26:29], v[142:145], v[198:201], v[26:29]
	v_mfma_f32_16x16x32_bf16 v[14:17], v[134:137], v[218:221], v[14:17]
	v_mfma_f32_16x16x32_bf16 v[10:13], v[142:145], v[218:221], v[10:13]
	v_mfma_f32_16x16x32_bf16 v[54:57], v[146:149], v[162:165], v[54:57]
	v_mfma_f32_16x16x32_bf16 v[50:53], v[154:157], v[162:165], v[50:53]
	v_mfma_f32_16x16x32_bf16 v[38:41], v[146:149], v[170:173], v[38:41]
	v_mfma_f32_16x16x32_bf16 v[34:37], v[154:157], v[170:173], v[34:37]
	v_mfma_f32_16x16x32_bf16 v[22:25], v[146:149], v[194:197], v[22:25]
	v_mfma_f32_16x16x32_bf16 v[18:21], v[154:157], v[194:197], v[18:21]
	v_mfma_f32_16x16x32_bf16 v[6:9], v[146:149], v[202:205], v[6:9]
	v_mfma_f32_16x16x32_bf16 v[2:5], v[154:157], v[202:205], v[2:5]
	v_mfma_f32_16x16x32_bf16 v[54:57], v[150:153], v[166:169], v[54:57]
	v_mfma_f32_16x16x32_bf16 v[50:53], v[158:161], v[166:169], v[50:53]
	v_mfma_f32_16x16x32_bf16 v[38:41], v[150:153], v[174:177], v[38:41]
	v_mfma_f32_16x16x32_bf16 v[34:37], v[158:161], v[174:177], v[34:37]
	v_mfma_f32_16x16x32_bf16 v[22:25], v[150:153], v[198:201], v[22:25]
	v_mfma_f32_16x16x32_bf16 v[18:21], v[158:161], v[198:201], v[18:21]
	v_mfma_f32_16x16x32_bf16 v[6:9], v[150:153], v[218:221], v[6:9]
	v_mfma_f32_16x16x32_bf16 v[2:5], v[158:161], v[218:221], v[2:5]
	s_setprio 0
	s_barrier
	s_add_i32 s85, s85, 2
	s_add_u32 s64, s64, 0x100
	s_addc_u32 s65, s65, 0
	s_add_u32 s83, s83, 0x100
	s_addc_u32 s84, s84, 0
.LBB0_520:
	ds_read_b128 v[130:133], v214
	ds_read_b128 v[134:137], v214 offset:1024
	ds_read_b128 v[138:141], v214 offset:2048
	ds_read_b128 v[142:145], v214 offset:3072
	ds_read_b128 v[146:149], v215
	ds_read_b128 v[150:153], v215 offset:1024
	ds_read_b128 v[154:157], v215 offset:2048
	ds_read_b128 v[158:161], v215 offset:3072
	s_add_u32 s66, s64, 0xfffc0080
	s_addc_u32 s67, s65, -1
	s_cmp_eq_u32 s85, 12
	s_cselect_b32 s69, s55, s67
	s_cselect_b32 s68, s61, s66
	s_cselect_b32 s67, s53, s84
	s_cselect_b32 s66, s82, s83
	v_lshl_add_u64 v[222:223], s[64:65], 0, v[186:187]
	s_add_i32 m0, s63, 0xc000
	ds_read_b128 v[162:165], v216
	ds_read_b128 v[166:169], v216 offset:1024
	ds_read_b128 v[170:173], v216 offset:2048
	ds_read_b128 v[174:177], v216 offset:3072
	ds_read_b128 v[194:197], v216 offset:4096
	ds_read_b128 v[198:201], v216 offset:5120
	ds_read_b128 v[202:205], v216 offset:6144
	ds_read_b128 v[218:221], v216 offset:7168
	global_load_lds_dwordx4 v[222:223], off
	v_lshl_add_u64 v[222:223], s[64:65], 0, v[188:189]
	s_add_i32 m0, s63, 0xe000
	s_nop 0
	global_load_lds_dwordx4 v[222:223], off
	s_waitcnt vmcnt(8)
	s_waitcnt lgkmcnt(0)
	s_barrier
; #define PG8_STAGE(bufoff, gbase, voff) do { _Pragma("unroll") for (int _i = 0; _i < 2; ++_i) \
;         __builtin_amdgcn_global_load_lds((const unsigned*)((const char*)(gbase) + (voff)[_i]), (LAS unsigned*)(lds + (bufoff) + ldsw + _i * 8192), 16, 0, 0); } while (0)
; #define PG8_LDA(dst, b, h) do { _Pragma("unroll") for (int m = 0; m < 4; ++m) _Pragma("unroll") for (int k = 0; k < 2; ++k) dst[m][k] = *(const LAS bf16x8*)(lds + PG8_SA(b, h) + aoff + m * 2048 + k * 1024); } while (0)
; #define PG8_LDB(dst, b, h) do { _Pragma("unroll") for (int n = 0; n < 2; ++n) _Pragma("unroll") for (int k = 0; k < 2; ++k) dst[n][k] = *(const LAS bf16x8*)(lds + PG8_SB(b, h) + boff + n * 2048 + k * 1024); } while (0)
; #define PG8_MMA(ai, bj, At, Bt) do { __builtin_amdgcn_s_setprio(3); _Pragma("unroll") for (int m = 0; m < 4; ++m) _Pragma("unroll") for (int n = 0; n < 2; ++n) _Pragma("unroll") for (int k = 0; k < 2; ++k) \
;         acc[ai][bj][m][n] = __builtin_amdgcn_mfma_f32_16x16x32_bf16(Bt[n][k], At[m][k], acc[ai][bj][m][n], 0, 0, 0); __builtin_amdgcn_s_setprio(0); } while (0)
; #define PG8_WAIT_V(n) asm volatile("s_waitcnt vmcnt(" #n ")" ::: "memory")
; #define PG8_WAIT_L(n) asm volatile("s_waitcnt lgkmcnt(" #n ")" ::: "memory")
; #define PG8_BAR __builtin_amdgcn_s_barrier()
; #define PG8_SCHED __builtin_amdgcn_sched_barrier(0)
; template <class Epi, bool ALIGN_EPI>
; __device__ __forceinline__ void gemm_phase(LAS unsigned char* lds, const Gemm g, const StaticOrder& S, const Epi& E) {
;     ...
;             PG8_LDB(B0, 0, 0); PG8_LDB(B1, 0, 1); PG8_SCHED; PG8_LDA(At, 0, 0); PG8_STAGE(PG8_SA(1, 1), a1 + hstep, voffA);
;             PG8_WAIT_V(8); PG8_WAIT_L(0); PG8_BAR; PG8_MMA(0, 0, At, B0); PG8_MMA(0, 1, At, B1); PG8_BAR; PG8_SCHED;
;             PG8_LDA(At, 0, 1); PG8_STAGE(PG8_SB(0, 0), b2, voffB); PG8_STAGE(PG8_SB(0, 1), b2 + hstep, voffB); PG8_STAGE(PG8_SA(0, 0), a2, voffA);
;             PG8_WAIT_V(8); PG8_WAIT_L(0); PG8_BAR; PG8_MMA(1, 0, At, B0); PG8_MMA(1, 1, At, B1); PG8_BAR; PG8_SCHED;
	s_setprio 3
	s_waitcnt lgkmcnt(0)
	v_mfma_f32_16x16x32_bf16 v[126:129], v[130:133], v[162:165], v[126:129]
	v_mfma_f32_16x16x32_bf16 v[122:125], v[138:141], v[162:165], v[122:125]
	v_mfma_f32_16x16x32_bf16 v[110:113], v[130:133], v[170:173], v[110:113]
	v_mfma_f32_16x16x32_bf16 v[106:109], v[138:141], v[170:173], v[106:109]
	v_mfma_f32_16x16x32_bf16 v[94:97], v[130:133], v[194:197], v[94:97]
	v_mfma_f32_16x16x32_bf16 v[90:93], v[138:141], v[194:197], v[90:93]
	v_mfma_f32_16x16x32_bf16 v[78:81], v[130:133], v[202:205], v[78:81]
	v_mfma_f32_16x16x32_bf16 v[74:77], v[138:141], v[202:205], v[74:77]
	v_mfma_f32_16x16x32_bf16 v[126:129], v[134:137], v[166:169], v[126:129]
	v_mfma_f32_16x16x32_bf16 v[122:125], v[142:145], v[166:169], v[122:125]
	v_mfma_f32_16x16x32_bf16 v[110:113], v[134:137], v[174:177], v[110:113]
	v_mfma_f32_16x16x32_bf16 v[106:109], v[142:145], v[174:177], v[106:109]
	v_mfma_f32_16x16x32_bf16 v[94:97], v[134:137], v[198:201], v[94:97]
	v_mfma_f32_16x16x32_bf16 v[90:93], v[142:145], v[198:201], v[90:93]
	v_mfma_f32_16x16x32_bf16 v[78:81], v[134:137], v[218:221], v[78:81]
	v_mfma_f32_16x16x32_bf16 v[74:77], v[142:145], v[218:221], v[74:77]
	v_mfma_f32_16x16x32_bf16 v[118:121], v[146:149], v[162:165], v[118:121]
	v_mfma_f32_16x16x32_bf16 v[114:117], v[154:157], v[162:165], v[114:117]
	v_mfma_f32_16x16x32_bf16 v[102:105], v[146:149], v[170:173], v[102:105]
	v_mfma_f32_16x16x32_bf16 v[98:101], v[154:157], v[170:173], v[98:101]
	v_mfma_f32_16x16x32_bf16 v[86:89], v[146:149], v[194:197], v[86:89]
	v_mfma_f32_16x16x32_bf16 v[82:85], v[154:157], v[194:197], v[82:85]
	v_mfma_f32_16x16x32_bf16 v[70:73], v[146:149], v[202:205], v[70:73]
	v_mfma_f32_16x16x32_bf16 v[66:69], v[154:157], v[202:205], v[66:69]
	v_mfma_f32_16x16x32_bf16 v[118:121], v[150:153], v[166:169], v[118:121]
	v_mfma_f32_16x16x32_bf16 v[114:117], v[158:161], v[166:169], v[114:117]
	v_mfma_f32_16x16x32_bf16 v[102:105], v[150:153], v[174:177], v[102:105]
	v_mfma_f32_16x16x32_bf16 v[98:101], v[158:161], v[174:177], v[98:101]
	v_mfma_f32_16x16x32_bf16 v[86:89], v[150:153], v[198:201], v[86:89]
	v_mfma_f32_16x16x32_bf16 v[82:85], v[158:161], v[198:201], v[82:85]
	v_mfma_f32_16x16x32_bf16 v[70:73], v[150:153], v[218:221], v[70:73]
	v_mfma_f32_16x16x32_bf16 v[66:69], v[158:161], v[218:221], v[66:69]
	s_setprio 0
	s_barrier
	s_add_i32 s86, s80, s33
	v_lshl_add_u64 v[222:223], s[66:67], 0, v[180:181]
	s_mov_b32 m0, s86
	ds_read_b128 v[162:165], v216 offset:16384
	ds_read_b128 v[166:169], v216 offset:17408
	ds_read_b128 v[170:173], v216 offset:18432
	ds_read_b128 v[174:177], v216 offset:19456
	ds_read_b128 v[194:197], v216 offset:20480
	ds_read_b128 v[198:201], v216 offset:21504
	ds_read_b128 v[202:205], v216 offset:22528
	ds_read_b128 v[218:221], v216 offset:23552
	global_load_lds_dwordx4 v[222:223], off
	s_add_i32 m0, s86, 0x2000
	s_add_u32 s86, s66, 0x40000
	v_lshl_add_u64 v[224:225], s[66:67], 0, v[184:185]
	s_addc_u32 s87, s67, 0
	s_add_i32 s88, s81, s33
	global_load_lds_dwordx4 v[224:225], off
	v_lshl_add_u64 v[226:227], s[86:87], 0, v[180:181]
	s_mov_b32 m0, s88
	v_lshl_add_u64 v[228:229], s[68:69], 0, v[182:183]
	global_load_lds_dwordx4 v[226:227], off
	v_lshl_add_u64 v[226:227], s[86:87], 0, v[184:185]
	s_add_i32 m0, s88, 0x2000
	s_nop 0
	global_load_lds_dwordx4 v[226:227], off
	v_lshl_add_u64 v[226:227], s[68:69], 0, v[178:179]
	s_mov_b32 m0, s63
	s_nop 0
	global_load_lds_dwordx4 v[226:227], off
	s_mov_b32 m0, s70
	s_nop 0
	global_load_lds_dwordx4 v[228:229], off
	s_waitcnt vmcnt(8)
	s_waitcnt lgkmcnt(0)
	s_barrier
	s_setprio 3
	s_waitcnt lgkmcnt(0)
	v_mfma_f32_16x16x32_bf16 v[62:65], v[130:133], v[162:165], v[62:65]
	v_mfma_f32_16x16x32_bf16 v[58:61], v[138:141], v[162:165], v[58:61]
	v_mfma_f32_16x16x32_bf16 v[46:49], v[130:133], v[170:173], v[46:49]
	v_mfma_f32_16x16x32_bf16 v[42:45], v[138:141], v[170:173], v[42:45]
	v_mfma_f32_16x16x32_bf16 v[30:33], v[130:133], v[194:197], v[30:33]
	v_mfma_f32_16x16x32_bf16 v[26:29], v[138:141], v[194:197], v[26:29]
	v_mfma_f32_16x16x32_bf16 v[14:17], v[130:133], v[202:205], v[14:17]
	v_mfma_f32_16x16x32_bf16 v[10:13], v[138:141], v[202:205], v[10:13]
	v_mfma_f32_16x16x32_bf16 v[62:65], v[134:137], v[166:169], v[62:65]
	v_mfma_f32_16x16x32_bf16 v[58:61], v[142:145], v[166:169], v[58:61]
	v_mfma_f32_16x16x32_bf16 v[46:49], v[134:137], v[174:177], v[46:49]
	v_mfma_f32_16x16x32_bf16 v[42:45], v[142:145], v[174:177], v[42:45]
	v_mfma_f32_16x16x32_bf16 v[30:33], v[134:137], v[198:201], v[30:33]
	v_mfma_f32_16x16x32_bf16 v[26:29], v[142:145], v[198:201], v[26:29]
	v_mfma_f32_16x16x32_bf16 v[14:17], v[134:137], v[218:221], v[14:17]
	v_mfma_f32_16x16x32_bf16 v[10:13], v[142:145], v[218:221], v[10:13]
	v_mfma_f32_16x16x32_bf16 v[54:57], v[146:149], v[162:165], v[54:57]
	v_mfma_f32_16x16x32_bf16 v[50:53], v[154:157], v[162:165], v[50:53]
	v_mfma_f32_16x16x32_bf16 v[38:41], v[146:149], v[170:173], v[38:41]
	v_mfma_f32_16x16x32_bf16 v[34:37], v[154:157], v[170:173], v[34:37]
	v_mfma_f32_16x16x32_bf16 v[22:25], v[146:149], v[194:197], v[22:25]
	v_mfma_f32_16x16x32_bf16 v[18:21], v[154:157], v[194:197], v[18:21]
	v_mfma_f32_16x16x32_bf16 v[6:9], v[146:149], v[202:205], v[6:9]
	v_mfma_f32_16x16x32_bf16 v[2:5], v[154:157], v[202:205], v[2:5]
	v_mfma_f32_16x16x32_bf16 v[54:57], v[150:153], v[166:169], v[54:57]
	v_mfma_f32_16x16x32_bf16 v[50:53], v[158:161], v[166:169], v[50:53]
	v_mfma_f32_16x16x32_bf16 v[38:41], v[150:153], v[174:177], v[38:41]
	v_mfma_f32_16x16x32_bf16 v[34:37], v[158:161], v[174:177], v[34:37]
	v_mfma_f32_16x16x32_bf16 v[22:25], v[150:153], v[198:201], v[22:25]
	v_mfma_f32_16x16x32_bf16 v[18:21], v[158:161], v[198:201], v[18:21]
	v_mfma_f32_16x16x32_bf16 v[6:9], v[150:153], v[218:221], v[6:9]
	v_mfma_f32_16x16x32_bf16 v[2:5], v[158:161], v[218:221], v[2:5]
	s_setprio 0
	s_barrier
; #define PG8_STAGE(bufoff, gbase, voff) do { _Pragma("unroll") for (int _i = 0; _i < 2; ++_i) \
;         __builtin_amdgcn_global_load_lds((const unsigned*)((const char*)(gbase) + (voff)[_i]), (LAS unsigned*)(lds + (bufoff) + ldsw + _i * 8192), 16, 0, 0); } while (0)
; #define PG8_LDA(dst, b, h) do { _Pragma("unroll") for (int m = 0; m < 4; ++m) _Pragma("unroll") for (int k = 0; k < 2; ++k) dst[m][k] = *(const LAS bf16x8*)(lds + PG8_SA(b, h) + aoff + m * 2048 + k * 1024); } while (0)
; #define PG8_LDB(dst, b, h) do { _Pragma("unroll") for (int n = 0; n < 2; ++n) _Pragma("unroll") for (int k = 0; k < 2; ++k) dst[n][k] = *(const LAS bf16x8*)(lds + PG8_SB(b, h) + boff + n * 2048 + k * 1024); } while (0)
; #define PG8_MMA(ai, bj, At, Bt) do { __builtin_amdgcn_s_setprio(3); _Pragma("unroll") for (int m = 0; m < 4; ++m) _Pragma("unroll") for (int n = 0; n < 2; ++n) _Pragma("unroll") for (int k = 0; k < 2; ++k) \
;         acc[ai][bj][m][n] = __builtin_amdgcn_mfma_f32_16x16x32_bf16(Bt[n][k], At[m][k], acc[ai][bj][m][n], 0, 0, 0); __builtin_amdgcn_s_setprio(0); } while (0)
; #define PG8_WAIT_V(n) asm volatile("s_waitcnt vmcnt(" #n ")" ::: "memory")
; #define PG8_WAIT_L(n) asm volatile("s_waitcnt lgkmcnt(" #n ")" ::: "memory")
; #define PG8_BAR __builtin_amdgcn_s_barrier()
; #define PG8_SCHED __builtin_amdgcn_sched_barrier(0)
; template <class Epi, bool ALIGN_EPI>
; __device__ __forceinline__ void gemm_phase(LAS unsigned char* lds, const Gemm g, const StaticOrder& S, const Epi& E) {
;     ...
;             PG8_LDB(B0, 1, 0); PG8_LDB(B1, 1, 1); PG8_SCHED; PG8_LDA(At, 1, 0); PG8_STAGE(PG8_SA(0, 1), a2 + hstep, voffA);
;             PG8_WAIT_V(8); PG8_WAIT_L(0); PG8_BAR; PG8_MMA(0, 0, At, B0); PG8_MMA(0, 1, At, B1); PG8_BAR; PG8_SCHED;
	s_add_i32 s86, 0, 0x18000
	s_add_i32 s87, 0, 0x1c000
	v_add_u32_e32 v142, s86, v212
	v_add_u32_e32 v158, s87, v212
	ds_read_b128 v[130:133], v142
	ds_read_b128 v[134:137], v142 offset:1024
	ds_read_b128 v[138:141], v142 offset:2048
	ds_read_b128 v[142:145], v142 offset:3072
	ds_read_b128 v[146:149], v158
	ds_read_b128 v[150:153], v158 offset:1024
	ds_read_b128 v[154:157], v158 offset:2048
	ds_read_b128 v[158:161], v158 offset:3072
	s_add_u32 s68, s68, 0x40000
	s_addc_u32 s69, s69, 0
	s_mov_b32 m0, s71
	v_lshl_add_u64 v[230:231], s[68:69], 0, v[178:179]
	ds_read_b128 v[162:165], v216 offset:32768
	ds_read_b128 v[166:169], v216 offset:33792
	ds_read_b128 v[170:173], v216 offset:34816
	ds_read_b128 v[174:177], v216 offset:35840
	ds_read_b128 v[194:197], v216 offset:36864
	ds_read_b128 v[198:201], v216 offset:37888
	ds_read_b128 v[202:205], v216 offset:38912
	ds_read_b128 v[218:221], v216 offset:39936
	global_load_lds_dwordx4 v[230:231], off
	v_lshl_add_u64 v[230:231], s[68:69], 0, v[182:183]
	s_mov_b32 m0, s72
	s_nop 0
	global_load_lds_dwordx4 v[230:231], off
	s_waitcnt vmcnt(8)
	s_waitcnt lgkmcnt(0)
	s_barrier
	s_setprio 3
	s_waitcnt lgkmcnt(0)
	v_mfma_f32_16x16x32_bf16 v[126:129], v[130:133], v[162:165], v[126:129]
	v_mfma_f32_16x16x32_bf16 v[122:125], v[138:141], v[162:165], v[122:125]
	v_mfma_f32_16x16x32_bf16 v[110:113], v[130:133], v[170:173], v[110:113]
	v_mfma_f32_16x16x32_bf16 v[106:109], v[138:141], v[170:173], v[106:109]
	v_mfma_f32_16x16x32_bf16 v[94:97], v[130:133], v[194:197], v[94:97]
	v_mfma_f32_16x16x32_bf16 v[90:93], v[138:141], v[194:197], v[90:93]
	v_mfma_f32_16x16x32_bf16 v[78:81], v[130:133], v[202:205], v[78:81]
	v_mfma_f32_16x16x32_bf16 v[74:77], v[138:141], v[202:205], v[74:77]
	v_mfma_f32_16x16x32_bf16 v[126:129], v[134:137], v[166:169], v[126:129]
	v_mfma_f32_16x16x32_bf16 v[122:125], v[142:145], v[166:169], v[122:125]
	v_mfma_f32_16x16x32_bf16 v[110:113], v[134:137], v[174:177], v[110:113]
	v_mfma_f32_16x16x32_bf16 v[106:109], v[142:145], v[174:177], v[106:109]
	v_mfma_f32_16x16x32_bf16 v[94:97], v[134:137], v[198:201], v[94:97]
	v_mfma_f32_16x16x32_bf16 v[90:93], v[142:145], v[198:201], v[90:93]
	v_mfma_f32_16x16x32_bf16 v[78:81], v[134:137], v[218:221], v[78:81]
	v_mfma_f32_16x16x32_bf16 v[74:77], v[142:145], v[218:221], v[74:77]
	v_mfma_f32_16x16x32_bf16 v[118:121], v[146:149], v[162:165], v[118:121]
	v_mfma_f32_16x16x32_bf16 v[114:117], v[154:157], v[162:165], v[114:117]
	v_mfma_f32_16x16x32_bf16 v[102:105], v[146:149], v[170:173], v[102:105]
	v_mfma_f32_16x16x32_bf16 v[98:101], v[154:157], v[170:173], v[98:101]
	v_mfma_f32_16x16x32_bf16 v[86:89], v[146:149], v[194:197], v[86:89]
	v_mfma_f32_16x16x32_bf16 v[82:85], v[154:157], v[194:197], v[82:85]
	v_mfma_f32_16x16x32_bf16 v[70:73], v[146:149], v[202:205], v[70:73]
	v_mfma_f32_16x16x32_bf16 v[66:69], v[154:157], v[202:205], v[66:69]
	v_mfma_f32_16x16x32_bf16 v[118:121], v[150:153], v[166:169], v[118:121]
	v_mfma_f32_16x16x32_bf16 v[114:117], v[158:161], v[166:169], v[114:117]
	v_mfma_f32_16x16x32_bf16 v[102:105], v[150:153], v[174:177], v[102:105]
	v_mfma_f32_16x16x32_bf16 v[98:101], v[158:161], v[174:177], v[98:101]
	v_mfma_f32_16x16x32_bf16 v[86:89], v[150:153], v[198:201], v[86:89]
	v_mfma_f32_16x16x32_bf16 v[82:85], v[158:161], v[198:201], v[82:85]
	v_mfma_f32_16x16x32_bf16 v[70:73], v[150:153], v[218:221], v[70:73]
	v_mfma_f32_16x16x32_bf16 v[66:69], v[158:161], v[218:221], v[66:69]
	s_setprio 0
	s_barrier
; #define PG8_STAGE(bufoff, gbase, voff) do { _Pragma("unroll") for (int _i = 0; _i < 2; ++_i) \
;         __builtin_amdgcn_global_load_lds((const unsigned*)((const char*)(gbase) + (voff)[_i]), (LAS unsigned*)(lds + (bufoff) + ldsw + _i * 8192), 16, 0, 0); } while (0)
; #define PG8_LDA(dst, b, h) do { _Pragma("unroll") for (int m = 0; m < 4; ++m) _Pragma("unroll") for (int k = 0; k < 2; ++k) dst[m][k] = *(const LAS bf16x8*)(lds + PG8_SA(b, h) + aoff + m * 2048 + k * 1024); } while (0)
; #define PG8_MMA(ai, bj, At, Bt) do { __builtin_amdgcn_s_setprio(3); _Pragma("unroll") for (int m = 0; m < 4; ++m) _Pragma("unroll") for (int n = 0; n < 2; ++n) _Pragma("unroll") for (int k = 0; k < 2; ++k) \
;         acc[ai][bj][m][n] = __builtin_amdgcn_mfma_f32_16x16x32_bf16(Bt[n][k], At[m][k], acc[ai][bj][m][n], 0, 0, 0); __builtin_amdgcn_s_setprio(0); } while (0)
; #define PG8_WAIT_V(n) asm volatile("s_waitcnt vmcnt(" #n ")" ::: "memory")
; #define PG8_WAIT_L(n) asm volatile("s_waitcnt lgkmcnt(" #n ")" ::: "memory")
; #define PG8_BAR __builtin_amdgcn_s_barrier()
; #define PG8_SCHED __builtin_amdgcn_sched_barrier(0)
; template <class Epi, bool ALIGN_EPI>
; __device__ __forceinline__ void gemm_phase(LAS unsigned char* lds, const Gemm g, const StaticOrder& S, const Epi& E) {
;     ...
;             PG8_LDA(At, 1, 1); PG8_STAGE(PG8_SB(1, 0), b3, voffB); PG8_STAGE(PG8_SB(1, 1), b3 + hstep, voffB); PG8_STAGE(PG8_SA(1, 0), a3, voffA);
;             PG8_WAIT_V(8); PG8_WAIT_L(0); PG8_BAR; PG8_MMA(1, 0, At, B0); PG8_MMA(1, 1, At, B1); PG8_BAR; PG8_SCHED;
;         }
;         if constexpr (ALIGN_EPI) { if (wr == 0) PG8_BAR; }
;         E(acc, cur, wr, wc, fr, fq);
;         if (!has_next) break;
	s_add_i32 s68, s86, s33
	v_lshl_add_u64 v[222:223], v[222:223], 0, s[18:19]
	s_mov_b32 m0, s68
	ds_read_b128 v[162:165], v216 offset:49152
	ds_read_b128 v[166:169], v216 offset:50176
	ds_read_b128 v[170:173], v216 offset:51200
	ds_read_b128 v[174:177], v216 offset:52224
	ds_read_b128 v[194:197], v216 offset:53248
	ds_read_b128 v[198:201], v216 offset:54272
	ds_read_b128 v[202:205], v216 offset:55296
	ds_read_b128 v[218:221], v216 offset:56320
	global_load_lds_dwordx4 v[222:223], off
	s_add_i32 m0, s68, 0x2000
	s_add_u32 s66, s66, 0x40080
	v_lshl_add_u64 v[222:223], v[224:225], 0, s[18:19]
	s_addc_u32 s67, s67, 0
	s_add_i32 s68, s87, s33
	global_load_lds_dwordx4 v[222:223], off
	v_lshl_add_u64 v[222:223], s[66:67], 0, v[180:181]
	s_mov_b32 m0, s68
	s_nop 0
	global_load_lds_dwordx4 v[222:223], off
	v_lshl_add_u64 v[222:223], s[66:67], 0, v[184:185]
	s_add_i32 m0, s68, 0x2000
	s_nop 0
	global_load_lds_dwordx4 v[222:223], off
	v_lshl_add_u64 v[222:223], v[226:227], 0, s[18:19]
	s_mov_b32 m0, s78
	s_nop 0
	global_load_lds_dwordx4 v[222:223], off
	v_lshl_add_u64 v[222:223], v[228:229], 0, s[18:19]
	s_mov_b32 m0, s79
	s_nop 0
	global_load_lds_dwordx4 v[222:223], off
	s_waitcnt vmcnt(8)
	s_waitcnt lgkmcnt(0)
	s_barrier
	s_setprio 3
	s_waitcnt lgkmcnt(0)
	v_mfma_f32_16x16x32_bf16 v[62:65], v[130:133], v[162:165], v[62:65]
	v_mfma_f32_16x16x32_bf16 v[58:61], v[138:141], v[162:165], v[58:61]
	v_mfma_f32_16x16x32_bf16 v[46:49], v[130:133], v[170:173], v[46:49]
	v_mfma_f32_16x16x32_bf16 v[42:45], v[138:141], v[170:173], v[42:45]
	v_mfma_f32_16x16x32_bf16 v[30:33], v[130:133], v[194:197], v[30:33]
	v_mfma_f32_16x16x32_bf16 v[26:29], v[138:141], v[194:197], v[26:29]
	v_mfma_f32_16x16x32_bf16 v[14:17], v[130:133], v[202:205], v[14:17]
	v_mfma_f32_16x16x32_bf16 v[10:13], v[138:141], v[202:205], v[10:13]
	v_mfma_f32_16x16x32_bf16 v[62:65], v[134:137], v[166:169], v[62:65]
	v_mfma_f32_16x16x32_bf16 v[58:61], v[142:145], v[166:169], v[58:61]
	v_mfma_f32_16x16x32_bf16 v[46:49], v[134:137], v[174:177], v[46:49]
	v_mfma_f32_16x16x32_bf16 v[42:45], v[142:145], v[174:177], v[42:45]
	v_mfma_f32_16x16x32_bf16 v[30:33], v[134:137], v[198:201], v[30:33]
	v_mfma_f32_16x16x32_bf16 v[26:29], v[142:145], v[198:201], v[26:29]
	v_mfma_f32_16x16x32_bf16 v[14:17], v[134:137], v[218:221], v[14:17]
	v_mfma_f32_16x16x32_bf16 v[10:13], v[142:145], v[218:221], v[10:13]
	v_mfma_f32_16x16x32_bf16 v[54:57], v[146:149], v[162:165], v[54:57]
	v_mfma_f32_16x16x32_bf16 v[50:53], v[154:157], v[162:165], v[50:53]
	v_mfma_f32_16x16x32_bf16 v[38:41], v[146:149], v[170:173], v[38:41]
	v_mfma_f32_16x16x32_bf16 v[34:37], v[154:157], v[170:173], v[34:37]
	v_mfma_f32_16x16x32_bf16 v[22:25], v[146:149], v[194:197], v[22:25]
	v_mfma_f32_16x16x32_bf16 v[18:21], v[154:157], v[194:197], v[18:21]
	v_mfma_f32_16x16x32_bf16 v[6:9], v[146:149], v[202:205], v[6:9]
	v_mfma_f32_16x16x32_bf16 v[2:5], v[154:157], v[202:205], v[2:5]
	v_mfma_f32_16x16x32_bf16 v[54:57], v[150:153], v[166:169], v[54:57]
	v_mfma_f32_16x16x32_bf16 v[50:53], v[158:161], v[166:169], v[50:53]
	v_mfma_f32_16x16x32_bf16 v[38:41], v[150:153], v[174:177], v[38:41]
	v_mfma_f32_16x16x32_bf16 v[34:37], v[158:161], v[174:177], v[34:37]
	v_mfma_f32_16x16x32_bf16 v[22:25], v[150:153], v[198:201], v[22:25]
	v_mfma_f32_16x16x32_bf16 v[18:21], v[158:161], v[198:201], v[18:21]
	v_mfma_f32_16x16x32_bf16 v[6:9], v[150:153], v[218:221], v[6:9]
	v_mfma_f32_16x16x32_bf16 v[2:5], v[158:161], v[218:221], v[2:5]
	s_setprio 0
	s_barrier
	s_add_i32 s85, s85, 2
	s_add_u32 s64, s64, 0x100
	s_addc_u32 s65, s65, 0
	s_add_u32 s83, s83, 0x100
	s_addc_u32 s84, s84, 0
	s_cmp_gt_u32 s85, 13
	s_cbranch_scc0 .LBB0_520
	s_and_b64 vcc, exec, s[50:51]
	s_cbranch_vccz .LBB0_523
	s_barrier

; #define PG8_STAGE(bufoff, gbase, voff) do { _Pragma("unroll") for (int _i = 0; _i < 2; ++_i) \
;         __builtin_amdgcn_global_load_lds((const unsigned*)((const char*)(gbase) + (voff)[_i]), (LAS unsigned*)(lds + (bufoff) + ldsw + _i * 8192), 16, 0, 0); } while (0)
; #define PG8_LDA(dst, b, h) do { _Pragma("unroll") for (int m = 0; m < 4; ++m) _Pragma("unroll") for (int k = 0; k < 2; ++k) dst[m][k] = *(const LAS bf16x8*)(lds + PG8_SA(b, h) + aoff + m * 2048 + k * 1024); } while (0)
; #define PG8_LDB(dst, b, h) do { _Pragma("unroll") for (int n = 0; n < 2; ++n) _Pragma("unroll") for (int k = 0; k < 2; ++k) dst[n][k] = *(const LAS bf16x8*)(lds + PG8_SB(b, h) + boff + n * 2048 + k * 1024); } while (0)
; #define PG8_MMA(ai, bj, At, Bt) do { __builtin_amdgcn_s_setprio(3); _Pragma("unroll") for (int m = 0; m < 4; ++m) _Pragma("unroll") for (int n = 0; n < 2; ++n) _Pragma("unroll") for (int k = 0; k < 2; ++k) \
;         acc[ai][bj][m][n] = __builtin_amdgcn_mfma_f32_16x16x32_bf16(Bt[n][k], At[m][k], acc[ai][bj][m][n], 0, 0, 0); __builtin_amdgcn_s_setprio(0); } while (0)
; #define PG8_BAR __builtin_amdgcn_s_barrier()
; template <class Epi, bool ALIGN_EPI>
; __device__ __forceinline__ void gemm_phase(LAS unsigned char* lds, const Gemm g, const StaticOrder& S, const Epi& E) {
;     ...
;         const bool has_next = S.next(ui + 1, nxt);
;         const char* nA = has_next ? (const char*)g.A + (size_t)nxt.pm * tstep : cA; const char* nB = has_next ? (const char*)g.Bt + (size_t)nxt.pn * tstep : cB;
;         for (int t = 0; t < nt; t += 2) {
;             const bool last = (t == nt - 2);
;             const char* a1 = cA + (size_t)(t + 1) * kstep;
;             const char* a2 = last ? nA : cA + (size_t)(t + 2) * kstep; const char* b2 = last ? nB : cB + (size_t)(t + 2) * kstep;
;             const char* a3 = a2 + kstep; const char* b3 = b2 + kstep;
;             PG8_LDB(B0, 0, 0); PG8_LDB(B1, 0, 1); PG8_SCHED; PG8_LDA(At, 0, 0); PG8_STAGE(PG8_SA(1, 1), a1 + hstep, voffA);
;             PG8_WAIT_V(8); PG8_WAIT_L(0); PG8_BAR; PG8_MMA(0, 0, At, B0); PG8_MMA(0, 1, At, B1); PG8_BAR; PG8_SCHED;
;             PG8_LDA(At, 0, 1); PG8_STAGE(PG8_SB(0, 0), b2, voffB); PG8_STAGE(PG8_SB(0, 1), b2 + hstep, voffB); PG8_STAGE(PG8_SA(0, 0), a2, voffA);
;             PG8_WAIT_V(8); PG8_WAIT_L(0); PG8_BAR; PG8_MMA(1, 0, At, B0); PG8_MMA(1, 1, At, B1); PG8_BAR; PG8_SCHED;
.LBB0_608:
	s_ashr_i32 s63, s62, 31
	s_lshl_b64 s[10:11], s[62:63], 19
	s_add_u32 s64, s34, s10
	s_addc_u32 s65, s35, s11
	s_and_b64 s[10:11], s[0:1], exec
	s_cselect_b32 s12, s65, s7
	s_cselect_b32 s13, s64, s6
	s_ashr_i32 s61, s60, 31
	s_lshl_b64 s[10:11], s[60:61], 19
	s_add_u32 s66, s52, s10
	s_addc_u32 s67, s53, s11
	s_and_b64 s[10:11], s[0:1], exec
	s_cselect_b32 s14, s67, s9
	s_cselect_b32 s15, s66, s8
	s_add_u32 s6, s6, 0x40080
	s_addc_u32 s7, s7, 0
	s_add_u32 s16, s8, 0x100
	s_addc_u32 s17, s9, 0
	s_mov_b32 s61, -2
	ds_read_b128 v[146:149], v168
	ds_read_b128 v[150:153], v168 offset:1024
	ds_read_b128 v[154:157], v168 offset:2048
	ds_read_b128 v[158:161], v168 offset:3072
	ds_read_b128 v[172:175], v169
	ds_read_b128 v[176:179], v169 offset:1024
	ds_read_b128 v[180:183], v169 offset:2048
	ds_read_b128 v[184:187], v169 offset:3072
	s_add_u32 s8, s6, 0xfffc0080
	s_addc_u32 s9, s7, -1
	s_cmp_eq_u32 s61, 12
	s_cselect_b32 s11, s12, s9
	s_cselect_b32 s10, s13, s8
	s_cselect_b32 s9, s14, s17
	s_cselect_b32 s8, s15, s16
	v_lshl_add_u64 v[220:221], s[6:7], 0, v[138:139]
	s_add_i32 m0, s70, 0xc000
	ds_read_b128 v[188:191], v170
	ds_read_b128 v[192:195], v170 offset:1024
	ds_read_b128 v[196:199], v170 offset:2048
	ds_read_b128 v[200:203], v170 offset:3072
	ds_read_b128 v[204:207], v170 offset:4096
	ds_read_b128 v[208:211], v170 offset:5120
	ds_read_b128 v[212:215], v170 offset:6144
	ds_read_b128 v[216:219], v170 offset:7168
	global_load_lds_dwordx4 v[220:221], off
	v_lshl_add_u64 v[220:221], s[6:7], 0, v[140:141]
	s_add_i32 m0, s70, 0xe000
	s_nop 0
	global_load_lds_dwordx4 v[220:221], off
	s_waitcnt vmcnt(8)
	s_waitcnt lgkmcnt(0)
	s_barrier
	s_setprio 3
	s_waitcnt lgkmcnt(0)
	v_mfma_f32_16x16x32_bf16 v[126:129], v[146:149], v[188:191], 0
	v_mfma_f32_16x16x32_bf16 v[118:121], v[154:157], v[188:191], 0
	v_mfma_f32_16x16x32_bf16 v[110:113], v[146:149], v[196:199], 0
	v_mfma_f32_16x16x32_bf16 v[102:105], v[154:157], v[196:199], 0
	v_mfma_f32_16x16x32_bf16 v[94:97], v[146:149], v[204:207], 0
	v_mfma_f32_16x16x32_bf16 v[86:89], v[154:157], v[204:207], 0
	v_mfma_f32_16x16x32_bf16 v[78:81], v[146:149], v[212:215], 0
	v_mfma_f32_16x16x32_bf16 v[70:73], v[154:157], v[212:215], 0
	v_mfma_f32_16x16x32_bf16 v[126:129], v[150:153], v[192:195], v[126:129]
	v_mfma_f32_16x16x32_bf16 v[118:121], v[158:161], v[192:195], v[118:121]
	v_mfma_f32_16x16x32_bf16 v[110:113], v[150:153], v[200:203], v[110:113]
	v_mfma_f32_16x16x32_bf16 v[102:105], v[158:161], v[200:203], v[102:105]
	v_mfma_f32_16x16x32_bf16 v[94:97], v[150:153], v[208:211], v[94:97]
	v_mfma_f32_16x16x32_bf16 v[86:89], v[158:161], v[208:211], v[86:89]
	v_mfma_f32_16x16x32_bf16 v[78:81], v[150:153], v[216:219], v[78:81]
	v_mfma_f32_16x16x32_bf16 v[70:73], v[158:161], v[216:219], v[70:73]
	v_mfma_f32_16x16x32_bf16 v[122:125], v[172:175], v[188:191], 0
	v_mfma_f32_16x16x32_bf16 v[114:117], v[180:183], v[188:191], 0
	v_mfma_f32_16x16x32_bf16 v[106:109], v[172:175], v[196:199], 0
	v_mfma_f32_16x16x32_bf16 v[98:101], v[180:183], v[196:199], 0
	v_mfma_f32_16x16x32_bf16 v[90:93], v[172:175], v[204:207], 0
	v_mfma_f32_16x16x32_bf16 v[82:85], v[180:183], v[204:207], 0
	v_mfma_f32_16x16x32_bf16 v[74:77], v[172:175], v[212:215], 0
	v_mfma_f32_16x16x32_bf16 v[66:69], v[180:183], v[212:215], 0
	v_mfma_f32_16x16x32_bf16 v[122:125], v[176:179], v[192:195], v[122:125]
	v_mfma_f32_16x16x32_bf16 v[114:117], v[184:187], v[192:195], v[114:117]
	v_mfma_f32_16x16x32_bf16 v[106:109], v[176:179], v[200:203], v[106:109]
	v_mfma_f32_16x16x32_bf16 v[98:101], v[184:187], v[200:203], v[98:101]
	v_mfma_f32_16x16x32_bf16 v[90:93], v[176:179], v[208:211], v[90:93]
	v_mfma_f32_16x16x32_bf16 v[82:85], v[184:187], v[208:211], v[82:85]
	v_mfma_f32_16x16x32_bf16 v[74:77], v[176:179], v[216:219], v[74:77]
	v_mfma_f32_16x16x32_bf16 v[66:69], v[184:187], v[216:219], v[66:69]
	s_setprio 0
	s_barrier
	s_add_i32 s63, s80, s33
	v_lshl_add_u64 v[220:221], s[8:9], 0, v[132:133]
	s_mov_b32 m0, s63
	ds_read_b128 v[188:191], v170 offset:16384
	ds_read_b128 v[192:195], v170 offset:17408
	ds_read_b128 v[196:199], v170 offset:18432
	ds_read_b128 v[200:203], v170 offset:19456
	ds_read_b128 v[204:207], v170 offset:20480
	ds_read_b128 v[208:211], v170 offset:21504
	ds_read_b128 v[212:215], v170 offset:22528
	ds_read_b128 v[216:219], v170 offset:23552
	global_load_lds_dwordx4 v[220:221], off
	s_add_i32 m0, s63, 0x2000
	s_add_u32 s84, s8, 0x40000
	v_lshl_add_u64 v[222:223], s[8:9], 0, v[136:137]
	s_addc_u32 s85, s9, 0
	s_add_i32 s63, s81, s33
	global_load_lds_dwordx4 v[222:223], off
	v_lshl_add_u64 v[224:225], s[84:85], 0, v[132:133]
	s_mov_b32 m0, s63
	v_lshl_add_u64 v[226:227], s[10:11], 0, v[134:135]
	global_load_lds_dwordx4 v[224:225], off
	v_lshl_add_u64 v[224:225], s[84:85], 0, v[136:137]
	s_add_i32 m0, s63, 0x2000
	s_nop 0
	global_load_lds_dwordx4 v[224:225], off
	v_lshl_add_u64 v[224:225], s[10:11], 0, v[130:131]
	s_mov_b32 m0, s70
	s_nop 0
	global_load_lds_dwordx4 v[224:225], off
	s_mov_b32 m0, s71
	s_nop 0
	global_load_lds_dwordx4 v[226:227], off
	s_waitcnt vmcnt(8)
	s_waitcnt lgkmcnt(0)
	s_barrier
; #define PG8_STAGE(bufoff, gbase, voff) do { _Pragma("unroll") for (int _i = 0; _i < 2; ++_i) \
;         __builtin_amdgcn_global_load_lds((const unsigned*)((const char*)(gbase) + (voff)[_i]), (LAS unsigned*)(lds + (bufoff) + ldsw + _i * 8192), 16, 0, 0); } while (0)
; #define PG8_LDA(dst, b, h) do { _Pragma("unroll") for (int m = 0; m < 4; ++m) _Pragma("unroll") for (int k = 0; k < 2; ++k) dst[m][k] = *(const LAS bf16x8*)(lds + PG8_SA(b, h) + aoff + m * 2048 + k * 1024); } while (0)
; #define PG8_LDB(dst, b, h) do { _Pragma("unroll") for (int n = 0; n < 2; ++n) _Pragma("unroll") for (int k = 0; k < 2; ++k) dst[n][k] = *(const LAS bf16x8*)(lds + PG8_SB(b, h) + boff + n * 2048 + k * 1024); } while (0)
; #define PG8_MMA(ai, bj, At, Bt) do { __builtin_amdgcn_s_setprio(3); _Pragma("unroll") for (int m = 0; m < 4; ++m) _Pragma("unroll") for (int n = 0; n < 2; ++n) _Pragma("unroll") for (int k = 0; k < 2; ++k) \
;         acc[ai][bj][m][n] = __builtin_amdgcn_mfma_f32_16x16x32_bf16(Bt[n][k], At[m][k], acc[ai][bj][m][n], 0, 0, 0); __builtin_amdgcn_s_setprio(0); } while (0)
; #define PG8_WAIT_V(n) asm volatile("s_waitcnt vmcnt(" #n ")" ::: "memory")
; #define PG8_WAIT_L(n) asm volatile("s_waitcnt lgkmcnt(" #n ")" ::: "memory")
; #define PG8_BAR __builtin_amdgcn_s_barrier()
; #define PG8_SCHED __builtin_amdgcn_sched_barrier(0)
; template <class Epi, bool ALIGN_EPI>
; __device__ __forceinline__ void gemm_phase(LAS unsigned char* lds, const Gemm g, const StaticOrder& S, const Epi& E) {
;     ...
;             PG8_WAIT_V(8); PG8_WAIT_L(0); PG8_BAR; PG8_MMA(1, 0, At, B0); PG8_MMA(1, 1, At, B1); PG8_BAR; PG8_SCHED;
;             PG8_LDB(B0, 1, 0); PG8_LDB(B1, 1, 1); PG8_SCHED; PG8_LDA(At, 1, 0); PG8_STAGE(PG8_SA(0, 1), a2 + hstep, voffA);
;             PG8_WAIT_V(8); PG8_WAIT_L(0); PG8_BAR; PG8_MMA(0, 0, At, B0); PG8_MMA(0, 1, At, B1); PG8_BAR; PG8_SCHED;
	s_setprio 3
	s_waitcnt lgkmcnt(0)
	v_mfma_f32_16x16x32_bf16 v[62:65], v[146:149], v[188:191], 0
	v_mfma_f32_16x16x32_bf16 v[54:57], v[154:157], v[188:191], 0
	v_mfma_f32_16x16x32_bf16 v[46:49], v[146:149], v[196:199], 0
	v_mfma_f32_16x16x32_bf16 v[38:41], v[154:157], v[196:199], 0
	v_mfma_f32_16x16x32_bf16 v[30:33], v[146:149], v[204:207], 0
	v_mfma_f32_16x16x32_bf16 v[22:25], v[154:157], v[204:207], 0
	v_mfma_f32_16x16x32_bf16 v[14:17], v[146:149], v[212:215], 0
	v_mfma_f32_16x16x32_bf16 v[6:9], v[154:157], v[212:215], 0
	v_mfma_f32_16x16x32_bf16 v[62:65], v[150:153], v[192:195], v[62:65]
	v_mfma_f32_16x16x32_bf16 v[54:57], v[158:161], v[192:195], v[54:57]
	v_mfma_f32_16x16x32_bf16 v[46:49], v[150:153], v[200:203], v[46:49]
	v_mfma_f32_16x16x32_bf16 v[38:41], v[158:161], v[200:203], v[38:41]
	v_mfma_f32_16x16x32_bf16 v[30:33], v[150:153], v[208:211], v[30:33]
	v_mfma_f32_16x16x32_bf16 v[22:25], v[158:161], v[208:211], v[22:25]
	v_mfma_f32_16x16x32_bf16 v[14:17], v[150:153], v[216:219], v[14:17]
	v_mfma_f32_16x16x32_bf16 v[6:9], v[158:161], v[216:219], v[6:9]
	v_mfma_f32_16x16x32_bf16 v[58:61], v[172:175], v[188:191], 0
	v_mfma_f32_16x16x32_bf16 v[50:53], v[180:183], v[188:191], 0
	v_mfma_f32_16x16x32_bf16 v[42:45], v[172:175], v[196:199], 0
	v_mfma_f32_16x16x32_bf16 v[34:37], v[180:183], v[196:199], 0
	v_mfma_f32_16x16x32_bf16 v[26:29], v[172:175], v[204:207], 0
	v_mfma_f32_16x16x32_bf16 v[18:21], v[180:183], v[204:207], 0
	v_mfma_f32_16x16x32_bf16 v[10:13], v[172:175], v[212:215], 0
	v_mfma_f32_16x16x32_bf16 v[2:5], v[180:183], v[212:215], 0
	v_mfma_f32_16x16x32_bf16 v[58:61], v[176:179], v[192:195], v[58:61]
	v_mfma_f32_16x16x32_bf16 v[50:53], v[184:187], v[192:195], v[50:53]
	v_mfma_f32_16x16x32_bf16 v[42:45], v[176:179], v[200:203], v[42:45]
	v_mfma_f32_16x16x32_bf16 v[34:37], v[184:187], v[200:203], v[34:37]
	v_mfma_f32_16x16x32_bf16 v[26:29], v[176:179], v[208:211], v[26:29]
	v_mfma_f32_16x16x32_bf16 v[18:21], v[184:187], v[208:211], v[18:21]
	v_mfma_f32_16x16x32_bf16 v[10:13], v[176:179], v[216:219], v[10:13]
	v_mfma_f32_16x16x32_bf16 v[2:5], v[184:187], v[216:219], v[2:5]
	s_setprio 0
	s_barrier
	s_add_i32 s63, 0, 0x18000
	s_add_i32 s84, 0, 0x1c000
	v_add_u32_e32 v158, s63, v166
	v_add_u32_e32 v184, s84, v166
	ds_read_b128 v[146:149], v158
	ds_read_b128 v[150:153], v158 offset:1024
	ds_read_b128 v[154:157], v158 offset:2048
	ds_read_b128 v[158:161], v158 offset:3072
	ds_read_b128 v[172:175], v184
	ds_read_b128 v[176:179], v184 offset:1024
	ds_read_b128 v[180:183], v184 offset:2048
	ds_read_b128 v[184:187], v184 offset:3072
	s_add_u32 s10, s10, 0x40000
	s_addc_u32 s11, s11, 0
	s_mov_b32 m0, s72
	v_lshl_add_u64 v[228:229], s[10:11], 0, v[130:131]
	ds_read_b128 v[188:191], v170 offset:32768
	ds_read_b128 v[192:195], v170 offset:33792
	ds_read_b128 v[196:199], v170 offset:34816
	ds_read_b128 v[200:203], v170 offset:35840
	ds_read_b128 v[204:207], v170 offset:36864
	ds_read_b128 v[208:211], v170 offset:37888
	ds_read_b128 v[212:215], v170 offset:38912
	ds_read_b128 v[216:219], v170 offset:39936
	global_load_lds_dwordx4 v[228:229], off
	v_lshl_add_u64 v[228:229], s[10:11], 0, v[134:135]
	s_mov_b32 m0, s73
	s_nop 0
	global_load_lds_dwordx4 v[228:229], off
	s_waitcnt vmcnt(8)
	s_waitcnt lgkmcnt(0)
	s_barrier
	s_setprio 3
	s_waitcnt lgkmcnt(0)
	v_mfma_f32_16x16x32_bf16 v[126:129], v[146:149], v[188:191], v[126:129]
	v_mfma_f32_16x16x32_bf16 v[118:121], v[154:157], v[188:191], v[118:121]
	v_mfma_f32_16x16x32_bf16 v[110:113], v[146:149], v[196:199], v[110:113]
	v_mfma_f32_16x16x32_bf16 v[102:105], v[154:157], v[196:199], v[102:105]
	v_mfma_f32_16x16x32_bf16 v[94:97], v[146:149], v[204:207], v[94:97]
	v_mfma_f32_16x16x32_bf16 v[86:89], v[154:157], v[204:207], v[86:89]
	v_mfma_f32_16x16x32_bf16 v[78:81], v[146:149], v[212:215], v[78:81]
	v_mfma_f32_16x16x32_bf16 v[70:73], v[154:157], v[212:215], v[70:73]
	v_mfma_f32_16x16x32_bf16 v[126:129], v[150:153], v[192:195], v[126:129]
	v_mfma_f32_16x16x32_bf16 v[118:121], v[158:161], v[192:195], v[118:121]
	v_mfma_f32_16x16x32_bf16 v[110:113], v[150:153], v[200:203], v[110:113]
	v_mfma_f32_16x16x32_bf16 v[102:105], v[158:161], v[200:203], v[102:105]
	v_mfma_f32_16x16x32_bf16 v[94:97], v[150:153], v[208:211], v[94:97]
	v_mfma_f32_16x16x32_bf16 v[86:89], v[158:161], v[208:211], v[86:89]
	v_mfma_f32_16x16x32_bf16 v[78:81], v[150:153], v[216:219], v[78:81]
	v_mfma_f32_16x16x32_bf16 v[70:73], v[158:161], v[216:219], v[70:73]
	v_mfma_f32_16x16x32_bf16 v[122:125], v[172:175], v[188:191], v[122:125]
	v_mfma_f32_16x16x32_bf16 v[114:117], v[180:183], v[188:191], v[114:117]
	v_mfma_f32_16x16x32_bf16 v[106:109], v[172:175], v[196:199], v[106:109]
	v_mfma_f32_16x16x32_bf16 v[98:101], v[180:183], v[196:199], v[98:101]
	v_mfma_f32_16x16x32_bf16 v[90:93], v[172:175], v[204:207], v[90:93]
	v_mfma_f32_16x16x32_bf16 v[82:85], v[180:183], v[204:207], v[82:85]
	v_mfma_f32_16x16x32_bf16 v[74:77], v[172:175], v[212:215], v[74:77]
	v_mfma_f32_16x16x32_bf16 v[66:69], v[180:183], v[212:215], v[66:69]
	v_mfma_f32_16x16x32_bf16 v[122:125], v[176:179], v[192:195], v[122:125]
	v_mfma_f32_16x16x32_bf16 v[114:117], v[184:187], v[192:195], v[114:117]
	v_mfma_f32_16x16x32_bf16 v[106:109], v[176:179], v[200:203], v[106:109]
	v_mfma_f32_16x16x32_bf16 v[98:101], v[184:187], v[200:203], v[98:101]
	v_mfma_f32_16x16x32_bf16 v[90:93], v[176:179], v[208:211], v[90:93]
	v_mfma_f32_16x16x32_bf16 v[82:85], v[184:187], v[208:211], v[82:85]
	v_mfma_f32_16x16x32_bf16 v[74:77], v[176:179], v[216:219], v[74:77]
	v_mfma_f32_16x16x32_bf16 v[66:69], v[184:187], v[216:219], v[66:69]
	s_setprio 0
	s_barrier
; #define PG8_STAGE(bufoff, gbase, voff) do { _Pragma("unroll") for (int _i = 0; _i < 2; ++_i) \
;         __builtin_amdgcn_global_load_lds((const unsigned*)((const char*)(gbase) + (voff)[_i]), (LAS unsigned*)(lds + (bufoff) + ldsw + _i * 8192), 16, 0, 0); } while (0)
; #define PG8_LDA(dst, b, h) do { _Pragma("unroll") for (int m = 0; m < 4; ++m) _Pragma("unroll") for (int k = 0; k < 2; ++k) dst[m][k] = *(const LAS bf16x8*)(lds + PG8_SA(b, h) + aoff + m * 2048 + k * 1024); } while (0)
; #define PG8_LDB(dst, b, h) do { _Pragma("unroll") for (int n = 0; n < 2; ++n) _Pragma("unroll") for (int k = 0; k < 2; ++k) dst[n][k] = *(const LAS bf16x8*)(lds + PG8_SB(b, h) + boff + n * 2048 + k * 1024); } while (0)
; #define PG8_MMA(ai, bj, At, Bt) do { __builtin_amdgcn_s_setprio(3); _Pragma("unroll") for (int m = 0; m < 4; ++m) _Pragma("unroll") for (int n = 0; n < 2; ++n) _Pragma("unroll") for (int k = 0; k < 2; ++k) \
;         acc[ai][bj][m][n] = __builtin_amdgcn_mfma_f32_16x16x32_bf16(Bt[n][k], At[m][k], acc[ai][bj][m][n], 0, 0, 0); __builtin_amdgcn_s_setprio(0); } while (0)
; #define PG8_WAIT_V(n) asm volatile("s_waitcnt vmcnt(" #n ")" ::: "memory")
; #define PG8_WAIT_L(n) asm volatile("s_waitcnt lgkmcnt(" #n ")" ::: "memory")
; #define PG8_BAR __builtin_amdgcn_s_barrier()
; #define PG8_SCHED __builtin_amdgcn_sched_barrier(0)
; template <class Epi, bool ALIGN_EPI>
; __device__ __forceinline__ void gemm_phase(LAS unsigned char* lds, const Gemm g, const StaticOrder& S, const Epi& E) {
;     ...
;             PG8_LDB(B0, 0, 0); PG8_LDB(B1, 0, 1); PG8_SCHED; PG8_LDA(At, 0, 0); PG8_STAGE(PG8_SA(1, 1), a1 + hstep, voffA);
;             PG8_WAIT_V(8); PG8_WAIT_L(0); PG8_BAR; PG8_MMA(0, 0, At, B0); PG8_MMA(0, 1, At, B1); PG8_BAR; PG8_SCHED;
;     ...
;             PG8_LDA(At, 1, 1); PG8_STAGE(PG8_SB(1, 0), b3, voffB); PG8_STAGE(PG8_SB(1, 1), b3 + hstep, voffB); PG8_STAGE(PG8_SA(1, 0), a3, voffA);
;             PG8_WAIT_V(8); PG8_WAIT_L(0); PG8_BAR; PG8_MMA(1, 0, At, B0); PG8_MMA(1, 1, At, B1); PG8_BAR; PG8_SCHED;
	s_add_i32 s10, s63, s33
	v_lshl_add_u64 v[220:221], v[220:221], 0, s[56:57]
	s_mov_b32 m0, s10
	ds_read_b128 v[188:191], v170 offset:49152
	ds_read_b128 v[192:195], v170 offset:50176
	ds_read_b128 v[196:199], v170 offset:51200
	ds_read_b128 v[200:203], v170 offset:52224
	ds_read_b128 v[204:207], v170 offset:53248
	ds_read_b128 v[208:211], v170 offset:54272
	ds_read_b128 v[212:215], v170 offset:55296
	ds_read_b128 v[216:219], v170 offset:56320
	global_load_lds_dwordx4 v[220:221], off
	s_add_i32 m0, s10, 0x2000
	s_add_u32 s8, s8, 0x40080
	v_lshl_add_u64 v[220:221], v[222:223], 0, s[56:57]
	s_addc_u32 s9, s9, 0
	s_add_i32 s10, s84, s33
	global_load_lds_dwordx4 v[220:221], off
	v_lshl_add_u64 v[220:221], s[8:9], 0, v[132:133]
	s_mov_b32 m0, s10
	s_nop 0
	global_load_lds_dwordx4 v[220:221], off
	v_lshl_add_u64 v[220:221], s[8:9], 0, v[136:137]
	s_add_i32 m0, s10, 0x2000
	s_nop 0
	global_load_lds_dwordx4 v[220:221], off
	v_lshl_add_u64 v[220:221], v[224:225], 0, s[56:57]
	s_mov_b32 m0, s78
	s_nop 0
	global_load_lds_dwordx4 v[220:221], off
	v_lshl_add_u64 v[220:221], v[226:227], 0, s[56:57]
	s_mov_b32 m0, s79
	s_nop 0
	global_load_lds_dwordx4 v[220:221], off
	s_waitcnt vmcnt(8)
	s_waitcnt lgkmcnt(0)
	s_barrier
	s_setprio 3
	s_waitcnt lgkmcnt(0)
	v_mfma_f32_16x16x32_bf16 v[62:65], v[146:149], v[188:191], v[62:65]
	v_mfma_f32_16x16x32_bf16 v[54:57], v[154:157], v[188:191], v[54:57]
	v_mfma_f32_16x16x32_bf16 v[46:49], v[146:149], v[196:199], v[46:49]
	v_mfma_f32_16x16x32_bf16 v[38:41], v[154:157], v[196:199], v[38:41]
	v_mfma_f32_16x16x32_bf16 v[30:33], v[146:149], v[204:207], v[30:33]
	v_mfma_f32_16x16x32_bf16 v[22:25], v[154:157], v[204:207], v[22:25]
	v_mfma_f32_16x16x32_bf16 v[14:17], v[146:149], v[212:215], v[14:17]
	v_mfma_f32_16x16x32_bf16 v[6:9], v[154:157], v[212:215], v[6:9]
	v_mfma_f32_16x16x32_bf16 v[62:65], v[150:153], v[192:195], v[62:65]
	v_mfma_f32_16x16x32_bf16 v[54:57], v[158:161], v[192:195], v[54:57]
	v_mfma_f32_16x16x32_bf16 v[46:49], v[150:153], v[200:203], v[46:49]
	v_mfma_f32_16x16x32_bf16 v[38:41], v[158:161], v[200:203], v[38:41]
	v_mfma_f32_16x16x32_bf16 v[30:33], v[150:153], v[208:211], v[30:33]
	v_mfma_f32_16x16x32_bf16 v[22:25], v[158:161], v[208:211], v[22:25]
	v_mfma_f32_16x16x32_bf16 v[14:17], v[150:153], v[216:219], v[14:17]
	v_mfma_f32_16x16x32_bf16 v[6:9], v[158:161], v[216:219], v[6:9]
	v_mfma_f32_16x16x32_bf16 v[58:61], v[172:175], v[188:191], v[58:61]
	v_mfma_f32_16x16x32_bf16 v[50:53], v[180:183], v[188:191], v[50:53]
	v_mfma_f32_16x16x32_bf16 v[42:45], v[172:175], v[196:199], v[42:45]
	v_mfma_f32_16x16x32_bf16 v[34:37], v[180:183], v[196:199], v[34:37]
	v_mfma_f32_16x16x32_bf16 v[26:29], v[172:175], v[204:207], v[26:29]
	v_mfma_f32_16x16x32_bf16 v[18:21], v[180:183], v[204:207], v[18:21]
	v_mfma_f32_16x16x32_bf16 v[10:13], v[172:175], v[212:215], v[10:13]
	v_mfma_f32_16x16x32_bf16 v[2:5], v[180:183], v[212:215], v[2:5]
	v_mfma_f32_16x16x32_bf16 v[58:61], v[176:179], v[192:195], v[58:61]
	v_mfma_f32_16x16x32_bf16 v[50:53], v[184:187], v[192:195], v[50:53]
	v_mfma_f32_16x16x32_bf16 v[42:45], v[176:179], v[200:203], v[42:45]
	v_mfma_f32_16x16x32_bf16 v[34:37], v[184:187], v[200:203], v[34:37]
	v_mfma_f32_16x16x32_bf16 v[26:29], v[176:179], v[208:211], v[26:29]
	v_mfma_f32_16x16x32_bf16 v[18:21], v[184:187], v[208:211], v[18:21]
	v_mfma_f32_16x16x32_bf16 v[10:13], v[176:179], v[216:219], v[10:13]
	v_mfma_f32_16x16x32_bf16 v[2:5], v[184:187], v[216:219], v[2:5]
	s_setprio 0
	s_barrier
	s_add_i32 s61, s61, 2
	s_add_u32 s6, s6, 0x100
	s_addc_u32 s7, s7, 0
	s_add_u32 s16, s16, 0x100
	s_addc_u32 s17, s17, 0
.LBB0_609:
	ds_read_b128 v[146:149], v168
	ds_read_b128 v[150:153], v168 offset:1024
	ds_read_b128 v[154:157], v168 offset:2048
	ds_read_b128 v[158:161], v168 offset:3072
	ds_read_b128 v[172:175], v169
	ds_read_b128 v[176:179], v169 offset:1024
	ds_read_b128 v[180:183], v169 offset:2048
	ds_read_b128 v[184:187], v169 offset:3072
	s_add_u32 s8, s6, 0xfffc0080
	s_addc_u32 s9, s7, -1
	s_cmp_eq_u32 s61, 12
	s_cselect_b32 s11, s12, s9
	s_cselect_b32 s10, s13, s8
	s_cselect_b32 s9, s14, s17
	s_cselect_b32 s8, s15, s16
	v_lshl_add_u64 v[220:221], s[6:7], 0, v[138:139]
	s_add_i32 m0, s70, 0xc000
	ds_read_b128 v[188:191], v170
	ds_read_b128 v[192:195], v170 offset:1024
	ds_read_b128 v[196:199], v170 offset:2048
	ds_read_b128 v[200:203], v170 offset:3072
	ds_read_b128 v[204:207], v170 offset:4096
	ds_read_b128 v[208:211], v170 offset:5120
	ds_read_b128 v[212:215], v170 offset:6144
	ds_read_b128 v[216:219], v170 offset:7168
	global_load_lds_dwordx4 v[220:221], off
	v_lshl_add_u64 v[220:221], s[6:7], 0, v[140:141]
	s_add_i32 m0, s70, 0xe000
	s_nop 0
	global_load_lds_dwordx4 v[220:221], off
	s_waitcnt vmcnt(8)
	s_waitcnt lgkmcnt(0)
	s_barrier
; #define PG8_STAGE(bufoff, gbase, voff) do { _Pragma("unroll") for (int _i = 0; _i < 2; ++_i) \
;         __builtin_amdgcn_global_load_lds((const unsigned*)((const char*)(gbase) + (voff)[_i]), (LAS unsigned*)(lds + (bufoff) + ldsw + _i * 8192), 16, 0, 0); } while (0)
; #define PG8_LDA(dst, b, h) do { _Pragma("unroll") for (int m = 0; m < 4; ++m) _Pragma("unroll") for (int k = 0; k < 2; ++k) dst[m][k] = *(const LAS bf16x8*)(lds + PG8_SA(b, h) + aoff + m * 2048 + k * 1024); } while (0)
; #define PG8_MMA(ai, bj, At, Bt) do { __builtin_amdgcn_s_setprio(3); _Pragma("unroll") for (int m = 0; m < 4; ++m) _Pragma("unroll") for (int n = 0; n < 2; ++n) _Pragma("unroll") for (int k = 0; k < 2; ++k) \
;         acc[ai][bj][m][n] = __builtin_amdgcn_mfma_f32_16x16x32_bf16(Bt[n][k], At[m][k], acc[ai][bj][m][n], 0, 0, 0); __builtin_amdgcn_s_setprio(0); } while (0)
; #define PG8_WAIT_V(n) asm volatile("s_waitcnt vmcnt(" #n ")" ::: "memory")
; #define PG8_WAIT_L(n) asm volatile("s_waitcnt lgkmcnt(" #n ")" ::: "memory")
; #define PG8_BAR __builtin_amdgcn_s_barrier()
; #define PG8_SCHED __builtin_amdgcn_sched_barrier(0)
; template <class Epi, bool ALIGN_EPI>
; __device__ __forceinline__ void gemm_phase(LAS unsigned char* lds, const Gemm g, const StaticOrder& S, const Epi& E) {
;     ...
;             PG8_WAIT_V(8); PG8_WAIT_L(0); PG8_BAR; PG8_MMA(0, 0, At, B0); PG8_MMA(0, 1, At, B1); PG8_BAR; PG8_SCHED;
;             PG8_LDA(At, 0, 1); PG8_STAGE(PG8_SB(0, 0), b2, voffB); PG8_STAGE(PG8_SB(0, 1), b2 + hstep, voffB); PG8_STAGE(PG8_SA(0, 0), a2, voffA);
;             PG8_WAIT_V(8); PG8_WAIT_L(0); PG8_BAR; PG8_MMA(1, 0, At, B0); PG8_MMA(1, 1, At, B1); PG8_BAR; PG8_SCHED;
	s_setprio 3
	s_waitcnt lgkmcnt(0)
	v_mfma_f32_16x16x32_bf16 v[126:129], v[146:149], v[188:191], v[126:129]
	v_mfma_f32_16x16x32_bf16 v[118:121], v[154:157], v[188:191], v[118:121]
	v_mfma_f32_16x16x32_bf16 v[110:113], v[146:149], v[196:199], v[110:113]
	v_mfma_f32_16x16x32_bf16 v[102:105], v[154:157], v[196:199], v[102:105]
	v_mfma_f32_16x16x32_bf16 v[94:97], v[146:149], v[204:207], v[94:97]
	v_mfma_f32_16x16x32_bf16 v[86:89], v[154:157], v[204:207], v[86:89]
	v_mfma_f32_16x16x32_bf16 v[78:81], v[146:149], v[212:215], v[78:81]
	v_mfma_f32_16x16x32_bf16 v[70:73], v[154:157], v[212:215], v[70:73]
	v_mfma_f32_16x16x32_bf16 v[126:129], v[150:153], v[192:195], v[126:129]
	v_mfma_f32_16x16x32_bf16 v[118:121], v[158:161], v[192:195], v[118:121]
	v_mfma_f32_16x16x32_bf16 v[110:113], v[150:153], v[200:203], v[110:113]
	v_mfma_f32_16x16x32_bf16 v[102:105], v[158:161], v[200:203], v[102:105]
	v_mfma_f32_16x16x32_bf16 v[94:97], v[150:153], v[208:211], v[94:97]
	v_mfma_f32_16x16x32_bf16 v[86:89], v[158:161], v[208:211], v[86:89]
	v_mfma_f32_16x16x32_bf16 v[78:81], v[150:153], v[216:219], v[78:81]
	v_mfma_f32_16x16x32_bf16 v[70:73], v[158:161], v[216:219], v[70:73]
	v_mfma_f32_16x16x32_bf16 v[122:125], v[172:175], v[188:191], v[122:125]
	v_mfma_f32_16x16x32_bf16 v[114:117], v[180:183], v[188:191], v[114:117]
	v_mfma_f32_16x16x32_bf16 v[106:109], v[172:175], v[196:199], v[106:109]
	v_mfma_f32_16x16x32_bf16 v[98:101], v[180:183], v[196:199], v[98:101]
	v_mfma_f32_16x16x32_bf16 v[90:93], v[172:175], v[204:207], v[90:93]
	v_mfma_f32_16x16x32_bf16 v[82:85], v[180:183], v[204:207], v[82:85]
	v_mfma_f32_16x16x32_bf16 v[74:77], v[172:175], v[212:215], v[74:77]
	v_mfma_f32_16x16x32_bf16 v[66:69], v[180:183], v[212:215], v[66:69]
	v_mfma_f32_16x16x32_bf16 v[122:125], v[176:179], v[192:195], v[122:125]
	v_mfma_f32_16x16x32_bf16 v[114:117], v[184:187], v[192:195], v[114:117]
	v_mfma_f32_16x16x32_bf16 v[106:109], v[176:179], v[200:203], v[106:109]
	v_mfma_f32_16x16x32_bf16 v[98:101], v[184:187], v[200:203], v[98:101]
	v_mfma_f32_16x16x32_bf16 v[90:93], v[176:179], v[208:211], v[90:93]
	v_mfma_f32_16x16x32_bf16 v[82:85], v[184:187], v[208:211], v[82:85]
	v_mfma_f32_16x16x32_bf16 v[74:77], v[176:179], v[216:219], v[74:77]
	v_mfma_f32_16x16x32_bf16 v[66:69], v[184:187], v[216:219], v[66:69]
	s_setprio 0
	s_barrier
	s_add_i32 s63, s80, s33
	v_lshl_add_u64 v[220:221], s[8:9], 0, v[132:133]
	s_mov_b32 m0, s63
	ds_read_b128 v[188:191], v170 offset:16384
	ds_read_b128 v[192:195], v170 offset:17408
	ds_read_b128 v[196:199], v170 offset:18432
	ds_read_b128 v[200:203], v170 offset:19456
	ds_read_b128 v[204:207], v170 offset:20480
	ds_read_b128 v[208:211], v170 offset:21504
	ds_read_b128 v[212:215], v170 offset:22528
	ds_read_b128 v[216:219], v170 offset:23552
	global_load_lds_dwordx4 v[220:221], off
	s_add_i32 m0, s63, 0x2000
	s_add_u32 s84, s8, 0x40000
	v_lshl_add_u64 v[222:223], s[8:9], 0, v[136:137]
	s_addc_u32 s85, s9, 0
	s_add_i32 s63, s81, s33
	global_load_lds_dwordx4 v[222:223], off
	v_lshl_add_u64 v[224:225], s[84:85], 0, v[132:133]
	s_mov_b32 m0, s63
	v_lshl_add_u64 v[226:227], s[10:11], 0, v[134:135]
	global_load_lds_dwordx4 v[224:225], off
	v_lshl_add_u64 v[224:225], s[84:85], 0, v[136:137]
	s_add_i32 m0, s63, 0x2000
	s_nop 0
	global_load_lds_dwordx4 v[224:225], off
	v_lshl_add_u64 v[224:225], s[10:11], 0, v[130:131]
	s_mov_b32 m0, s70
	s_nop 0
	global_load_lds_dwordx4 v[224:225], off
	s_mov_b32 m0, s71
	s_nop 0
	global_load_lds_dwordx4 v[226:227], off
	s_waitcnt vmcnt(8)
	s_waitcnt lgkmcnt(0)
	s_barrier
	s_setprio 3
	s_waitcnt lgkmcnt(0)
	v_mfma_f32_16x16x32_bf16 v[62:65], v[146:149], v[188:191], v[62:65]
	v_mfma_f32_16x16x32_bf16 v[54:57], v[154:157], v[188:191], v[54:57]
	v_mfma_f32_16x16x32_bf16 v[46:49], v[146:149], v[196:199], v[46:49]
	v_mfma_f32_16x16x32_bf16 v[38:41], v[154:157], v[196:199], v[38:41]
	v_mfma_f32_16x16x32_bf16 v[30:33], v[146:149], v[204:207], v[30:33]
	v_mfma_f32_16x16x32_bf16 v[22:25], v[154:157], v[204:207], v[22:25]
	v_mfma_f32_16x16x32_bf16 v[14:17], v[146:149], v[212:215], v[14:17]
	v_mfma_f32_16x16x32_bf16 v[6:9], v[154:157], v[212:215], v[6:9]
	v_mfma_f32_16x16x32_bf16 v[62:65], v[150:153], v[192:195], v[62:65]
	v_mfma_f32_16x16x32_bf16 v[54:57], v[158:161], v[192:195], v[54:57]
	v_mfma_f32_16x16x32_bf16 v[46:49], v[150:153], v[200:203], v[46:49]
	v_mfma_f32_16x16x32_bf16 v[38:41], v[158:161], v[200:203], v[38:41]
	v_mfma_f32_16x16x32_bf16 v[30:33], v[150:153], v[208:211], v[30:33]
	v_mfma_f32_16x16x32_bf16 v[22:25], v[158:161], v[208:211], v[22:25]
	v_mfma_f32_16x16x32_bf16 v[14:17], v[150:153], v[216:219], v[14:17]
	v_mfma_f32_16x16x32_bf16 v[6:9], v[158:161], v[216:219], v[6:9]
	v_mfma_f32_16x16x32_bf16 v[58:61], v[172:175], v[188:191], v[58:61]
	v_mfma_f32_16x16x32_bf16 v[50:53], v[180:183], v[188:191], v[50:53]
	v_mfma_f32_16x16x32_bf16 v[42:45], v[172:175], v[196:199], v[42:45]
	v_mfma_f32_16x16x32_bf16 v[34:37], v[180:183], v[196:199], v[34:37]
	v_mfma_f32_16x16x32_bf16 v[26:29], v[172:175], v[204:207], v[26:29]
	v_mfma_f32_16x16x32_bf16 v[18:21], v[180:183], v[204:207], v[18:21]
	v_mfma_f32_16x16x32_bf16 v[10:13], v[172:175], v[212:215], v[10:13]
	v_mfma_f32_16x16x32_bf16 v[2:5], v[180:183], v[212:215], v[2:5]
	v_mfma_f32_16x16x32_bf16 v[58:61], v[176:179], v[192:195], v[58:61]
	v_mfma_f32_16x16x32_bf16 v[50:53], v[184:187], v[192:195], v[50:53]
	v_mfma_f32_16x16x32_bf16 v[42:45], v[176:179], v[200:203], v[42:45]
	v_mfma_f32_16x16x32_bf16 v[34:37], v[184:187], v[200:203], v[34:37]
	v_mfma_f32_16x16x32_bf16 v[26:29], v[176:179], v[208:211], v[26:29]
	v_mfma_f32_16x16x32_bf16 v[18:21], v[184:187], v[208:211], v[18:21]
	v_mfma_f32_16x16x32_bf16 v[10:13], v[176:179], v[216:219], v[10:13]
	v_mfma_f32_16x16x32_bf16 v[2:5], v[184:187], v[216:219], v[2:5]
	s_setprio 0
	s_barrier
; #define PG8_STAGE(bufoff, gbase, voff) do { _Pragma("unroll") for (int _i = 0; _i < 2; ++_i) \
;         __builtin_amdgcn_global_load_lds((const unsigned*)((const char*)(gbase) + (voff)[_i]), (LAS unsigned*)(lds + (bufoff) + ldsw + _i * 8192), 16, 0, 0); } while (0)
; #define PG8_LDA(dst, b, h) do { _Pragma("unroll") for (int m = 0; m < 4; ++m) _Pragma("unroll") for (int k = 0; k < 2; ++k) dst[m][k] = *(const LAS bf16x8*)(lds + PG8_SA(b, h) + aoff + m * 2048 + k * 1024); } while (0)
; #define PG8_LDB(dst, b, h) do { _Pragma("unroll") for (int n = 0; n < 2; ++n) _Pragma("unroll") for (int k = 0; k < 2; ++k) dst[n][k] = *(const LAS bf16x8*)(lds + PG8_SB(b, h) + boff + n * 2048 + k * 1024); } while (0)
; #define PG8_MMA(ai, bj, At, Bt) do { __builtin_amdgcn_s_setprio(3); _Pragma("unroll") for (int m = 0; m < 4; ++m) _Pragma("unroll") for (int n = 0; n < 2; ++n) _Pragma("unroll") for (int k = 0; k < 2; ++k) \
;         acc[ai][bj][m][n] = __builtin_amdgcn_mfma_f32_16x16x32_bf16(Bt[n][k], At[m][k], acc[ai][bj][m][n], 0, 0, 0); __builtin_amdgcn_s_setprio(0); } while (0)
; #define PG8_WAIT_V(n) asm volatile("s_waitcnt vmcnt(" #n ")" ::: "memory")
; #define PG8_WAIT_L(n) asm volatile("s_waitcnt lgkmcnt(" #n ")" ::: "memory")
; #define PG8_BAR __builtin_amdgcn_s_barrier()
; #define PG8_SCHED __builtin_amdgcn_sched_barrier(0)
; template <class Epi, bool ALIGN_EPI>
; __device__ __forceinline__ void gemm_phase(LAS unsigned char* lds, const Gemm g, const StaticOrder& S, const Epi& E) {
;     ...
;             PG8_LDB(B0, 1, 0); PG8_LDB(B1, 1, 1); PG8_SCHED; PG8_LDA(At, 1, 0); PG8_STAGE(PG8_SA(0, 1), a2 + hstep, voffA);
;             PG8_WAIT_V(8); PG8_WAIT_L(0); PG8_BAR; PG8_MMA(0, 0, At, B0); PG8_MMA(0, 1, At, B1); PG8_BAR; PG8_SCHED;
	s_add_i32 s63, 0, 0x18000
	s_add_i32 s84, 0, 0x1c000
	v_add_u32_e32 v158, s63, v166
	v_add_u32_e32 v184, s84, v166
	ds_read_b128 v[146:149], v158
	ds_read_b128 v[150:153], v158 offset:1024
	ds_read_b128 v[154:157], v158 offset:2048
	ds_read_b128 v[158:161], v158 offset:3072
	ds_read_b128 v[172:175], v184
	ds_read_b128 v[176:179], v184 offset:1024
	ds_read_b128 v[180:183], v184 offset:2048
	ds_read_b128 v[184:187], v184 offset:3072
	s_add_u32 s10, s10, 0x40000
	s_addc_u32 s11, s11, 0
	s_mov_b32 m0, s72
	v_lshl_add_u64 v[228:229], s[10:11], 0, v[130:131]
	ds_read_b128 v[188:191], v170 offset:32768
	ds_read_b128 v[192:195], v170 offset:33792
	ds_read_b128 v[196:199], v170 offset:34816
	ds_read_b128 v[200:203], v170 offset:35840
	ds_read_b128 v[204:207], v170 offset:36864
	ds_read_b128 v[208:211], v170 offset:37888
	ds_read_b128 v[212:215], v170 offset:38912
	ds_read_b128 v[216:219], v170 offset:39936
	global_load_lds_dwordx4 v[228:229], off
	v_lshl_add_u64 v[228:229], s[10:11], 0, v[134:135]
	s_mov_b32 m0, s73
	s_nop 0
	global_load_lds_dwordx4 v[228:229], off
	s_waitcnt vmcnt(8)
	s_waitcnt lgkmcnt(0)
	s_barrier
	s_setprio 3
	s_waitcnt lgkmcnt(0)
	v_mfma_f32_16x16x32_bf16 v[126:129], v[146:149], v[188:191], v[126:129]
	v_mfma_f32_16x16x32_bf16 v[118:121], v[154:157], v[188:191], v[118:121]
	v_mfma_f32_16x16x32_bf16 v[110:113], v[146:149], v[196:199], v[110:113]
	v_mfma_f32_16x16x32_bf16 v[102:105], v[154:157], v[196:199], v[102:105]
	v_mfma_f32_16x16x32_bf16 v[94:97], v[146:149], v[204:207], v[94:97]
	v_mfma_f32_16x16x32_bf16 v[86:89], v[154:157], v[204:207], v[86:89]
	v_mfma_f32_16x16x32_bf16 v[78:81], v[146:149], v[212:215], v[78:81]
	v_mfma_f32_16x16x32_bf16 v[70:73], v[154:157], v[212:215], v[70:73]
	v_mfma_f32_16x16x32_bf16 v[126:129], v[150:153], v[192:195], v[126:129]
	v_mfma_f32_16x16x32_bf16 v[118:121], v[158:161], v[192:195], v[118:121]
	v_mfma_f32_16x16x32_bf16 v[110:113], v[150:153], v[200:203], v[110:113]
	v_mfma_f32_16x16x32_bf16 v[102:105], v[158:161], v[200:203], v[102:105]
	v_mfma_f32_16x16x32_bf16 v[94:97], v[150:153], v[208:211], v[94:97]
	v_mfma_f32_16x16x32_bf16 v[86:89], v[158:161], v[208:211], v[86:89]
	v_mfma_f32_16x16x32_bf16 v[78:81], v[150:153], v[216:219], v[78:81]
	v_mfma_f32_16x16x32_bf16 v[70:73], v[158:161], v[216:219], v[70:73]
	v_mfma_f32_16x16x32_bf16 v[122:125], v[172:175], v[188:191], v[122:125]
	v_mfma_f32_16x16x32_bf16 v[114:117], v[180:183], v[188:191], v[114:117]
	v_mfma_f32_16x16x32_bf16 v[106:109], v[172:175], v[196:199], v[106:109]
	v_mfma_f32_16x16x32_bf16 v[98:101], v[180:183], v[196:199], v[98:101]
	v_mfma_f32_16x16x32_bf16 v[90:93], v[172:175], v[204:207], v[90:93]
	v_mfma_f32_16x16x32_bf16 v[82:85], v[180:183], v[204:207], v[82:85]
	v_mfma_f32_16x16x32_bf16 v[74:77], v[172:175], v[212:215], v[74:77]
	v_mfma_f32_16x16x32_bf16 v[66:69], v[180:183], v[212:215], v[66:69]
	v_mfma_f32_16x16x32_bf16 v[122:125], v[176:179], v[192:195], v[122:125]
	v_mfma_f32_16x16x32_bf16 v[114:117], v[184:187], v[192:195], v[114:117]
	v_mfma_f32_16x16x32_bf16 v[106:109], v[176:179], v[200:203], v[106:109]
	v_mfma_f32_16x16x32_bf16 v[98:101], v[184:187], v[200:203], v[98:101]
	v_mfma_f32_16x16x32_bf16 v[90:93], v[176:179], v[208:211], v[90:93]
	v_mfma_f32_16x16x32_bf16 v[82:85], v[184:187], v[208:211], v[82:85]
	v_mfma_f32_16x16x32_bf16 v[74:77], v[176:179], v[216:219], v[74:77]
	v_mfma_f32_16x16x32_bf16 v[66:69], v[184:187], v[216:219], v[66:69]
	s_setprio 0
	s_barrier
; #define PG8_STAGE(bufoff, gbase, voff) do { _Pragma("unroll") for (int _i = 0; _i < 2; ++_i) \
;         __builtin_amdgcn_global_load_lds((const unsigned*)((const char*)(gbase) + (voff)[_i]), (LAS unsigned*)(lds + (bufoff) + ldsw + _i * 8192), 16, 0, 0); } while (0)
; #define PG8_LDA(dst, b, h) do { _Pragma("unroll") for (int m = 0; m < 4; ++m) _Pragma("unroll") for (int k = 0; k < 2; ++k) dst[m][k] = *(const LAS bf16x8*)(lds + PG8_SA(b, h) + aoff + m * 2048 + k * 1024); } while (0)
; #define PG8_MMA(ai, bj, At, Bt) do { __builtin_amdgcn_s_setprio(3); _Pragma("unroll") for (int m = 0; m < 4; ++m) _Pragma("unroll") for (int n = 0; n < 2; ++n) _Pragma("unroll") for (int k = 0; k < 2; ++k) \
;         acc[ai][bj][m][n] = __builtin_amdgcn_mfma_f32_16x16x32_bf16(Bt[n][k], At[m][k], acc[ai][bj][m][n], 0, 0, 0); __builtin_amdgcn_s_setprio(0); } while (0)
; #define PG8_WAIT_V(n) asm volatile("s_waitcnt vmcnt(" #n ")" ::: "memory")
; #define PG8_WAIT_L(n) asm volatile("s_waitcnt lgkmcnt(" #n ")" ::: "memory")
; #define PG8_BAR __builtin_amdgcn_s_barrier()
; #define PG8_SCHED __builtin_amdgcn_sched_barrier(0)
; template <class Epi, bool ALIGN_EPI>
; __device__ __forceinline__ void gemm_phase(LAS unsigned char* lds, const Gemm g, const StaticOrder& S, const Epi& E) {
;     ...
;             PG8_LDA(At, 1, 1); PG8_STAGE(PG8_SB(1, 0), b3, voffB); PG8_STAGE(PG8_SB(1, 1), b3 + hstep, voffB); PG8_STAGE(PG8_SA(1, 0), a3, voffA);
;             PG8_WAIT_V(8); PG8_WAIT_L(0); PG8_BAR; PG8_MMA(1, 0, At, B0); PG8_MMA(1, 1, At, B1); PG8_BAR; PG8_SCHED;
;         }
;         if constexpr (ALIGN_EPI) { if (wr == 0) PG8_BAR; }
;         E(acc, cur, wr, wc, fr, fq);
;         if (!has_next) break;
	s_add_i32 s10, s63, s33
	v_lshl_add_u64 v[220:221], v[220:221], 0, s[56:57]
	s_mov_b32 m0, s10
	ds_read_b128 v[188:191], v170 offset:49152
	ds_read_b128 v[192:195], v170 offset:50176
	ds_read_b128 v[196:199], v170 offset:51200
	ds_read_b128 v[200:203], v170 offset:52224
	ds_read_b128 v[204:207], v170 offset:53248
	ds_read_b128 v[208:211], v170 offset:54272
	ds_read_b128 v[212:215], v170 offset:55296
	ds_read_b128 v[216:219], v170 offset:56320
	global_load_lds_dwordx4 v[220:221], off
	s_add_i32 m0, s10, 0x2000
	s_add_u32 s8, s8, 0x40080
	v_lshl_add_u64 v[220:221], v[222:223], 0, s[56:57]
	s_addc_u32 s9, s9, 0
	s_add_i32 s10, s84, s33
	global_load_lds_dwordx4 v[220:221], off
	v_lshl_add_u64 v[220:221], s[8:9], 0, v[132:133]
	s_mov_b32 m0, s10
	s_nop 0
	global_load_lds_dwordx4 v[220:221], off
	v_lshl_add_u64 v[220:221], s[8:9], 0, v[136:137]
	s_add_i32 m0, s10, 0x2000
	s_nop 0
	global_load_lds_dwordx4 v[220:221], off
	v_lshl_add_u64 v[220:221], v[224:225], 0, s[56:57]
	s_mov_b32 m0, s78
	s_nop 0
	global_load_lds_dwordx4 v[220:221], off
	v_lshl_add_u64 v[220:221], v[226:227], 0, s[56:57]
	s_mov_b32 m0, s79
	s_nop 0
	global_load_lds_dwordx4 v[220:221], off
	s_waitcnt vmcnt(8)
	s_waitcnt lgkmcnt(0)
	s_barrier
	s_setprio 3
	s_waitcnt lgkmcnt(0)
	v_mfma_f32_16x16x32_bf16 v[62:65], v[146:149], v[188:191], v[62:65]
	v_mfma_f32_16x16x32_bf16 v[54:57], v[154:157], v[188:191], v[54:57]
	v_mfma_f32_16x16x32_bf16 v[46:49], v[146:149], v[196:199], v[46:49]
	v_mfma_f32_16x16x32_bf16 v[38:41], v[154:157], v[196:199], v[38:41]
	v_mfma_f32_16x16x32_bf16 v[30:33], v[146:149], v[204:207], v[30:33]
	v_mfma_f32_16x16x32_bf16 v[22:25], v[154:157], v[204:207], v[22:25]
	v_mfma_f32_16x16x32_bf16 v[14:17], v[146:149], v[212:215], v[14:17]
	v_mfma_f32_16x16x32_bf16 v[6:9], v[154:157], v[212:215], v[6:9]
	v_mfma_f32_16x16x32_bf16 v[62:65], v[150:153], v[192:195], v[62:65]
	v_mfma_f32_16x16x32_bf16 v[54:57], v[158:161], v[192:195], v[54:57]
	v_mfma_f32_16x16x32_bf16 v[46:49], v[150:153], v[200:203], v[46:49]
	v_mfma_f32_16x16x32_bf16 v[38:41], v[158:161], v[200:203], v[38:41]
	v_mfma_f32_16x16x32_bf16 v[30:33], v[150:153], v[208:211], v[30:33]
	v_mfma_f32_16x16x32_bf16 v[22:25], v[158:161], v[208:211], v[22:25]
	v_mfma_f32_16x16x32_bf16 v[14:17], v[150:153], v[216:219], v[14:17]
	v_mfma_f32_16x16x32_bf16 v[6:9], v[158:161], v[216:219], v[6:9]
	v_mfma_f32_16x16x32_bf16 v[58:61], v[172:175], v[188:191], v[58:61]
	v_mfma_f32_16x16x32_bf16 v[50:53], v[180:183], v[188:191], v[50:53]
	v_mfma_f32_16x16x32_bf16 v[42:45], v[172:175], v[196:199], v[42:45]
	v_mfma_f32_16x16x32_bf16 v[34:37], v[180:183], v[196:199], v[34:37]
	v_mfma_f32_16x16x32_bf16 v[26:29], v[172:175], v[204:207], v[26:29]
	v_mfma_f32_16x16x32_bf16 v[18:21], v[180:183], v[204:207], v[18:21]
	v_mfma_f32_16x16x32_bf16 v[10:13], v[172:175], v[212:215], v[10:13]
	v_mfma_f32_16x16x32_bf16 v[2:5], v[180:183], v[212:215], v[2:5]
	v_mfma_f32_16x16x32_bf16 v[58:61], v[176:179], v[192:195], v[58:61]
	v_mfma_f32_16x16x32_bf16 v[50:53], v[184:187], v[192:195], v[50:53]
	v_mfma_f32_16x16x32_bf16 v[42:45], v[176:179], v[200:203], v[42:45]
	v_mfma_f32_16x16x32_bf16 v[34:37], v[184:187], v[200:203], v[34:37]
	v_mfma_f32_16x16x32_bf16 v[26:29], v[176:179], v[208:211], v[26:29]
	v_mfma_f32_16x16x32_bf16 v[18:21], v[184:187], v[208:211], v[18:21]
	v_mfma_f32_16x16x32_bf16 v[10:13], v[176:179], v[216:219], v[10:13]
	v_mfma_f32_16x16x32_bf16 v[2:5], v[184:187], v[216:219], v[2:5]
	s_setprio 0
	s_barrier
	s_add_i32 s61, s61, 2
	s_add_u32 s6, s6, 0x100
	s_addc_u32 s7, s7, 0
	s_add_u32 s16, s16, 0x100
	s_addc_u32 s17, s17, 0
	s_cmp_gt_u32 s61, 13
	s_cbranch_scc0 .LBB0_609
	s_and_b64 vcc, exec, s[58:59]
	s_cbranch_vccz .LBB0_612
	s_barrier

; #define PG8_STAGE(bufoff, gbase, voff) do { _Pragma("unroll") for (int _i = 0; _i < 2; ++_i) \
;         __builtin_amdgcn_global_load_lds((const unsigned*)((const char*)(gbase) + (voff)[_i]), (LAS unsigned*)(lds + (bufoff) + ldsw + _i * 8192), 16, 0, 0); } while (0)
; #define PG8_LDA(dst, b, h) do { _Pragma("unroll") for (int m = 0; m < 4; ++m) _Pragma("unroll") for (int k = 0; k < 2; ++k) dst[m][k] = *(const LAS bf16x8*)(lds + PG8_SA(b, h) + aoff + m * 2048 + k * 1024); } while (0)
; #define PG8_LDB(dst, b, h) do { _Pragma("unroll") for (int n = 0; n < 2; ++n) _Pragma("unroll") for (int k = 0; k < 2; ++k) dst[n][k] = *(const LAS bf16x8*)(lds + PG8_SB(b, h) + boff + n * 2048 + k * 1024); } while (0)
; #define PG8_MMA(ai, bj, At, Bt) do { __builtin_amdgcn_s_setprio(3); _Pragma("unroll") for (int m = 0; m < 4; ++m) _Pragma("unroll") for (int n = 0; n < 2; ++n) _Pragma("unroll") for (int k = 0; k < 2; ++k) \
;         acc[ai][bj][m][n] = __builtin_amdgcn_mfma_f32_16x16x32_bf16(Bt[n][k], At[m][k], acc[ai][bj][m][n], 0, 0, 0); __builtin_amdgcn_s_setprio(0); } while (0)
; #define PG8_WAIT_V(n) asm volatile("s_waitcnt vmcnt(" #n ")" ::: "memory")
; #define PG8_WAIT_L(n) asm volatile("s_waitcnt lgkmcnt(" #n ")" ::: "memory")
; #define PG8_BAR __builtin_amdgcn_s_barrier()
; #define PG8_SCHED __builtin_amdgcn_sched_barrier(0)
; template <class Epi, bool ALIGN_EPI>
; __device__ __forceinline__ void gemm_phase(LAS unsigned char* lds, const Gemm g, const StaticOrder& S, const Epi& E) {
;     ...
;             const char* a1 = cA + (size_t)(t + 1) * kstep;
;             const char* a2 = last ? nA : cA + (size_t)(t + 2) * kstep; const char* b2 = last ? nB : cB + (size_t)(t + 2) * kstep;
;             const char* a3 = a2 + kstep; const char* b3 = b2 + kstep;
;             PG8_LDB(B0, 0, 0); PG8_LDB(B1, 0, 1); PG8_SCHED; PG8_LDA(At, 0, 0); PG8_STAGE(PG8_SA(1, 1), a1 + hstep, voffA);
;             PG8_WAIT_V(8); PG8_WAIT_L(0); PG8_BAR; PG8_MMA(0, 0, At, B0); PG8_MMA(0, 1, At, B1); PG8_BAR; PG8_SCHED;
;             PG8_LDA(At, 0, 1); PG8_STAGE(PG8_SB(0, 0), b2, voffB); PG8_STAGE(PG8_SB(0, 1), b2 + hstep, voffB); PG8_STAGE(PG8_SA(0, 0), a2, voffA);
.LBB0_695:
	s_add_u32 s50, s50, 0xb0080
	s_addc_u32 s51, s51, 0
	s_add_u32 s73, s52, 0x100
	s_addc_u32 s76, s53, 0
	s_mov_b32 s77, -2
	s_waitcnt lgkmcnt(0)
	ds_read_b128 v[130:133], v196
	ds_read_b128 v[134:137], v196 offset:1024
	ds_read_b128 v[138:141], v196 offset:2048
	ds_read_b128 v[142:145], v196 offset:3072
	ds_read_b128 v[146:149], v197
	ds_read_b128 v[150:153], v197 offset:1024
	ds_read_b128 v[170:173], v197 offset:2048
	ds_read_b128 v[174:177], v197 offset:3072
	s_add_u32 s52, s50, 0xfff50080
	s_addc_u32 s53, s51, -1
	s_cmp_eq_u32 s77, 40
	s_cselect_b32 s55, s5, s53
	s_cselect_b32 s54, s4, s52
	s_cselect_b32 s53, s19, s76
	s_cselect_b32 s52, s18, s73
	v_lshl_add_u64 v[186:187], s[50:51], 0, v[162:163]
	s_add_i32 m0, s58, 0xc000
	ds_read_b128 v[178:181], v198
	ds_read_b128 v[182:185], v198 offset:1024
	ds_read_b128 v[200:203], v198 offset:2048
	ds_read_b128 v[204:207], v198 offset:3072
	ds_read_b128 v[208:211], v198 offset:4096
	ds_read_b128 v[212:215], v198 offset:5120
	ds_read_b128 v[216:219], v198 offset:6144
	ds_read_b128 v[220:223], v198 offset:7168
	global_load_lds_dwordx4 v[186:187], off
	v_lshl_add_u64 v[186:187], s[50:51], 0, v[164:165]
	s_add_i32 m0, s58, 0xe000
	s_nop 0
	global_load_lds_dwordx4 v[186:187], off
	s_waitcnt vmcnt(8)
	s_waitcnt lgkmcnt(0)
	s_barrier
	s_setprio 3
	s_waitcnt lgkmcnt(0)
	v_mfma_f32_16x16x32_bf16 v[126:129], v[130:133], v[178:181], 0
	v_mfma_f32_16x16x32_bf16 v[122:125], v[138:141], v[178:181], 0
	v_mfma_f32_16x16x32_bf16 v[110:113], v[130:133], v[200:203], 0
	v_mfma_f32_16x16x32_bf16 v[106:109], v[138:141], v[200:203], 0
	v_mfma_f32_16x16x32_bf16 v[94:97], v[130:133], v[208:211], 0
	v_mfma_f32_16x16x32_bf16 v[90:93], v[138:141], v[208:211], 0
	v_mfma_f32_16x16x32_bf16 v[78:81], v[130:133], v[216:219], 0
	v_mfma_f32_16x16x32_bf16 v[74:77], v[138:141], v[216:219], 0
	v_mfma_f32_16x16x32_bf16 v[126:129], v[134:137], v[182:185], v[126:129]
	v_mfma_f32_16x16x32_bf16 v[122:125], v[142:145], v[182:185], v[122:125]
	v_mfma_f32_16x16x32_bf16 v[110:113], v[134:137], v[204:207], v[110:113]
	v_mfma_f32_16x16x32_bf16 v[106:109], v[142:145], v[204:207], v[106:109]
	v_mfma_f32_16x16x32_bf16 v[94:97], v[134:137], v[212:215], v[94:97]
	v_mfma_f32_16x16x32_bf16 v[90:93], v[142:145], v[212:215], v[90:93]
	v_mfma_f32_16x16x32_bf16 v[78:81], v[134:137], v[220:223], v[78:81]
	v_mfma_f32_16x16x32_bf16 v[74:77], v[142:145], v[220:223], v[74:77]
	v_mfma_f32_16x16x32_bf16 v[118:121], v[146:149], v[178:181], 0
	v_mfma_f32_16x16x32_bf16 v[114:117], v[170:173], v[178:181], 0
	v_mfma_f32_16x16x32_bf16 v[102:105], v[146:149], v[200:203], 0
	v_mfma_f32_16x16x32_bf16 v[98:101], v[170:173], v[200:203], 0
	v_mfma_f32_16x16x32_bf16 v[86:89], v[146:149], v[208:211], 0
	v_mfma_f32_16x16x32_bf16 v[82:85], v[170:173], v[208:211], 0
	v_mfma_f32_16x16x32_bf16 v[70:73], v[146:149], v[216:219], 0
	v_mfma_f32_16x16x32_bf16 v[66:69], v[170:173], v[216:219], 0
	v_mfma_f32_16x16x32_bf16 v[118:121], v[150:153], v[182:185], v[118:121]
	v_mfma_f32_16x16x32_bf16 v[114:117], v[174:177], v[182:185], v[114:117]
	v_mfma_f32_16x16x32_bf16 v[102:105], v[150:153], v[204:207], v[102:105]
	v_mfma_f32_16x16x32_bf16 v[98:101], v[174:177], v[204:207], v[98:101]
	v_mfma_f32_16x16x32_bf16 v[86:89], v[150:153], v[212:215], v[86:89]
	v_mfma_f32_16x16x32_bf16 v[82:85], v[174:177], v[212:215], v[82:85]
	v_mfma_f32_16x16x32_bf16 v[70:73], v[150:153], v[220:223], v[70:73]
	v_mfma_f32_16x16x32_bf16 v[66:69], v[174:177], v[220:223], v[66:69]
	s_setprio 0
	s_barrier
	s_add_i32 s78, s67, s57
	v_lshl_add_u64 v[186:187], s[52:53], 0, v[156:157]
	s_mov_b32 m0, s78
	ds_read_b128 v[178:181], v198 offset:16384
	ds_read_b128 v[182:185], v198 offset:17408
	ds_read_b128 v[200:203], v198 offset:18432
	ds_read_b128 v[204:207], v198 offset:19456
	ds_read_b128 v[208:211], v198 offset:20480
	ds_read_b128 v[212:215], v198 offset:21504
	ds_read_b128 v[216:219], v198 offset:22528
	ds_read_b128 v[220:223], v198 offset:23552
	global_load_lds_dwordx4 v[186:187], off
	s_add_i32 m0, s78, 0x2000
	s_add_u32 s78, s52, 0xb0000
	v_lshl_add_u64 v[224:225], s[52:53], 0, v[160:161]
	s_addc_u32 s79, s53, 0
	s_add_i32 s80, s68, s57
	global_load_lds_dwordx4 v[224:225], off
	v_lshl_add_u64 v[226:227], s[78:79], 0, v[156:157]
	s_mov_b32 m0, s80
	v_lshl_add_u64 v[228:229], s[54:55], 0, v[158:159]
	global_load_lds_dwordx4 v[226:227], off
	v_lshl_add_u64 v[226:227], s[78:79], 0, v[160:161]
	s_add_i32 m0, s80, 0x2000
	s_nop 0
	global_load_lds_dwordx4 v[226:227], off
	v_lshl_add_u64 v[226:227], s[54:55], 0, v[154:155]
	s_mov_b32 m0, s58
	s_nop 0
	global_load_lds_dwordx4 v[226:227], off
	s_mov_b32 m0, s59
	s_nop 0
	global_load_lds_dwordx4 v[228:229], off
	s_waitcnt vmcnt(8)
	s_waitcnt lgkmcnt(0)
	s_barrier
; #define PG8_STAGE(bufoff, gbase, voff) do { _Pragma("unroll") for (int _i = 0; _i < 2; ++_i) \
;         __builtin_amdgcn_global_load_lds((const unsigned*)((const char*)(gbase) + (voff)[_i]), (LAS unsigned*)(lds + (bufoff) + ldsw + _i * 8192), 16, 0, 0); } while (0)
; #define PG8_LDA(dst, b, h) do { _Pragma("unroll") for (int m = 0; m < 4; ++m) _Pragma("unroll") for (int k = 0; k < 2; ++k) dst[m][k] = *(const LAS bf16x8*)(lds + PG8_SA(b, h) + aoff + m * 2048 + k * 1024); } while (0)
; #define PG8_LDB(dst, b, h) do { _Pragma("unroll") for (int n = 0; n < 2; ++n) _Pragma("unroll") for (int k = 0; k < 2; ++k) dst[n][k] = *(const LAS bf16x8*)(lds + PG8_SB(b, h) + boff + n * 2048 + k * 1024); } while (0)
; #define PG8_MMA(ai, bj, At, Bt) do { __builtin_amdgcn_s_setprio(3); _Pragma("unroll") for (int m = 0; m < 4; ++m) _Pragma("unroll") for (int n = 0; n < 2; ++n) _Pragma("unroll") for (int k = 0; k < 2; ++k) \
;         acc[ai][bj][m][n] = __builtin_amdgcn_mfma_f32_16x16x32_bf16(Bt[n][k], At[m][k], acc[ai][bj][m][n], 0, 0, 0); __builtin_amdgcn_s_setprio(0); } while (0)
; #define PG8_WAIT_V(n) asm volatile("s_waitcnt vmcnt(" #n ")" ::: "memory")
; #define PG8_WAIT_L(n) asm volatile("s_waitcnt lgkmcnt(" #n ")" ::: "memory")
; #define PG8_BAR __builtin_amdgcn_s_barrier()
; #define PG8_SCHED __builtin_amdgcn_sched_barrier(0)
; template <class Epi, bool ALIGN_EPI>
; __device__ __forceinline__ void gemm_phase(LAS unsigned char* lds, const Gemm g, const StaticOrder& S, const Epi& E) {
;     ...
;             PG8_WAIT_V(8); PG8_WAIT_L(0); PG8_BAR; PG8_MMA(1, 0, At, B0); PG8_MMA(1, 1, At, B1); PG8_BAR; PG8_SCHED;
;             PG8_LDB(B0, 1, 0); PG8_LDB(B1, 1, 1); PG8_SCHED; PG8_LDA(At, 1, 0); PG8_STAGE(PG8_SA(0, 1), a2 + hstep, voffA);
;             PG8_WAIT_V(8); PG8_WAIT_L(0); PG8_BAR; PG8_MMA(0, 0, At, B0); PG8_MMA(0, 1, At, B1); PG8_BAR; PG8_SCHED;
	s_setprio 3
	s_waitcnt lgkmcnt(0)
	v_mfma_f32_16x16x32_bf16 v[62:65], v[130:133], v[178:181], 0
	v_mfma_f32_16x16x32_bf16 v[58:61], v[138:141], v[178:181], 0
	v_mfma_f32_16x16x32_bf16 v[46:49], v[130:133], v[200:203], 0
	v_mfma_f32_16x16x32_bf16 v[42:45], v[138:141], v[200:203], 0
	v_mfma_f32_16x16x32_bf16 v[30:33], v[130:133], v[208:211], 0
	v_mfma_f32_16x16x32_bf16 v[26:29], v[138:141], v[208:211], 0
	v_mfma_f32_16x16x32_bf16 v[14:17], v[130:133], v[216:219], 0
	v_mfma_f32_16x16x32_bf16 v[10:13], v[138:141], v[216:219], 0
	v_mfma_f32_16x16x32_bf16 v[62:65], v[134:137], v[182:185], v[62:65]
	v_mfma_f32_16x16x32_bf16 v[58:61], v[142:145], v[182:185], v[58:61]
	v_mfma_f32_16x16x32_bf16 v[46:49], v[134:137], v[204:207], v[46:49]
	v_mfma_f32_16x16x32_bf16 v[42:45], v[142:145], v[204:207], v[42:45]
	v_mfma_f32_16x16x32_bf16 v[30:33], v[134:137], v[212:215], v[30:33]
	v_mfma_f32_16x16x32_bf16 v[26:29], v[142:145], v[212:215], v[26:29]
	v_mfma_f32_16x16x32_bf16 v[14:17], v[134:137], v[220:223], v[14:17]
	v_mfma_f32_16x16x32_bf16 v[10:13], v[142:145], v[220:223], v[10:13]
	v_mfma_f32_16x16x32_bf16 v[54:57], v[146:149], v[178:181], 0
	v_mfma_f32_16x16x32_bf16 v[50:53], v[170:173], v[178:181], 0
	v_mfma_f32_16x16x32_bf16 v[38:41], v[146:149], v[200:203], 0
	v_mfma_f32_16x16x32_bf16 v[34:37], v[170:173], v[200:203], 0
	v_mfma_f32_16x16x32_bf16 v[22:25], v[146:149], v[208:211], 0
	v_mfma_f32_16x16x32_bf16 v[18:21], v[170:173], v[208:211], 0
	v_mfma_f32_16x16x32_bf16 v[6:9], v[146:149], v[216:219], 0
	v_mfma_f32_16x16x32_bf16 v[2:5], v[170:173], v[216:219], 0
	v_mfma_f32_16x16x32_bf16 v[54:57], v[150:153], v[182:185], v[54:57]
	v_mfma_f32_16x16x32_bf16 v[50:53], v[174:177], v[182:185], v[50:53]
	v_mfma_f32_16x16x32_bf16 v[38:41], v[150:153], v[204:207], v[38:41]
	v_mfma_f32_16x16x32_bf16 v[34:37], v[174:177], v[204:207], v[34:37]
	v_mfma_f32_16x16x32_bf16 v[22:25], v[150:153], v[212:215], v[22:25]
	v_mfma_f32_16x16x32_bf16 v[18:21], v[174:177], v[212:215], v[18:21]
	v_mfma_f32_16x16x32_bf16 v[6:9], v[150:153], v[220:223], v[6:9]
	v_mfma_f32_16x16x32_bf16 v[2:5], v[174:177], v[220:223], v[2:5]
	s_setprio 0
	s_barrier
	s_add_i32 s78, 0, 0x18000
	s_add_i32 s79, 0, 0x1c000
	v_add_u32_e32 v142, s78, v194
	v_add_u32_e32 v174, s79, v194
	ds_read_b128 v[130:133], v142
	ds_read_b128 v[134:137], v142 offset:1024
	ds_read_b128 v[138:141], v142 offset:2048
	ds_read_b128 v[142:145], v142 offset:3072
	ds_read_b128 v[146:149], v174
	ds_read_b128 v[150:153], v174 offset:1024
	ds_read_b128 v[170:173], v174 offset:2048
	ds_read_b128 v[174:177], v174 offset:3072
	s_add_u32 s54, s54, 0xb0000
	s_addc_u32 s55, s55, 0
	s_mov_b32 m0, s60
	v_lshl_add_u64 v[230:231], s[54:55], 0, v[154:155]
	ds_read_b128 v[178:181], v198 offset:32768
	ds_read_b128 v[182:185], v198 offset:33792
	ds_read_b128 v[200:203], v198 offset:34816
	ds_read_b128 v[204:207], v198 offset:35840
	ds_read_b128 v[208:211], v198 offset:36864
	ds_read_b128 v[212:215], v198 offset:37888
	ds_read_b128 v[216:219], v198 offset:38912
	ds_read_b128 v[220:223], v198 offset:39936
	global_load_lds_dwordx4 v[230:231], off
	v_lshl_add_u64 v[230:231], s[54:55], 0, v[158:159]
	s_mov_b32 m0, s61
	s_nop 0
	global_load_lds_dwordx4 v[230:231], off
	s_waitcnt vmcnt(8)
	s_waitcnt lgkmcnt(0)
	s_barrier
	s_setprio 3
	s_waitcnt lgkmcnt(0)
	v_mfma_f32_16x16x32_bf16 v[126:129], v[130:133], v[178:181], v[126:129]
	v_mfma_f32_16x16x32_bf16 v[122:125], v[138:141], v[178:181], v[122:125]
	v_mfma_f32_16x16x32_bf16 v[110:113], v[130:133], v[200:203], v[110:113]
	v_mfma_f32_16x16x32_bf16 v[106:109], v[138:141], v[200:203], v[106:109]
	v_mfma_f32_16x16x32_bf16 v[94:97], v[130:133], v[208:211], v[94:97]
	v_mfma_f32_16x16x32_bf16 v[90:93], v[138:141], v[208:211], v[90:93]
	v_mfma_f32_16x16x32_bf16 v[78:81], v[130:133], v[216:219], v[78:81]
	v_mfma_f32_16x16x32_bf16 v[74:77], v[138:141], v[216:219], v[74:77]
	v_mfma_f32_16x16x32_bf16 v[126:129], v[134:137], v[182:185], v[126:129]
	v_mfma_f32_16x16x32_bf16 v[122:125], v[142:145], v[182:185], v[122:125]
	v_mfma_f32_16x16x32_bf16 v[110:113], v[134:137], v[204:207], v[110:113]
	v_mfma_f32_16x16x32_bf16 v[106:109], v[142:145], v[204:207], v[106:109]
	v_mfma_f32_16x16x32_bf16 v[94:97], v[134:137], v[212:215], v[94:97]
	v_mfma_f32_16x16x32_bf16 v[90:93], v[142:145], v[212:215], v[90:93]
	v_mfma_f32_16x16x32_bf16 v[78:81], v[134:137], v[220:223], v[78:81]
	v_mfma_f32_16x16x32_bf16 v[74:77], v[142:145], v[220:223], v[74:77]
	v_mfma_f32_16x16x32_bf16 v[118:121], v[146:149], v[178:181], v[118:121]
	v_mfma_f32_16x16x32_bf16 v[114:117], v[170:173], v[178:181], v[114:117]
	v_mfma_f32_16x16x32_bf16 v[102:105], v[146:149], v[200:203], v[102:105]
	v_mfma_f32_16x16x32_bf16 v[98:101], v[170:173], v[200:203], v[98:101]
	v_mfma_f32_16x16x32_bf16 v[86:89], v[146:149], v[208:211], v[86:89]
	v_mfma_f32_16x16x32_bf16 v[82:85], v[170:173], v[208:211], v[82:85]
	v_mfma_f32_16x16x32_bf16 v[70:73], v[146:149], v[216:219], v[70:73]
	v_mfma_f32_16x16x32_bf16 v[66:69], v[170:173], v[216:219], v[66:69]
	v_mfma_f32_16x16x32_bf16 v[118:121], v[150:153], v[182:185], v[118:121]
	v_mfma_f32_16x16x32_bf16 v[114:117], v[174:177], v[182:185], v[114:117]
	v_mfma_f32_16x16x32_bf16 v[102:105], v[150:153], v[204:207], v[102:105]
	v_mfma_f32_16x16x32_bf16 v[98:101], v[174:177], v[204:207], v[98:101]
	v_mfma_f32_16x16x32_bf16 v[86:89], v[150:153], v[212:215], v[86:89]
	v_mfma_f32_16x16x32_bf16 v[82:85], v[174:177], v[212:215], v[82:85]
	v_mfma_f32_16x16x32_bf16 v[70:73], v[150:153], v[220:223], v[70:73]
	v_mfma_f32_16x16x32_bf16 v[66:69], v[174:177], v[220:223], v[66:69]
	s_setprio 0
	s_barrier
; #define PG8_STAGE(bufoff, gbase, voff) do { _Pragma("unroll") for (int _i = 0; _i < 2; ++_i) \
;         __builtin_amdgcn_global_load_lds((const unsigned*)((const char*)(gbase) + (voff)[_i]), (LAS unsigned*)(lds + (bufoff) + ldsw + _i * 8192), 16, 0, 0); } while (0)
; #define PG8_LDA(dst, b, h) do { _Pragma("unroll") for (int m = 0; m < 4; ++m) _Pragma("unroll") for (int k = 0; k < 2; ++k) dst[m][k] = *(const LAS bf16x8*)(lds + PG8_SA(b, h) + aoff + m * 2048 + k * 1024); } while (0)
; #define PG8_LDB(dst, b, h) do { _Pragma("unroll") for (int n = 0; n < 2; ++n) _Pragma("unroll") for (int k = 0; k < 2; ++k) dst[n][k] = *(const LAS bf16x8*)(lds + PG8_SB(b, h) + boff + n * 2048 + k * 1024); } while (0)
; #define PG8_MMA(ai, bj, At, Bt) do { __builtin_amdgcn_s_setprio(3); _Pragma("unroll") for (int m = 0; m < 4; ++m) _Pragma("unroll") for (int n = 0; n < 2; ++n) _Pragma("unroll") for (int k = 0; k < 2; ++k) \
;         acc[ai][bj][m][n] = __builtin_amdgcn_mfma_f32_16x16x32_bf16(Bt[n][k], At[m][k], acc[ai][bj][m][n], 0, 0, 0); __builtin_amdgcn_s_setprio(0); } while (0)
; #define PG8_WAIT_V(n) asm volatile("s_waitcnt vmcnt(" #n ")" ::: "memory")
; #define PG8_WAIT_L(n) asm volatile("s_waitcnt lgkmcnt(" #n ")" ::: "memory")
; #define PG8_BAR __builtin_amdgcn_s_barrier()
; #define PG8_SCHED __builtin_amdgcn_sched_barrier(0)
; template <class Epi, bool ALIGN_EPI>
; __device__ __forceinline__ void gemm_phase(LAS unsigned char* lds, const Gemm g, const StaticOrder& S, const Epi& E) {
;     ...
;             PG8_LDB(B0, 0, 0); PG8_LDB(B1, 0, 1); PG8_SCHED; PG8_LDA(At, 0, 0); PG8_STAGE(PG8_SA(1, 1), a1 + hstep, voffA);
;             PG8_WAIT_V(8); PG8_WAIT_L(0); PG8_BAR; PG8_MMA(0, 0, At, B0); PG8_MMA(0, 1, At, B1); PG8_BAR; PG8_SCHED;
;     ...
;             PG8_LDA(At, 1, 1); PG8_STAGE(PG8_SB(1, 0), b3, voffB); PG8_STAGE(PG8_SB(1, 1), b3 + hstep, voffB); PG8_STAGE(PG8_SA(1, 0), a3, voffA);
;             PG8_WAIT_V(8); PG8_WAIT_L(0); PG8_BAR; PG8_MMA(1, 0, At, B0); PG8_MMA(1, 1, At, B1); PG8_BAR; PG8_SCHED;
	s_add_i32 s54, s78, s57
	v_lshl_add_u64 v[186:187], v[186:187], 0, s[14:15]
	s_mov_b32 m0, s54
	ds_read_b128 v[178:181], v198 offset:49152
	ds_read_b128 v[182:185], v198 offset:50176
	ds_read_b128 v[200:203], v198 offset:51200
	ds_read_b128 v[204:207], v198 offset:52224
	ds_read_b128 v[208:211], v198 offset:53248
	ds_read_b128 v[212:215], v198 offset:54272
	ds_read_b128 v[216:219], v198 offset:55296
	ds_read_b128 v[220:223], v198 offset:56320
	global_load_lds_dwordx4 v[186:187], off
	s_add_i32 m0, s54, 0x2000
	s_add_u32 s52, s52, 0xb0080
	v_lshl_add_u64 v[186:187], v[224:225], 0, s[14:15]
	s_addc_u32 s53, s53, 0
	s_add_i32 s54, s79, s57
	global_load_lds_dwordx4 v[186:187], off
	v_lshl_add_u64 v[186:187], s[52:53], 0, v[156:157]
	s_mov_b32 m0, s54
	s_nop 0
	global_load_lds_dwordx4 v[186:187], off
	v_lshl_add_u64 v[186:187], s[52:53], 0, v[160:161]
	s_add_i32 m0, s54, 0x2000
	s_nop 0
	global_load_lds_dwordx4 v[186:187], off
	v_lshl_add_u64 v[186:187], v[226:227], 0, s[14:15]
	s_mov_b32 m0, s63
	s_nop 0
	global_load_lds_dwordx4 v[186:187], off
	v_lshl_add_u64 v[186:187], v[228:229], 0, s[14:15]
	s_mov_b32 m0, s64
	s_nop 0
	global_load_lds_dwordx4 v[186:187], off
	s_waitcnt vmcnt(8)
	s_waitcnt lgkmcnt(0)
	s_barrier
	s_setprio 3
	s_waitcnt lgkmcnt(0)
	v_mfma_f32_16x16x32_bf16 v[62:65], v[130:133], v[178:181], v[62:65]
	v_mfma_f32_16x16x32_bf16 v[58:61], v[138:141], v[178:181], v[58:61]
	v_mfma_f32_16x16x32_bf16 v[46:49], v[130:133], v[200:203], v[46:49]
	v_mfma_f32_16x16x32_bf16 v[42:45], v[138:141], v[200:203], v[42:45]
	v_mfma_f32_16x16x32_bf16 v[30:33], v[130:133], v[208:211], v[30:33]
	v_mfma_f32_16x16x32_bf16 v[26:29], v[138:141], v[208:211], v[26:29]
	v_mfma_f32_16x16x32_bf16 v[14:17], v[130:133], v[216:219], v[14:17]
	v_mfma_f32_16x16x32_bf16 v[10:13], v[138:141], v[216:219], v[10:13]
	v_mfma_f32_16x16x32_bf16 v[62:65], v[134:137], v[182:185], v[62:65]
	v_mfma_f32_16x16x32_bf16 v[58:61], v[142:145], v[182:185], v[58:61]
	v_mfma_f32_16x16x32_bf16 v[46:49], v[134:137], v[204:207], v[46:49]
	v_mfma_f32_16x16x32_bf16 v[42:45], v[142:145], v[204:207], v[42:45]
	v_mfma_f32_16x16x32_bf16 v[30:33], v[134:137], v[212:215], v[30:33]
	v_mfma_f32_16x16x32_bf16 v[26:29], v[142:145], v[212:215], v[26:29]
	v_mfma_f32_16x16x32_bf16 v[14:17], v[134:137], v[220:223], v[14:17]
	v_mfma_f32_16x16x32_bf16 v[10:13], v[142:145], v[220:223], v[10:13]
	v_mfma_f32_16x16x32_bf16 v[54:57], v[146:149], v[178:181], v[54:57]
	v_mfma_f32_16x16x32_bf16 v[50:53], v[170:173], v[178:181], v[50:53]
	v_mfma_f32_16x16x32_bf16 v[38:41], v[146:149], v[200:203], v[38:41]
	v_mfma_f32_16x16x32_bf16 v[34:37], v[170:173], v[200:203], v[34:37]
	v_mfma_f32_16x16x32_bf16 v[22:25], v[146:149], v[208:211], v[22:25]
	v_mfma_f32_16x16x32_bf16 v[18:21], v[170:173], v[208:211], v[18:21]
	v_mfma_f32_16x16x32_bf16 v[6:9], v[146:149], v[216:219], v[6:9]
	v_mfma_f32_16x16x32_bf16 v[2:5], v[170:173], v[216:219], v[2:5]
	v_mfma_f32_16x16x32_bf16 v[54:57], v[150:153], v[182:185], v[54:57]
	v_mfma_f32_16x16x32_bf16 v[50:53], v[174:177], v[182:185], v[50:53]
	v_mfma_f32_16x16x32_bf16 v[38:41], v[150:153], v[204:207], v[38:41]
	v_mfma_f32_16x16x32_bf16 v[34:37], v[174:177], v[204:207], v[34:37]
	v_mfma_f32_16x16x32_bf16 v[22:25], v[150:153], v[212:215], v[22:25]
	v_mfma_f32_16x16x32_bf16 v[18:21], v[174:177], v[212:215], v[18:21]
	v_mfma_f32_16x16x32_bf16 v[6:9], v[150:153], v[220:223], v[6:9]
	v_mfma_f32_16x16x32_bf16 v[2:5], v[174:177], v[220:223], v[2:5]
	s_setprio 0
	s_barrier
	s_add_i32 s77, s77, 2
	s_add_u32 s50, s50, 0x100
	s_addc_u32 s51, s51, 0
	s_add_u32 s73, s73, 0x100
	s_addc_u32 s76, s76, 0
.LBB0_696:
	ds_read_b128 v[130:133], v196
	ds_read_b128 v[134:137], v196 offset:1024
	ds_read_b128 v[138:141], v196 offset:2048
	ds_read_b128 v[142:145], v196 offset:3072
	ds_read_b128 v[146:149], v197
	ds_read_b128 v[150:153], v197 offset:1024
	ds_read_b128 v[170:173], v197 offset:2048
	ds_read_b128 v[174:177], v197 offset:3072
	s_add_u32 s52, s50, 0xfff50080
	s_addc_u32 s53, s51, -1
	s_cmp_eq_u32 s77, 40
	s_cselect_b32 s55, s5, s53
	s_cselect_b32 s54, s4, s52
	s_cselect_b32 s53, s19, s76
	s_cselect_b32 s52, s18, s73
	v_lshl_add_u64 v[186:187], s[50:51], 0, v[162:163]
	s_add_i32 m0, s58, 0xc000
	ds_read_b128 v[178:181], v198
	ds_read_b128 v[182:185], v198 offset:1024
	ds_read_b128 v[200:203], v198 offset:2048
	ds_read_b128 v[204:207], v198 offset:3072
	ds_read_b128 v[208:211], v198 offset:4096
	ds_read_b128 v[212:215], v198 offset:5120
	ds_read_b128 v[216:219], v198 offset:6144
	ds_read_b128 v[220:223], v198 offset:7168
	global_load_lds_dwordx4 v[186:187], off
	v_lshl_add_u64 v[186:187], s[50:51], 0, v[164:165]
	s_add_i32 m0, s58, 0xe000
	s_nop 0
	global_load_lds_dwordx4 v[186:187], off
	s_waitcnt vmcnt(8)
	s_waitcnt lgkmcnt(0)
	s_barrier
; #define PG8_STAGE(bufoff, gbase, voff) do { _Pragma("unroll") for (int _i = 0; _i < 2; ++_i) \
;         __builtin_amdgcn_global_load_lds((const unsigned*)((const char*)(gbase) + (voff)[_i]), (LAS unsigned*)(lds + (bufoff) + ldsw + _i * 8192), 16, 0, 0); } while (0)
; #define PG8_LDA(dst, b, h) do { _Pragma("unroll") for (int m = 0; m < 4; ++m) _Pragma("unroll") for (int k = 0; k < 2; ++k) dst[m][k] = *(const LAS bf16x8*)(lds + PG8_SA(b, h) + aoff + m * 2048 + k * 1024); } while (0)
; #define PG8_MMA(ai, bj, At, Bt) do { __builtin_amdgcn_s_setprio(3); _Pragma("unroll") for (int m = 0; m < 4; ++m) _Pragma("unroll") for (int n = 0; n < 2; ++n) _Pragma("unroll") for (int k = 0; k < 2; ++k) \
;         acc[ai][bj][m][n] = __builtin_amdgcn_mfma_f32_16x16x32_bf16(Bt[n][k], At[m][k], acc[ai][bj][m][n], 0, 0, 0); __builtin_amdgcn_s_setprio(0); } while (0)
; #define PG8_WAIT_V(n) asm volatile("s_waitcnt vmcnt(" #n ")" ::: "memory")
; #define PG8_WAIT_L(n) asm volatile("s_waitcnt lgkmcnt(" #n ")" ::: "memory")
; #define PG8_BAR __builtin_amdgcn_s_barrier()
; #define PG8_SCHED __builtin_amdgcn_sched_barrier(0)
; template <class Epi, bool ALIGN_EPI>
; __device__ __forceinline__ void gemm_phase(LAS unsigned char* lds, const Gemm g, const StaticOrder& S, const Epi& E) {
;     ...
;             PG8_WAIT_V(8); PG8_WAIT_L(0); PG8_BAR; PG8_MMA(0, 0, At, B0); PG8_MMA(0, 1, At, B1); PG8_BAR; PG8_SCHED;
;             PG8_LDA(At, 0, 1); PG8_STAGE(PG8_SB(0, 0), b2, voffB); PG8_STAGE(PG8_SB(0, 1), b2 + hstep, voffB); PG8_STAGE(PG8_SA(0, 0), a2, voffA);
;             PG8_WAIT_V(8); PG8_WAIT_L(0); PG8_BAR; PG8_MMA(1, 0, At, B0); PG8_MMA(1, 1, At, B1); PG8_BAR; PG8_SCHED;
	s_setprio 3
	s_waitcnt lgkmcnt(0)
	v_mfma_f32_16x16x32_bf16 v[126:129], v[130:133], v[178:181], v[126:129]
	v_mfma_f32_16x16x32_bf16 v[122:125], v[138:141], v[178:181], v[122:125]
	v_mfma_f32_16x16x32_bf16 v[110:113], v[130:133], v[200:203], v[110:113]
	v_mfma_f32_16x16x32_bf16 v[106:109], v[138:141], v[200:203], v[106:109]
	v_mfma_f32_16x16x32_bf16 v[94:97], v[130:133], v[208:211], v[94:97]
	v_mfma_f32_16x16x32_bf16 v[90:93], v[138:141], v[208:211], v[90:93]
	v_mfma_f32_16x16x32_bf16 v[78:81], v[130:133], v[216:219], v[78:81]
	v_mfma_f32_16x16x32_bf16 v[74:77], v[138:141], v[216:219], v[74:77]
	v_mfma_f32_16x16x32_bf16 v[126:129], v[134:137], v[182:185], v[126:129]
	v_mfma_f32_16x16x32_bf16 v[122:125], v[142:145], v[182:185], v[122:125]
	v_mfma_f32_16x16x32_bf16 v[110:113], v[134:137], v[204:207], v[110:113]
	v_mfma_f32_16x16x32_bf16 v[106:109], v[142:145], v[204:207], v[106:109]
	v_mfma_f32_16x16x32_bf16 v[94:97], v[134:137], v[212:215], v[94:97]
	v_mfma_f32_16x16x32_bf16 v[90:93], v[142:145], v[212:215], v[90:93]
	v_mfma_f32_16x16x32_bf16 v[78:81], v[134:137], v[220:223], v[78:81]
	v_mfma_f32_16x16x32_bf16 v[74:77], v[142:145], v[220:223], v[74:77]
	v_mfma_f32_16x16x32_bf16 v[118:121], v[146:149], v[178:181], v[118:121]
	v_mfma_f32_16x16x32_bf16 v[114:117], v[170:173], v[178:181], v[114:117]
	v_mfma_f32_16x16x32_bf16 v[102:105], v[146:149], v[200:203], v[102:105]
	v_mfma_f32_16x16x32_bf16 v[98:101], v[170:173], v[200:203], v[98:101]
	v_mfma_f32_16x16x32_bf16 v[86:89], v[146:149], v[208:211], v[86:89]
	v_mfma_f32_16x16x32_bf16 v[82:85], v[170:173], v[208:211], v[82:85]
	v_mfma_f32_16x16x32_bf16 v[70:73], v[146:149], v[216:219], v[70:73]
	v_mfma_f32_16x16x32_bf16 v[66:69], v[170:173], v[216:219], v[66:69]
	v_mfma_f32_16x16x32_bf16 v[118:121], v[150:153], v[182:185], v[118:121]
	v_mfma_f32_16x16x32_bf16 v[114:117], v[174:177], v[182:185], v[114:117]
	v_mfma_f32_16x16x32_bf16 v[102:105], v[150:153], v[204:207], v[102:105]
	v_mfma_f32_16x16x32_bf16 v[98:101], v[174:177], v[204:207], v[98:101]
	v_mfma_f32_16x16x32_bf16 v[86:89], v[150:153], v[212:215], v[86:89]
	v_mfma_f32_16x16x32_bf16 v[82:85], v[174:177], v[212:215], v[82:85]
	v_mfma_f32_16x16x32_bf16 v[70:73], v[150:153], v[220:223], v[70:73]
	v_mfma_f32_16x16x32_bf16 v[66:69], v[174:177], v[220:223], v[66:69]
	s_setprio 0
	s_barrier
	s_add_i32 s78, s67, s57
	v_lshl_add_u64 v[186:187], s[52:53], 0, v[156:157]
	s_mov_b32 m0, s78
	ds_read_b128 v[178:181], v198 offset:16384
	ds_read_b128 v[182:185], v198 offset:17408
	ds_read_b128 v[200:203], v198 offset:18432
	ds_read_b128 v[204:207], v198 offset:19456
	ds_read_b128 v[208:211], v198 offset:20480
	ds_read_b128 v[212:215], v198 offset:21504
	ds_read_b128 v[216:219], v198 offset:22528
	ds_read_b128 v[220:223], v198 offset:23552
	global_load_lds_dwordx4 v[186:187], off
	s_add_i32 m0, s78, 0x2000
	s_add_u32 s78, s52, 0xb0000
	v_lshl_add_u64 v[224:225], s[52:53], 0, v[160:161]
	s_addc_u32 s79, s53, 0
	s_add_i32 s80, s68, s57
	global_load_lds_dwordx4 v[224:225], off
	v_lshl_add_u64 v[226:227], s[78:79], 0, v[156:157]
	s_mov_b32 m0, s80
	v_lshl_add_u64 v[228:229], s[54:55], 0, v[158:159]
	global_load_lds_dwordx4 v[226:227], off
	v_lshl_add_u64 v[226:227], s[78:79], 0, v[160:161]
	s_add_i32 m0, s80, 0x2000
	s_nop 0
	global_load_lds_dwordx4 v[226:227], off
	v_lshl_add_u64 v[226:227], s[54:55], 0, v[154:155]
	s_mov_b32 m0, s58
	s_nop 0
	global_load_lds_dwordx4 v[226:227], off
	s_mov_b32 m0, s59
	s_nop 0
	global_load_lds_dwordx4 v[228:229], off
	s_waitcnt vmcnt(8)
	s_waitcnt lgkmcnt(0)
	s_barrier
	s_setprio 3
	s_waitcnt lgkmcnt(0)
	v_mfma_f32_16x16x32_bf16 v[62:65], v[130:133], v[178:181], v[62:65]
	v_mfma_f32_16x16x32_bf16 v[58:61], v[138:141], v[178:181], v[58:61]
	v_mfma_f32_16x16x32_bf16 v[46:49], v[130:133], v[200:203], v[46:49]
	v_mfma_f32_16x16x32_bf16 v[42:45], v[138:141], v[200:203], v[42:45]
	v_mfma_f32_16x16x32_bf16 v[30:33], v[130:133], v[208:211], v[30:33]
	v_mfma_f32_16x16x32_bf16 v[26:29], v[138:141], v[208:211], v[26:29]
	v_mfma_f32_16x16x32_bf16 v[14:17], v[130:133], v[216:219], v[14:17]
	v_mfma_f32_16x16x32_bf16 v[10:13], v[138:141], v[216:219], v[10:13]
	v_mfma_f32_16x16x32_bf16 v[62:65], v[134:137], v[182:185], v[62:65]
	v_mfma_f32_16x16x32_bf16 v[58:61], v[142:145], v[182:185], v[58:61]
	v_mfma_f32_16x16x32_bf16 v[46:49], v[134:137], v[204:207], v[46:49]
	v_mfma_f32_16x16x32_bf16 v[42:45], v[142:145], v[204:207], v[42:45]
	v_mfma_f32_16x16x32_bf16 v[30:33], v[134:137], v[212:215], v[30:33]
	v_mfma_f32_16x16x32_bf16 v[26:29], v[142:145], v[212:215], v[26:29]
	v_mfma_f32_16x16x32_bf16 v[14:17], v[134:137], v[220:223], v[14:17]
	v_mfma_f32_16x16x32_bf16 v[10:13], v[142:145], v[220:223], v[10:13]
	v_mfma_f32_16x16x32_bf16 v[54:57], v[146:149], v[178:181], v[54:57]
	v_mfma_f32_16x16x32_bf16 v[50:53], v[170:173], v[178:181], v[50:53]
	v_mfma_f32_16x16x32_bf16 v[38:41], v[146:149], v[200:203], v[38:41]
	v_mfma_f32_16x16x32_bf16 v[34:37], v[170:173], v[200:203], v[34:37]
	v_mfma_f32_16x16x32_bf16 v[22:25], v[146:149], v[208:211], v[22:25]
	v_mfma_f32_16x16x32_bf16 v[18:21], v[170:173], v[208:211], v[18:21]
	v_mfma_f32_16x16x32_bf16 v[6:9], v[146:149], v[216:219], v[6:9]
	v_mfma_f32_16x16x32_bf16 v[2:5], v[170:173], v[216:219], v[2:5]
	v_mfma_f32_16x16x32_bf16 v[54:57], v[150:153], v[182:185], v[54:57]
	v_mfma_f32_16x16x32_bf16 v[50:53], v[174:177], v[182:185], v[50:53]
	v_mfma_f32_16x16x32_bf16 v[38:41], v[150:153], v[204:207], v[38:41]
	v_mfma_f32_16x16x32_bf16 v[34:37], v[174:177], v[204:207], v[34:37]
	v_mfma_f32_16x16x32_bf16 v[22:25], v[150:153], v[212:215], v[22:25]
	v_mfma_f32_16x16x32_bf16 v[18:21], v[174:177], v[212:215], v[18:21]
	v_mfma_f32_16x16x32_bf16 v[6:9], v[150:153], v[220:223], v[6:9]
	v_mfma_f32_16x16x32_bf16 v[2:5], v[174:177], v[220:223], v[2:5]
	s_setprio 0
	s_barrier
; #define PG8_STAGE(bufoff, gbase, voff) do { _Pragma("unroll") for (int _i = 0; _i < 2; ++_i) \
;         __builtin_amdgcn_global_load_lds((const unsigned*)((const char*)(gbase) + (voff)[_i]), (LAS unsigned*)(lds + (bufoff) + ldsw + _i * 8192), 16, 0, 0); } while (0)
; #define PG8_LDA(dst, b, h) do { _Pragma("unroll") for (int m = 0; m < 4; ++m) _Pragma("unroll") for (int k = 0; k < 2; ++k) dst[m][k] = *(const LAS bf16x8*)(lds + PG8_SA(b, h) + aoff + m * 2048 + k * 1024); } while (0)
; #define PG8_LDB(dst, b, h) do { _Pragma("unroll") for (int n = 0; n < 2; ++n) _Pragma("unroll") for (int k = 0; k < 2; ++k) dst[n][k] = *(const LAS bf16x8*)(lds + PG8_SB(b, h) + boff + n * 2048 + k * 1024); } while (0)
; #define PG8_MMA(ai, bj, At, Bt) do { __builtin_amdgcn_s_setprio(3); _Pragma("unroll") for (int m = 0; m < 4; ++m) _Pragma("unroll") for (int n = 0; n < 2; ++n) _Pragma("unroll") for (int k = 0; k < 2; ++k) \
;         acc[ai][bj][m][n] = __builtin_amdgcn_mfma_f32_16x16x32_bf16(Bt[n][k], At[m][k], acc[ai][bj][m][n], 0, 0, 0); __builtin_amdgcn_s_setprio(0); } while (0)
; #define PG8_WAIT_V(n) asm volatile("s_waitcnt vmcnt(" #n ")" ::: "memory")
; #define PG8_WAIT_L(n) asm volatile("s_waitcnt lgkmcnt(" #n ")" ::: "memory")
; #define PG8_BAR __builtin_amdgcn_s_barrier()
; #define PG8_SCHED __builtin_amdgcn_sched_barrier(0)
; template <class Epi, bool ALIGN_EPI>
; __device__ __forceinline__ void gemm_phase(LAS unsigned char* lds, const Gemm g, const StaticOrder& S, const Epi& E) {
;     ...
;             PG8_LDB(B0, 1, 0); PG8_LDB(B1, 1, 1); PG8_SCHED; PG8_LDA(At, 1, 0); PG8_STAGE(PG8_SA(0, 1), a2 + hstep, voffA);
;             PG8_WAIT_V(8); PG8_WAIT_L(0); PG8_BAR; PG8_MMA(0, 0, At, B0); PG8_MMA(0, 1, At, B1); PG8_BAR; PG8_SCHED;
	s_add_i32 s78, 0, 0x18000
	s_add_i32 s79, 0, 0x1c000
	v_add_u32_e32 v142, s78, v194
	v_add_u32_e32 v174, s79, v194
	ds_read_b128 v[130:133], v142
	ds_read_b128 v[134:137], v142 offset:1024
	ds_read_b128 v[138:141], v142 offset:2048
	ds_read_b128 v[142:145], v142 offset:3072
	ds_read_b128 v[146:149], v174
	ds_read_b128 v[150:153], v174 offset:1024
	ds_read_b128 v[170:173], v174 offset:2048
	ds_read_b128 v[174:177], v174 offset:3072
	s_add_u32 s54, s54, 0xb0000
	s_addc_u32 s55, s55, 0
	s_mov_b32 m0, s60
	v_lshl_add_u64 v[230:231], s[54:55], 0, v[154:155]
	ds_read_b128 v[178:181], v198 offset:32768
	ds_read_b128 v[182:185], v198 offset:33792
	ds_read_b128 v[200:203], v198 offset:34816
	ds_read_b128 v[204:207], v198 offset:35840
	ds_read_b128 v[208:211], v198 offset:36864
	ds_read_b128 v[212:215], v198 offset:37888
	ds_read_b128 v[216:219], v198 offset:38912
	ds_read_b128 v[220:223], v198 offset:39936
	global_load_lds_dwordx4 v[230:231], off
	v_lshl_add_u64 v[230:231], s[54:55], 0, v[158:159]
	s_mov_b32 m0, s61
	s_nop 0
	global_load_lds_dwordx4 v[230:231], off
	s_waitcnt vmcnt(8)
	s_waitcnt lgkmcnt(0)
	s_barrier
	s_setprio 3
	s_waitcnt lgkmcnt(0)
	v_mfma_f32_16x16x32_bf16 v[126:129], v[130:133], v[178:181], v[126:129]
	v_mfma_f32_16x16x32_bf16 v[122:125], v[138:141], v[178:181], v[122:125]
	v_mfma_f32_16x16x32_bf16 v[110:113], v[130:133], v[200:203], v[110:113]
	v_mfma_f32_16x16x32_bf16 v[106:109], v[138:141], v[200:203], v[106:109]
	v_mfma_f32_16x16x32_bf16 v[94:97], v[130:133], v[208:211], v[94:97]
	v_mfma_f32_16x16x32_bf16 v[90:93], v[138:141], v[208:211], v[90:93]
	v_mfma_f32_16x16x32_bf16 v[78:81], v[130:133], v[216:219], v[78:81]
	v_mfma_f32_16x16x32_bf16 v[74:77], v[138:141], v[216:219], v[74:77]
	v_mfma_f32_16x16x32_bf16 v[126:129], v[134:137], v[182:185], v[126:129]
	v_mfma_f32_16x16x32_bf16 v[122:125], v[142:145], v[182:185], v[122:125]
	v_mfma_f32_16x16x32_bf16 v[110:113], v[134:137], v[204:207], v[110:113]
	v_mfma_f32_16x16x32_bf16 v[106:109], v[142:145], v[204:207], v[106:109]
	v_mfma_f32_16x16x32_bf16 v[94:97], v[134:137], v[212:215], v[94:97]
	v_mfma_f32_16x16x32_bf16 v[90:93], v[142:145], v[212:215], v[90:93]
	v_mfma_f32_16x16x32_bf16 v[78:81], v[134:137], v[220:223], v[78:81]
	v_mfma_f32_16x16x32_bf16 v[74:77], v[142:145], v[220:223], v[74:77]
	v_mfma_f32_16x16x32_bf16 v[118:121], v[146:149], v[178:181], v[118:121]
	v_mfma_f32_16x16x32_bf16 v[114:117], v[170:173], v[178:181], v[114:117]
	v_mfma_f32_16x16x32_bf16 v[102:105], v[146:149], v[200:203], v[102:105]
	v_mfma_f32_16x16x32_bf16 v[98:101], v[170:173], v[200:203], v[98:101]
	v_mfma_f32_16x16x32_bf16 v[86:89], v[146:149], v[208:211], v[86:89]
	v_mfma_f32_16x16x32_bf16 v[82:85], v[170:173], v[208:211], v[82:85]
	v_mfma_f32_16x16x32_bf16 v[70:73], v[146:149], v[216:219], v[70:73]
	v_mfma_f32_16x16x32_bf16 v[66:69], v[170:173], v[216:219], v[66:69]
	v_mfma_f32_16x16x32_bf16 v[118:121], v[150:153], v[182:185], v[118:121]
	v_mfma_f32_16x16x32_bf16 v[114:117], v[174:177], v[182:185], v[114:117]
	v_mfma_f32_16x16x32_bf16 v[102:105], v[150:153], v[204:207], v[102:105]
	v_mfma_f32_16x16x32_bf16 v[98:101], v[174:177], v[204:207], v[98:101]
	v_mfma_f32_16x16x32_bf16 v[86:89], v[150:153], v[212:215], v[86:89]
	v_mfma_f32_16x16x32_bf16 v[82:85], v[174:177], v[212:215], v[82:85]
	v_mfma_f32_16x16x32_bf16 v[70:73], v[150:153], v[220:223], v[70:73]
	v_mfma_f32_16x16x32_bf16 v[66:69], v[174:177], v[220:223], v[66:69]
	s_setprio 0
	s_barrier
; #define PG8_STAGE(bufoff, gbase, voff) do { _Pragma("unroll") for (int _i = 0; _i < 2; ++_i) \
;         __builtin_amdgcn_global_load_lds((const unsigned*)((const char*)(gbase) + (voff)[_i]), (LAS unsigned*)(lds + (bufoff) + ldsw + _i * 8192), 16, 0, 0); } while (0)
; #define PG8_LDA(dst, b, h) do { _Pragma("unroll") for (int m = 0; m < 4; ++m) _Pragma("unroll") for (int k = 0; k < 2; ++k) dst[m][k] = *(const LAS bf16x8*)(lds + PG8_SA(b, h) + aoff + m * 2048 + k * 1024); } while (0)
; #define PG8_MMA(ai, bj, At, Bt) do { __builtin_amdgcn_s_setprio(3); _Pragma("unroll") for (int m = 0; m < 4; ++m) _Pragma("unroll") for (int n = 0; n < 2; ++n) _Pragma("unroll") for (int k = 0; k < 2; ++k) \
;         acc[ai][bj][m][n] = __builtin_amdgcn_mfma_f32_16x16x32_bf16(Bt[n][k], At[m][k], acc[ai][bj][m][n], 0, 0, 0); __builtin_amdgcn_s_setprio(0); } while (0)
; #define PG8_WAIT_V(n) asm volatile("s_waitcnt vmcnt(" #n ")" ::: "memory")
; #define PG8_WAIT_L(n) asm volatile("s_waitcnt lgkmcnt(" #n ")" ::: "memory")
; #define PG8_BAR __builtin_amdgcn_s_barrier()
; #define PG8_SCHED __builtin_amdgcn_sched_barrier(0)
; template <class Epi, bool ALIGN_EPI>
; __device__ __forceinline__ void gemm_phase(LAS unsigned char* lds, const Gemm g, const StaticOrder& S, const Epi& E) {
;     ...
;             PG8_LDA(At, 1, 1); PG8_STAGE(PG8_SB(1, 0), b3, voffB); PG8_STAGE(PG8_SB(1, 1), b3 + hstep, voffB); PG8_STAGE(PG8_SA(1, 0), a3, voffA);
;             PG8_WAIT_V(8); PG8_WAIT_L(0); PG8_BAR; PG8_MMA(1, 0, At, B0); PG8_MMA(1, 1, At, B1); PG8_BAR; PG8_SCHED;
;         }
;         if constexpr (ALIGN_EPI) { if (wr == 0) PG8_BAR; }
;         E(acc, cur, wr, wc, fr, fq);
;         if (!has_next) break;
	s_add_i32 s54, s78, s57
	v_lshl_add_u64 v[186:187], v[186:187], 0, s[14:15]
	s_mov_b32 m0, s54
	ds_read_b128 v[178:181], v198 offset:49152
	ds_read_b128 v[182:185], v198 offset:50176
	ds_read_b128 v[200:203], v198 offset:51200
	ds_read_b128 v[204:207], v198 offset:52224
	ds_read_b128 v[208:211], v198 offset:53248
	ds_read_b128 v[212:215], v198 offset:54272
	ds_read_b128 v[216:219], v198 offset:55296
	ds_read_b128 v[220:223], v198 offset:56320
	global_load_lds_dwordx4 v[186:187], off
	s_add_i32 m0, s54, 0x2000
	s_add_u32 s52, s52, 0xb0080
	v_lshl_add_u64 v[186:187], v[224:225], 0, s[14:15]
	s_addc_u32 s53, s53, 0
	s_add_i32 s54, s79, s57
	global_load_lds_dwordx4 v[186:187], off
	v_lshl_add_u64 v[186:187], s[52:53], 0, v[156:157]
	s_mov_b32 m0, s54
	s_nop 0
	global_load_lds_dwordx4 v[186:187], off
	v_lshl_add_u64 v[186:187], s[52:53], 0, v[160:161]
	s_add_i32 m0, s54, 0x2000
	s_nop 0
	global_load_lds_dwordx4 v[186:187], off
	v_lshl_add_u64 v[186:187], v[226:227], 0, s[14:15]
	s_mov_b32 m0, s63
	s_nop 0
	global_load_lds_dwordx4 v[186:187], off
	v_lshl_add_u64 v[186:187], v[228:229], 0, s[14:15]
	s_mov_b32 m0, s64
	s_nop 0
	global_load_lds_dwordx4 v[186:187], off
	s_waitcnt vmcnt(8)
	s_waitcnt lgkmcnt(0)
	s_barrier
	s_setprio 3
	s_waitcnt lgkmcnt(0)
	v_mfma_f32_16x16x32_bf16 v[62:65], v[130:133], v[178:181], v[62:65]
	v_mfma_f32_16x16x32_bf16 v[58:61], v[138:141], v[178:181], v[58:61]
	v_mfma_f32_16x16x32_bf16 v[46:49], v[130:133], v[200:203], v[46:49]
	v_mfma_f32_16x16x32_bf16 v[42:45], v[138:141], v[200:203], v[42:45]
	v_mfma_f32_16x16x32_bf16 v[30:33], v[130:133], v[208:211], v[30:33]
	v_mfma_f32_16x16x32_bf16 v[26:29], v[138:141], v[208:211], v[26:29]
	v_mfma_f32_16x16x32_bf16 v[14:17], v[130:133], v[216:219], v[14:17]
	v_mfma_f32_16x16x32_bf16 v[10:13], v[138:141], v[216:219], v[10:13]
	v_mfma_f32_16x16x32_bf16 v[62:65], v[134:137], v[182:185], v[62:65]
	v_mfma_f32_16x16x32_bf16 v[58:61], v[142:145], v[182:185], v[58:61]
	v_mfma_f32_16x16x32_bf16 v[46:49], v[134:137], v[204:207], v[46:49]
	v_mfma_f32_16x16x32_bf16 v[42:45], v[142:145], v[204:207], v[42:45]
	v_mfma_f32_16x16x32_bf16 v[30:33], v[134:137], v[212:215], v[30:33]
	v_mfma_f32_16x16x32_bf16 v[26:29], v[142:145], v[212:215], v[26:29]
	v_mfma_f32_16x16x32_bf16 v[14:17], v[134:137], v[220:223], v[14:17]
	v_mfma_f32_16x16x32_bf16 v[10:13], v[142:145], v[220:223], v[10:13]
	v_mfma_f32_16x16x32_bf16 v[54:57], v[146:149], v[178:181], v[54:57]
	v_mfma_f32_16x16x32_bf16 v[50:53], v[170:173], v[178:181], v[50:53]
	v_mfma_f32_16x16x32_bf16 v[38:41], v[146:149], v[200:203], v[38:41]
	v_mfma_f32_16x16x32_bf16 v[34:37], v[170:173], v[200:203], v[34:37]
	v_mfma_f32_16x16x32_bf16 v[22:25], v[146:149], v[208:211], v[22:25]
	v_mfma_f32_16x16x32_bf16 v[18:21], v[170:173], v[208:211], v[18:21]
	v_mfma_f32_16x16x32_bf16 v[6:9], v[146:149], v[216:219], v[6:9]
	v_mfma_f32_16x16x32_bf16 v[2:5], v[170:173], v[216:219], v[2:5]
	v_mfma_f32_16x16x32_bf16 v[54:57], v[150:153], v[182:185], v[54:57]
	v_mfma_f32_16x16x32_bf16 v[50:53], v[174:177], v[182:185], v[50:53]
	v_mfma_f32_16x16x32_bf16 v[38:41], v[150:153], v[204:207], v[38:41]
	v_mfma_f32_16x16x32_bf16 v[34:37], v[174:177], v[204:207], v[34:37]
	v_mfma_f32_16x16x32_bf16 v[22:25], v[150:153], v[212:215], v[22:25]
	v_mfma_f32_16x16x32_bf16 v[18:21], v[174:177], v[212:215], v[18:21]
	v_mfma_f32_16x16x32_bf16 v[6:9], v[150:153], v[220:223], v[6:9]
	v_mfma_f32_16x16x32_bf16 v[2:5], v[174:177], v[220:223], v[2:5]
	s_setprio 0
	s_barrier
	s_add_i32 s77, s77, 2
	s_add_u32 s50, s50, 0x100
	s_addc_u32 s51, s51, 0
	s_add_u32 s73, s73, 0x100
	s_addc_u32 s76, s76, 0
	s_cmp_gt_u32 s77, 41
	s_cbranch_scc0 .LBB0_696
	s_and_b64 vcc, exec, s[16:17]
	s_cbranch_vccz .LBB0_699
	s_barrier

; #define PG8_STAGE(bufoff, gbase, voff) do { _Pragma("unroll") for (int _i = 0; _i < 2; ++_i) \
;         __builtin_amdgcn_global_load_lds((const unsigned*)((const char*)(gbase) + (voff)[_i]), (LAS unsigned*)(lds + (bufoff) + ldsw + _i * 8192), 16, 0, 0); } while (0)
; #define PG8_LDA(dst, b, h) do { _Pragma("unroll") for (int m = 0; m < 4; ++m) _Pragma("unroll") for (int k = 0; k < 2; ++k) dst[m][k] = *(const LAS bf16x8*)(lds + PG8_SA(b, h) + aoff + m * 2048 + k * 1024); } while (0)
; #define PG8_LDB(dst, b, h) do { _Pragma("unroll") for (int n = 0; n < 2; ++n) _Pragma("unroll") for (int k = 0; k < 2; ++k) dst[n][k] = *(const LAS bf16x8*)(lds + PG8_SB(b, h) + boff + n * 2048 + k * 1024); } while (0)
; #define PG8_MMA(ai, bj, At, Bt) do { __builtin_amdgcn_s_setprio(3); _Pragma("unroll") for (int m = 0; m < 4; ++m) _Pragma("unroll") for (int n = 0; n < 2; ++n) _Pragma("unroll") for (int k = 0; k < 2; ++k) \
;         acc[ai][bj][m][n] = __builtin_amdgcn_mfma_f32_16x16x32_bf16(Bt[n][k], At[m][k], acc[ai][bj][m][n], 0, 0, 0); __builtin_amdgcn_s_setprio(0); } while (0)
; #define PG8_BAR __builtin_amdgcn_s_barrier()
; template <class Epi, bool ALIGN_EPI>
; __device__ __forceinline__ void gemm_phase(LAS unsigned char* lds, const Gemm g, const StaticOrder& S, const Epi& E) {
;     ...
;         const bool has_next = S.next(ui + 1, nxt);
;         const char* nA = has_next ? (const char*)g.A + (size_t)nxt.pm * tstep : cA; const char* nB = has_next ? (const char*)g.Bt + (size_t)nxt.pn * tstep : cB;
;         for (int t = 0; t < nt; t += 2) {
;             const bool last = (t == nt - 2);
;             const char* a1 = cA + (size_t)(t + 1) * kstep;
;             const char* a2 = last ? nA : cA + (size_t)(t + 2) * kstep; const char* b2 = last ? nB : cB + (size_t)(t + 2) * kstep;
;             const char* a3 = a2 + kstep; const char* b3 = b2 + kstep;
;             PG8_LDB(B0, 0, 0); PG8_LDB(B1, 0, 1); PG8_SCHED; PG8_LDA(At, 0, 0); PG8_STAGE(PG8_SA(1, 1), a1 + hstep, voffA);
;             PG8_WAIT_V(8); PG8_WAIT_L(0); PG8_BAR; PG8_MMA(0, 0, At, B0); PG8_MMA(0, 1, At, B1); PG8_BAR; PG8_SCHED;
;             PG8_LDA(At, 0, 1); PG8_STAGE(PG8_SB(0, 0), b2, voffB); PG8_STAGE(PG8_SB(0, 1), b2 + hstep, voffB); PG8_STAGE(PG8_SA(0, 0), a2, voffA);
;             PG8_WAIT_V(8); PG8_WAIT_L(0); PG8_BAR; PG8_MMA(1, 0, At, B0); PG8_MMA(1, 1, At, B1); PG8_BAR; PG8_SCHED;
.LBB0_786:
	s_ashr_i32 s79, s78, 31
	s_lshl_b64 s[8:9], s[78:79], 19
	s_add_u32 s80, s34, s8
	s_addc_u32 s81, s35, s9
	s_and_b64 s[8:9], s[10:11], exec
	s_cselect_b32 s50, s81, s5
	s_cselect_b32 s55, s80, s4
	s_ashr_i32 s73, s72, 31
	s_lshl_b64 s[8:9], s[72:73], 19
	s_add_u32 s82, s18, s8
	s_addc_u32 s83, s19, s9
	s_and_b64 s[8:9], s[10:11], exec
	s_cselect_b32 s73, s83, s7
	s_cselect_b32 s79, s82, s6
	s_add_u32 s4, s4, 0x40080
	s_addc_u32 s5, s5, 0
	s_add_u32 s85, s6, 0x100
	s_addc_u32 s88, s7, 0
	s_mov_b32 s89, -2
	s_waitcnt lgkmcnt(0)
	ds_read_b128 v[130:133], v220
	ds_read_b128 v[134:137], v220 offset:1024
	ds_read_b128 v[138:141], v220 offset:2048
	ds_read_b128 v[142:145], v220 offset:3072
	ds_read_b128 v[166:169], v221
	ds_read_b128 v[170:173], v221 offset:1024
	ds_read_b128 v[174:177], v221 offset:2048
	ds_read_b128 v[178:181], v221 offset:3072
	s_add_u32 s6, s4, 0xfffc0080
	s_addc_u32 s7, s5, -1
	s_cmp_eq_u32 s89, 12
	s_cselect_b32 s9, s50, s7
	s_cselect_b32 s8, s55, s6
	s_cselect_b32 s7, s73, s88
	s_cselect_b32 s6, s79, s85
	v_lshl_add_u64 v[230:231], s[4:5], 0, v[158:159]
	s_add_i32 m0, s77, 0xc000
	ds_read_b128 v[182:185], v222
	ds_read_b128 v[186:189], v222 offset:1024
	ds_read_b128 v[190:193], v222 offset:2048
	ds_read_b128 v[194:197], v222 offset:3072
	ds_read_b128 v[198:201], v222 offset:4096
	ds_read_b128 v[202:205], v222 offset:5120
	ds_read_b128 v[206:209], v222 offset:6144
	ds_read_b128 v[226:229], v222 offset:7168
	global_load_lds_dwordx4 v[230:231], off
	v_lshl_add_u64 v[230:231], s[4:5], 0, v[160:161]
	s_add_i32 m0, s77, 0xe000
	s_nop 0
	global_load_lds_dwordx4 v[230:231], off
	s_waitcnt vmcnt(8)
	s_waitcnt lgkmcnt(0)
	s_barrier
	s_setprio 3
	s_waitcnt lgkmcnt(0)
	v_mfma_f32_16x16x32_bf16 v[126:129], v[130:133], v[182:185], 0
	v_mfma_f32_16x16x32_bf16 v[122:125], v[138:141], v[182:185], 0
	v_mfma_f32_16x16x32_bf16 v[110:113], v[130:133], v[190:193], 0
	v_mfma_f32_16x16x32_bf16 v[106:109], v[138:141], v[190:193], 0
	v_mfma_f32_16x16x32_bf16 v[94:97], v[130:133], v[198:201], 0
	v_mfma_f32_16x16x32_bf16 v[90:93], v[138:141], v[198:201], 0
	v_mfma_f32_16x16x32_bf16 v[78:81], v[130:133], v[206:209], 0
	v_mfma_f32_16x16x32_bf16 v[74:77], v[138:141], v[206:209], 0
	v_mfma_f32_16x16x32_bf16 v[126:129], v[134:137], v[186:189], v[126:129]
	v_mfma_f32_16x16x32_bf16 v[122:125], v[142:145], v[186:189], v[122:125]
	v_mfma_f32_16x16x32_bf16 v[110:113], v[134:137], v[194:197], v[110:113]
	v_mfma_f32_16x16x32_bf16 v[106:109], v[142:145], v[194:197], v[106:109]
	v_mfma_f32_16x16x32_bf16 v[94:97], v[134:137], v[202:205], v[94:97]
	v_mfma_f32_16x16x32_bf16 v[90:93], v[142:145], v[202:205], v[90:93]
	v_mfma_f32_16x16x32_bf16 v[78:81], v[134:137], v[226:229], v[78:81]
	v_mfma_f32_16x16x32_bf16 v[74:77], v[142:145], v[226:229], v[74:77]
	v_mfma_f32_16x16x32_bf16 v[118:121], v[166:169], v[182:185], 0
	v_mfma_f32_16x16x32_bf16 v[114:117], v[174:177], v[182:185], 0
	v_mfma_f32_16x16x32_bf16 v[102:105], v[166:169], v[190:193], 0
	v_mfma_f32_16x16x32_bf16 v[98:101], v[174:177], v[190:193], 0
	v_mfma_f32_16x16x32_bf16 v[86:89], v[166:169], v[198:201], 0
	v_mfma_f32_16x16x32_bf16 v[82:85], v[174:177], v[198:201], 0
	v_mfma_f32_16x16x32_bf16 v[70:73], v[166:169], v[206:209], 0
	v_mfma_f32_16x16x32_bf16 v[66:69], v[174:177], v[206:209], 0
	v_mfma_f32_16x16x32_bf16 v[118:121], v[170:173], v[186:189], v[118:121]
	v_mfma_f32_16x16x32_bf16 v[114:117], v[178:181], v[186:189], v[114:117]
	v_mfma_f32_16x16x32_bf16 v[102:105], v[170:173], v[194:197], v[102:105]
	v_mfma_f32_16x16x32_bf16 v[98:101], v[178:181], v[194:197], v[98:101]
	v_mfma_f32_16x16x32_bf16 v[86:89], v[170:173], v[202:205], v[86:89]
	v_mfma_f32_16x16x32_bf16 v[82:85], v[178:181], v[202:205], v[82:85]
	v_mfma_f32_16x16x32_bf16 v[70:73], v[170:173], v[226:229], v[70:73]
	v_mfma_f32_16x16x32_bf16 v[66:69], v[178:181], v[226:229], v[66:69]
	s_setprio 0
	s_barrier
	s_add_i32 s90, s69, s76
	v_lshl_add_u64 v[230:231], s[6:7], 0, v[148:149]
	s_mov_b32 m0, s90
	ds_read_b128 v[182:185], v222 offset:16384
	ds_read_b128 v[186:189], v222 offset:17408
	ds_read_b128 v[190:193], v222 offset:18432
	ds_read_b128 v[194:197], v222 offset:19456
	ds_read_b128 v[198:201], v222 offset:20480
	ds_read_b128 v[202:205], v222 offset:21504
	ds_read_b128 v[206:209], v222 offset:22528
	ds_read_b128 v[226:229], v222 offset:23552
	global_load_lds_dwordx4 v[230:231], off
	s_add_i32 m0, s90, 0x2000
	s_add_u32 s90, s6, 0x40000
	v_lshl_add_u64 v[232:233], s[6:7], 0, v[152:153]
	s_addc_u32 s91, s7, 0
	s_add_i32 s92, s70, s76
	global_load_lds_dwordx4 v[232:233], off
	v_lshl_add_u64 v[234:235], s[90:91], 0, v[148:149]
	s_mov_b32 m0, s92
	v_lshl_add_u64 v[236:237], s[8:9], 0, v[150:151]
	global_load_lds_dwordx4 v[234:235], off
	v_lshl_add_u64 v[234:235], s[90:91], 0, v[152:153]
	s_add_i32 m0, s92, 0x2000
	s_nop 0
	global_load_lds_dwordx4 v[234:235], off
	v_lshl_add_u64 v[234:235], s[8:9], 0, v[146:147]
	s_mov_b32 m0, s77
	s_nop 0
	global_load_lds_dwordx4 v[234:235], off
	s_mov_b32 m0, s87
	s_nop 0
	global_load_lds_dwordx4 v[236:237], off
	s_waitcnt vmcnt(8)
	s_waitcnt lgkmcnt(0)
	s_barrier
; #define PG8_STAGE(bufoff, gbase, voff) do { _Pragma("unroll") for (int _i = 0; _i < 2; ++_i) \
;         __builtin_amdgcn_global_load_lds((const unsigned*)((const char*)(gbase) + (voff)[_i]), (LAS unsigned*)(lds + (bufoff) + ldsw + _i * 8192), 16, 0, 0); } while (0)
; #define PG8_LDA(dst, b, h) do { _Pragma("unroll") for (int m = 0; m < 4; ++m) _Pragma("unroll") for (int k = 0; k < 2; ++k) dst[m][k] = *(const LAS bf16x8*)(lds + PG8_SA(b, h) + aoff + m * 2048 + k * 1024); } while (0)
; #define PG8_LDB(dst, b, h) do { _Pragma("unroll") for (int n = 0; n < 2; ++n) _Pragma("unroll") for (int k = 0; k < 2; ++k) dst[n][k] = *(const LAS bf16x8*)(lds + PG8_SB(b, h) + boff + n * 2048 + k * 1024); } while (0)
; #define PG8_MMA(ai, bj, At, Bt) do { __builtin_amdgcn_s_setprio(3); _Pragma("unroll") for (int m = 0; m < 4; ++m) _Pragma("unroll") for (int n = 0; n < 2; ++n) _Pragma("unroll") for (int k = 0; k < 2; ++k) \
;         acc[ai][bj][m][n] = __builtin_amdgcn_mfma_f32_16x16x32_bf16(Bt[n][k], At[m][k], acc[ai][bj][m][n], 0, 0, 0); __builtin_amdgcn_s_setprio(0); } while (0)
; #define PG8_WAIT_V(n) asm volatile("s_waitcnt vmcnt(" #n ")" ::: "memory")
; #define PG8_WAIT_L(n) asm volatile("s_waitcnt lgkmcnt(" #n ")" ::: "memory")
; #define PG8_BAR __builtin_amdgcn_s_barrier()
; #define PG8_SCHED __builtin_amdgcn_sched_barrier(0)
; template <class Epi, bool ALIGN_EPI>
; __device__ __forceinline__ void gemm_phase(LAS unsigned char* lds, const Gemm g, const StaticOrder& S, const Epi& E) {
;     ...
;             PG8_WAIT_V(8); PG8_WAIT_L(0); PG8_BAR; PG8_MMA(1, 0, At, B0); PG8_MMA(1, 1, At, B1); PG8_BAR; PG8_SCHED;
;             PG8_LDB(B0, 1, 0); PG8_LDB(B1, 1, 1); PG8_SCHED; PG8_LDA(At, 1, 0); PG8_STAGE(PG8_SA(0, 1), a2 + hstep, voffA);
;             PG8_WAIT_V(8); PG8_WAIT_L(0); PG8_BAR; PG8_MMA(0, 0, At, B0); PG8_MMA(0, 1, At, B1); PG8_BAR; PG8_SCHED;
	s_setprio 3
	s_waitcnt lgkmcnt(0)
	v_mfma_f32_16x16x32_bf16 v[62:65], v[130:133], v[182:185], 0
	v_mfma_f32_16x16x32_bf16 v[58:61], v[138:141], v[182:185], 0
	v_mfma_f32_16x16x32_bf16 v[46:49], v[130:133], v[190:193], 0
	v_mfma_f32_16x16x32_bf16 v[42:45], v[138:141], v[190:193], 0
	v_mfma_f32_16x16x32_bf16 v[30:33], v[130:133], v[198:201], 0
	v_mfma_f32_16x16x32_bf16 v[26:29], v[138:141], v[198:201], 0
	v_mfma_f32_16x16x32_bf16 v[14:17], v[130:133], v[206:209], 0
	v_mfma_f32_16x16x32_bf16 v[10:13], v[138:141], v[206:209], 0
	v_mfma_f32_16x16x32_bf16 v[62:65], v[134:137], v[186:189], v[62:65]
	v_mfma_f32_16x16x32_bf16 v[58:61], v[142:145], v[186:189], v[58:61]
	v_mfma_f32_16x16x32_bf16 v[46:49], v[134:137], v[194:197], v[46:49]
	v_mfma_f32_16x16x32_bf16 v[42:45], v[142:145], v[194:197], v[42:45]
	v_mfma_f32_16x16x32_bf16 v[30:33], v[134:137], v[202:205], v[30:33]
	v_mfma_f32_16x16x32_bf16 v[26:29], v[142:145], v[202:205], v[26:29]
	v_mfma_f32_16x16x32_bf16 v[14:17], v[134:137], v[226:229], v[14:17]
	v_mfma_f32_16x16x32_bf16 v[10:13], v[142:145], v[226:229], v[10:13]
	v_mfma_f32_16x16x32_bf16 v[54:57], v[166:169], v[182:185], 0
	v_mfma_f32_16x16x32_bf16 v[50:53], v[174:177], v[182:185], 0
	v_mfma_f32_16x16x32_bf16 v[38:41], v[166:169], v[190:193], 0
	v_mfma_f32_16x16x32_bf16 v[34:37], v[174:177], v[190:193], 0
	v_mfma_f32_16x16x32_bf16 v[22:25], v[166:169], v[198:201], 0
	v_mfma_f32_16x16x32_bf16 v[18:21], v[174:177], v[198:201], 0
	v_mfma_f32_16x16x32_bf16 v[6:9], v[166:169], v[206:209], 0
	v_mfma_f32_16x16x32_bf16 v[2:5], v[174:177], v[206:209], 0
	v_mfma_f32_16x16x32_bf16 v[54:57], v[170:173], v[186:189], v[54:57]
	v_mfma_f32_16x16x32_bf16 v[50:53], v[178:181], v[186:189], v[50:53]
	v_mfma_f32_16x16x32_bf16 v[38:41], v[170:173], v[194:197], v[38:41]
	v_mfma_f32_16x16x32_bf16 v[34:37], v[178:181], v[194:197], v[34:37]
	v_mfma_f32_16x16x32_bf16 v[22:25], v[170:173], v[202:205], v[22:25]
	v_mfma_f32_16x16x32_bf16 v[18:21], v[178:181], v[202:205], v[18:21]
	v_mfma_f32_16x16x32_bf16 v[6:9], v[170:173], v[226:229], v[6:9]
	v_mfma_f32_16x16x32_bf16 v[2:5], v[178:181], v[226:229], v[2:5]
	s_setprio 0
	s_barrier
	s_add_i32 s90, 0, 0x18000
	s_add_i32 s91, 0, 0x1c000
	v_add_u32_e32 v142, s90, v217
	v_add_u32_e32 v154, s91, v217
	ds_read_b128 v[130:133], v142
	ds_read_b128 v[134:137], v142 offset:1024
	ds_read_b128 v[138:141], v142 offset:2048
	ds_read_b128 v[142:145], v142 offset:3072
	ds_read_b128 v[166:169], v154
	ds_read_b128 v[170:173], v154 offset:1024
	ds_read_b128 v[174:177], v154 offset:2048
	ds_read_b128 v[178:181], v154 offset:3072
	s_add_u32 s8, s8, 0x40000
	s_addc_u32 s9, s9, 0
	s_mov_b32 m0, s33
	v_lshl_add_u64 v[238:239], s[8:9], 0, v[146:147]
	ds_read_b128 v[182:185], v222 offset:32768
	ds_read_b128 v[186:189], v222 offset:33792
	ds_read_b128 v[190:193], v222 offset:34816
	ds_read_b128 v[194:197], v222 offset:35840
	ds_read_b128 v[198:201], v222 offset:36864
	ds_read_b128 v[202:205], v222 offset:37888
	ds_read_b128 v[206:209], v222 offset:38912
	ds_read_b128 v[226:229], v222 offset:39936
	global_load_lds_dwordx4 v[238:239], off
	v_lshl_add_u64 v[238:239], s[8:9], 0, v[150:151]
	s_mov_b32 m0, s14
	s_nop 0
	global_load_lds_dwordx4 v[238:239], off
	s_waitcnt vmcnt(8)
	s_waitcnt lgkmcnt(0)
	s_barrier
	s_setprio 3
	s_waitcnt lgkmcnt(0)
	v_mfma_f32_16x16x32_bf16 v[126:129], v[130:133], v[182:185], v[126:129]
	v_mfma_f32_16x16x32_bf16 v[122:125], v[138:141], v[182:185], v[122:125]
	v_mfma_f32_16x16x32_bf16 v[110:113], v[130:133], v[190:193], v[110:113]
	v_mfma_f32_16x16x32_bf16 v[106:109], v[138:141], v[190:193], v[106:109]
	v_mfma_f32_16x16x32_bf16 v[94:97], v[130:133], v[198:201], v[94:97]
	v_mfma_f32_16x16x32_bf16 v[90:93], v[138:141], v[198:201], v[90:93]
	v_mfma_f32_16x16x32_bf16 v[78:81], v[130:133], v[206:209], v[78:81]
	v_mfma_f32_16x16x32_bf16 v[74:77], v[138:141], v[206:209], v[74:77]
	v_mfma_f32_16x16x32_bf16 v[126:129], v[134:137], v[186:189], v[126:129]
	v_mfma_f32_16x16x32_bf16 v[122:125], v[142:145], v[186:189], v[122:125]
	v_mfma_f32_16x16x32_bf16 v[110:113], v[134:137], v[194:197], v[110:113]
	v_mfma_f32_16x16x32_bf16 v[106:109], v[142:145], v[194:197], v[106:109]
	v_mfma_f32_16x16x32_bf16 v[94:97], v[134:137], v[202:205], v[94:97]
	v_mfma_f32_16x16x32_bf16 v[90:93], v[142:145], v[202:205], v[90:93]
	v_mfma_f32_16x16x32_bf16 v[78:81], v[134:137], v[226:229], v[78:81]
	v_mfma_f32_16x16x32_bf16 v[74:77], v[142:145], v[226:229], v[74:77]
	v_mfma_f32_16x16x32_bf16 v[118:121], v[166:169], v[182:185], v[118:121]
	v_mfma_f32_16x16x32_bf16 v[114:117], v[174:177], v[182:185], v[114:117]
	v_mfma_f32_16x16x32_bf16 v[102:105], v[166:169], v[190:193], v[102:105]
	v_mfma_f32_16x16x32_bf16 v[98:101], v[174:177], v[190:193], v[98:101]
	v_mfma_f32_16x16x32_bf16 v[86:89], v[166:169], v[198:201], v[86:89]
	v_mfma_f32_16x16x32_bf16 v[82:85], v[174:177], v[198:201], v[82:85]
	v_mfma_f32_16x16x32_bf16 v[70:73], v[166:169], v[206:209], v[70:73]
	v_mfma_f32_16x16x32_bf16 v[66:69], v[174:177], v[206:209], v[66:69]
	v_mfma_f32_16x16x32_bf16 v[118:121], v[170:173], v[186:189], v[118:121]
	v_mfma_f32_16x16x32_bf16 v[114:117], v[178:181], v[186:189], v[114:117]
	v_mfma_f32_16x16x32_bf16 v[102:105], v[170:173], v[194:197], v[102:105]
	v_mfma_f32_16x16x32_bf16 v[98:101], v[178:181], v[194:197], v[98:101]
	v_mfma_f32_16x16x32_bf16 v[86:89], v[170:173], v[202:205], v[86:89]
	v_mfma_f32_16x16x32_bf16 v[82:85], v[178:181], v[202:205], v[82:85]
	v_mfma_f32_16x16x32_bf16 v[70:73], v[170:173], v[226:229], v[70:73]
	v_mfma_f32_16x16x32_bf16 v[66:69], v[178:181], v[226:229], v[66:69]
	s_setprio 0
	s_barrier
; #define PG8_STAGE(bufoff, gbase, voff) do { _Pragma("unroll") for (int _i = 0; _i < 2; ++_i) \
;         __builtin_amdgcn_global_load_lds((const unsigned*)((const char*)(gbase) + (voff)[_i]), (LAS unsigned*)(lds + (bufoff) + ldsw + _i * 8192), 16, 0, 0); } while (0)
; #define PG8_LDA(dst, b, h) do { _Pragma("unroll") for (int m = 0; m < 4; ++m) _Pragma("unroll") for (int k = 0; k < 2; ++k) dst[m][k] = *(const LAS bf16x8*)(lds + PG8_SA(b, h) + aoff + m * 2048 + k * 1024); } while (0)
; #define PG8_LDB(dst, b, h) do { _Pragma("unroll") for (int n = 0; n < 2; ++n) _Pragma("unroll") for (int k = 0; k < 2; ++k) dst[n][k] = *(const LAS bf16x8*)(lds + PG8_SB(b, h) + boff + n * 2048 + k * 1024); } while (0)
; #define PG8_MMA(ai, bj, At, Bt) do { __builtin_amdgcn_s_setprio(3); _Pragma("unroll") for (int m = 0; m < 4; ++m) _Pragma("unroll") for (int n = 0; n < 2; ++n) _Pragma("unroll") for (int k = 0; k < 2; ++k) \
;         acc[ai][bj][m][n] = __builtin_amdgcn_mfma_f32_16x16x32_bf16(Bt[n][k], At[m][k], acc[ai][bj][m][n], 0, 0, 0); __builtin_amdgcn_s_setprio(0); } while (0)
; #define PG8_WAIT_V(n) asm volatile("s_waitcnt vmcnt(" #n ")" ::: "memory")
; #define PG8_WAIT_L(n) asm volatile("s_waitcnt lgkmcnt(" #n ")" ::: "memory")
; #define PG8_BAR __builtin_amdgcn_s_barrier()
; #define PG8_SCHED __builtin_amdgcn_sched_barrier(0)
; template <class Epi, bool ALIGN_EPI>
; __device__ __forceinline__ void gemm_phase(LAS unsigned char* lds, const Gemm g, const StaticOrder& S, const Epi& E) {
;     ...
;             PG8_LDB(B0, 0, 0); PG8_LDB(B1, 0, 1); PG8_SCHED; PG8_LDA(At, 0, 0); PG8_STAGE(PG8_SA(1, 1), a1 + hstep, voffA);
;             PG8_WAIT_V(8); PG8_WAIT_L(0); PG8_BAR; PG8_MMA(0, 0, At, B0); PG8_MMA(0, 1, At, B1); PG8_BAR; PG8_SCHED;
;     ...
;             PG8_LDA(At, 1, 1); PG8_STAGE(PG8_SB(1, 0), b3, voffB); PG8_STAGE(PG8_SB(1, 1), b3 + hstep, voffB); PG8_STAGE(PG8_SA(1, 0), a3, voffA);
;             PG8_WAIT_V(8); PG8_WAIT_L(0); PG8_BAR; PG8_MMA(1, 0, At, B0); PG8_MMA(1, 1, At, B1); PG8_BAR; PG8_SCHED;
	s_add_i32 s8, s90, s76
	v_lshl_add_u64 v[230:231], v[230:231], 0, s[60:61]
	s_mov_b32 m0, s8
	ds_read_b128 v[182:185], v222 offset:49152
	ds_read_b128 v[186:189], v222 offset:50176
	ds_read_b128 v[190:193], v222 offset:51200
	ds_read_b128 v[194:197], v222 offset:52224
	ds_read_b128 v[198:201], v222 offset:53248
	ds_read_b128 v[202:205], v222 offset:54272
	ds_read_b128 v[206:209], v222 offset:55296
	ds_read_b128 v[226:229], v222 offset:56320
	global_load_lds_dwordx4 v[230:231], off
	s_add_i32 m0, s8, 0x2000
	s_add_u32 s6, s6, 0x40080
	v_lshl_add_u64 v[230:231], v[232:233], 0, s[60:61]
	s_addc_u32 s7, s7, 0
	s_add_i32 s8, s91, s76
	global_load_lds_dwordx4 v[230:231], off
	v_lshl_add_u64 v[230:231], s[6:7], 0, v[148:149]
	s_mov_b32 m0, s8
	s_nop 0
	global_load_lds_dwordx4 v[230:231], off
	v_lshl_add_u64 v[230:231], s[6:7], 0, v[152:153]
	s_add_i32 m0, s8, 0x2000
	s_nop 0
	global_load_lds_dwordx4 v[230:231], off
	v_lshl_add_u64 v[230:231], v[234:235], 0, s[60:61]
	s_mov_b32 m0, s65
	s_nop 0
	global_load_lds_dwordx4 v[230:231], off
	v_lshl_add_u64 v[230:231], v[236:237], 0, s[60:61]
	s_mov_b32 m0, s66
	s_nop 0
	global_load_lds_dwordx4 v[230:231], off
	s_waitcnt vmcnt(8)
	s_waitcnt lgkmcnt(0)
	s_barrier
	s_setprio 3
	s_waitcnt lgkmcnt(0)
	v_mfma_f32_16x16x32_bf16 v[62:65], v[130:133], v[182:185], v[62:65]
	v_mfma_f32_16x16x32_bf16 v[58:61], v[138:141], v[182:185], v[58:61]
	v_mfma_f32_16x16x32_bf16 v[46:49], v[130:133], v[190:193], v[46:49]
	v_mfma_f32_16x16x32_bf16 v[42:45], v[138:141], v[190:193], v[42:45]
	v_mfma_f32_16x16x32_bf16 v[30:33], v[130:133], v[198:201], v[30:33]
	v_mfma_f32_16x16x32_bf16 v[26:29], v[138:141], v[198:201], v[26:29]
	v_mfma_f32_16x16x32_bf16 v[14:17], v[130:133], v[206:209], v[14:17]
	v_mfma_f32_16x16x32_bf16 v[10:13], v[138:141], v[206:209], v[10:13]
	v_mfma_f32_16x16x32_bf16 v[62:65], v[134:137], v[186:189], v[62:65]
	v_mfma_f32_16x16x32_bf16 v[58:61], v[142:145], v[186:189], v[58:61]
	v_mfma_f32_16x16x32_bf16 v[46:49], v[134:137], v[194:197], v[46:49]
	v_mfma_f32_16x16x32_bf16 v[42:45], v[142:145], v[194:197], v[42:45]
	v_mfma_f32_16x16x32_bf16 v[30:33], v[134:137], v[202:205], v[30:33]
	v_mfma_f32_16x16x32_bf16 v[26:29], v[142:145], v[202:205], v[26:29]
	v_mfma_f32_16x16x32_bf16 v[14:17], v[134:137], v[226:229], v[14:17]
	v_mfma_f32_16x16x32_bf16 v[10:13], v[142:145], v[226:229], v[10:13]
	v_mfma_f32_16x16x32_bf16 v[54:57], v[166:169], v[182:185], v[54:57]
	v_mfma_f32_16x16x32_bf16 v[50:53], v[174:177], v[182:185], v[50:53]
	v_mfma_f32_16x16x32_bf16 v[38:41], v[166:169], v[190:193], v[38:41]
	v_mfma_f32_16x16x32_bf16 v[34:37], v[174:177], v[190:193], v[34:37]
	v_mfma_f32_16x16x32_bf16 v[22:25], v[166:169], v[198:201], v[22:25]
	v_mfma_f32_16x16x32_bf16 v[18:21], v[174:177], v[198:201], v[18:21]
	v_mfma_f32_16x16x32_bf16 v[6:9], v[166:169], v[206:209], v[6:9]
	v_mfma_f32_16x16x32_bf16 v[2:5], v[174:177], v[206:209], v[2:5]
	v_mfma_f32_16x16x32_bf16 v[54:57], v[170:173], v[186:189], v[54:57]
	v_mfma_f32_16x16x32_bf16 v[50:53], v[178:181], v[186:189], v[50:53]
	v_mfma_f32_16x16x32_bf16 v[38:41], v[170:173], v[194:197], v[38:41]
	v_mfma_f32_16x16x32_bf16 v[34:37], v[178:181], v[194:197], v[34:37]
	v_mfma_f32_16x16x32_bf16 v[22:25], v[170:173], v[202:205], v[22:25]
	v_mfma_f32_16x16x32_bf16 v[18:21], v[178:181], v[202:205], v[18:21]
	v_mfma_f32_16x16x32_bf16 v[6:9], v[170:173], v[226:229], v[6:9]
	v_mfma_f32_16x16x32_bf16 v[2:5], v[178:181], v[226:229], v[2:5]
	s_setprio 0
	s_barrier
	s_add_i32 s89, s89, 2
	s_add_u32 s4, s4, 0x100
	s_addc_u32 s5, s5, 0
	s_add_u32 s85, s85, 0x100
	s_addc_u32 s88, s88, 0
.LBB0_787:
	s_waitcnt lgkmcnt(0)
	ds_read_b128 v[130:133], v220
	ds_read_b128 v[134:137], v220 offset:1024
	ds_read_b128 v[138:141], v220 offset:2048
	ds_read_b128 v[142:145], v220 offset:3072
	ds_read_b128 v[166:169], v221
	ds_read_b128 v[170:173], v221 offset:1024
	ds_read_b128 v[174:177], v221 offset:2048
	ds_read_b128 v[178:181], v221 offset:3072
	s_add_u32 s6, s4, 0xfffc0080
	s_addc_u32 s7, s5, -1
	s_cmp_eq_u32 s89, 12
	s_cselect_b32 s9, s50, s7
	s_cselect_b32 s8, s55, s6
	s_cselect_b32 s7, s73, s88
	s_cselect_b32 s6, s79, s85
	v_lshl_add_u64 v[230:231], s[4:5], 0, v[158:159]
	s_add_i32 m0, s77, 0xc000
	ds_read_b128 v[182:185], v222
	ds_read_b128 v[186:189], v222 offset:1024
	ds_read_b128 v[190:193], v222 offset:2048
	ds_read_b128 v[194:197], v222 offset:3072
	ds_read_b128 v[198:201], v222 offset:4096
	ds_read_b128 v[202:205], v222 offset:5120
	ds_read_b128 v[206:209], v222 offset:6144
	ds_read_b128 v[226:229], v222 offset:7168
	global_load_lds_dwordx4 v[230:231], off
	v_lshl_add_u64 v[230:231], s[4:5], 0, v[160:161]
	s_add_i32 m0, s77, 0xe000
	s_nop 0
	global_load_lds_dwordx4 v[230:231], off
	s_waitcnt vmcnt(8)
	s_waitcnt lgkmcnt(0)
	s_barrier
; #define PG8_STAGE(bufoff, gbase, voff) do { _Pragma("unroll") for (int _i = 0; _i < 2; ++_i) \
;         __builtin_amdgcn_global_load_lds((const unsigned*)((const char*)(gbase) + (voff)[_i]), (LAS unsigned*)(lds + (bufoff) + ldsw + _i * 8192), 16, 0, 0); } while (0)
; #define PG8_LDA(dst, b, h) do { _Pragma("unroll") for (int m = 0; m < 4; ++m) _Pragma("unroll") for (int k = 0; k < 2; ++k) dst[m][k] = *(const LAS bf16x8*)(lds + PG8_SA(b, h) + aoff + m * 2048 + k * 1024); } while (0)
; #define PG8_MMA(ai, bj, At, Bt) do { __builtin_amdgcn_s_setprio(3); _Pragma("unroll") for (int m = 0; m < 4; ++m) _Pragma("unroll") for (int n = 0; n < 2; ++n) _Pragma("unroll") for (int k = 0; k < 2; ++k) \
;         acc[ai][bj][m][n] = __builtin_amdgcn_mfma_f32_16x16x32_bf16(Bt[n][k], At[m][k], acc[ai][bj][m][n], 0, 0, 0); __builtin_amdgcn_s_setprio(0); } while (0)
; #define PG8_WAIT_V(n) asm volatile("s_waitcnt vmcnt(" #n ")" ::: "memory")
; #define PG8_WAIT_L(n) asm volatile("s_waitcnt lgkmcnt(" #n ")" ::: "memory")
; #define PG8_BAR __builtin_amdgcn_s_barrier()
; #define PG8_SCHED __builtin_amdgcn_sched_barrier(0)
; template <class Epi, bool ALIGN_EPI>
; __device__ __forceinline__ void gemm_phase(LAS unsigned char* lds, const Gemm g, const StaticOrder& S, const Epi& E) {
;     ...
;             PG8_WAIT_V(8); PG8_WAIT_L(0); PG8_BAR; PG8_MMA(0, 0, At, B0); PG8_MMA(0, 1, At, B1); PG8_BAR; PG8_SCHED;
;             PG8_LDA(At, 0, 1); PG8_STAGE(PG8_SB(0, 0), b2, voffB); PG8_STAGE(PG8_SB(0, 1), b2 + hstep, voffB); PG8_STAGE(PG8_SA(0, 0), a2, voffA);
;             PG8_WAIT_V(8); PG8_WAIT_L(0); PG8_BAR; PG8_MMA(1, 0, At, B0); PG8_MMA(1, 1, At, B1); PG8_BAR; PG8_SCHED;
	s_setprio 3
	s_waitcnt lgkmcnt(0)
	v_mfma_f32_16x16x32_bf16 v[126:129], v[130:133], v[182:185], v[126:129]
	v_mfma_f32_16x16x32_bf16 v[122:125], v[138:141], v[182:185], v[122:125]
	v_mfma_f32_16x16x32_bf16 v[110:113], v[130:133], v[190:193], v[110:113]
	v_mfma_f32_16x16x32_bf16 v[106:109], v[138:141], v[190:193], v[106:109]
	v_mfma_f32_16x16x32_bf16 v[94:97], v[130:133], v[198:201], v[94:97]
	v_mfma_f32_16x16x32_bf16 v[90:93], v[138:141], v[198:201], v[90:93]
	v_mfma_f32_16x16x32_bf16 v[78:81], v[130:133], v[206:209], v[78:81]
	v_mfma_f32_16x16x32_bf16 v[74:77], v[138:141], v[206:209], v[74:77]
	v_mfma_f32_16x16x32_bf16 v[126:129], v[134:137], v[186:189], v[126:129]
	v_mfma_f32_16x16x32_bf16 v[122:125], v[142:145], v[186:189], v[122:125]
	v_mfma_f32_16x16x32_bf16 v[110:113], v[134:137], v[194:197], v[110:113]
	v_mfma_f32_16x16x32_bf16 v[106:109], v[142:145], v[194:197], v[106:109]
	v_mfma_f32_16x16x32_bf16 v[94:97], v[134:137], v[202:205], v[94:97]
	v_mfma_f32_16x16x32_bf16 v[90:93], v[142:145], v[202:205], v[90:93]
	v_mfma_f32_16x16x32_bf16 v[78:81], v[134:137], v[226:229], v[78:81]
	v_mfma_f32_16x16x32_bf16 v[74:77], v[142:145], v[226:229], v[74:77]
	v_mfma_f32_16x16x32_bf16 v[118:121], v[166:169], v[182:185], v[118:121]
	v_mfma_f32_16x16x32_bf16 v[114:117], v[174:177], v[182:185], v[114:117]
	v_mfma_f32_16x16x32_bf16 v[102:105], v[166:169], v[190:193], v[102:105]
	v_mfma_f32_16x16x32_bf16 v[98:101], v[174:177], v[190:193], v[98:101]
	v_mfma_f32_16x16x32_bf16 v[86:89], v[166:169], v[198:201], v[86:89]
	v_mfma_f32_16x16x32_bf16 v[82:85], v[174:177], v[198:201], v[82:85]
	v_mfma_f32_16x16x32_bf16 v[70:73], v[166:169], v[206:209], v[70:73]
	v_mfma_f32_16x16x32_bf16 v[66:69], v[174:177], v[206:209], v[66:69]
	v_mfma_f32_16x16x32_bf16 v[118:121], v[170:173], v[186:189], v[118:121]
	v_mfma_f32_16x16x32_bf16 v[114:117], v[178:181], v[186:189], v[114:117]
	v_mfma_f32_16x16x32_bf16 v[102:105], v[170:173], v[194:197], v[102:105]
	v_mfma_f32_16x16x32_bf16 v[98:101], v[178:181], v[194:197], v[98:101]
	v_mfma_f32_16x16x32_bf16 v[86:89], v[170:173], v[202:205], v[86:89]
	v_mfma_f32_16x16x32_bf16 v[82:85], v[178:181], v[202:205], v[82:85]
	v_mfma_f32_16x16x32_bf16 v[70:73], v[170:173], v[226:229], v[70:73]
	v_mfma_f32_16x16x32_bf16 v[66:69], v[178:181], v[226:229], v[66:69]
	s_setprio 0
	s_barrier
	s_add_i32 s90, s69, s76
	v_lshl_add_u64 v[230:231], s[6:7], 0, v[148:149]
	s_mov_b32 m0, s90
	ds_read_b128 v[182:185], v222 offset:16384
	ds_read_b128 v[186:189], v222 offset:17408
	ds_read_b128 v[190:193], v222 offset:18432
	ds_read_b128 v[194:197], v222 offset:19456
	ds_read_b128 v[198:201], v222 offset:20480
	ds_read_b128 v[202:205], v222 offset:21504
	ds_read_b128 v[206:209], v222 offset:22528
	ds_read_b128 v[226:229], v222 offset:23552
	global_load_lds_dwordx4 v[230:231], off
	s_add_i32 m0, s90, 0x2000
	s_add_u32 s90, s6, 0x40000
	v_lshl_add_u64 v[232:233], s[6:7], 0, v[152:153]
	s_addc_u32 s91, s7, 0
	s_add_i32 s92, s70, s76
	global_load_lds_dwordx4 v[232:233], off
	v_lshl_add_u64 v[234:235], s[90:91], 0, v[148:149]
	s_mov_b32 m0, s92
	v_lshl_add_u64 v[236:237], s[8:9], 0, v[150:151]
	global_load_lds_dwordx4 v[234:235], off
	v_lshl_add_u64 v[234:235], s[90:91], 0, v[152:153]
	s_add_i32 m0, s92, 0x2000
	s_nop 0
	global_load_lds_dwordx4 v[234:235], off
	v_lshl_add_u64 v[234:235], s[8:9], 0, v[146:147]
	s_mov_b32 m0, s77
	s_nop 0
	global_load_lds_dwordx4 v[234:235], off
	s_mov_b32 m0, s87
	s_nop 0
	global_load_lds_dwordx4 v[236:237], off
	s_waitcnt vmcnt(8)
	s_waitcnt lgkmcnt(0)
	s_barrier
	s_setprio 3
	s_waitcnt lgkmcnt(0)
	v_mfma_f32_16x16x32_bf16 v[62:65], v[130:133], v[182:185], v[62:65]
	v_mfma_f32_16x16x32_bf16 v[58:61], v[138:141], v[182:185], v[58:61]
	v_mfma_f32_16x16x32_bf16 v[46:49], v[130:133], v[190:193], v[46:49]
	v_mfma_f32_16x16x32_bf16 v[42:45], v[138:141], v[190:193], v[42:45]
	v_mfma_f32_16x16x32_bf16 v[30:33], v[130:133], v[198:201], v[30:33]
	v_mfma_f32_16x16x32_bf16 v[26:29], v[138:141], v[198:201], v[26:29]
	v_mfma_f32_16x16x32_bf16 v[14:17], v[130:133], v[206:209], v[14:17]
	v_mfma_f32_16x16x32_bf16 v[10:13], v[138:141], v[206:209], v[10:13]
	v_mfma_f32_16x16x32_bf16 v[62:65], v[134:137], v[186:189], v[62:65]
	v_mfma_f32_16x16x32_bf16 v[58:61], v[142:145], v[186:189], v[58:61]
	v_mfma_f32_16x16x32_bf16 v[46:49], v[134:137], v[194:197], v[46:49]
	v_mfma_f32_16x16x32_bf16 v[42:45], v[142:145], v[194:197], v[42:45]
	v_mfma_f32_16x16x32_bf16 v[30:33], v[134:137], v[202:205], v[30:33]
	v_mfma_f32_16x16x32_bf16 v[26:29], v[142:145], v[202:205], v[26:29]
	v_mfma_f32_16x16x32_bf16 v[14:17], v[134:137], v[226:229], v[14:17]
	v_mfma_f32_16x16x32_bf16 v[10:13], v[142:145], v[226:229], v[10:13]
	v_mfma_f32_16x16x32_bf16 v[54:57], v[166:169], v[182:185], v[54:57]
	v_mfma_f32_16x16x32_bf16 v[50:53], v[174:177], v[182:185], v[50:53]
	v_mfma_f32_16x16x32_bf16 v[38:41], v[166:169], v[190:193], v[38:41]
	v_mfma_f32_16x16x32_bf16 v[34:37], v[174:177], v[190:193], v[34:37]
	v_mfma_f32_16x16x32_bf16 v[22:25], v[166:169], v[198:201], v[22:25]
	v_mfma_f32_16x16x32_bf16 v[18:21], v[174:177], v[198:201], v[18:21]
	v_mfma_f32_16x16x32_bf16 v[6:9], v[166:169], v[206:209], v[6:9]
	v_mfma_f32_16x16x32_bf16 v[2:5], v[174:177], v[206:209], v[2:5]
	v_mfma_f32_16x16x32_bf16 v[54:57], v[170:173], v[186:189], v[54:57]
	v_mfma_f32_16x16x32_bf16 v[50:53], v[178:181], v[186:189], v[50:53]
	v_mfma_f32_16x16x32_bf16 v[38:41], v[170:173], v[194:197], v[38:41]
	v_mfma_f32_16x16x32_bf16 v[34:37], v[178:181], v[194:197], v[34:37]
	v_mfma_f32_16x16x32_bf16 v[22:25], v[170:173], v[202:205], v[22:25]
	v_mfma_f32_16x16x32_bf16 v[18:21], v[178:181], v[202:205], v[18:21]
	v_mfma_f32_16x16x32_bf16 v[6:9], v[170:173], v[226:229], v[6:9]
	v_mfma_f32_16x16x32_bf16 v[2:5], v[178:181], v[226:229], v[2:5]
	s_setprio 0
	s_barrier
; #define PG8_STAGE(bufoff, gbase, voff) do { _Pragma("unroll") for (int _i = 0; _i < 2; ++_i) \
;         __builtin_amdgcn_global_load_lds((const unsigned*)((const char*)(gbase) + (voff)[_i]), (LAS unsigned*)(lds + (bufoff) + ldsw + _i * 8192), 16, 0, 0); } while (0)
; #define PG8_LDA(dst, b, h) do { _Pragma("unroll") for (int m = 0; m < 4; ++m) _Pragma("unroll") for (int k = 0; k < 2; ++k) dst[m][k] = *(const LAS bf16x8*)(lds + PG8_SA(b, h) + aoff + m * 2048 + k * 1024); } while (0)
; #define PG8_LDB(dst, b, h) do { _Pragma("unroll") for (int n = 0; n < 2; ++n) _Pragma("unroll") for (int k = 0; k < 2; ++k) dst[n][k] = *(const LAS bf16x8*)(lds + PG8_SB(b, h) + boff + n * 2048 + k * 1024); } while (0)
; #define PG8_MMA(ai, bj, At, Bt) do { __builtin_amdgcn_s_setprio(3); _Pragma("unroll") for (int m = 0; m < 4; ++m) _Pragma("unroll") for (int n = 0; n < 2; ++n) _Pragma("unroll") for (int k = 0; k < 2; ++k) \
;         acc[ai][bj][m][n] = __builtin_amdgcn_mfma_f32_16x16x32_bf16(Bt[n][k], At[m][k], acc[ai][bj][m][n], 0, 0, 0); __builtin_amdgcn_s_setprio(0); } while (0)
; #define PG8_WAIT_V(n) asm volatile("s_waitcnt vmcnt(" #n ")" ::: "memory")
; #define PG8_WAIT_L(n) asm volatile("s_waitcnt lgkmcnt(" #n ")" ::: "memory")
; #define PG8_BAR __builtin_amdgcn_s_barrier()
; #define PG8_SCHED __builtin_amdgcn_sched_barrier(0)
; template <class Epi, bool ALIGN_EPI>
; __device__ __forceinline__ void gemm_phase(LAS unsigned char* lds, const Gemm g, const StaticOrder& S, const Epi& E) {
;     ...
;             PG8_LDB(B0, 1, 0); PG8_LDB(B1, 1, 1); PG8_SCHED; PG8_LDA(At, 1, 0); PG8_STAGE(PG8_SA(0, 1), a2 + hstep, voffA);
;             PG8_WAIT_V(8); PG8_WAIT_L(0); PG8_BAR; PG8_MMA(0, 0, At, B0); PG8_MMA(0, 1, At, B1); PG8_BAR; PG8_SCHED;
	s_add_i32 s90, 0, 0x18000
	s_add_i32 s91, 0, 0x1c000
	v_add_u32_e32 v142, s90, v217
	v_add_u32_e32 v154, s91, v217
	ds_read_b128 v[130:133], v142
	ds_read_b128 v[134:137], v142 offset:1024
	ds_read_b128 v[138:141], v142 offset:2048
	ds_read_b128 v[142:145], v142 offset:3072
	ds_read_b128 v[166:169], v154
	ds_read_b128 v[170:173], v154 offset:1024
	ds_read_b128 v[174:177], v154 offset:2048
	ds_read_b128 v[178:181], v154 offset:3072
	s_add_u32 s8, s8, 0x40000
	s_addc_u32 s9, s9, 0
	s_mov_b32 m0, s33
	v_lshl_add_u64 v[238:239], s[8:9], 0, v[146:147]
	ds_read_b128 v[182:185], v222 offset:32768
	ds_read_b128 v[186:189], v222 offset:33792
	ds_read_b128 v[190:193], v222 offset:34816
	ds_read_b128 v[194:197], v222 offset:35840
	ds_read_b128 v[198:201], v222 offset:36864
	ds_read_b128 v[202:205], v222 offset:37888
	ds_read_b128 v[206:209], v222 offset:38912
	ds_read_b128 v[226:229], v222 offset:39936
	global_load_lds_dwordx4 v[238:239], off
	v_lshl_add_u64 v[238:239], s[8:9], 0, v[150:151]
	s_mov_b32 m0, s14
	s_nop 0
	global_load_lds_dwordx4 v[238:239], off
	s_waitcnt vmcnt(8)
	s_waitcnt lgkmcnt(0)
	s_barrier
	s_setprio 3
	s_waitcnt lgkmcnt(0)
	v_mfma_f32_16x16x32_bf16 v[126:129], v[130:133], v[182:185], v[126:129]
	v_mfma_f32_16x16x32_bf16 v[122:125], v[138:141], v[182:185], v[122:125]
	v_mfma_f32_16x16x32_bf16 v[110:113], v[130:133], v[190:193], v[110:113]
	v_mfma_f32_16x16x32_bf16 v[106:109], v[138:141], v[190:193], v[106:109]
	v_mfma_f32_16x16x32_bf16 v[94:97], v[130:133], v[198:201], v[94:97]
	v_mfma_f32_16x16x32_bf16 v[90:93], v[138:141], v[198:201], v[90:93]
	v_mfma_f32_16x16x32_bf16 v[78:81], v[130:133], v[206:209], v[78:81]
	v_mfma_f32_16x16x32_bf16 v[74:77], v[138:141], v[206:209], v[74:77]
	v_mfma_f32_16x16x32_bf16 v[126:129], v[134:137], v[186:189], v[126:129]
	v_mfma_f32_16x16x32_bf16 v[122:125], v[142:145], v[186:189], v[122:125]
	v_mfma_f32_16x16x32_bf16 v[110:113], v[134:137], v[194:197], v[110:113]
	v_mfma_f32_16x16x32_bf16 v[106:109], v[142:145], v[194:197], v[106:109]
	v_mfma_f32_16x16x32_bf16 v[94:97], v[134:137], v[202:205], v[94:97]
	v_mfma_f32_16x16x32_bf16 v[90:93], v[142:145], v[202:205], v[90:93]
	v_mfma_f32_16x16x32_bf16 v[78:81], v[134:137], v[226:229], v[78:81]
	v_mfma_f32_16x16x32_bf16 v[74:77], v[142:145], v[226:229], v[74:77]
	v_mfma_f32_16x16x32_bf16 v[118:121], v[166:169], v[182:185], v[118:121]
	v_mfma_f32_16x16x32_bf16 v[114:117], v[174:177], v[182:185], v[114:117]
	v_mfma_f32_16x16x32_bf16 v[102:105], v[166:169], v[190:193], v[102:105]
	v_mfma_f32_16x16x32_bf16 v[98:101], v[174:177], v[190:193], v[98:101]
	v_mfma_f32_16x16x32_bf16 v[86:89], v[166:169], v[198:201], v[86:89]
	v_mfma_f32_16x16x32_bf16 v[82:85], v[174:177], v[198:201], v[82:85]
	v_mfma_f32_16x16x32_bf16 v[70:73], v[166:169], v[206:209], v[70:73]
	v_mfma_f32_16x16x32_bf16 v[66:69], v[174:177], v[206:209], v[66:69]
	v_mfma_f32_16x16x32_bf16 v[118:121], v[170:173], v[186:189], v[118:121]
	v_mfma_f32_16x16x32_bf16 v[114:117], v[178:181], v[186:189], v[114:117]
	v_mfma_f32_16x16x32_bf16 v[102:105], v[170:173], v[194:197], v[102:105]
	v_mfma_f32_16x16x32_bf16 v[98:101], v[178:181], v[194:197], v[98:101]
	v_mfma_f32_16x16x32_bf16 v[86:89], v[170:173], v[202:205], v[86:89]
	v_mfma_f32_16x16x32_bf16 v[82:85], v[178:181], v[202:205], v[82:85]
	v_mfma_f32_16x16x32_bf16 v[70:73], v[170:173], v[226:229], v[70:73]
	v_mfma_f32_16x16x32_bf16 v[66:69], v[178:181], v[226:229], v[66:69]
	s_setprio 0
	s_barrier
; #define PG8_STAGE(bufoff, gbase, voff) do { _Pragma("unroll") for (int _i = 0; _i < 2; ++_i) \
;         __builtin_amdgcn_global_load_lds((const unsigned*)((const char*)(gbase) + (voff)[_i]), (LAS unsigned*)(lds + (bufoff) + ldsw + _i * 8192), 16, 0, 0); } while (0)
; #define PG8_LDA(dst, b, h) do { _Pragma("unroll") for (int m = 0; m < 4; ++m) _Pragma("unroll") for (int k = 0; k < 2; ++k) dst[m][k] = *(const LAS bf16x8*)(lds + PG8_SA(b, h) + aoff + m * 2048 + k * 1024); } while (0)
; #define PG8_MMA(ai, bj, At, Bt) do { __builtin_amdgcn_s_setprio(3); _Pragma("unroll") for (int m = 0; m < 4; ++m) _Pragma("unroll") for (int n = 0; n < 2; ++n) _Pragma("unroll") for (int k = 0; k < 2; ++k) \
;         acc[ai][bj][m][n] = __builtin_amdgcn_mfma_f32_16x16x32_bf16(Bt[n][k], At[m][k], acc[ai][bj][m][n], 0, 0, 0); __builtin_amdgcn_s_setprio(0); } while (0)
; #define PG8_WAIT_V(n) asm volatile("s_waitcnt vmcnt(" #n ")" ::: "memory")
; #define PG8_WAIT_L(n) asm volatile("s_waitcnt lgkmcnt(" #n ")" ::: "memory")
; #define PG8_BAR __builtin_amdgcn_s_barrier()
; #define PG8_SCHED __builtin_amdgcn_sched_barrier(0)
; template <class Epi, bool ALIGN_EPI>
; __device__ __forceinline__ void gemm_phase(LAS unsigned char* lds, const Gemm g, const StaticOrder& S, const Epi& E) {
;     ...
;             PG8_LDA(At, 1, 1); PG8_STAGE(PG8_SB(1, 0), b3, voffB); PG8_STAGE(PG8_SB(1, 1), b3 + hstep, voffB); PG8_STAGE(PG8_SA(1, 0), a3, voffA);
;             PG8_WAIT_V(8); PG8_WAIT_L(0); PG8_BAR; PG8_MMA(1, 0, At, B0); PG8_MMA(1, 1, At, B1); PG8_BAR; PG8_SCHED;
;         }
;         if constexpr (ALIGN_EPI) { if (wr == 0) PG8_BAR; }
;         E(acc, cur, wr, wc, fr, fq);
;         if (!has_next) break;
	s_add_i32 s8, s90, s76
	v_lshl_add_u64 v[230:231], v[230:231], 0, s[60:61]
	s_mov_b32 m0, s8
	ds_read_b128 v[182:185], v222 offset:49152
	ds_read_b128 v[186:189], v222 offset:50176
	ds_read_b128 v[190:193], v222 offset:51200
	ds_read_b128 v[194:197], v222 offset:52224
	ds_read_b128 v[198:201], v222 offset:53248
	ds_read_b128 v[202:205], v222 offset:54272
	ds_read_b128 v[206:209], v222 offset:55296
	ds_read_b128 v[226:229], v222 offset:56320
	global_load_lds_dwordx4 v[230:231], off
	s_add_i32 m0, s8, 0x2000
	s_add_u32 s6, s6, 0x40080
	v_lshl_add_u64 v[230:231], v[232:233], 0, s[60:61]
	s_addc_u32 s7, s7, 0
	s_add_i32 s8, s91, s76
	global_load_lds_dwordx4 v[230:231], off
	v_lshl_add_u64 v[230:231], s[6:7], 0, v[148:149]
	s_mov_b32 m0, s8
	s_nop 0
	global_load_lds_dwordx4 v[230:231], off
	v_lshl_add_u64 v[230:231], s[6:7], 0, v[152:153]
	s_add_i32 m0, s8, 0x2000
	s_nop 0
	global_load_lds_dwordx4 v[230:231], off
	v_lshl_add_u64 v[230:231], v[234:235], 0, s[60:61]
	s_mov_b32 m0, s65
	s_nop 0
	global_load_lds_dwordx4 v[230:231], off
	v_lshl_add_u64 v[230:231], v[236:237], 0, s[60:61]
	s_mov_b32 m0, s66
	s_nop 0
	global_load_lds_dwordx4 v[230:231], off
	s_waitcnt vmcnt(8)
	s_waitcnt lgkmcnt(0)
	s_barrier
	s_setprio 3
	s_waitcnt lgkmcnt(0)
	v_mfma_f32_16x16x32_bf16 v[62:65], v[130:133], v[182:185], v[62:65]
	v_mfma_f32_16x16x32_bf16 v[58:61], v[138:141], v[182:185], v[58:61]
	v_mfma_f32_16x16x32_bf16 v[46:49], v[130:133], v[190:193], v[46:49]
	v_mfma_f32_16x16x32_bf16 v[42:45], v[138:141], v[190:193], v[42:45]
	v_mfma_f32_16x16x32_bf16 v[30:33], v[130:133], v[198:201], v[30:33]
	v_mfma_f32_16x16x32_bf16 v[26:29], v[138:141], v[198:201], v[26:29]
	v_mfma_f32_16x16x32_bf16 v[14:17], v[130:133], v[206:209], v[14:17]
	v_mfma_f32_16x16x32_bf16 v[10:13], v[138:141], v[206:209], v[10:13]
	v_mfma_f32_16x16x32_bf16 v[62:65], v[134:137], v[186:189], v[62:65]
	v_mfma_f32_16x16x32_bf16 v[58:61], v[142:145], v[186:189], v[58:61]
	v_mfma_f32_16x16x32_bf16 v[46:49], v[134:137], v[194:197], v[46:49]
	v_mfma_f32_16x16x32_bf16 v[42:45], v[142:145], v[194:197], v[42:45]
	v_mfma_f32_16x16x32_bf16 v[30:33], v[134:137], v[202:205], v[30:33]
	v_mfma_f32_16x16x32_bf16 v[26:29], v[142:145], v[202:205], v[26:29]
	v_mfma_f32_16x16x32_bf16 v[14:17], v[134:137], v[226:229], v[14:17]
	v_mfma_f32_16x16x32_bf16 v[10:13], v[142:145], v[226:229], v[10:13]
	v_mfma_f32_16x16x32_bf16 v[54:57], v[166:169], v[182:185], v[54:57]
	v_mfma_f32_16x16x32_bf16 v[50:53], v[174:177], v[182:185], v[50:53]
	v_mfma_f32_16x16x32_bf16 v[38:41], v[166:169], v[190:193], v[38:41]
	v_mfma_f32_16x16x32_bf16 v[34:37], v[174:177], v[190:193], v[34:37]
	v_mfma_f32_16x16x32_bf16 v[22:25], v[166:169], v[198:201], v[22:25]
	v_mfma_f32_16x16x32_bf16 v[18:21], v[174:177], v[198:201], v[18:21]
	v_mfma_f32_16x16x32_bf16 v[6:9], v[166:169], v[206:209], v[6:9]
	v_mfma_f32_16x16x32_bf16 v[2:5], v[174:177], v[206:209], v[2:5]
	v_mfma_f32_16x16x32_bf16 v[54:57], v[170:173], v[186:189], v[54:57]
	v_mfma_f32_16x16x32_bf16 v[50:53], v[178:181], v[186:189], v[50:53]
	v_mfma_f32_16x16x32_bf16 v[38:41], v[170:173], v[194:197], v[38:41]
	v_mfma_f32_16x16x32_bf16 v[34:37], v[178:181], v[194:197], v[34:37]
	v_mfma_f32_16x16x32_bf16 v[22:25], v[170:173], v[202:205], v[22:25]
	v_mfma_f32_16x16x32_bf16 v[18:21], v[178:181], v[202:205], v[18:21]
	v_mfma_f32_16x16x32_bf16 v[6:9], v[170:173], v[226:229], v[6:9]
	v_mfma_f32_16x16x32_bf16 v[2:5], v[178:181], v[226:229], v[2:5]
	s_setprio 0
	s_barrier
	s_add_i32 s89, s89, 2
	s_add_u32 s4, s4, 0x100
	s_addc_u32 s5, s5, 0
	s_add_u32 s85, s85, 0x100
	s_addc_u32 s88, s88, 0
	s_cmp_gt_u32 s89, 13
	s_cbranch_scc0 .LBB0_787
	s_and_b64 vcc, exec, s[62:63]
	s_cbranch_vccz .LBB0_790
	s_barrier

; #define PG8_STAGE(bufoff, gbase, voff) do { _Pragma("unroll") for (int _i = 0; _i < 2; ++_i) \
;         __builtin_amdgcn_global_load_lds((const unsigned*)((const char*)(gbase) + (voff)[_i]), (LAS unsigned*)(lds + (bufoff) + ldsw + _i * 8192), 16, 0, 0); } while (0)
; #define PG8_LDA(dst, b, h) do { _Pragma("unroll") for (int m = 0; m < 4; ++m) _Pragma("unroll") for (int k = 0; k < 2; ++k) dst[m][k] = *(const LAS bf16x8*)(lds + PG8_SA(b, h) + aoff + m * 2048 + k * 1024); } while (0)
; #define PG8_LDB(dst, b, h) do { _Pragma("unroll") for (int n = 0; n < 2; ++n) _Pragma("unroll") for (int k = 0; k < 2; ++k) dst[n][k] = *(const LAS bf16x8*)(lds + PG8_SB(b, h) + boff + n * 2048 + k * 1024); } while (0)
; #define PG8_MMA(ai, bj, At, Bt) do { __builtin_amdgcn_s_setprio(3); _Pragma("unroll") for (int m = 0; m < 4; ++m) _Pragma("unroll") for (int n = 0; n < 2; ++n) _Pragma("unroll") for (int k = 0; k < 2; ++k) \
;         acc[ai][bj][m][n] = __builtin_amdgcn_mfma_f32_16x16x32_bf16(Bt[n][k], At[m][k], acc[ai][bj][m][n], 0, 0, 0); __builtin_amdgcn_s_setprio(0); } while (0)
; #define PG8_BAR __builtin_amdgcn_s_barrier()
; template <class Epi, bool ALIGN_EPI>
; __device__ __forceinline__ void gemm_phase(LAS unsigned char* lds, const Gemm g, const StaticOrder& S, const Epi& E) {
;     ...
;         const bool has_next = S.next(ui + 1, nxt);
;         const char* nA = has_next ? (const char*)g.A + (size_t)nxt.pm * tstep : cA; const char* nB = has_next ? (const char*)g.Bt + (size_t)nxt.pn * tstep : cB;
;         for (int t = 0; t < nt; t += 2) {
;             const bool last = (t == nt - 2);
;             const char* a1 = cA + (size_t)(t + 1) * kstep;
;             const char* a2 = last ? nA : cA + (size_t)(t + 2) * kstep; const char* b2 = last ? nB : cB + (size_t)(t + 2) * kstep;
;             const char* a3 = a2 + kstep; const char* b3 = b2 + kstep;
;             PG8_LDB(B0, 0, 0); PG8_LDB(B1, 0, 1); PG8_SCHED; PG8_LDA(At, 0, 0); PG8_STAGE(PG8_SA(1, 1), a1 + hstep, voffA);
;             PG8_WAIT_V(8); PG8_WAIT_L(0); PG8_BAR; PG8_MMA(0, 0, At, B0); PG8_MMA(0, 1, At, B1); PG8_BAR; PG8_SCHED;
;             PG8_LDA(At, 0, 1); PG8_STAGE(PG8_SB(0, 0), b2, voffB); PG8_STAGE(PG8_SB(0, 1), b2 + hstep, voffB); PG8_STAGE(PG8_SA(0, 0), a2, voffA);
;             PG8_WAIT_V(8); PG8_WAIT_L(0); PG8_BAR; PG8_MMA(1, 0, At, B0); PG8_MMA(1, 1, At, B1); PG8_BAR; PG8_SCHED;
.LBB0_1338:
	s_ashr_i32 s19, s18, 31
	s_lshl_b64 s[20:21], s[18:19], 19
	s_add_u32 s20, s26, s20
	s_addc_u32 s21, s27, s21
	s_and_b64 s[22:23], s[4:5], exec
	s_cselect_b32 s19, s21, s41
	s_cselect_b32 s37, s20, s40
	s_ashr_i32 s17, s16, 31
	s_lshl_b64 s[22:23], s[16:17], 19
	s_add_u32 s22, s33, s22
	s_addc_u32 s23, s46, s23
	s_and_b64 s[44:45], s[4:5], exec
	s_cselect_b32 s17, s23, s43
	s_cselect_b32 s58, s22, s42
	s_add_u32 s40, s40, 0x40080
	s_addc_u32 s41, s41, 0
	s_add_u32 s59, s42, 0x100
	s_addc_u32 s60, s43, 0
	s_mov_b32 s61, -2
	s_waitcnt lgkmcnt(0)
	ds_read_b128 v[130:133], v196
	ds_read_b128 v[134:137], v196 offset:1024
	ds_read_b128 v[138:141], v196 offset:2048
	ds_read_b128 v[142:145], v196 offset:3072
	ds_read_b128 v[146:149], v197
	ds_read_b128 v[150:153], v197 offset:1024
	ds_read_b128 v[170:173], v197 offset:2048
	ds_read_b128 v[174:177], v197 offset:3072
	s_add_u32 s42, s40, 0xfffc0080
	s_addc_u32 s43, s41, -1
	s_cmp_eq_u32 s61, 12
	s_cselect_b32 s45, s19, s43
	s_cselect_b32 s44, s37, s42
	s_cselect_b32 s43, s17, s60
	s_cselect_b32 s42, s58, s59
	v_lshl_add_u64 v[186:187], s[40:41], 0, v[162:163]
	s_add_i32 m0, s39, 0xc000
	ds_read_b128 v[178:181], v198
	ds_read_b128 v[182:185], v198 offset:1024
	ds_read_b128 v[200:203], v198 offset:2048
	ds_read_b128 v[204:207], v198 offset:3072
	ds_read_b128 v[208:211], v198 offset:4096
	ds_read_b128 v[212:215], v198 offset:5120
	ds_read_b128 v[216:219], v198 offset:6144
	ds_read_b128 v[220:223], v198 offset:7168
	global_load_lds_dwordx4 v[186:187], off
	v_lshl_add_u64 v[186:187], s[40:41], 0, v[164:165]
	s_add_i32 m0, s39, 0xe000
	s_nop 0
	global_load_lds_dwordx4 v[186:187], off
	s_waitcnt vmcnt(8)
	s_waitcnt lgkmcnt(0)
	s_barrier
	s_setprio 3
	s_waitcnt lgkmcnt(0)
	v_mfma_f32_16x16x32_bf16 v[126:129], v[130:133], v[178:181], 0
	v_mfma_f32_16x16x32_bf16 v[122:125], v[138:141], v[178:181], 0
	v_mfma_f32_16x16x32_bf16 v[110:113], v[130:133], v[200:203], 0
	v_mfma_f32_16x16x32_bf16 v[106:109], v[138:141], v[200:203], 0
	v_mfma_f32_16x16x32_bf16 v[94:97], v[130:133], v[208:211], 0
	v_mfma_f32_16x16x32_bf16 v[90:93], v[138:141], v[208:211], 0
	v_mfma_f32_16x16x32_bf16 v[78:81], v[130:133], v[216:219], 0
	v_mfma_f32_16x16x32_bf16 v[74:77], v[138:141], v[216:219], 0
	v_mfma_f32_16x16x32_bf16 v[126:129], v[134:137], v[182:185], v[126:129]
	v_mfma_f32_16x16x32_bf16 v[122:125], v[142:145], v[182:185], v[122:125]
	v_mfma_f32_16x16x32_bf16 v[110:113], v[134:137], v[204:207], v[110:113]
	v_mfma_f32_16x16x32_bf16 v[106:109], v[142:145], v[204:207], v[106:109]
	v_mfma_f32_16x16x32_bf16 v[94:97], v[134:137], v[212:215], v[94:97]
	v_mfma_f32_16x16x32_bf16 v[90:93], v[142:145], v[212:215], v[90:93]
	v_mfma_f32_16x16x32_bf16 v[78:81], v[134:137], v[220:223], v[78:81]
	v_mfma_f32_16x16x32_bf16 v[74:77], v[142:145], v[220:223], v[74:77]
	v_mfma_f32_16x16x32_bf16 v[118:121], v[146:149], v[178:181], 0
	v_mfma_f32_16x16x32_bf16 v[114:117], v[170:173], v[178:181], 0
	v_mfma_f32_16x16x32_bf16 v[102:105], v[146:149], v[200:203], 0
	v_mfma_f32_16x16x32_bf16 v[98:101], v[170:173], v[200:203], 0
	v_mfma_f32_16x16x32_bf16 v[86:89], v[146:149], v[208:211], 0
	v_mfma_f32_16x16x32_bf16 v[82:85], v[170:173], v[208:211], 0
	v_mfma_f32_16x16x32_bf16 v[70:73], v[146:149], v[216:219], 0
	v_mfma_f32_16x16x32_bf16 v[66:69], v[170:173], v[216:219], 0
	v_mfma_f32_16x16x32_bf16 v[118:121], v[150:153], v[182:185], v[118:121]
	v_mfma_f32_16x16x32_bf16 v[114:117], v[174:177], v[182:185], v[114:117]
	v_mfma_f32_16x16x32_bf16 v[102:105], v[150:153], v[204:207], v[102:105]
	v_mfma_f32_16x16x32_bf16 v[98:101], v[174:177], v[204:207], v[98:101]
	v_mfma_f32_16x16x32_bf16 v[86:89], v[150:153], v[212:215], v[86:89]
	v_mfma_f32_16x16x32_bf16 v[82:85], v[174:177], v[212:215], v[82:85]
	v_mfma_f32_16x16x32_bf16 v[70:73], v[150:153], v[220:223], v[70:73]
	v_mfma_f32_16x16x32_bf16 v[66:69], v[174:177], v[220:223], v[66:69]
	s_setprio 0
	s_barrier
	s_add_i32 s62, s56, s47
	v_lshl_add_u64 v[186:187], s[42:43], 0, v[156:157]
	s_mov_b32 m0, s62
	ds_read_b128 v[178:181], v198 offset:16384
	ds_read_b128 v[182:185], v198 offset:17408
	ds_read_b128 v[200:203], v198 offset:18432
	ds_read_b128 v[204:207], v198 offset:19456
	ds_read_b128 v[208:211], v198 offset:20480
	ds_read_b128 v[212:215], v198 offset:21504
	ds_read_b128 v[216:219], v198 offset:22528
	ds_read_b128 v[220:223], v198 offset:23552
	global_load_lds_dwordx4 v[186:187], off
	s_add_i32 m0, s62, 0x2000
	s_add_u32 s62, s42, 0x40000
	v_lshl_add_u64 v[224:225], s[42:43], 0, v[160:161]
	s_addc_u32 s63, s43, 0
	s_add_i32 s64, s57, s47
	global_load_lds_dwordx4 v[224:225], off
	v_lshl_add_u64 v[226:227], s[62:63], 0, v[156:157]
	s_mov_b32 m0, s64
	v_lshl_add_u64 v[228:229], s[44:45], 0, v[158:159]
	global_load_lds_dwordx4 v[226:227], off
	v_lshl_add_u64 v[226:227], s[62:63], 0, v[160:161]
	s_add_i32 m0, s64, 0x2000
	s_nop 0
	global_load_lds_dwordx4 v[226:227], off
	v_lshl_add_u64 v[226:227], s[44:45], 0, v[154:155]
	s_mov_b32 m0, s39
	s_nop 0
	global_load_lds_dwordx4 v[226:227], off
	s_mov_b32 m0, s48
	s_nop 0
	global_load_lds_dwordx4 v[228:229], off
	s_waitcnt vmcnt(8)
	s_waitcnt lgkmcnt(0)
	s_barrier
; #define PG8_STAGE(bufoff, gbase, voff) do { _Pragma("unroll") for (int _i = 0; _i < 2; ++_i) \
;         __builtin_amdgcn_global_load_lds((const unsigned*)((const char*)(gbase) + (voff)[_i]), (LAS unsigned*)(lds + (bufoff) + ldsw + _i * 8192), 16, 0, 0); } while (0)
; #define PG8_LDA(dst, b, h) do { _Pragma("unroll") for (int m = 0; m < 4; ++m) _Pragma("unroll") for (int k = 0; k < 2; ++k) dst[m][k] = *(const LAS bf16x8*)(lds + PG8_SA(b, h) + aoff + m * 2048 + k * 1024); } while (0)
; #define PG8_LDB(dst, b, h) do { _Pragma("unroll") for (int n = 0; n < 2; ++n) _Pragma("unroll") for (int k = 0; k < 2; ++k) dst[n][k] = *(const LAS bf16x8*)(lds + PG8_SB(b, h) + boff + n * 2048 + k * 1024); } while (0)
; #define PG8_MMA(ai, bj, At, Bt) do { __builtin_amdgcn_s_setprio(3); _Pragma("unroll") for (int m = 0; m < 4; ++m) _Pragma("unroll") for (int n = 0; n < 2; ++n) _Pragma("unroll") for (int k = 0; k < 2; ++k) \
;         acc[ai][bj][m][n] = __builtin_amdgcn_mfma_f32_16x16x32_bf16(Bt[n][k], At[m][k], acc[ai][bj][m][n], 0, 0, 0); __builtin_amdgcn_s_setprio(0); } while (0)
; #define PG8_WAIT_V(n) asm volatile("s_waitcnt vmcnt(" #n ")" ::: "memory")
; #define PG8_WAIT_L(n) asm volatile("s_waitcnt lgkmcnt(" #n ")" ::: "memory")
; #define PG8_BAR __builtin_amdgcn_s_barrier()
; #define PG8_SCHED __builtin_amdgcn_sched_barrier(0)
; template <class Epi, bool ALIGN_EPI>
; __device__ __forceinline__ void gemm_phase(LAS unsigned char* lds, const Gemm g, const StaticOrder& S, const Epi& E) {
;     ...
;             PG8_WAIT_V(8); PG8_WAIT_L(0); PG8_BAR; PG8_MMA(1, 0, At, B0); PG8_MMA(1, 1, At, B1); PG8_BAR; PG8_SCHED;
;             PG8_LDB(B0, 1, 0); PG8_LDB(B1, 1, 1); PG8_SCHED; PG8_LDA(At, 1, 0); PG8_STAGE(PG8_SA(0, 1), a2 + hstep, voffA);
;             PG8_WAIT_V(8); PG8_WAIT_L(0); PG8_BAR; PG8_MMA(0, 0, At, B0); PG8_MMA(0, 1, At, B1); PG8_BAR; PG8_SCHED;
	s_setprio 3
	s_waitcnt lgkmcnt(0)
	v_mfma_f32_16x16x32_bf16 v[62:65], v[130:133], v[178:181], 0
	v_mfma_f32_16x16x32_bf16 v[58:61], v[138:141], v[178:181], 0
	v_mfma_f32_16x16x32_bf16 v[46:49], v[130:133], v[200:203], 0
	v_mfma_f32_16x16x32_bf16 v[42:45], v[138:141], v[200:203], 0
	v_mfma_f32_16x16x32_bf16 v[30:33], v[130:133], v[208:211], 0
	v_mfma_f32_16x16x32_bf16 v[26:29], v[138:141], v[208:211], 0
	v_mfma_f32_16x16x32_bf16 v[14:17], v[130:133], v[216:219], 0
	v_mfma_f32_16x16x32_bf16 v[10:13], v[138:141], v[216:219], 0
	v_mfma_f32_16x16x32_bf16 v[62:65], v[134:137], v[182:185], v[62:65]
	v_mfma_f32_16x16x32_bf16 v[58:61], v[142:145], v[182:185], v[58:61]
	v_mfma_f32_16x16x32_bf16 v[46:49], v[134:137], v[204:207], v[46:49]
	v_mfma_f32_16x16x32_bf16 v[42:45], v[142:145], v[204:207], v[42:45]
	v_mfma_f32_16x16x32_bf16 v[30:33], v[134:137], v[212:215], v[30:33]
	v_mfma_f32_16x16x32_bf16 v[26:29], v[142:145], v[212:215], v[26:29]
	v_mfma_f32_16x16x32_bf16 v[14:17], v[134:137], v[220:223], v[14:17]
	v_mfma_f32_16x16x32_bf16 v[10:13], v[142:145], v[220:223], v[10:13]
	v_mfma_f32_16x16x32_bf16 v[54:57], v[146:149], v[178:181], 0
	v_mfma_f32_16x16x32_bf16 v[50:53], v[170:173], v[178:181], 0
	v_mfma_f32_16x16x32_bf16 v[38:41], v[146:149], v[200:203], 0
	v_mfma_f32_16x16x32_bf16 v[34:37], v[170:173], v[200:203], 0
	v_mfma_f32_16x16x32_bf16 v[22:25], v[146:149], v[208:211], 0
	v_mfma_f32_16x16x32_bf16 v[18:21], v[170:173], v[208:211], 0
	v_mfma_f32_16x16x32_bf16 v[6:9], v[146:149], v[216:219], 0
	v_mfma_f32_16x16x32_bf16 v[2:5], v[170:173], v[216:219], 0
	v_mfma_f32_16x16x32_bf16 v[54:57], v[150:153], v[182:185], v[54:57]
	v_mfma_f32_16x16x32_bf16 v[50:53], v[174:177], v[182:185], v[50:53]
	v_mfma_f32_16x16x32_bf16 v[38:41], v[150:153], v[204:207], v[38:41]
	v_mfma_f32_16x16x32_bf16 v[34:37], v[174:177], v[204:207], v[34:37]
	v_mfma_f32_16x16x32_bf16 v[22:25], v[150:153], v[212:215], v[22:25]
	v_mfma_f32_16x16x32_bf16 v[18:21], v[174:177], v[212:215], v[18:21]
	v_mfma_f32_16x16x32_bf16 v[6:9], v[150:153], v[220:223], v[6:9]
	v_mfma_f32_16x16x32_bf16 v[2:5], v[174:177], v[220:223], v[2:5]
	s_setprio 0
	s_barrier
	s_add_i32 s62, 0, 0x18000
	s_add_i32 s63, 0, 0x1c000
	v_add_u32_e32 v142, s62, v194
	v_add_u32_e32 v174, s63, v194
	ds_read_b128 v[130:133], v142
	ds_read_b128 v[134:137], v142 offset:1024
	ds_read_b128 v[138:141], v142 offset:2048
	ds_read_b128 v[142:145], v142 offset:3072
	ds_read_b128 v[146:149], v174
	ds_read_b128 v[150:153], v174 offset:1024
	ds_read_b128 v[170:173], v174 offset:2048
	ds_read_b128 v[174:177], v174 offset:3072
	s_add_u32 s44, s44, 0x40000
	s_addc_u32 s45, s45, 0
	s_mov_b32 m0, s49
	v_lshl_add_u64 v[230:231], s[44:45], 0, v[154:155]
	ds_read_b128 v[178:181], v198 offset:32768
	ds_read_b128 v[182:185], v198 offset:33792
	ds_read_b128 v[200:203], v198 offset:34816
	ds_read_b128 v[204:207], v198 offset:35840
	ds_read_b128 v[208:211], v198 offset:36864
	ds_read_b128 v[212:215], v198 offset:37888
	ds_read_b128 v[216:219], v198 offset:38912
	ds_read_b128 v[220:223], v198 offset:39936
	global_load_lds_dwordx4 v[230:231], off
	v_lshl_add_u64 v[230:231], s[44:45], 0, v[158:159]
	s_mov_b32 m0, s50
	s_nop 0
	global_load_lds_dwordx4 v[230:231], off
	s_waitcnt vmcnt(8)
	s_waitcnt lgkmcnt(0)
	s_barrier
	s_setprio 3
	s_waitcnt lgkmcnt(0)
	v_mfma_f32_16x16x32_bf16 v[126:129], v[130:133], v[178:181], v[126:129]
	v_mfma_f32_16x16x32_bf16 v[122:125], v[138:141], v[178:181], v[122:125]
	v_mfma_f32_16x16x32_bf16 v[110:113], v[130:133], v[200:203], v[110:113]
	v_mfma_f32_16x16x32_bf16 v[106:109], v[138:141], v[200:203], v[106:109]
	v_mfma_f32_16x16x32_bf16 v[94:97], v[130:133], v[208:211], v[94:97]
	v_mfma_f32_16x16x32_bf16 v[90:93], v[138:141], v[208:211], v[90:93]
	v_mfma_f32_16x16x32_bf16 v[78:81], v[130:133], v[216:219], v[78:81]
	v_mfma_f32_16x16x32_bf16 v[74:77], v[138:141], v[216:219], v[74:77]
	v_mfma_f32_16x16x32_bf16 v[126:129], v[134:137], v[182:185], v[126:129]
	v_mfma_f32_16x16x32_bf16 v[122:125], v[142:145], v[182:185], v[122:125]
	v_mfma_f32_16x16x32_bf16 v[110:113], v[134:137], v[204:207], v[110:113]
	v_mfma_f32_16x16x32_bf16 v[106:109], v[142:145], v[204:207], v[106:109]
	v_mfma_f32_16x16x32_bf16 v[94:97], v[134:137], v[212:215], v[94:97]
	v_mfma_f32_16x16x32_bf16 v[90:93], v[142:145], v[212:215], v[90:93]
	v_mfma_f32_16x16x32_bf16 v[78:81], v[134:137], v[220:223], v[78:81]
	v_mfma_f32_16x16x32_bf16 v[74:77], v[142:145], v[220:223], v[74:77]
	v_mfma_f32_16x16x32_bf16 v[118:121], v[146:149], v[178:181], v[118:121]
	v_mfma_f32_16x16x32_bf16 v[114:117], v[170:173], v[178:181], v[114:117]
	v_mfma_f32_16x16x32_bf16 v[102:105], v[146:149], v[200:203], v[102:105]
	v_mfma_f32_16x16x32_bf16 v[98:101], v[170:173], v[200:203], v[98:101]
	v_mfma_f32_16x16x32_bf16 v[86:89], v[146:149], v[208:211], v[86:89]
	v_mfma_f32_16x16x32_bf16 v[82:85], v[170:173], v[208:211], v[82:85]
	v_mfma_f32_16x16x32_bf16 v[70:73], v[146:149], v[216:219], v[70:73]
	v_mfma_f32_16x16x32_bf16 v[66:69], v[170:173], v[216:219], v[66:69]
	v_mfma_f32_16x16x32_bf16 v[118:121], v[150:153], v[182:185], v[118:121]
	v_mfma_f32_16x16x32_bf16 v[114:117], v[174:177], v[182:185], v[114:117]
	v_mfma_f32_16x16x32_bf16 v[102:105], v[150:153], v[204:207], v[102:105]
	v_mfma_f32_16x16x32_bf16 v[98:101], v[174:177], v[204:207], v[98:101]
	v_mfma_f32_16x16x32_bf16 v[86:89], v[150:153], v[212:215], v[86:89]
	v_mfma_f32_16x16x32_bf16 v[82:85], v[174:177], v[212:215], v[82:85]
	v_mfma_f32_16x16x32_bf16 v[70:73], v[150:153], v[220:223], v[70:73]
	v_mfma_f32_16x16x32_bf16 v[66:69], v[174:177], v[220:223], v[66:69]
	s_setprio 0
	s_barrier
; #define PG8_STAGE(bufoff, gbase, voff) do { _Pragma("unroll") for (int _i = 0; _i < 2; ++_i) \
;         __builtin_amdgcn_global_load_lds((const unsigned*)((const char*)(gbase) + (voff)[_i]), (LAS unsigned*)(lds + (bufoff) + ldsw + _i * 8192), 16, 0, 0); } while (0)
; #define PG8_LDA(dst, b, h) do { _Pragma("unroll") for (int m = 0; m < 4; ++m) _Pragma("unroll") for (int k = 0; k < 2; ++k) dst[m][k] = *(const LAS bf16x8*)(lds + PG8_SA(b, h) + aoff + m * 2048 + k * 1024); } while (0)
; #define PG8_LDB(dst, b, h) do { _Pragma("unroll") for (int n = 0; n < 2; ++n) _Pragma("unroll") for (int k = 0; k < 2; ++k) dst[n][k] = *(const LAS bf16x8*)(lds + PG8_SB(b, h) + boff + n * 2048 + k * 1024); } while (0)
; #define PG8_MMA(ai, bj, At, Bt) do { __builtin_amdgcn_s_setprio(3); _Pragma("unroll") for (int m = 0; m < 4; ++m) _Pragma("unroll") for (int n = 0; n < 2; ++n) _Pragma("unroll") for (int k = 0; k < 2; ++k) \
;         acc[ai][bj][m][n] = __builtin_amdgcn_mfma_f32_16x16x32_bf16(Bt[n][k], At[m][k], acc[ai][bj][m][n], 0, 0, 0); __builtin_amdgcn_s_setprio(0); } while (0)
; #define PG8_WAIT_V(n) asm volatile("s_waitcnt vmcnt(" #n ")" ::: "memory")
; #define PG8_WAIT_L(n) asm volatile("s_waitcnt lgkmcnt(" #n ")" ::: "memory")
; #define PG8_BAR __builtin_amdgcn_s_barrier()
; #define PG8_SCHED __builtin_amdgcn_sched_barrier(0)
; template <class Epi, bool ALIGN_EPI>
; __device__ __forceinline__ void gemm_phase(LAS unsigned char* lds, const Gemm g, const StaticOrder& S, const Epi& E) {
;     ...
;             PG8_LDB(B0, 0, 0); PG8_LDB(B1, 0, 1); PG8_SCHED; PG8_LDA(At, 0, 0); PG8_STAGE(PG8_SA(1, 1), a1 + hstep, voffA);
;             PG8_WAIT_V(8); PG8_WAIT_L(0); PG8_BAR; PG8_MMA(0, 0, At, B0); PG8_MMA(0, 1, At, B1); PG8_BAR; PG8_SCHED;
;     ...
;             PG8_LDA(At, 1, 1); PG8_STAGE(PG8_SB(1, 0), b3, voffB); PG8_STAGE(PG8_SB(1, 1), b3 + hstep, voffB); PG8_STAGE(PG8_SA(1, 0), a3, voffA);
;             PG8_WAIT_V(8); PG8_WAIT_L(0); PG8_BAR; PG8_MMA(1, 0, At, B0); PG8_MMA(1, 1, At, B1); PG8_BAR; PG8_SCHED;
	s_add_i32 s44, s62, s47
	v_lshl_add_u64 v[186:187], v[186:187], 0, s[12:13]
	s_mov_b32 m0, s44
	ds_read_b128 v[178:181], v198 offset:49152
	ds_read_b128 v[182:185], v198 offset:50176
	ds_read_b128 v[200:203], v198 offset:51200
	ds_read_b128 v[204:207], v198 offset:52224
	ds_read_b128 v[208:211], v198 offset:53248
	ds_read_b128 v[212:215], v198 offset:54272
	ds_read_b128 v[216:219], v198 offset:55296
	ds_read_b128 v[220:223], v198 offset:56320
	global_load_lds_dwordx4 v[186:187], off
	s_add_i32 m0, s44, 0x2000
	s_add_u32 s42, s42, 0x40080
	v_lshl_add_u64 v[186:187], v[224:225], 0, s[12:13]
	s_addc_u32 s43, s43, 0
	s_add_i32 s44, s63, s47
	global_load_lds_dwordx4 v[186:187], off
	v_lshl_add_u64 v[186:187], s[42:43], 0, v[156:157]
	s_mov_b32 m0, s44
	s_nop 0
	global_load_lds_dwordx4 v[186:187], off
	v_lshl_add_u64 v[186:187], s[42:43], 0, v[160:161]
	s_add_i32 m0, s44, 0x2000
	s_nop 0
	global_load_lds_dwordx4 v[186:187], off
	v_lshl_add_u64 v[186:187], v[226:227], 0, s[12:13]
	s_mov_b32 m0, s52
	s_nop 0
	global_load_lds_dwordx4 v[186:187], off
	v_lshl_add_u64 v[186:187], v[228:229], 0, s[12:13]
	s_mov_b32 m0, s53
	s_nop 0
	global_load_lds_dwordx4 v[186:187], off
	s_waitcnt vmcnt(8)
	s_waitcnt lgkmcnt(0)
	s_barrier
	s_setprio 3
	s_waitcnt lgkmcnt(0)
	v_mfma_f32_16x16x32_bf16 v[62:65], v[130:133], v[178:181], v[62:65]
	v_mfma_f32_16x16x32_bf16 v[58:61], v[138:141], v[178:181], v[58:61]
	v_mfma_f32_16x16x32_bf16 v[46:49], v[130:133], v[200:203], v[46:49]
	v_mfma_f32_16x16x32_bf16 v[42:45], v[138:141], v[200:203], v[42:45]
	v_mfma_f32_16x16x32_bf16 v[30:33], v[130:133], v[208:211], v[30:33]
	v_mfma_f32_16x16x32_bf16 v[26:29], v[138:141], v[208:211], v[26:29]
	v_mfma_f32_16x16x32_bf16 v[14:17], v[130:133], v[216:219], v[14:17]
	v_mfma_f32_16x16x32_bf16 v[10:13], v[138:141], v[216:219], v[10:13]
	v_mfma_f32_16x16x32_bf16 v[62:65], v[134:137], v[182:185], v[62:65]
	v_mfma_f32_16x16x32_bf16 v[58:61], v[142:145], v[182:185], v[58:61]
	v_mfma_f32_16x16x32_bf16 v[46:49], v[134:137], v[204:207], v[46:49]
	v_mfma_f32_16x16x32_bf16 v[42:45], v[142:145], v[204:207], v[42:45]
	v_mfma_f32_16x16x32_bf16 v[30:33], v[134:137], v[212:215], v[30:33]
	v_mfma_f32_16x16x32_bf16 v[26:29], v[142:145], v[212:215], v[26:29]
	v_mfma_f32_16x16x32_bf16 v[14:17], v[134:137], v[220:223], v[14:17]
	v_mfma_f32_16x16x32_bf16 v[10:13], v[142:145], v[220:223], v[10:13]
	v_mfma_f32_16x16x32_bf16 v[54:57], v[146:149], v[178:181], v[54:57]
	v_mfma_f32_16x16x32_bf16 v[50:53], v[170:173], v[178:181], v[50:53]
	v_mfma_f32_16x16x32_bf16 v[38:41], v[146:149], v[200:203], v[38:41]
	v_mfma_f32_16x16x32_bf16 v[34:37], v[170:173], v[200:203], v[34:37]
	v_mfma_f32_16x16x32_bf16 v[22:25], v[146:149], v[208:211], v[22:25]
	v_mfma_f32_16x16x32_bf16 v[18:21], v[170:173], v[208:211], v[18:21]
	v_mfma_f32_16x16x32_bf16 v[6:9], v[146:149], v[216:219], v[6:9]
	v_mfma_f32_16x16x32_bf16 v[2:5], v[170:173], v[216:219], v[2:5]
	v_mfma_f32_16x16x32_bf16 v[54:57], v[150:153], v[182:185], v[54:57]
	v_mfma_f32_16x16x32_bf16 v[50:53], v[174:177], v[182:185], v[50:53]
	v_mfma_f32_16x16x32_bf16 v[38:41], v[150:153], v[204:207], v[38:41]
	v_mfma_f32_16x16x32_bf16 v[34:37], v[174:177], v[204:207], v[34:37]
	v_mfma_f32_16x16x32_bf16 v[22:25], v[150:153], v[212:215], v[22:25]
	v_mfma_f32_16x16x32_bf16 v[18:21], v[174:177], v[212:215], v[18:21]
	v_mfma_f32_16x16x32_bf16 v[6:9], v[150:153], v[220:223], v[6:9]
	v_mfma_f32_16x16x32_bf16 v[2:5], v[174:177], v[220:223], v[2:5]
	s_setprio 0
	s_barrier
	s_add_i32 s61, s61, 2
	s_add_u32 s40, s40, 0x100
	s_addc_u32 s41, s41, 0
	s_add_u32 s59, s59, 0x100
	s_addc_u32 s60, s60, 0
.LBB0_1339:
	ds_read_b128 v[130:133], v196
	ds_read_b128 v[134:137], v196 offset:1024
	ds_read_b128 v[138:141], v196 offset:2048
	ds_read_b128 v[142:145], v196 offset:3072
	ds_read_b128 v[146:149], v197
	ds_read_b128 v[150:153], v197 offset:1024
	ds_read_b128 v[170:173], v197 offset:2048
	ds_read_b128 v[174:177], v197 offset:3072
	s_add_u32 s42, s40, 0xfffc0080
	s_addc_u32 s43, s41, -1
	s_cmp_eq_u32 s61, 12
	s_cselect_b32 s45, s19, s43
	s_cselect_b32 s44, s37, s42
	s_cselect_b32 s43, s17, s60
	s_cselect_b32 s42, s58, s59
	v_lshl_add_u64 v[186:187], s[40:41], 0, v[162:163]
	s_add_i32 m0, s39, 0xc000
	ds_read_b128 v[178:181], v198
	ds_read_b128 v[182:185], v198 offset:1024
	ds_read_b128 v[200:203], v198 offset:2048
	ds_read_b128 v[204:207], v198 offset:3072
	ds_read_b128 v[208:211], v198 offset:4096
	ds_read_b128 v[212:215], v198 offset:5120
	ds_read_b128 v[216:219], v198 offset:6144
	ds_read_b128 v[220:223], v198 offset:7168
	global_load_lds_dwordx4 v[186:187], off
	v_lshl_add_u64 v[186:187], s[40:41], 0, v[164:165]
	s_add_i32 m0, s39, 0xe000
	s_nop 0
	global_load_lds_dwordx4 v[186:187], off
	s_waitcnt vmcnt(8)
	s_waitcnt lgkmcnt(0)
	s_barrier
; #define PG8_STAGE(bufoff, gbase, voff) do { _Pragma("unroll") for (int _i = 0; _i < 2; ++_i) \
;         __builtin_amdgcn_global_load_lds((const unsigned*)((const char*)(gbase) + (voff)[_i]), (LAS unsigned*)(lds + (bufoff) + ldsw + _i * 8192), 16, 0, 0); } while (0)
; #define PG8_LDA(dst, b, h) do { _Pragma("unroll") for (int m = 0; m < 4; ++m) _Pragma("unroll") for (int k = 0; k < 2; ++k) dst[m][k] = *(const LAS bf16x8*)(lds + PG8_SA(b, h) + aoff + m * 2048 + k * 1024); } while (0)
; #define PG8_MMA(ai, bj, At, Bt) do { __builtin_amdgcn_s_setprio(3); _Pragma("unroll") for (int m = 0; m < 4; ++m) _Pragma("unroll") for (int n = 0; n < 2; ++n) _Pragma("unroll") for (int k = 0; k < 2; ++k) \
;         acc[ai][bj][m][n] = __builtin_amdgcn_mfma_f32_16x16x32_bf16(Bt[n][k], At[m][k], acc[ai][bj][m][n], 0, 0, 0); __builtin_amdgcn_s_setprio(0); } while (0)
; #define PG8_WAIT_V(n) asm volatile("s_waitcnt vmcnt(" #n ")" ::: "memory")
; #define PG8_WAIT_L(n) asm volatile("s_waitcnt lgkmcnt(" #n ")" ::: "memory")
; #define PG8_BAR __builtin_amdgcn_s_barrier()
; #define PG8_SCHED __builtin_amdgcn_sched_barrier(0)
; template <class Epi, bool ALIGN_EPI>
; __device__ __forceinline__ void gemm_phase(LAS unsigned char* lds, const Gemm g, const StaticOrder& S, const Epi& E) {
;     ...
;             PG8_WAIT_V(8); PG8_WAIT_L(0); PG8_BAR; PG8_MMA(0, 0, At, B0); PG8_MMA(0, 1, At, B1); PG8_BAR; PG8_SCHED;
;             PG8_LDA(At, 0, 1); PG8_STAGE(PG8_SB(0, 0), b2, voffB); PG8_STAGE(PG8_SB(0, 1), b2 + hstep, voffB); PG8_STAGE(PG8_SA(0, 0), a2, voffA);
;             PG8_WAIT_V(8); PG8_WAIT_L(0); PG8_BAR; PG8_MMA(1, 0, At, B0); PG8_MMA(1, 1, At, B1); PG8_BAR; PG8_SCHED;
	s_setprio 3
	s_waitcnt lgkmcnt(0)
	v_mfma_f32_16x16x32_bf16 v[126:129], v[130:133], v[178:181], v[126:129]
	v_mfma_f32_16x16x32_bf16 v[122:125], v[138:141], v[178:181], v[122:125]
	v_mfma_f32_16x16x32_bf16 v[110:113], v[130:133], v[200:203], v[110:113]
	v_mfma_f32_16x16x32_bf16 v[106:109], v[138:141], v[200:203], v[106:109]
	v_mfma_f32_16x16x32_bf16 v[94:97], v[130:133], v[208:211], v[94:97]
	v_mfma_f32_16x16x32_bf16 v[90:93], v[138:141], v[208:211], v[90:93]
	v_mfma_f32_16x16x32_bf16 v[78:81], v[130:133], v[216:219], v[78:81]
	v_mfma_f32_16x16x32_bf16 v[74:77], v[138:141], v[216:219], v[74:77]
	v_mfma_f32_16x16x32_bf16 v[126:129], v[134:137], v[182:185], v[126:129]
	v_mfma_f32_16x16x32_bf16 v[122:125], v[142:145], v[182:185], v[122:125]
	v_mfma_f32_16x16x32_bf16 v[110:113], v[134:137], v[204:207], v[110:113]
	v_mfma_f32_16x16x32_bf16 v[106:109], v[142:145], v[204:207], v[106:109]
	v_mfma_f32_16x16x32_bf16 v[94:97], v[134:137], v[212:215], v[94:97]
	v_mfma_f32_16x16x32_bf16 v[90:93], v[142:145], v[212:215], v[90:93]
	v_mfma_f32_16x16x32_bf16 v[78:81], v[134:137], v[220:223], v[78:81]
	v_mfma_f32_16x16x32_bf16 v[74:77], v[142:145], v[220:223], v[74:77]
	v_mfma_f32_16x16x32_bf16 v[118:121], v[146:149], v[178:181], v[118:121]
	v_mfma_f32_16x16x32_bf16 v[114:117], v[170:173], v[178:181], v[114:117]
	v_mfma_f32_16x16x32_bf16 v[102:105], v[146:149], v[200:203], v[102:105]
	v_mfma_f32_16x16x32_bf16 v[98:101], v[170:173], v[200:203], v[98:101]
	v_mfma_f32_16x16x32_bf16 v[86:89], v[146:149], v[208:211], v[86:89]
	v_mfma_f32_16x16x32_bf16 v[82:85], v[170:173], v[208:211], v[82:85]
	v_mfma_f32_16x16x32_bf16 v[70:73], v[146:149], v[216:219], v[70:73]
	v_mfma_f32_16x16x32_bf16 v[66:69], v[170:173], v[216:219], v[66:69]
	v_mfma_f32_16x16x32_bf16 v[118:121], v[150:153], v[182:185], v[118:121]
	v_mfma_f32_16x16x32_bf16 v[114:117], v[174:177], v[182:185], v[114:117]
	v_mfma_f32_16x16x32_bf16 v[102:105], v[150:153], v[204:207], v[102:105]
	v_mfma_f32_16x16x32_bf16 v[98:101], v[174:177], v[204:207], v[98:101]
	v_mfma_f32_16x16x32_bf16 v[86:89], v[150:153], v[212:215], v[86:89]
	v_mfma_f32_16x16x32_bf16 v[82:85], v[174:177], v[212:215], v[82:85]
	v_mfma_f32_16x16x32_bf16 v[70:73], v[150:153], v[220:223], v[70:73]
	v_mfma_f32_16x16x32_bf16 v[66:69], v[174:177], v[220:223], v[66:69]
	s_setprio 0
	s_barrier
	s_add_i32 s62, s56, s47
	v_lshl_add_u64 v[186:187], s[42:43], 0, v[156:157]
	s_mov_b32 m0, s62
	ds_read_b128 v[178:181], v198 offset:16384
	ds_read_b128 v[182:185], v198 offset:17408
	ds_read_b128 v[200:203], v198 offset:18432
	ds_read_b128 v[204:207], v198 offset:19456
	ds_read_b128 v[208:211], v198 offset:20480
	ds_read_b128 v[212:215], v198 offset:21504
	ds_read_b128 v[216:219], v198 offset:22528
	ds_read_b128 v[220:223], v198 offset:23552
	global_load_lds_dwordx4 v[186:187], off
	s_add_i32 m0, s62, 0x2000
	s_add_u32 s62, s42, 0x40000
	v_lshl_add_u64 v[224:225], s[42:43], 0, v[160:161]
	s_addc_u32 s63, s43, 0
	s_add_i32 s64, s57, s47
	global_load_lds_dwordx4 v[224:225], off
	v_lshl_add_u64 v[226:227], s[62:63], 0, v[156:157]
	s_mov_b32 m0, s64
	v_lshl_add_u64 v[228:229], s[44:45], 0, v[158:159]
	global_load_lds_dwordx4 v[226:227], off
	v_lshl_add_u64 v[226:227], s[62:63], 0, v[160:161]
	s_add_i32 m0, s64, 0x2000
	s_nop 0
	global_load_lds_dwordx4 v[226:227], off
	v_lshl_add_u64 v[226:227], s[44:45], 0, v[154:155]
	s_mov_b32 m0, s39
	s_nop 0
	global_load_lds_dwordx4 v[226:227], off
	s_mov_b32 m0, s48
	s_nop 0
	global_load_lds_dwordx4 v[228:229], off
	s_waitcnt vmcnt(8)
	s_waitcnt lgkmcnt(0)
	s_barrier
	s_setprio 3
	s_waitcnt lgkmcnt(0)
	v_mfma_f32_16x16x32_bf16 v[62:65], v[130:133], v[178:181], v[62:65]
	v_mfma_f32_16x16x32_bf16 v[58:61], v[138:141], v[178:181], v[58:61]
	v_mfma_f32_16x16x32_bf16 v[46:49], v[130:133], v[200:203], v[46:49]
	v_mfma_f32_16x16x32_bf16 v[42:45], v[138:141], v[200:203], v[42:45]
	v_mfma_f32_16x16x32_bf16 v[30:33], v[130:133], v[208:211], v[30:33]
	v_mfma_f32_16x16x32_bf16 v[26:29], v[138:141], v[208:211], v[26:29]
	v_mfma_f32_16x16x32_bf16 v[14:17], v[130:133], v[216:219], v[14:17]
	v_mfma_f32_16x16x32_bf16 v[10:13], v[138:141], v[216:219], v[10:13]
	v_mfma_f32_16x16x32_bf16 v[62:65], v[134:137], v[182:185], v[62:65]
	v_mfma_f32_16x16x32_bf16 v[58:61], v[142:145], v[182:185], v[58:61]
	v_mfma_f32_16x16x32_bf16 v[46:49], v[134:137], v[204:207], v[46:49]
	v_mfma_f32_16x16x32_bf16 v[42:45], v[142:145], v[204:207], v[42:45]
	v_mfma_f32_16x16x32_bf16 v[30:33], v[134:137], v[212:215], v[30:33]
	v_mfma_f32_16x16x32_bf16 v[26:29], v[142:145], v[212:215], v[26:29]
	v_mfma_f32_16x16x32_bf16 v[14:17], v[134:137], v[220:223], v[14:17]
	v_mfma_f32_16x16x32_bf16 v[10:13], v[142:145], v[220:223], v[10:13]
	v_mfma_f32_16x16x32_bf16 v[54:57], v[146:149], v[178:181], v[54:57]
	v_mfma_f32_16x16x32_bf16 v[50:53], v[170:173], v[178:181], v[50:53]
	v_mfma_f32_16x16x32_bf16 v[38:41], v[146:149], v[200:203], v[38:41]
	v_mfma_f32_16x16x32_bf16 v[34:37], v[170:173], v[200:203], v[34:37]
	v_mfma_f32_16x16x32_bf16 v[22:25], v[146:149], v[208:211], v[22:25]
	v_mfma_f32_16x16x32_bf16 v[18:21], v[170:173], v[208:211], v[18:21]
	v_mfma_f32_16x16x32_bf16 v[6:9], v[146:149], v[216:219], v[6:9]
	v_mfma_f32_16x16x32_bf16 v[2:5], v[170:173], v[216:219], v[2:5]
	v_mfma_f32_16x16x32_bf16 v[54:57], v[150:153], v[182:185], v[54:57]
	v_mfma_f32_16x16x32_bf16 v[50:53], v[174:177], v[182:185], v[50:53]
	v_mfma_f32_16x16x32_bf16 v[38:41], v[150:153], v[204:207], v[38:41]
	v_mfma_f32_16x16x32_bf16 v[34:37], v[174:177], v[204:207], v[34:37]
	v_mfma_f32_16x16x32_bf16 v[22:25], v[150:153], v[212:215], v[22:25]
	v_mfma_f32_16x16x32_bf16 v[18:21], v[174:177], v[212:215], v[18:21]
	v_mfma_f32_16x16x32_bf16 v[6:9], v[150:153], v[220:223], v[6:9]
	v_mfma_f32_16x16x32_bf16 v[2:5], v[174:177], v[220:223], v[2:5]
	s_setprio 0
	s_barrier
; #define PG8_STAGE(bufoff, gbase, voff) do { _Pragma("unroll") for (int _i = 0; _i < 2; ++_i) \
;         __builtin_amdgcn_global_load_lds((const unsigned*)((const char*)(gbase) + (voff)[_i]), (LAS unsigned*)(lds + (bufoff) + ldsw + _i * 8192), 16, 0, 0); } while (0)
; #define PG8_LDA(dst, b, h) do { _Pragma("unroll") for (int m = 0; m < 4; ++m) _Pragma("unroll") for (int k = 0; k < 2; ++k) dst[m][k] = *(const LAS bf16x8*)(lds + PG8_SA(b, h) + aoff + m * 2048 + k * 1024); } while (0)
; #define PG8_LDB(dst, b, h) do { _Pragma("unroll") for (int n = 0; n < 2; ++n) _Pragma("unroll") for (int k = 0; k < 2; ++k) dst[n][k] = *(const LAS bf16x8*)(lds + PG8_SB(b, h) + boff + n * 2048 + k * 1024); } while (0)
; #define PG8_MMA(ai, bj, At, Bt) do { __builtin_amdgcn_s_setprio(3); _Pragma("unroll") for (int m = 0; m < 4; ++m) _Pragma("unroll") for (int n = 0; n < 2; ++n) _Pragma("unroll") for (int k = 0; k < 2; ++k) \
;         acc[ai][bj][m][n] = __builtin_amdgcn_mfma_f32_16x16x32_bf16(Bt[n][k], At[m][k], acc[ai][bj][m][n], 0, 0, 0); __builtin_amdgcn_s_setprio(0); } while (0)
; #define PG8_WAIT_V(n) asm volatile("s_waitcnt vmcnt(" #n ")" ::: "memory")
; #define PG8_WAIT_L(n) asm volatile("s_waitcnt lgkmcnt(" #n ")" ::: "memory")
; #define PG8_BAR __builtin_amdgcn_s_barrier()
; #define PG8_SCHED __builtin_amdgcn_sched_barrier(0)
; template <class Epi, bool ALIGN_EPI>
; __device__ __forceinline__ void gemm_phase(LAS unsigned char* lds, const Gemm g, const StaticOrder& S, const Epi& E) {
;     ...
;             PG8_LDB(B0, 1, 0); PG8_LDB(B1, 1, 1); PG8_SCHED; PG8_LDA(At, 1, 0); PG8_STAGE(PG8_SA(0, 1), a2 + hstep, voffA);
;             PG8_WAIT_V(8); PG8_WAIT_L(0); PG8_BAR; PG8_MMA(0, 0, At, B0); PG8_MMA(0, 1, At, B1); PG8_BAR; PG8_SCHED;
	s_add_i32 s62, 0, 0x18000
	s_add_i32 s63, 0, 0x1c000
	v_add_u32_e32 v142, s62, v194
	v_add_u32_e32 v174, s63, v194
	ds_read_b128 v[130:133], v142
	ds_read_b128 v[134:137], v142 offset:1024
	ds_read_b128 v[138:141], v142 offset:2048
	ds_read_b128 v[142:145], v142 offset:3072
	ds_read_b128 v[146:149], v174
	ds_read_b128 v[150:153], v174 offset:1024
	ds_read_b128 v[170:173], v174 offset:2048
	ds_read_b128 v[174:177], v174 offset:3072
	s_add_u32 s44, s44, 0x40000
	s_addc_u32 s45, s45, 0
	s_mov_b32 m0, s49
	v_lshl_add_u64 v[230:231], s[44:45], 0, v[154:155]
	ds_read_b128 v[178:181], v198 offset:32768
	ds_read_b128 v[182:185], v198 offset:33792
	ds_read_b128 v[200:203], v198 offset:34816
	ds_read_b128 v[204:207], v198 offset:35840
	ds_read_b128 v[208:211], v198 offset:36864
	ds_read_b128 v[212:215], v198 offset:37888
	ds_read_b128 v[216:219], v198 offset:38912
	ds_read_b128 v[220:223], v198 offset:39936
	global_load_lds_dwordx4 v[230:231], off
	v_lshl_add_u64 v[230:231], s[44:45], 0, v[158:159]
	s_mov_b32 m0, s50
	s_nop 0
	global_load_lds_dwordx4 v[230:231], off
	s_waitcnt vmcnt(8)
	s_waitcnt lgkmcnt(0)
	s_barrier
	s_setprio 3
	s_waitcnt lgkmcnt(0)
	v_mfma_f32_16x16x32_bf16 v[126:129], v[130:133], v[178:181], v[126:129]
	v_mfma_f32_16x16x32_bf16 v[122:125], v[138:141], v[178:181], v[122:125]
	v_mfma_f32_16x16x32_bf16 v[110:113], v[130:133], v[200:203], v[110:113]
	v_mfma_f32_16x16x32_bf16 v[106:109], v[138:141], v[200:203], v[106:109]
	v_mfma_f32_16x16x32_bf16 v[94:97], v[130:133], v[208:211], v[94:97]
	v_mfma_f32_16x16x32_bf16 v[90:93], v[138:141], v[208:211], v[90:93]
	v_mfma_f32_16x16x32_bf16 v[78:81], v[130:133], v[216:219], v[78:81]
	v_mfma_f32_16x16x32_bf16 v[74:77], v[138:141], v[216:219], v[74:77]
	v_mfma_f32_16x16x32_bf16 v[126:129], v[134:137], v[182:185], v[126:129]
	v_mfma_f32_16x16x32_bf16 v[122:125], v[142:145], v[182:185], v[122:125]
	v_mfma_f32_16x16x32_bf16 v[110:113], v[134:137], v[204:207], v[110:113]
	v_mfma_f32_16x16x32_bf16 v[106:109], v[142:145], v[204:207], v[106:109]
	v_mfma_f32_16x16x32_bf16 v[94:97], v[134:137], v[212:215], v[94:97]
	v_mfma_f32_16x16x32_bf16 v[90:93], v[142:145], v[212:215], v[90:93]
	v_mfma_f32_16x16x32_bf16 v[78:81], v[134:137], v[220:223], v[78:81]
	v_mfma_f32_16x16x32_bf16 v[74:77], v[142:145], v[220:223], v[74:77]
	v_mfma_f32_16x16x32_bf16 v[118:121], v[146:149], v[178:181], v[118:121]
	v_mfma_f32_16x16x32_bf16 v[114:117], v[170:173], v[178:181], v[114:117]
	v_mfma_f32_16x16x32_bf16 v[102:105], v[146:149], v[200:203], v[102:105]
	v_mfma_f32_16x16x32_bf16 v[98:101], v[170:173], v[200:203], v[98:101]
	v_mfma_f32_16x16x32_bf16 v[86:89], v[146:149], v[208:211], v[86:89]
	v_mfma_f32_16x16x32_bf16 v[82:85], v[170:173], v[208:211], v[82:85]
	v_mfma_f32_16x16x32_bf16 v[70:73], v[146:149], v[216:219], v[70:73]
	v_mfma_f32_16x16x32_bf16 v[66:69], v[170:173], v[216:219], v[66:69]
	v_mfma_f32_16x16x32_bf16 v[118:121], v[150:153], v[182:185], v[118:121]
	v_mfma_f32_16x16x32_bf16 v[114:117], v[174:177], v[182:185], v[114:117]
	v_mfma_f32_16x16x32_bf16 v[102:105], v[150:153], v[204:207], v[102:105]
	v_mfma_f32_16x16x32_bf16 v[98:101], v[174:177], v[204:207], v[98:101]
	v_mfma_f32_16x16x32_bf16 v[86:89], v[150:153], v[212:215], v[86:89]
	v_mfma_f32_16x16x32_bf16 v[82:85], v[174:177], v[212:215], v[82:85]
	v_mfma_f32_16x16x32_bf16 v[70:73], v[150:153], v[220:223], v[70:73]
	v_mfma_f32_16x16x32_bf16 v[66:69], v[174:177], v[220:223], v[66:69]
	s_setprio 0
	s_barrier
; #define PG8_STAGE(bufoff, gbase, voff) do { _Pragma("unroll") for (int _i = 0; _i < 2; ++_i) \
;         __builtin_amdgcn_global_load_lds((const unsigned*)((const char*)(gbase) + (voff)[_i]), (LAS unsigned*)(lds + (bufoff) + ldsw + _i * 8192), 16, 0, 0); } while (0)
; #define PG8_LDA(dst, b, h) do { _Pragma("unroll") for (int m = 0; m < 4; ++m) _Pragma("unroll") for (int k = 0; k < 2; ++k) dst[m][k] = *(const LAS bf16x8*)(lds + PG8_SA(b, h) + aoff + m * 2048 + k * 1024); } while (0)
; #define PG8_MMA(ai, bj, At, Bt) do { __builtin_amdgcn_s_setprio(3); _Pragma("unroll") for (int m = 0; m < 4; ++m) _Pragma("unroll") for (int n = 0; n < 2; ++n) _Pragma("unroll") for (int k = 0; k < 2; ++k) \
;         acc[ai][bj][m][n] = __builtin_amdgcn_mfma_f32_16x16x32_bf16(Bt[n][k], At[m][k], acc[ai][bj][m][n], 0, 0, 0); __builtin_amdgcn_s_setprio(0); } while (0)
; #define PG8_WAIT_V(n) asm volatile("s_waitcnt vmcnt(" #n ")" ::: "memory")
; #define PG8_WAIT_L(n) asm volatile("s_waitcnt lgkmcnt(" #n ")" ::: "memory")
; #define PG8_BAR __builtin_amdgcn_s_barrier()
; #define PG8_SCHED __builtin_amdgcn_sched_barrier(0)
; template <class Epi, bool ALIGN_EPI>
; __device__ __forceinline__ void gemm_phase(LAS unsigned char* lds, const Gemm g, const StaticOrder& S, const Epi& E) {
;     ...
;             PG8_LDA(At, 1, 1); PG8_STAGE(PG8_SB(1, 0), b3, voffB); PG8_STAGE(PG8_SB(1, 1), b3 + hstep, voffB); PG8_STAGE(PG8_SA(1, 0), a3, voffA);
;             PG8_WAIT_V(8); PG8_WAIT_L(0); PG8_BAR; PG8_MMA(1, 0, At, B0); PG8_MMA(1, 1, At, B1); PG8_BAR; PG8_SCHED;
;         }
;         if constexpr (ALIGN_EPI) { if (wr == 0) PG8_BAR; }
;         E(acc, cur, wr, wc, fr, fq);
;         if (!has_next) break;
	s_add_i32 s44, s62, s47
	v_lshl_add_u64 v[186:187], v[186:187], 0, s[12:13]
	s_mov_b32 m0, s44
	ds_read_b128 v[178:181], v198 offset:49152
	ds_read_b128 v[182:185], v198 offset:50176
	ds_read_b128 v[200:203], v198 offset:51200
	ds_read_b128 v[204:207], v198 offset:52224
	ds_read_b128 v[208:211], v198 offset:53248
	ds_read_b128 v[212:215], v198 offset:54272
	ds_read_b128 v[216:219], v198 offset:55296
	ds_read_b128 v[220:223], v198 offset:56320
	global_load_lds_dwordx4 v[186:187], off
	s_add_i32 m0, s44, 0x2000
	s_add_u32 s42, s42, 0x40080
	v_lshl_add_u64 v[186:187], v[224:225], 0, s[12:13]
	s_addc_u32 s43, s43, 0
	s_add_i32 s44, s63, s47
	global_load_lds_dwordx4 v[186:187], off
	v_lshl_add_u64 v[186:187], s[42:43], 0, v[156:157]
	s_mov_b32 m0, s44
	s_nop 0
	global_load_lds_dwordx4 v[186:187], off
	v_lshl_add_u64 v[186:187], s[42:43], 0, v[160:161]
	s_add_i32 m0, s44, 0x2000
	s_nop 0
	global_load_lds_dwordx4 v[186:187], off
	v_lshl_add_u64 v[186:187], v[226:227], 0, s[12:13]
	s_mov_b32 m0, s52
	s_nop 0
	global_load_lds_dwordx4 v[186:187], off
	v_lshl_add_u64 v[186:187], v[228:229], 0, s[12:13]
	s_mov_b32 m0, s53
	s_nop 0
	global_load_lds_dwordx4 v[186:187], off
	s_waitcnt vmcnt(8)
	s_waitcnt lgkmcnt(0)
	s_barrier
	s_setprio 3
	s_waitcnt lgkmcnt(0)
	v_mfma_f32_16x16x32_bf16 v[62:65], v[130:133], v[178:181], v[62:65]
	v_mfma_f32_16x16x32_bf16 v[58:61], v[138:141], v[178:181], v[58:61]
	v_mfma_f32_16x16x32_bf16 v[46:49], v[130:133], v[200:203], v[46:49]
	v_mfma_f32_16x16x32_bf16 v[42:45], v[138:141], v[200:203], v[42:45]
	v_mfma_f32_16x16x32_bf16 v[30:33], v[130:133], v[208:211], v[30:33]
	v_mfma_f32_16x16x32_bf16 v[26:29], v[138:141], v[208:211], v[26:29]
	v_mfma_f32_16x16x32_bf16 v[14:17], v[130:133], v[216:219], v[14:17]
	v_mfma_f32_16x16x32_bf16 v[10:13], v[138:141], v[216:219], v[10:13]
	v_mfma_f32_16x16x32_bf16 v[62:65], v[134:137], v[182:185], v[62:65]
	v_mfma_f32_16x16x32_bf16 v[58:61], v[142:145], v[182:185], v[58:61]
	v_mfma_f32_16x16x32_bf16 v[46:49], v[134:137], v[204:207], v[46:49]
	v_mfma_f32_16x16x32_bf16 v[42:45], v[142:145], v[204:207], v[42:45]
	v_mfma_f32_16x16x32_bf16 v[30:33], v[134:137], v[212:215], v[30:33]
	v_mfma_f32_16x16x32_bf16 v[26:29], v[142:145], v[212:215], v[26:29]
	v_mfma_f32_16x16x32_bf16 v[14:17], v[134:137], v[220:223], v[14:17]
	v_mfma_f32_16x16x32_bf16 v[10:13], v[142:145], v[220:223], v[10:13]
	v_mfma_f32_16x16x32_bf16 v[54:57], v[146:149], v[178:181], v[54:57]
	v_mfma_f32_16x16x32_bf16 v[50:53], v[170:173], v[178:181], v[50:53]
	v_mfma_f32_16x16x32_bf16 v[38:41], v[146:149], v[200:203], v[38:41]
	v_mfma_f32_16x16x32_bf16 v[34:37], v[170:173], v[200:203], v[34:37]
	v_mfma_f32_16x16x32_bf16 v[22:25], v[146:149], v[208:211], v[22:25]
	v_mfma_f32_16x16x32_bf16 v[18:21], v[170:173], v[208:211], v[18:21]
	v_mfma_f32_16x16x32_bf16 v[6:9], v[146:149], v[216:219], v[6:9]
	v_mfma_f32_16x16x32_bf16 v[2:5], v[170:173], v[216:219], v[2:5]
	v_mfma_f32_16x16x32_bf16 v[54:57], v[150:153], v[182:185], v[54:57]
	v_mfma_f32_16x16x32_bf16 v[50:53], v[174:177], v[182:185], v[50:53]
	v_mfma_f32_16x16x32_bf16 v[38:41], v[150:153], v[204:207], v[38:41]
	v_mfma_f32_16x16x32_bf16 v[34:37], v[174:177], v[204:207], v[34:37]
	v_mfma_f32_16x16x32_bf16 v[22:25], v[150:153], v[212:215], v[22:25]
	v_mfma_f32_16x16x32_bf16 v[18:21], v[174:177], v[212:215], v[18:21]
	v_mfma_f32_16x16x32_bf16 v[6:9], v[150:153], v[220:223], v[6:9]
	v_mfma_f32_16x16x32_bf16 v[2:5], v[174:177], v[220:223], v[2:5]
	s_setprio 0
	s_barrier
	s_add_i32 s61, s61, 2
	s_add_u32 s40, s40, 0x100
	s_addc_u32 s41, s41, 0
	s_add_u32 s59, s59, 0x100
	s_addc_u32 s60, s60, 0
	s_cmp_gt_u32 s61, 13
	s_cbranch_scc0 .LBB0_1339
	s_and_b64 vcc, exec, s[14:15]
	s_cbranch_vccz .LBB0_1342
	s_barrier

; #define PG8_STAGE(bufoff, gbase, voff) do { _Pragma("unroll") for (int _i = 0; _i < 2; ++_i) \
;         __builtin_amdgcn_global_load_lds((const unsigned*)((const char*)(gbase) + (voff)[_i]), (LAS unsigned*)(lds + (bufoff) + ldsw + _i * 8192), 16, 0, 0); } while (0)
; #define PG8_LDA(dst, b, h) do { _Pragma("unroll") for (int m = 0; m < 4; ++m) _Pragma("unroll") for (int k = 0; k < 2; ++k) dst[m][k] = *(const LAS bf16x8*)(lds + PG8_SA(b, h) + aoff + m * 2048 + k * 1024); } while (0)
; #define PG8_LDB(dst, b, h) do { _Pragma("unroll") for (int n = 0; n < 2; ++n) _Pragma("unroll") for (int k = 0; k < 2; ++k) dst[n][k] = *(const LAS bf16x8*)(lds + PG8_SB(b, h) + boff + n * 2048 + k * 1024); } while (0)
; #define PG8_MMA(ai, bj, At, Bt) do { __builtin_amdgcn_s_setprio(3); _Pragma("unroll") for (int m = 0; m < 4; ++m) _Pragma("unroll") for (int n = 0; n < 2; ++n) _Pragma("unroll") for (int k = 0; k < 2; ++k) \
;         acc[ai][bj][m][n] = __builtin_amdgcn_mfma_f32_16x16x32_bf16(Bt[n][k], At[m][k], acc[ai][bj][m][n], 0, 0, 0); __builtin_amdgcn_s_setprio(0); } while (0)
; #define PG8_BAR __builtin_amdgcn_s_barrier()
; template <class Epi, bool ALIGN_EPI>
; __device__ __forceinline__ void gemm_phase(LAS unsigned char* lds, const Gemm g, const StaticOrder& S, const Epi& E) {
;     ...
;         const bool has_next = S.next(ui + 1, nxt);
;         const char* nA = has_next ? (const char*)g.A + (size_t)nxt.pm * tstep : cA; const char* nB = has_next ? (const char*)g.Bt + (size_t)nxt.pn * tstep : cB;
;         for (int t = 0; t < nt; t += 2) {
;             const bool last = (t == nt - 2);
;             const char* a1 = cA + (size_t)(t + 1) * kstep;
;             const char* a2 = last ? nA : cA + (size_t)(t + 2) * kstep; const char* b2 = last ? nB : cB + (size_t)(t + 2) * kstep;
;             const char* a3 = a2 + kstep; const char* b3 = b2 + kstep;
;             PG8_LDB(B0, 0, 0); PG8_LDB(B1, 0, 1); PG8_SCHED; PG8_LDA(At, 0, 0); PG8_STAGE(PG8_SA(1, 1), a1 + hstep, voffA);
;             PG8_WAIT_V(8); PG8_WAIT_L(0); PG8_BAR; PG8_MMA(0, 0, At, B0); PG8_MMA(0, 1, At, B1); PG8_BAR; PG8_SCHED;
;             PG8_LDA(At, 0, 1); PG8_STAGE(PG8_SB(0, 0), b2, voffB); PG8_STAGE(PG8_SB(0, 1), b2 + hstep, voffB); PG8_STAGE(PG8_SA(0, 0), a2, voffA);
;             PG8_WAIT_V(8); PG8_WAIT_L(0); PG8_BAR; PG8_MMA(1, 0, At, B0); PG8_MMA(1, 1, At, B1); PG8_BAR; PG8_SCHED;
.LBB0_1427:
	s_ashr_i32 s43, s42, 31
	s_lshl_b64 s[10:11], s[42:43], 19
	s_add_u32 s44, s34, s10
	s_addc_u32 s45, s35, s11
	s_and_b64 s[10:11], s[0:1], exec
	s_cselect_b32 s12, s45, s7
	s_cselect_b32 s13, s44, s6
	s_ashr_i32 s41, s40, 31
	s_lshl_b64 s[10:11], s[40:41], 19
	s_add_u32 s46, s22, s10
	s_addc_u32 s47, s23, s11
	s_and_b64 s[10:11], s[0:1], exec
	s_cselect_b32 s14, s47, s9
	s_cselect_b32 s15, s46, s8
	s_add_u32 s6, s6, 0x40080
	s_addc_u32 s7, s7, 0
	s_add_u32 s16, s8, 0x100
	s_addc_u32 s17, s9, 0
	s_mov_b32 s41, -2
	ds_read_b128 v[146:149], v168
	ds_read_b128 v[150:153], v168 offset:1024
	ds_read_b128 v[154:157], v168 offset:2048
	ds_read_b128 v[158:161], v168 offset:3072
	ds_read_b128 v[172:175], v169
	ds_read_b128 v[176:179], v169 offset:1024
	ds_read_b128 v[180:183], v169 offset:2048
	ds_read_b128 v[184:187], v169 offset:3072
	s_add_u32 s8, s6, 0xfffc0080
	s_addc_u32 s9, s7, -1
	s_cmp_eq_u32 s41, 12
	s_cselect_b32 s11, s12, s9
	s_cselect_b32 s10, s13, s8
	s_cselect_b32 s9, s14, s17
	s_cselect_b32 s8, s15, s16
	v_lshl_add_u64 v[220:221], s[6:7], 0, v[138:139]
	s_add_i32 m0, s50, 0xc000
	ds_read_b128 v[188:191], v170
	ds_read_b128 v[192:195], v170 offset:1024
	ds_read_b128 v[196:199], v170 offset:2048
	ds_read_b128 v[200:203], v170 offset:3072
	ds_read_b128 v[204:207], v170 offset:4096
	ds_read_b128 v[208:211], v170 offset:5120
	ds_read_b128 v[212:215], v170 offset:6144
	ds_read_b128 v[216:219], v170 offset:7168
	global_load_lds_dwordx4 v[220:221], off
	v_lshl_add_u64 v[220:221], s[6:7], 0, v[140:141]
	s_add_i32 m0, s50, 0xe000
	s_nop 0
	global_load_lds_dwordx4 v[220:221], off
	s_waitcnt vmcnt(8)
	s_waitcnt lgkmcnt(0)
	s_barrier
	s_setprio 3
	s_waitcnt lgkmcnt(0)
	v_mfma_f32_16x16x32_bf16 v[126:129], v[146:149], v[188:191], 0
	v_mfma_f32_16x16x32_bf16 v[118:121], v[154:157], v[188:191], 0
	v_mfma_f32_16x16x32_bf16 v[110:113], v[146:149], v[196:199], 0
	v_mfma_f32_16x16x32_bf16 v[102:105], v[154:157], v[196:199], 0
	v_mfma_f32_16x16x32_bf16 v[94:97], v[146:149], v[204:207], 0
	v_mfma_f32_16x16x32_bf16 v[86:89], v[154:157], v[204:207], 0
	v_mfma_f32_16x16x32_bf16 v[78:81], v[146:149], v[212:215], 0
	v_mfma_f32_16x16x32_bf16 v[70:73], v[154:157], v[212:215], 0
	v_mfma_f32_16x16x32_bf16 v[126:129], v[150:153], v[192:195], v[126:129]
	v_mfma_f32_16x16x32_bf16 v[118:121], v[158:161], v[192:195], v[118:121]
	v_mfma_f32_16x16x32_bf16 v[110:113], v[150:153], v[200:203], v[110:113]
	v_mfma_f32_16x16x32_bf16 v[102:105], v[158:161], v[200:203], v[102:105]
	v_mfma_f32_16x16x32_bf16 v[94:97], v[150:153], v[208:211], v[94:97]
	v_mfma_f32_16x16x32_bf16 v[86:89], v[158:161], v[208:211], v[86:89]
	v_mfma_f32_16x16x32_bf16 v[78:81], v[150:153], v[216:219], v[78:81]
	v_mfma_f32_16x16x32_bf16 v[70:73], v[158:161], v[216:219], v[70:73]
	v_mfma_f32_16x16x32_bf16 v[122:125], v[172:175], v[188:191], 0
	v_mfma_f32_16x16x32_bf16 v[114:117], v[180:183], v[188:191], 0
	v_mfma_f32_16x16x32_bf16 v[106:109], v[172:175], v[196:199], 0
	v_mfma_f32_16x16x32_bf16 v[98:101], v[180:183], v[196:199], 0
	v_mfma_f32_16x16x32_bf16 v[90:93], v[172:175], v[204:207], 0
	v_mfma_f32_16x16x32_bf16 v[82:85], v[180:183], v[204:207], 0
	v_mfma_f32_16x16x32_bf16 v[74:77], v[172:175], v[212:215], 0
	v_mfma_f32_16x16x32_bf16 v[66:69], v[180:183], v[212:215], 0
	v_mfma_f32_16x16x32_bf16 v[122:125], v[176:179], v[192:195], v[122:125]
	v_mfma_f32_16x16x32_bf16 v[114:117], v[184:187], v[192:195], v[114:117]
	v_mfma_f32_16x16x32_bf16 v[106:109], v[176:179], v[200:203], v[106:109]
	v_mfma_f32_16x16x32_bf16 v[98:101], v[184:187], v[200:203], v[98:101]
	v_mfma_f32_16x16x32_bf16 v[90:93], v[176:179], v[208:211], v[90:93]
	v_mfma_f32_16x16x32_bf16 v[82:85], v[184:187], v[208:211], v[82:85]
	v_mfma_f32_16x16x32_bf16 v[74:77], v[176:179], v[216:219], v[74:77]
	v_mfma_f32_16x16x32_bf16 v[66:69], v[184:187], v[216:219], v[66:69]
	s_setprio 0
	s_barrier
	s_add_i32 s43, s58, s33
	v_lshl_add_u64 v[220:221], s[8:9], 0, v[132:133]
	s_mov_b32 m0, s43
	ds_read_b128 v[188:191], v170 offset:16384
	ds_read_b128 v[192:195], v170 offset:17408
	ds_read_b128 v[196:199], v170 offset:18432
	ds_read_b128 v[200:203], v170 offset:19456
	ds_read_b128 v[204:207], v170 offset:20480
	ds_read_b128 v[208:211], v170 offset:21504
	ds_read_b128 v[212:215], v170 offset:22528
	ds_read_b128 v[216:219], v170 offset:23552
	global_load_lds_dwordx4 v[220:221], off
	s_add_i32 m0, s43, 0x2000
	s_add_u32 s62, s8, 0x40000
	v_lshl_add_u64 v[222:223], s[8:9], 0, v[136:137]
	s_addc_u32 s63, s9, 0
	s_add_i32 s43, s59, s33
	global_load_lds_dwordx4 v[222:223], off
	v_lshl_add_u64 v[224:225], s[62:63], 0, v[132:133]
	s_mov_b32 m0, s43
	v_lshl_add_u64 v[226:227], s[10:11], 0, v[134:135]
	global_load_lds_dwordx4 v[224:225], off
	v_lshl_add_u64 v[224:225], s[62:63], 0, v[136:137]
	s_add_i32 m0, s43, 0x2000
	s_nop 0
	global_load_lds_dwordx4 v[224:225], off
	v_lshl_add_u64 v[224:225], s[10:11], 0, v[130:131]
	s_mov_b32 m0, s50
	s_nop 0
	global_load_lds_dwordx4 v[224:225], off
	s_mov_b32 m0, s51
	s_nop 0
	global_load_lds_dwordx4 v[226:227], off
	s_waitcnt vmcnt(8)
	s_waitcnt lgkmcnt(0)
	s_barrier
; #define PG8_STAGE(bufoff, gbase, voff) do { _Pragma("unroll") for (int _i = 0; _i < 2; ++_i) \
;         __builtin_amdgcn_global_load_lds((const unsigned*)((const char*)(gbase) + (voff)[_i]), (LAS unsigned*)(lds + (bufoff) + ldsw + _i * 8192), 16, 0, 0); } while (0)
; #define PG8_LDA(dst, b, h) do { _Pragma("unroll") for (int m = 0; m < 4; ++m) _Pragma("unroll") for (int k = 0; k < 2; ++k) dst[m][k] = *(const LAS bf16x8*)(lds + PG8_SA(b, h) + aoff + m * 2048 + k * 1024); } while (0)
; #define PG8_LDB(dst, b, h) do { _Pragma("unroll") for (int n = 0; n < 2; ++n) _Pragma("unroll") for (int k = 0; k < 2; ++k) dst[n][k] = *(const LAS bf16x8*)(lds + PG8_SB(b, h) + boff + n * 2048 + k * 1024); } while (0)
; #define PG8_MMA(ai, bj, At, Bt) do { __builtin_amdgcn_s_setprio(3); _Pragma("unroll") for (int m = 0; m < 4; ++m) _Pragma("unroll") for (int n = 0; n < 2; ++n) _Pragma("unroll") for (int k = 0; k < 2; ++k) \
;         acc[ai][bj][m][n] = __builtin_amdgcn_mfma_f32_16x16x32_bf16(Bt[n][k], At[m][k], acc[ai][bj][m][n], 0, 0, 0); __builtin_amdgcn_s_setprio(0); } while (0)
; #define PG8_WAIT_V(n) asm volatile("s_waitcnt vmcnt(" #n ")" ::: "memory")
; #define PG8_WAIT_L(n) asm volatile("s_waitcnt lgkmcnt(" #n ")" ::: "memory")
; #define PG8_BAR __builtin_amdgcn_s_barrier()
; #define PG8_SCHED __builtin_amdgcn_sched_barrier(0)
; template <class Epi, bool ALIGN_EPI>
; __device__ __forceinline__ void gemm_phase(LAS unsigned char* lds, const Gemm g, const StaticOrder& S, const Epi& E) {
;     ...
;             PG8_WAIT_V(8); PG8_WAIT_L(0); PG8_BAR; PG8_MMA(1, 0, At, B0); PG8_MMA(1, 1, At, B1); PG8_BAR; PG8_SCHED;
;             PG8_LDB(B0, 1, 0); PG8_LDB(B1, 1, 1); PG8_SCHED; PG8_LDA(At, 1, 0); PG8_STAGE(PG8_SA(0, 1), a2 + hstep, voffA);
;             PG8_WAIT_V(8); PG8_WAIT_L(0); PG8_BAR; PG8_MMA(0, 0, At, B0); PG8_MMA(0, 1, At, B1); PG8_BAR; PG8_SCHED;
	s_setprio 3
	s_waitcnt lgkmcnt(0)
	v_mfma_f32_16x16x32_bf16 v[62:65], v[146:149], v[188:191], 0
	v_mfma_f32_16x16x32_bf16 v[54:57], v[154:157], v[188:191], 0
	v_mfma_f32_16x16x32_bf16 v[46:49], v[146:149], v[196:199], 0
	v_mfma_f32_16x16x32_bf16 v[38:41], v[154:157], v[196:199], 0
	v_mfma_f32_16x16x32_bf16 v[30:33], v[146:149], v[204:207], 0
	v_mfma_f32_16x16x32_bf16 v[22:25], v[154:157], v[204:207], 0
	v_mfma_f32_16x16x32_bf16 v[14:17], v[146:149], v[212:215], 0
	v_mfma_f32_16x16x32_bf16 v[6:9], v[154:157], v[212:215], 0
	v_mfma_f32_16x16x32_bf16 v[62:65], v[150:153], v[192:195], v[62:65]
	v_mfma_f32_16x16x32_bf16 v[54:57], v[158:161], v[192:195], v[54:57]
	v_mfma_f32_16x16x32_bf16 v[46:49], v[150:153], v[200:203], v[46:49]
	v_mfma_f32_16x16x32_bf16 v[38:41], v[158:161], v[200:203], v[38:41]
	v_mfma_f32_16x16x32_bf16 v[30:33], v[150:153], v[208:211], v[30:33]
	v_mfma_f32_16x16x32_bf16 v[22:25], v[158:161], v[208:211], v[22:25]
	v_mfma_f32_16x16x32_bf16 v[14:17], v[150:153], v[216:219], v[14:17]
	v_mfma_f32_16x16x32_bf16 v[6:9], v[158:161], v[216:219], v[6:9]
	v_mfma_f32_16x16x32_bf16 v[58:61], v[172:175], v[188:191], 0
	v_mfma_f32_16x16x32_bf16 v[50:53], v[180:183], v[188:191], 0
	v_mfma_f32_16x16x32_bf16 v[42:45], v[172:175], v[196:199], 0
	v_mfma_f32_16x16x32_bf16 v[34:37], v[180:183], v[196:199], 0
	v_mfma_f32_16x16x32_bf16 v[26:29], v[172:175], v[204:207], 0
	v_mfma_f32_16x16x32_bf16 v[18:21], v[180:183], v[204:207], 0
	v_mfma_f32_16x16x32_bf16 v[10:13], v[172:175], v[212:215], 0
	v_mfma_f32_16x16x32_bf16 v[2:5], v[180:183], v[212:215], 0
	v_mfma_f32_16x16x32_bf16 v[58:61], v[176:179], v[192:195], v[58:61]
	v_mfma_f32_16x16x32_bf16 v[50:53], v[184:187], v[192:195], v[50:53]
	v_mfma_f32_16x16x32_bf16 v[42:45], v[176:179], v[200:203], v[42:45]
	v_mfma_f32_16x16x32_bf16 v[34:37], v[184:187], v[200:203], v[34:37]
	v_mfma_f32_16x16x32_bf16 v[26:29], v[176:179], v[208:211], v[26:29]
	v_mfma_f32_16x16x32_bf16 v[18:21], v[184:187], v[208:211], v[18:21]
	v_mfma_f32_16x16x32_bf16 v[10:13], v[176:179], v[216:219], v[10:13]
	v_mfma_f32_16x16x32_bf16 v[2:5], v[184:187], v[216:219], v[2:5]
	s_setprio 0
	s_barrier
	s_add_i32 s43, 0, 0x18000
	s_add_i32 s62, 0, 0x1c000
	v_add_u32_e32 v158, s43, v166
	v_add_u32_e32 v184, s62, v166
	ds_read_b128 v[146:149], v158
	ds_read_b128 v[150:153], v158 offset:1024
	ds_read_b128 v[154:157], v158 offset:2048
	ds_read_b128 v[158:161], v158 offset:3072
	ds_read_b128 v[172:175], v184
	ds_read_b128 v[176:179], v184 offset:1024
	ds_read_b128 v[180:183], v184 offset:2048
	ds_read_b128 v[184:187], v184 offset:3072
	s_add_u32 s10, s10, 0x40000
	s_addc_u32 s11, s11, 0
	s_mov_b32 m0, s52
	v_lshl_add_u64 v[228:229], s[10:11], 0, v[130:131]
	ds_read_b128 v[188:191], v170 offset:32768
	ds_read_b128 v[192:195], v170 offset:33792
	ds_read_b128 v[196:199], v170 offset:34816
	ds_read_b128 v[200:203], v170 offset:35840
	ds_read_b128 v[204:207], v170 offset:36864
	ds_read_b128 v[208:211], v170 offset:37888
	ds_read_b128 v[212:215], v170 offset:38912
	ds_read_b128 v[216:219], v170 offset:39936
	global_load_lds_dwordx4 v[228:229], off
	v_lshl_add_u64 v[228:229], s[10:11], 0, v[134:135]
	s_mov_b32 m0, s53
	s_nop 0
	global_load_lds_dwordx4 v[228:229], off
	s_waitcnt vmcnt(8)
	s_waitcnt lgkmcnt(0)
	s_barrier
	s_setprio 3
	s_waitcnt lgkmcnt(0)
	v_mfma_f32_16x16x32_bf16 v[126:129], v[146:149], v[188:191], v[126:129]
	v_mfma_f32_16x16x32_bf16 v[118:121], v[154:157], v[188:191], v[118:121]
	v_mfma_f32_16x16x32_bf16 v[110:113], v[146:149], v[196:199], v[110:113]
	v_mfma_f32_16x16x32_bf16 v[102:105], v[154:157], v[196:199], v[102:105]
	v_mfma_f32_16x16x32_bf16 v[94:97], v[146:149], v[204:207], v[94:97]
	v_mfma_f32_16x16x32_bf16 v[86:89], v[154:157], v[204:207], v[86:89]
	v_mfma_f32_16x16x32_bf16 v[78:81], v[146:149], v[212:215], v[78:81]
	v_mfma_f32_16x16x32_bf16 v[70:73], v[154:157], v[212:215], v[70:73]
	v_mfma_f32_16x16x32_bf16 v[126:129], v[150:153], v[192:195], v[126:129]
	v_mfma_f32_16x16x32_bf16 v[118:121], v[158:161], v[192:195], v[118:121]
	v_mfma_f32_16x16x32_bf16 v[110:113], v[150:153], v[200:203], v[110:113]
	v_mfma_f32_16x16x32_bf16 v[102:105], v[158:161], v[200:203], v[102:105]
	v_mfma_f32_16x16x32_bf16 v[94:97], v[150:153], v[208:211], v[94:97]
	v_mfma_f32_16x16x32_bf16 v[86:89], v[158:161], v[208:211], v[86:89]
	v_mfma_f32_16x16x32_bf16 v[78:81], v[150:153], v[216:219], v[78:81]
	v_mfma_f32_16x16x32_bf16 v[70:73], v[158:161], v[216:219], v[70:73]
	v_mfma_f32_16x16x32_bf16 v[122:125], v[172:175], v[188:191], v[122:125]
	v_mfma_f32_16x16x32_bf16 v[114:117], v[180:183], v[188:191], v[114:117]
	v_mfma_f32_16x16x32_bf16 v[106:109], v[172:175], v[196:199], v[106:109]
	v_mfma_f32_16x16x32_bf16 v[98:101], v[180:183], v[196:199], v[98:101]
	v_mfma_f32_16x16x32_bf16 v[90:93], v[172:175], v[204:207], v[90:93]
	v_mfma_f32_16x16x32_bf16 v[82:85], v[180:183], v[204:207], v[82:85]
	v_mfma_f32_16x16x32_bf16 v[74:77], v[172:175], v[212:215], v[74:77]
	v_mfma_f32_16x16x32_bf16 v[66:69], v[180:183], v[212:215], v[66:69]
	v_mfma_f32_16x16x32_bf16 v[122:125], v[176:179], v[192:195], v[122:125]
	v_mfma_f32_16x16x32_bf16 v[114:117], v[184:187], v[192:195], v[114:117]
	v_mfma_f32_16x16x32_bf16 v[106:109], v[176:179], v[200:203], v[106:109]
	v_mfma_f32_16x16x32_bf16 v[98:101], v[184:187], v[200:203], v[98:101]
	v_mfma_f32_16x16x32_bf16 v[90:93], v[176:179], v[208:211], v[90:93]
	v_mfma_f32_16x16x32_bf16 v[82:85], v[184:187], v[208:211], v[82:85]
	v_mfma_f32_16x16x32_bf16 v[74:77], v[176:179], v[216:219], v[74:77]
	v_mfma_f32_16x16x32_bf16 v[66:69], v[184:187], v[216:219], v[66:69]
	s_setprio 0
	s_barrier
; #define PG8_STAGE(bufoff, gbase, voff) do { _Pragma("unroll") for (int _i = 0; _i < 2; ++_i) \
;         __builtin_amdgcn_global_load_lds((const unsigned*)((const char*)(gbase) + (voff)[_i]), (LAS unsigned*)(lds + (bufoff) + ldsw + _i * 8192), 16, 0, 0); } while (0)
; #define PG8_LDA(dst, b, h) do { _Pragma("unroll") for (int m = 0; m < 4; ++m) _Pragma("unroll") for (int k = 0; k < 2; ++k) dst[m][k] = *(const LAS bf16x8*)(lds + PG8_SA(b, h) + aoff + m * 2048 + k * 1024); } while (0)
; #define PG8_LDB(dst, b, h) do { _Pragma("unroll") for (int n = 0; n < 2; ++n) _Pragma("unroll") for (int k = 0; k < 2; ++k) dst[n][k] = *(const LAS bf16x8*)(lds + PG8_SB(b, h) + boff + n * 2048 + k * 1024); } while (0)
; #define PG8_MMA(ai, bj, At, Bt) do { __builtin_amdgcn_s_setprio(3); _Pragma("unroll") for (int m = 0; m < 4; ++m) _Pragma("unroll") for (int n = 0; n < 2; ++n) _Pragma("unroll") for (int k = 0; k < 2; ++k) \
;         acc[ai][bj][m][n] = __builtin_amdgcn_mfma_f32_16x16x32_bf16(Bt[n][k], At[m][k], acc[ai][bj][m][n], 0, 0, 0); __builtin_amdgcn_s_setprio(0); } while (0)
; #define PG8_WAIT_V(n) asm volatile("s_waitcnt vmcnt(" #n ")" ::: "memory")
; #define PG8_WAIT_L(n) asm volatile("s_waitcnt lgkmcnt(" #n ")" ::: "memory")
; #define PG8_BAR __builtin_amdgcn_s_barrier()
; #define PG8_SCHED __builtin_amdgcn_sched_barrier(0)
; template <class Epi, bool ALIGN_EPI>
; __device__ __forceinline__ void gemm_phase(LAS unsigned char* lds, const Gemm g, const StaticOrder& S, const Epi& E) {
;     ...
;             PG8_LDB(B0, 0, 0); PG8_LDB(B1, 0, 1); PG8_SCHED; PG8_LDA(At, 0, 0); PG8_STAGE(PG8_SA(1, 1), a1 + hstep, voffA);
;             PG8_WAIT_V(8); PG8_WAIT_L(0); PG8_BAR; PG8_MMA(0, 0, At, B0); PG8_MMA(0, 1, At, B1); PG8_BAR; PG8_SCHED;
;     ...
;             PG8_LDA(At, 1, 1); PG8_STAGE(PG8_SB(1, 0), b3, voffB); PG8_STAGE(PG8_SB(1, 1), b3 + hstep, voffB); PG8_STAGE(PG8_SA(1, 0), a3, voffA);
;             PG8_WAIT_V(8); PG8_WAIT_L(0); PG8_BAR; PG8_MMA(1, 0, At, B0); PG8_MMA(1, 1, At, B1); PG8_BAR; PG8_SCHED;
	s_add_i32 s10, s43, s33
	v_lshl_add_u64 v[220:221], v[220:221], 0, s[36:37]
	s_mov_b32 m0, s10
	ds_read_b128 v[188:191], v170 offset:49152
	ds_read_b128 v[192:195], v170 offset:50176
	ds_read_b128 v[196:199], v170 offset:51200
	ds_read_b128 v[200:203], v170 offset:52224
	ds_read_b128 v[204:207], v170 offset:53248
	ds_read_b128 v[208:211], v170 offset:54272
	ds_read_b128 v[212:215], v170 offset:55296
	ds_read_b128 v[216:219], v170 offset:56320
	global_load_lds_dwordx4 v[220:221], off
	s_add_i32 m0, s10, 0x2000
	s_add_u32 s8, s8, 0x40080
	v_lshl_add_u64 v[220:221], v[222:223], 0, s[36:37]
	s_addc_u32 s9, s9, 0
	s_add_i32 s10, s62, s33
	global_load_lds_dwordx4 v[220:221], off
	v_lshl_add_u64 v[220:221], s[8:9], 0, v[132:133]
	s_mov_b32 m0, s10
	s_nop 0
	global_load_lds_dwordx4 v[220:221], off
	v_lshl_add_u64 v[220:221], s[8:9], 0, v[136:137]
	s_add_i32 m0, s10, 0x2000
	s_nop 0
	global_load_lds_dwordx4 v[220:221], off
	v_lshl_add_u64 v[220:221], v[224:225], 0, s[36:37]
	s_mov_b32 m0, s56
	s_nop 0
	global_load_lds_dwordx4 v[220:221], off
	v_lshl_add_u64 v[220:221], v[226:227], 0, s[36:37]
	s_mov_b32 m0, s57
	s_nop 0
	global_load_lds_dwordx4 v[220:221], off
	s_waitcnt vmcnt(8)
	s_waitcnt lgkmcnt(0)
	s_barrier
	s_setprio 3
	s_waitcnt lgkmcnt(0)
	v_mfma_f32_16x16x32_bf16 v[62:65], v[146:149], v[188:191], v[62:65]
	v_mfma_f32_16x16x32_bf16 v[54:57], v[154:157], v[188:191], v[54:57]
	v_mfma_f32_16x16x32_bf16 v[46:49], v[146:149], v[196:199], v[46:49]
	v_mfma_f32_16x16x32_bf16 v[38:41], v[154:157], v[196:199], v[38:41]
	v_mfma_f32_16x16x32_bf16 v[30:33], v[146:149], v[204:207], v[30:33]
	v_mfma_f32_16x16x32_bf16 v[22:25], v[154:157], v[204:207], v[22:25]
	v_mfma_f32_16x16x32_bf16 v[14:17], v[146:149], v[212:215], v[14:17]
	v_mfma_f32_16x16x32_bf16 v[6:9], v[154:157], v[212:215], v[6:9]
	v_mfma_f32_16x16x32_bf16 v[62:65], v[150:153], v[192:195], v[62:65]
	v_mfma_f32_16x16x32_bf16 v[54:57], v[158:161], v[192:195], v[54:57]
	v_mfma_f32_16x16x32_bf16 v[46:49], v[150:153], v[200:203], v[46:49]
	v_mfma_f32_16x16x32_bf16 v[38:41], v[158:161], v[200:203], v[38:41]
	v_mfma_f32_16x16x32_bf16 v[30:33], v[150:153], v[208:211], v[30:33]
	v_mfma_f32_16x16x32_bf16 v[22:25], v[158:161], v[208:211], v[22:25]
	v_mfma_f32_16x16x32_bf16 v[14:17], v[150:153], v[216:219], v[14:17]
	v_mfma_f32_16x16x32_bf16 v[6:9], v[158:161], v[216:219], v[6:9]
	v_mfma_f32_16x16x32_bf16 v[58:61], v[172:175], v[188:191], v[58:61]
	v_mfma_f32_16x16x32_bf16 v[50:53], v[180:183], v[188:191], v[50:53]
	v_mfma_f32_16x16x32_bf16 v[42:45], v[172:175], v[196:199], v[42:45]
	v_mfma_f32_16x16x32_bf16 v[34:37], v[180:183], v[196:199], v[34:37]
	v_mfma_f32_16x16x32_bf16 v[26:29], v[172:175], v[204:207], v[26:29]
	v_mfma_f32_16x16x32_bf16 v[18:21], v[180:183], v[204:207], v[18:21]
	v_mfma_f32_16x16x32_bf16 v[10:13], v[172:175], v[212:215], v[10:13]
	v_mfma_f32_16x16x32_bf16 v[2:5], v[180:183], v[212:215], v[2:5]
	v_mfma_f32_16x16x32_bf16 v[58:61], v[176:179], v[192:195], v[58:61]
	v_mfma_f32_16x16x32_bf16 v[50:53], v[184:187], v[192:195], v[50:53]
	v_mfma_f32_16x16x32_bf16 v[42:45], v[176:179], v[200:203], v[42:45]
	v_mfma_f32_16x16x32_bf16 v[34:37], v[184:187], v[200:203], v[34:37]
	v_mfma_f32_16x16x32_bf16 v[26:29], v[176:179], v[208:211], v[26:29]
	v_mfma_f32_16x16x32_bf16 v[18:21], v[184:187], v[208:211], v[18:21]
	v_mfma_f32_16x16x32_bf16 v[10:13], v[176:179], v[216:219], v[10:13]
	v_mfma_f32_16x16x32_bf16 v[2:5], v[184:187], v[216:219], v[2:5]
	s_setprio 0
	s_barrier
	s_add_i32 s41, s41, 2
	s_add_u32 s6, s6, 0x100
	s_addc_u32 s7, s7, 0
	s_add_u32 s16, s16, 0x100
	s_addc_u32 s17, s17, 0
.LBB0_1428:
	ds_read_b128 v[146:149], v168
	ds_read_b128 v[150:153], v168 offset:1024
	ds_read_b128 v[154:157], v168 offset:2048
	ds_read_b128 v[158:161], v168 offset:3072
	ds_read_b128 v[172:175], v169
	ds_read_b128 v[176:179], v169 offset:1024
	ds_read_b128 v[180:183], v169 offset:2048
	ds_read_b128 v[184:187], v169 offset:3072
	s_add_u32 s8, s6, 0xfffc0080
	s_addc_u32 s9, s7, -1
	s_cmp_eq_u32 s41, 12
	s_cselect_b32 s11, s12, s9
	s_cselect_b32 s10, s13, s8
	s_cselect_b32 s9, s14, s17
	s_cselect_b32 s8, s15, s16
	v_lshl_add_u64 v[220:221], s[6:7], 0, v[138:139]
	s_add_i32 m0, s50, 0xc000
	ds_read_b128 v[188:191], v170
	ds_read_b128 v[192:195], v170 offset:1024
	ds_read_b128 v[196:199], v170 offset:2048
	ds_read_b128 v[200:203], v170 offset:3072
	ds_read_b128 v[204:207], v170 offset:4096
	ds_read_b128 v[208:211], v170 offset:5120
	ds_read_b128 v[212:215], v170 offset:6144
	ds_read_b128 v[216:219], v170 offset:7168
	global_load_lds_dwordx4 v[220:221], off
	v_lshl_add_u64 v[220:221], s[6:7], 0, v[140:141]
	s_add_i32 m0, s50, 0xe000
	s_nop 0
	global_load_lds_dwordx4 v[220:221], off
	s_waitcnt vmcnt(8)
	s_waitcnt lgkmcnt(0)
	s_barrier
; #define PG8_STAGE(bufoff, gbase, voff) do { _Pragma("unroll") for (int _i = 0; _i < 2; ++_i) \
;         __builtin_amdgcn_global_load_lds((const unsigned*)((const char*)(gbase) + (voff)[_i]), (LAS unsigned*)(lds + (bufoff) + ldsw + _i * 8192), 16, 0, 0); } while (0)
; #define PG8_LDA(dst, b, h) do { _Pragma("unroll") for (int m = 0; m < 4; ++m) _Pragma("unroll") for (int k = 0; k < 2; ++k) dst[m][k] = *(const LAS bf16x8*)(lds + PG8_SA(b, h) + aoff + m * 2048 + k * 1024); } while (0)
; #define PG8_MMA(ai, bj, At, Bt) do { __builtin_amdgcn_s_setprio(3); _Pragma("unroll") for (int m = 0; m < 4; ++m) _Pragma("unroll") for (int n = 0; n < 2; ++n) _Pragma("unroll") for (int k = 0; k < 2; ++k) \
;         acc[ai][bj][m][n] = __builtin_amdgcn_mfma_f32_16x16x32_bf16(Bt[n][k], At[m][k], acc[ai][bj][m][n], 0, 0, 0); __builtin_amdgcn_s_setprio(0); } while (0)
; #define PG8_WAIT_V(n) asm volatile("s_waitcnt vmcnt(" #n ")" ::: "memory")
; #define PG8_WAIT_L(n) asm volatile("s_waitcnt lgkmcnt(" #n ")" ::: "memory")
; #define PG8_BAR __builtin_amdgcn_s_barrier()
; #define PG8_SCHED __builtin_amdgcn_sched_barrier(0)
; template <class Epi, bool ALIGN_EPI>
; __device__ __forceinline__ void gemm_phase(LAS unsigned char* lds, const Gemm g, const StaticOrder& S, const Epi& E) {
;     ...
;             PG8_WAIT_V(8); PG8_WAIT_L(0); PG8_BAR; PG8_MMA(0, 0, At, B0); PG8_MMA(0, 1, At, B1); PG8_BAR; PG8_SCHED;
;             PG8_LDA(At, 0, 1); PG8_STAGE(PG8_SB(0, 0), b2, voffB); PG8_STAGE(PG8_SB(0, 1), b2 + hstep, voffB); PG8_STAGE(PG8_SA(0, 0), a2, voffA);
;             PG8_WAIT_V(8); PG8_WAIT_L(0); PG8_BAR; PG8_MMA(1, 0, At, B0); PG8_MMA(1, 1, At, B1); PG8_BAR; PG8_SCHED;
	s_setprio 3
	s_waitcnt lgkmcnt(0)
	v_mfma_f32_16x16x32_bf16 v[126:129], v[146:149], v[188:191], v[126:129]
	v_mfma_f32_16x16x32_bf16 v[118:121], v[154:157], v[188:191], v[118:121]
	v_mfma_f32_16x16x32_bf16 v[110:113], v[146:149], v[196:199], v[110:113]
	v_mfma_f32_16x16x32_bf16 v[102:105], v[154:157], v[196:199], v[102:105]
	v_mfma_f32_16x16x32_bf16 v[94:97], v[146:149], v[204:207], v[94:97]
	v_mfma_f32_16x16x32_bf16 v[86:89], v[154:157], v[204:207], v[86:89]
	v_mfma_f32_16x16x32_bf16 v[78:81], v[146:149], v[212:215], v[78:81]
	v_mfma_f32_16x16x32_bf16 v[70:73], v[154:157], v[212:215], v[70:73]
	v_mfma_f32_16x16x32_bf16 v[126:129], v[150:153], v[192:195], v[126:129]
	v_mfma_f32_16x16x32_bf16 v[118:121], v[158:161], v[192:195], v[118:121]
	v_mfma_f32_16x16x32_bf16 v[110:113], v[150:153], v[200:203], v[110:113]
	v_mfma_f32_16x16x32_bf16 v[102:105], v[158:161], v[200:203], v[102:105]
	v_mfma_f32_16x16x32_bf16 v[94:97], v[150:153], v[208:211], v[94:97]
	v_mfma_f32_16x16x32_bf16 v[86:89], v[158:161], v[208:211], v[86:89]
	v_mfma_f32_16x16x32_bf16 v[78:81], v[150:153], v[216:219], v[78:81]
	v_mfma_f32_16x16x32_bf16 v[70:73], v[158:161], v[216:219], v[70:73]
	v_mfma_f32_16x16x32_bf16 v[122:125], v[172:175], v[188:191], v[122:125]
	v_mfma_f32_16x16x32_bf16 v[114:117], v[180:183], v[188:191], v[114:117]
	v_mfma_f32_16x16x32_bf16 v[106:109], v[172:175], v[196:199], v[106:109]
	v_mfma_f32_16x16x32_bf16 v[98:101], v[180:183], v[196:199], v[98:101]
	v_mfma_f32_16x16x32_bf16 v[90:93], v[172:175], v[204:207], v[90:93]
	v_mfma_f32_16x16x32_bf16 v[82:85], v[180:183], v[204:207], v[82:85]
	v_mfma_f32_16x16x32_bf16 v[74:77], v[172:175], v[212:215], v[74:77]
	v_mfma_f32_16x16x32_bf16 v[66:69], v[180:183], v[212:215], v[66:69]
	v_mfma_f32_16x16x32_bf16 v[122:125], v[176:179], v[192:195], v[122:125]
	v_mfma_f32_16x16x32_bf16 v[114:117], v[184:187], v[192:195], v[114:117]
	v_mfma_f32_16x16x32_bf16 v[106:109], v[176:179], v[200:203], v[106:109]
	v_mfma_f32_16x16x32_bf16 v[98:101], v[184:187], v[200:203], v[98:101]
	v_mfma_f32_16x16x32_bf16 v[90:93], v[176:179], v[208:211], v[90:93]
	v_mfma_f32_16x16x32_bf16 v[82:85], v[184:187], v[208:211], v[82:85]
	v_mfma_f32_16x16x32_bf16 v[74:77], v[176:179], v[216:219], v[74:77]
	v_mfma_f32_16x16x32_bf16 v[66:69], v[184:187], v[216:219], v[66:69]
	s_setprio 0
	s_barrier
	s_add_i32 s43, s58, s33
	v_lshl_add_u64 v[220:221], s[8:9], 0, v[132:133]
	s_mov_b32 m0, s43
	ds_read_b128 v[188:191], v170 offset:16384
	ds_read_b128 v[192:195], v170 offset:17408
	ds_read_b128 v[196:199], v170 offset:18432
	ds_read_b128 v[200:203], v170 offset:19456
	ds_read_b128 v[204:207], v170 offset:20480
	ds_read_b128 v[208:211], v170 offset:21504
	ds_read_b128 v[212:215], v170 offset:22528
	ds_read_b128 v[216:219], v170 offset:23552
	global_load_lds_dwordx4 v[220:221], off
	s_add_i32 m0, s43, 0x2000
	s_add_u32 s62, s8, 0x40000
	v_lshl_add_u64 v[222:223], s[8:9], 0, v[136:137]
	s_addc_u32 s63, s9, 0
	s_add_i32 s43, s59, s33
	global_load_lds_dwordx4 v[222:223], off
	v_lshl_add_u64 v[224:225], s[62:63], 0, v[132:133]
	s_mov_b32 m0, s43
	v_lshl_add_u64 v[226:227], s[10:11], 0, v[134:135]
	global_load_lds_dwordx4 v[224:225], off
	v_lshl_add_u64 v[224:225], s[62:63], 0, v[136:137]
	s_add_i32 m0, s43, 0x2000
	s_nop 0
	global_load_lds_dwordx4 v[224:225], off
	v_lshl_add_u64 v[224:225], s[10:11], 0, v[130:131]
	s_mov_b32 m0, s50
	s_nop 0
	global_load_lds_dwordx4 v[224:225], off
	s_mov_b32 m0, s51
	s_nop 0
	global_load_lds_dwordx4 v[226:227], off
	s_waitcnt vmcnt(8)
	s_waitcnt lgkmcnt(0)
	s_barrier
	s_setprio 3
	s_waitcnt lgkmcnt(0)
	v_mfma_f32_16x16x32_bf16 v[62:65], v[146:149], v[188:191], v[62:65]
	v_mfma_f32_16x16x32_bf16 v[54:57], v[154:157], v[188:191], v[54:57]
	v_mfma_f32_16x16x32_bf16 v[46:49], v[146:149], v[196:199], v[46:49]
	v_mfma_f32_16x16x32_bf16 v[38:41], v[154:157], v[196:199], v[38:41]
	v_mfma_f32_16x16x32_bf16 v[30:33], v[146:149], v[204:207], v[30:33]
	v_mfma_f32_16x16x32_bf16 v[22:25], v[154:157], v[204:207], v[22:25]
	v_mfma_f32_16x16x32_bf16 v[14:17], v[146:149], v[212:215], v[14:17]
	v_mfma_f32_16x16x32_bf16 v[6:9], v[154:157], v[212:215], v[6:9]
	v_mfma_f32_16x16x32_bf16 v[62:65], v[150:153], v[192:195], v[62:65]
	v_mfma_f32_16x16x32_bf16 v[54:57], v[158:161], v[192:195], v[54:57]
	v_mfma_f32_16x16x32_bf16 v[46:49], v[150:153], v[200:203], v[46:49]
	v_mfma_f32_16x16x32_bf16 v[38:41], v[158:161], v[200:203], v[38:41]
	v_mfma_f32_16x16x32_bf16 v[30:33], v[150:153], v[208:211], v[30:33]
	v_mfma_f32_16x16x32_bf16 v[22:25], v[158:161], v[208:211], v[22:25]
	v_mfma_f32_16x16x32_bf16 v[14:17], v[150:153], v[216:219], v[14:17]
	v_mfma_f32_16x16x32_bf16 v[6:9], v[158:161], v[216:219], v[6:9]
	v_mfma_f32_16x16x32_bf16 v[58:61], v[172:175], v[188:191], v[58:61]
	v_mfma_f32_16x16x32_bf16 v[50:53], v[180:183], v[188:191], v[50:53]
	v_mfma_f32_16x16x32_bf16 v[42:45], v[172:175], v[196:199], v[42:45]
	v_mfma_f32_16x16x32_bf16 v[34:37], v[180:183], v[196:199], v[34:37]
	v_mfma_f32_16x16x32_bf16 v[26:29], v[172:175], v[204:207], v[26:29]
	v_mfma_f32_16x16x32_bf16 v[18:21], v[180:183], v[204:207], v[18:21]
	v_mfma_f32_16x16x32_bf16 v[10:13], v[172:175], v[212:215], v[10:13]
	v_mfma_f32_16x16x32_bf16 v[2:5], v[180:183], v[212:215], v[2:5]
	v_mfma_f32_16x16x32_bf16 v[58:61], v[176:179], v[192:195], v[58:61]
	v_mfma_f32_16x16x32_bf16 v[50:53], v[184:187], v[192:195], v[50:53]
	v_mfma_f32_16x16x32_bf16 v[42:45], v[176:179], v[200:203], v[42:45]
	v_mfma_f32_16x16x32_bf16 v[34:37], v[184:187], v[200:203], v[34:37]
	v_mfma_f32_16x16x32_bf16 v[26:29], v[176:179], v[208:211], v[26:29]
	v_mfma_f32_16x16x32_bf16 v[18:21], v[184:187], v[208:211], v[18:21]
	v_mfma_f32_16x16x32_bf16 v[10:13], v[176:179], v[216:219], v[10:13]
	v_mfma_f32_16x16x32_bf16 v[2:5], v[184:187], v[216:219], v[2:5]
	s_setprio 0
	s_barrier
; #define PG8_STAGE(bufoff, gbase, voff) do { _Pragma("unroll") for (int _i = 0; _i < 2; ++_i) \
;         __builtin_amdgcn_global_load_lds((const unsigned*)((const char*)(gbase) + (voff)[_i]), (LAS unsigned*)(lds + (bufoff) + ldsw + _i * 8192), 16, 0, 0); } while (0)
; #define PG8_LDA(dst, b, h) do { _Pragma("unroll") for (int m = 0; m < 4; ++m) _Pragma("unroll") for (int k = 0; k < 2; ++k) dst[m][k] = *(const LAS bf16x8*)(lds + PG8_SA(b, h) + aoff + m * 2048 + k * 1024); } while (0)
; #define PG8_LDB(dst, b, h) do { _Pragma("unroll") for (int n = 0; n < 2; ++n) _Pragma("unroll") for (int k = 0; k < 2; ++k) dst[n][k] = *(const LAS bf16x8*)(lds + PG8_SB(b, h) + boff + n * 2048 + k * 1024); } while (0)
; #define PG8_MMA(ai, bj, At, Bt) do { __builtin_amdgcn_s_setprio(3); _Pragma("unroll") for (int m = 0; m < 4; ++m) _Pragma("unroll") for (int n = 0; n < 2; ++n) _Pragma("unroll") for (int k = 0; k < 2; ++k) \
;         acc[ai][bj][m][n] = __builtin_amdgcn_mfma_f32_16x16x32_bf16(Bt[n][k], At[m][k], acc[ai][bj][m][n], 0, 0, 0); __builtin_amdgcn_s_setprio(0); } while (0)
; #define PG8_WAIT_V(n) asm volatile("s_waitcnt vmcnt(" #n ")" ::: "memory")
; #define PG8_WAIT_L(n) asm volatile("s_waitcnt lgkmcnt(" #n ")" ::: "memory")
; #define PG8_BAR __builtin_amdgcn_s_barrier()
; #define PG8_SCHED __builtin_amdgcn_sched_barrier(0)
; template <class Epi, bool ALIGN_EPI>
; __device__ __forceinline__ void gemm_phase(LAS unsigned char* lds, const Gemm g, const StaticOrder& S, const Epi& E) {
;     ...
;             PG8_LDB(B0, 1, 0); PG8_LDB(B1, 1, 1); PG8_SCHED; PG8_LDA(At, 1, 0); PG8_STAGE(PG8_SA(0, 1), a2 + hstep, voffA);
;             PG8_WAIT_V(8); PG8_WAIT_L(0); PG8_BAR; PG8_MMA(0, 0, At, B0); PG8_MMA(0, 1, At, B1); PG8_BAR; PG8_SCHED;
	s_add_i32 s43, 0, 0x18000
	s_add_i32 s62, 0, 0x1c000
	v_add_u32_e32 v158, s43, v166
	v_add_u32_e32 v184, s62, v166
	ds_read_b128 v[146:149], v158
	ds_read_b128 v[150:153], v158 offset:1024
	ds_read_b128 v[154:157], v158 offset:2048
	ds_read_b128 v[158:161], v158 offset:3072
	ds_read_b128 v[172:175], v184
	ds_read_b128 v[176:179], v184 offset:1024
	ds_read_b128 v[180:183], v184 offset:2048
	ds_read_b128 v[184:187], v184 offset:3072
	s_add_u32 s10, s10, 0x40000
	s_addc_u32 s11, s11, 0
	s_mov_b32 m0, s52
	v_lshl_add_u64 v[228:229], s[10:11], 0, v[130:131]
	ds_read_b128 v[188:191], v170 offset:32768
	ds_read_b128 v[192:195], v170 offset:33792
	ds_read_b128 v[196:199], v170 offset:34816
	ds_read_b128 v[200:203], v170 offset:35840
	ds_read_b128 v[204:207], v170 offset:36864
	ds_read_b128 v[208:211], v170 offset:37888
	ds_read_b128 v[212:215], v170 offset:38912
	ds_read_b128 v[216:219], v170 offset:39936
	global_load_lds_dwordx4 v[228:229], off
	v_lshl_add_u64 v[228:229], s[10:11], 0, v[134:135]
	s_mov_b32 m0, s53
	s_nop 0
	global_load_lds_dwordx4 v[228:229], off
	s_waitcnt vmcnt(8)
	s_waitcnt lgkmcnt(0)
	s_barrier
	s_setprio 3
	s_waitcnt lgkmcnt(0)
	v_mfma_f32_16x16x32_bf16 v[126:129], v[146:149], v[188:191], v[126:129]
	v_mfma_f32_16x16x32_bf16 v[118:121], v[154:157], v[188:191], v[118:121]
	v_mfma_f32_16x16x32_bf16 v[110:113], v[146:149], v[196:199], v[110:113]
	v_mfma_f32_16x16x32_bf16 v[102:105], v[154:157], v[196:199], v[102:105]
	v_mfma_f32_16x16x32_bf16 v[94:97], v[146:149], v[204:207], v[94:97]
	v_mfma_f32_16x16x32_bf16 v[86:89], v[154:157], v[204:207], v[86:89]
	v_mfma_f32_16x16x32_bf16 v[78:81], v[146:149], v[212:215], v[78:81]
	v_mfma_f32_16x16x32_bf16 v[70:73], v[154:157], v[212:215], v[70:73]
	v_mfma_f32_16x16x32_bf16 v[126:129], v[150:153], v[192:195], v[126:129]
	v_mfma_f32_16x16x32_bf16 v[118:121], v[158:161], v[192:195], v[118:121]
	v_mfma_f32_16x16x32_bf16 v[110:113], v[150:153], v[200:203], v[110:113]
	v_mfma_f32_16x16x32_bf16 v[102:105], v[158:161], v[200:203], v[102:105]
	v_mfma_f32_16x16x32_bf16 v[94:97], v[150:153], v[208:211], v[94:97]
	v_mfma_f32_16x16x32_bf16 v[86:89], v[158:161], v[208:211], v[86:89]
	v_mfma_f32_16x16x32_bf16 v[78:81], v[150:153], v[216:219], v[78:81]
	v_mfma_f32_16x16x32_bf16 v[70:73], v[158:161], v[216:219], v[70:73]
	v_mfma_f32_16x16x32_bf16 v[122:125], v[172:175], v[188:191], v[122:125]
	v_mfma_f32_16x16x32_bf16 v[114:117], v[180:183], v[188:191], v[114:117]
	v_mfma_f32_16x16x32_bf16 v[106:109], v[172:175], v[196:199], v[106:109]
	v_mfma_f32_16x16x32_bf16 v[98:101], v[180:183], v[196:199], v[98:101]
	v_mfma_f32_16x16x32_bf16 v[90:93], v[172:175], v[204:207], v[90:93]
	v_mfma_f32_16x16x32_bf16 v[82:85], v[180:183], v[204:207], v[82:85]
	v_mfma_f32_16x16x32_bf16 v[74:77], v[172:175], v[212:215], v[74:77]
	v_mfma_f32_16x16x32_bf16 v[66:69], v[180:183], v[212:215], v[66:69]
	v_mfma_f32_16x16x32_bf16 v[122:125], v[176:179], v[192:195], v[122:125]
	v_mfma_f32_16x16x32_bf16 v[114:117], v[184:187], v[192:195], v[114:117]
	v_mfma_f32_16x16x32_bf16 v[106:109], v[176:179], v[200:203], v[106:109]
	v_mfma_f32_16x16x32_bf16 v[98:101], v[184:187], v[200:203], v[98:101]
	v_mfma_f32_16x16x32_bf16 v[90:93], v[176:179], v[208:211], v[90:93]
	v_mfma_f32_16x16x32_bf16 v[82:85], v[184:187], v[208:211], v[82:85]
	v_mfma_f32_16x16x32_bf16 v[74:77], v[176:179], v[216:219], v[74:77]
	v_mfma_f32_16x16x32_bf16 v[66:69], v[184:187], v[216:219], v[66:69]
	s_setprio 0
	s_barrier
; #define PG8_STAGE(bufoff, gbase, voff) do { _Pragma("unroll") for (int _i = 0; _i < 2; ++_i) \
;         __builtin_amdgcn_global_load_lds((const unsigned*)((const char*)(gbase) + (voff)[_i]), (LAS unsigned*)(lds + (bufoff) + ldsw + _i * 8192), 16, 0, 0); } while (0)
; #define PG8_LDA(dst, b, h) do { _Pragma("unroll") for (int m = 0; m < 4; ++m) _Pragma("unroll") for (int k = 0; k < 2; ++k) dst[m][k] = *(const LAS bf16x8*)(lds + PG8_SA(b, h) + aoff + m * 2048 + k * 1024); } while (0)
; #define PG8_MMA(ai, bj, At, Bt) do { __builtin_amdgcn_s_setprio(3); _Pragma("unroll") for (int m = 0; m < 4; ++m) _Pragma("unroll") for (int n = 0; n < 2; ++n) _Pragma("unroll") for (int k = 0; k < 2; ++k) \
;         acc[ai][bj][m][n] = __builtin_amdgcn_mfma_f32_16x16x32_bf16(Bt[n][k], At[m][k], acc[ai][bj][m][n], 0, 0, 0); __builtin_amdgcn_s_setprio(0); } while (0)
; #define PG8_WAIT_V(n) asm volatile("s_waitcnt vmcnt(" #n ")" ::: "memory")
; #define PG8_WAIT_L(n) asm volatile("s_waitcnt lgkmcnt(" #n ")" ::: "memory")
; #define PG8_BAR __builtin_amdgcn_s_barrier()
; #define PG8_SCHED __builtin_amdgcn_sched_barrier(0)
; template <class Epi, bool ALIGN_EPI>
; __device__ __forceinline__ void gemm_phase(LAS unsigned char* lds, const Gemm g, const StaticOrder& S, const Epi& E) {
;     ...
;             PG8_LDA(At, 1, 1); PG8_STAGE(PG8_SB(1, 0), b3, voffB); PG8_STAGE(PG8_SB(1, 1), b3 + hstep, voffB); PG8_STAGE(PG8_SA(1, 0), a3, voffA);
;             PG8_WAIT_V(8); PG8_WAIT_L(0); PG8_BAR; PG8_MMA(1, 0, At, B0); PG8_MMA(1, 1, At, B1); PG8_BAR; PG8_SCHED;
;         }
;         if constexpr (ALIGN_EPI) { if (wr == 0) PG8_BAR; }
	s_add_i32 s10, s43, s33
	v_lshl_add_u64 v[220:221], v[220:221], 0, s[36:37]
	s_mov_b32 m0, s10
	ds_read_b128 v[188:191], v170 offset:49152
	ds_read_b128 v[192:195], v170 offset:50176
	ds_read_b128 v[196:199], v170 offset:51200
	ds_read_b128 v[200:203], v170 offset:52224
	ds_read_b128 v[204:207], v170 offset:53248
	ds_read_b128 v[208:211], v170 offset:54272
	ds_read_b128 v[212:215], v170 offset:55296
	ds_read_b128 v[216:219], v170 offset:56320
	global_load_lds_dwordx4 v[220:221], off
	s_add_i32 m0, s10, 0x2000
	s_add_u32 s8, s8, 0x40080
	v_lshl_add_u64 v[220:221], v[222:223], 0, s[36:37]
	s_addc_u32 s9, s9, 0
	s_add_i32 s10, s62, s33
	global_load_lds_dwordx4 v[220:221], off
	v_lshl_add_u64 v[220:221], s[8:9], 0, v[132:133]
	s_mov_b32 m0, s10
	s_nop 0
	global_load_lds_dwordx4 v[220:221], off
	v_lshl_add_u64 v[220:221], s[8:9], 0, v[136:137]
	s_add_i32 m0, s10, 0x2000
	s_nop 0
	global_load_lds_dwordx4 v[220:221], off
	v_lshl_add_u64 v[220:221], v[224:225], 0, s[36:37]
	s_mov_b32 m0, s56
	s_nop 0
	global_load_lds_dwordx4 v[220:221], off
	v_lshl_add_u64 v[220:221], v[226:227], 0, s[36:37]
	s_mov_b32 m0, s57
	s_nop 0
	global_load_lds_dwordx4 v[220:221], off
	s_waitcnt vmcnt(8)
	s_waitcnt lgkmcnt(0)
	s_barrier
	s_setprio 3
	s_waitcnt lgkmcnt(0)
	v_mfma_f32_16x16x32_bf16 v[62:65], v[146:149], v[188:191], v[62:65]
	v_mfma_f32_16x16x32_bf16 v[54:57], v[154:157], v[188:191], v[54:57]
	v_mfma_f32_16x16x32_bf16 v[46:49], v[146:149], v[196:199], v[46:49]
	v_mfma_f32_16x16x32_bf16 v[38:41], v[154:157], v[196:199], v[38:41]
	v_mfma_f32_16x16x32_bf16 v[30:33], v[146:149], v[204:207], v[30:33]
	v_mfma_f32_16x16x32_bf16 v[22:25], v[154:157], v[204:207], v[22:25]
	v_mfma_f32_16x16x32_bf16 v[14:17], v[146:149], v[212:215], v[14:17]
	v_mfma_f32_16x16x32_bf16 v[6:9], v[154:157], v[212:215], v[6:9]
	v_mfma_f32_16x16x32_bf16 v[62:65], v[150:153], v[192:195], v[62:65]
	v_mfma_f32_16x16x32_bf16 v[54:57], v[158:161], v[192:195], v[54:57]
	v_mfma_f32_16x16x32_bf16 v[46:49], v[150:153], v[200:203], v[46:49]
	v_mfma_f32_16x16x32_bf16 v[38:41], v[158:161], v[200:203], v[38:41]
	v_mfma_f32_16x16x32_bf16 v[30:33], v[150:153], v[208:211], v[30:33]
	v_mfma_f32_16x16x32_bf16 v[22:25], v[158:161], v[208:211], v[22:25]
	v_mfma_f32_16x16x32_bf16 v[14:17], v[150:153], v[216:219], v[14:17]
	v_mfma_f32_16x16x32_bf16 v[6:9], v[158:161], v[216:219], v[6:9]
	v_mfma_f32_16x16x32_bf16 v[58:61], v[172:175], v[188:191], v[58:61]
	v_mfma_f32_16x16x32_bf16 v[50:53], v[180:183], v[188:191], v[50:53]
	v_mfma_f32_16x16x32_bf16 v[42:45], v[172:175], v[196:199], v[42:45]
	v_mfma_f32_16x16x32_bf16 v[34:37], v[180:183], v[196:199], v[34:37]
	v_mfma_f32_16x16x32_bf16 v[26:29], v[172:175], v[204:207], v[26:29]
	v_mfma_f32_16x16x32_bf16 v[18:21], v[180:183], v[204:207], v[18:21]
	v_mfma_f32_16x16x32_bf16 v[10:13], v[172:175], v[212:215], v[10:13]
	v_mfma_f32_16x16x32_bf16 v[2:5], v[180:183], v[212:215], v[2:5]
	v_mfma_f32_16x16x32_bf16 v[58:61], v[176:179], v[192:195], v[58:61]
	v_mfma_f32_16x16x32_bf16 v[50:53], v[184:187], v[192:195], v[50:53]
	v_mfma_f32_16x16x32_bf16 v[42:45], v[176:179], v[200:203], v[42:45]
	v_mfma_f32_16x16x32_bf16 v[34:37], v[184:187], v[200:203], v[34:37]
	v_mfma_f32_16x16x32_bf16 v[26:29], v[176:179], v[208:211], v[26:29]
	v_mfma_f32_16x16x32_bf16 v[18:21], v[184:187], v[208:211], v[18:21]
	v_mfma_f32_16x16x32_bf16 v[10:13], v[176:179], v[216:219], v[10:13]
	v_mfma_f32_16x16x32_bf16 v[2:5], v[184:187], v[216:219], v[2:5]
	s_setprio 0
	s_barrier
	s_add_i32 s41, s41, 2
	s_add_u32 s6, s6, 0x100
	s_addc_u32 s7, s7, 0
	s_add_u32 s16, s16, 0x100
	s_addc_u32 s17, s17, 0
	s_cmp_gt_u32 s41, 13
	s_cbranch_scc0 .LBB0_1428
	s_and_b64 vcc, exec, s[38:39]
	s_cbranch_vccz .LBB0_1431
	s_barrier

; #define PG8_STAGE(bufoff, gbase, voff) do { _Pragma("unroll") for (int _i = 0; _i < 2; ++_i) \
;         __builtin_amdgcn_global_load_lds((const unsigned*)((const char*)(gbase) + (voff)[_i]), (LAS unsigned*)(lds + (bufoff) + ldsw + _i * 8192), 16, 0, 0); } while (0)
; #define PG8_LDA(dst, b, h) do { _Pragma("unroll") for (int m = 0; m < 4; ++m) _Pragma("unroll") for (int k = 0; k < 2; ++k) dst[m][k] = *(const LAS bf16x8*)(lds + PG8_SA(b, h) + aoff + m * 2048 + k * 1024); } while (0)
; #define PG8_LDB(dst, b, h) do { _Pragma("unroll") for (int n = 0; n < 2; ++n) _Pragma("unroll") for (int k = 0; k < 2; ++k) dst[n][k] = *(const LAS bf16x8*)(lds + PG8_SB(b, h) + boff + n * 2048 + k * 1024); } while (0)
; #define PG8_MMA(ai, bj, At, Bt) do { __builtin_amdgcn_s_setprio(3); _Pragma("unroll") for (int m = 0; m < 4; ++m) _Pragma("unroll") for (int n = 0; n < 2; ++n) _Pragma("unroll") for (int k = 0; k < 2; ++k) \
;         acc[ai][bj][m][n] = __builtin_amdgcn_mfma_f32_16x16x32_bf16(Bt[n][k], At[m][k], acc[ai][bj][m][n], 0, 0, 0); __builtin_amdgcn_s_setprio(0); } while (0)
; #define PG8_WAIT_V(n) asm volatile("s_waitcnt vmcnt(" #n ")" ::: "memory")
; #define PG8_WAIT_L(n) asm volatile("s_waitcnt lgkmcnt(" #n ")" ::: "memory")
; #define PG8_BAR __builtin_amdgcn_s_barrier()
; #define PG8_SCHED __builtin_amdgcn_sched_barrier(0)
; template <class Epi, bool ALIGN_EPI>
; __device__ __forceinline__ void gemm_phase(LAS unsigned char* lds, const Gemm g, const StaticOrder& S, const Epi& E) {
;     ...
;         for (int t = 0; t < nt; t += 2) {
;             const bool last = (t == nt - 2);
;             const char* a1 = cA + (size_t)(t + 1) * kstep;
;             const char* a2 = last ? nA : cA + (size_t)(t + 2) * kstep; const char* b2 = last ? nB : cB + (size_t)(t + 2) * kstep;
;             const char* a3 = a2 + kstep; const char* b3 = b2 + kstep;
;             PG8_LDB(B0, 0, 0); PG8_LDB(B1, 0, 1); PG8_SCHED; PG8_LDA(At, 0, 0); PG8_STAGE(PG8_SA(1, 1), a1 + hstep, voffA);
;             PG8_WAIT_V(8); PG8_WAIT_L(0); PG8_BAR; PG8_MMA(0, 0, At, B0); PG8_MMA(0, 1, At, B1); PG8_BAR; PG8_SCHED;
;             PG8_LDA(At, 0, 1); PG8_STAGE(PG8_SB(0, 0), b2, voffB); PG8_STAGE(PG8_SB(0, 1), b2 + hstep, voffB); PG8_STAGE(PG8_SA(0, 0), a2, voffA);
;             PG8_WAIT_V(8); PG8_WAIT_L(0); PG8_BAR; PG8_MMA(1, 0, At, B0); PG8_MMA(1, 1, At, B1); PG8_BAR; PG8_SCHED;
.LBB0_1512:
	s_add_u32 s14, s14, 0xb0080
	s_addc_u32 s15, s15, 0
	s_add_u32 s43, s16, 0x100
	s_addc_u32 s44, s17, 0
	s_mov_b32 s45, -2
	ds_read_b128 v[144:147], v158
	ds_read_b128 v[148:151], v158 offset:1024
	ds_read_b128 v[162:165], v158 offset:2048
	ds_read_b128 v[166:169], v158 offset:3072
	ds_read_b128 v[170:173], v159
	ds_read_b128 v[174:177], v159 offset:1024
	ds_read_b128 v[178:181], v159 offset:2048
	ds_read_b128 v[182:185], v159 offset:3072
	s_add_u32 s16, s14, 0xfff50080
	s_addc_u32 s17, s15, -1
	s_cmp_eq_u32 s45, 40
	s_cselect_b32 s19, s5, s17
	s_cselect_b32 s18, s4, s16
	s_cselect_b32 s17, s13, s44
	s_cselect_b32 s16, s12, s43
	v_lshl_add_u64 v[218:219], s[14:15], 0, v[136:137]
	s_add_i32 m0, s26, 0xc000
	ds_read_b128 v[186:189], v160
	ds_read_b128 v[190:193], v160 offset:1024
	ds_read_b128 v[194:197], v160 offset:2048
	ds_read_b128 v[198:201], v160 offset:3072
	ds_read_b128 v[202:205], v160 offset:4096
	ds_read_b128 v[206:209], v160 offset:5120
	ds_read_b128 v[210:213], v160 offset:6144
	ds_read_b128 v[214:217], v160 offset:7168
	global_load_lds_dwordx4 v[218:219], off
	v_lshl_add_u64 v[218:219], s[14:15], 0, v[138:139]
	s_add_i32 m0, s26, 0xe000
	s_nop 0
	global_load_lds_dwordx4 v[218:219], off
	s_waitcnt vmcnt(8)
	s_waitcnt lgkmcnt(0)
	s_barrier
	s_setprio 3
	s_waitcnt lgkmcnt(0)
	v_mfma_f32_16x16x32_bf16 v[124:127], v[144:147], v[186:189], 0
	v_mfma_f32_16x16x32_bf16 v[120:123], v[162:165], v[186:189], 0
	v_mfma_f32_16x16x32_bf16 v[108:111], v[144:147], v[194:197], 0
	v_mfma_f32_16x16x32_bf16 v[104:107], v[162:165], v[194:197], 0
	v_mfma_f32_16x16x32_bf16 v[96:99], v[144:147], v[202:205], 0
	v_mfma_f32_16x16x32_bf16 v[88:91], v[162:165], v[202:205], 0
	v_mfma_f32_16x16x32_bf16 v[80:83], v[144:147], v[210:213], 0
	v_mfma_f32_16x16x32_bf16 v[72:75], v[162:165], v[210:213], 0
	v_mfma_f32_16x16x32_bf16 v[124:127], v[148:151], v[190:193], v[124:127]
	v_mfma_f32_16x16x32_bf16 v[120:123], v[166:169], v[190:193], v[120:123]
	v_mfma_f32_16x16x32_bf16 v[108:111], v[148:151], v[198:201], v[108:111]
	v_mfma_f32_16x16x32_bf16 v[104:107], v[166:169], v[198:201], v[104:107]
	v_mfma_f32_16x16x32_bf16 v[96:99], v[148:151], v[206:209], v[96:99]
	v_mfma_f32_16x16x32_bf16 v[88:91], v[166:169], v[206:209], v[88:91]
	v_mfma_f32_16x16x32_bf16 v[80:83], v[148:151], v[214:217], v[80:83]
	v_mfma_f32_16x16x32_bf16 v[72:75], v[166:169], v[214:217], v[72:75]
	v_mfma_f32_16x16x32_bf16 v[116:119], v[170:173], v[186:189], 0
	v_mfma_f32_16x16x32_bf16 v[112:115], v[178:181], v[186:189], 0
	v_mfma_f32_16x16x32_bf16 v[100:103], v[170:173], v[194:197], 0
	v_mfma_f32_16x16x32_bf16 v[92:95], v[178:181], v[194:197], 0
	v_mfma_f32_16x16x32_bf16 v[84:87], v[170:173], v[202:205], 0
	v_mfma_f32_16x16x32_bf16 v[76:79], v[178:181], v[202:205], 0
	v_mfma_f32_16x16x32_bf16 v[68:71], v[170:173], v[210:213], 0
	v_mfma_f32_16x16x32_bf16 v[64:67], v[178:181], v[210:213], 0
	v_mfma_f32_16x16x32_bf16 v[116:119], v[174:177], v[190:193], v[116:119]
	v_mfma_f32_16x16x32_bf16 v[112:115], v[182:185], v[190:193], v[112:115]
	v_mfma_f32_16x16x32_bf16 v[100:103], v[174:177], v[198:201], v[100:103]
	v_mfma_f32_16x16x32_bf16 v[92:95], v[182:185], v[198:201], v[92:95]
	v_mfma_f32_16x16x32_bf16 v[84:87], v[174:177], v[206:209], v[84:87]
	v_mfma_f32_16x16x32_bf16 v[76:79], v[182:185], v[206:209], v[76:79]
	v_mfma_f32_16x16x32_bf16 v[68:71], v[174:177], v[214:217], v[68:71]
	v_mfma_f32_16x16x32_bf16 v[64:67], v[182:185], v[214:217], v[64:67]
	s_setprio 0
	s_barrier
	s_add_i32 s46, s37, s23
	v_lshl_add_u64 v[218:219], s[16:17], 0, v[130:131]
	s_mov_b32 m0, s46
	ds_read_b128 v[186:189], v160 offset:16384
	ds_read_b128 v[190:193], v160 offset:17408
	ds_read_b128 v[194:197], v160 offset:18432
	ds_read_b128 v[198:201], v160 offset:19456
	ds_read_b128 v[202:205], v160 offset:20480
	ds_read_b128 v[206:209], v160 offset:21504
	ds_read_b128 v[210:213], v160 offset:22528
	ds_read_b128 v[214:217], v160 offset:23552
	global_load_lds_dwordx4 v[218:219], off
	s_add_i32 m0, s46, 0x2000
	s_add_u32 s46, s16, 0xb0000
	v_lshl_add_u64 v[220:221], s[16:17], 0, v[134:135]
	s_addc_u32 s47, s17, 0
	s_add_i32 s48, s38, s23
	global_load_lds_dwordx4 v[220:221], off
	v_lshl_add_u64 v[222:223], s[46:47], 0, v[130:131]
	s_mov_b32 m0, s48
	v_lshl_add_u64 v[224:225], s[18:19], 0, v[132:133]
	global_load_lds_dwordx4 v[222:223], off
	v_lshl_add_u64 v[222:223], s[46:47], 0, v[134:135]
	s_add_i32 m0, s48, 0x2000
	s_nop 0
	global_load_lds_dwordx4 v[222:223], off
	v_lshl_add_u64 v[222:223], s[18:19], 0, v[128:129]
	s_mov_b32 m0, s26
	s_nop 0
	global_load_lds_dwordx4 v[222:223], off
	s_mov_b32 m0, s27
	s_nop 0
	global_load_lds_dwordx4 v[224:225], off
	s_waitcnt vmcnt(8)
	s_waitcnt lgkmcnt(0)
	s_barrier
; #define PG8_STAGE(bufoff, gbase, voff) do { _Pragma("unroll") for (int _i = 0; _i < 2; ++_i) \
;         __builtin_amdgcn_global_load_lds((const unsigned*)((const char*)(gbase) + (voff)[_i]), (LAS unsigned*)(lds + (bufoff) + ldsw + _i * 8192), 16, 0, 0); } while (0)
; #define PG8_LDA(dst, b, h) do { _Pragma("unroll") for (int m = 0; m < 4; ++m) _Pragma("unroll") for (int k = 0; k < 2; ++k) dst[m][k] = *(const LAS bf16x8*)(lds + PG8_SA(b, h) + aoff + m * 2048 + k * 1024); } while (0)
; #define PG8_LDB(dst, b, h) do { _Pragma("unroll") for (int n = 0; n < 2; ++n) _Pragma("unroll") for (int k = 0; k < 2; ++k) dst[n][k] = *(const LAS bf16x8*)(lds + PG8_SB(b, h) + boff + n * 2048 + k * 1024); } while (0)
; #define PG8_MMA(ai, bj, At, Bt) do { __builtin_amdgcn_s_setprio(3); _Pragma("unroll") for (int m = 0; m < 4; ++m) _Pragma("unroll") for (int n = 0; n < 2; ++n) _Pragma("unroll") for (int k = 0; k < 2; ++k) \
;         acc[ai][bj][m][n] = __builtin_amdgcn_mfma_f32_16x16x32_bf16(Bt[n][k], At[m][k], acc[ai][bj][m][n], 0, 0, 0); __builtin_amdgcn_s_setprio(0); } while (0)
; #define PG8_WAIT_V(n) asm volatile("s_waitcnt vmcnt(" #n ")" ::: "memory")
; #define PG8_WAIT_L(n) asm volatile("s_waitcnt lgkmcnt(" #n ")" ::: "memory")
; #define PG8_BAR __builtin_amdgcn_s_barrier()
; #define PG8_SCHED __builtin_amdgcn_sched_barrier(0)
; template <class Epi, bool ALIGN_EPI>
; __device__ __forceinline__ void gemm_phase(LAS unsigned char* lds, const Gemm g, const StaticOrder& S, const Epi& E) {
;     ...
;             PG8_WAIT_V(8); PG8_WAIT_L(0); PG8_BAR; PG8_MMA(1, 0, At, B0); PG8_MMA(1, 1, At, B1); PG8_BAR; PG8_SCHED;
;             PG8_LDB(B0, 1, 0); PG8_LDB(B1, 1, 1); PG8_SCHED; PG8_LDA(At, 1, 0); PG8_STAGE(PG8_SA(0, 1), a2 + hstep, voffA);
;             PG8_WAIT_V(8); PG8_WAIT_L(0); PG8_BAR; PG8_MMA(0, 0, At, B0); PG8_MMA(0, 1, At, B1); PG8_BAR; PG8_SCHED;
	s_setprio 3
	s_waitcnt lgkmcnt(0)
	v_mfma_f32_16x16x32_bf16 v[60:63], v[144:147], v[186:189], 0
	v_mfma_f32_16x16x32_bf16 v[56:59], v[162:165], v[186:189], 0
	v_mfma_f32_16x16x32_bf16 v[48:51], v[144:147], v[194:197], 0
	v_mfma_f32_16x16x32_bf16 v[40:43], v[162:165], v[194:197], 0
	v_mfma_f32_16x16x32_bf16 v[32:35], v[144:147], v[202:205], 0
	v_mfma_f32_16x16x32_bf16 v[24:27], v[162:165], v[202:205], 0
	v_mfma_f32_16x16x32_bf16 v[16:19], v[144:147], v[210:213], 0
	v_mfma_f32_16x16x32_bf16 v[8:11], v[162:165], v[210:213], 0
	v_mfma_f32_16x16x32_bf16 v[60:63], v[148:151], v[190:193], v[60:63]
	v_mfma_f32_16x16x32_bf16 v[56:59], v[166:169], v[190:193], v[56:59]
	v_mfma_f32_16x16x32_bf16 v[48:51], v[148:151], v[198:201], v[48:51]
	v_mfma_f32_16x16x32_bf16 v[40:43], v[166:169], v[198:201], v[40:43]
	v_mfma_f32_16x16x32_bf16 v[32:35], v[148:151], v[206:209], v[32:35]
	v_mfma_f32_16x16x32_bf16 v[24:27], v[166:169], v[206:209], v[24:27]
	v_mfma_f32_16x16x32_bf16 v[16:19], v[148:151], v[214:217], v[16:19]
	v_mfma_f32_16x16x32_bf16 v[8:11], v[166:169], v[214:217], v[8:11]
	v_mfma_f32_16x16x32_bf16 v[52:55], v[170:173], v[186:189], 0
	v_mfma_f32_16x16x32_bf16 v[44:47], v[178:181], v[186:189], 0
	v_mfma_f32_16x16x32_bf16 v[36:39], v[170:173], v[194:197], 0
	v_mfma_f32_16x16x32_bf16 v[28:31], v[178:181], v[194:197], 0
	v_mfma_f32_16x16x32_bf16 v[20:23], v[170:173], v[202:205], 0
	v_mfma_f32_16x16x32_bf16 v[12:15], v[178:181], v[202:205], 0
	v_mfma_f32_16x16x32_bf16 v[4:7], v[170:173], v[210:213], 0
	v_mfma_f32_16x16x32_bf16 v[0:3], v[178:181], v[210:213], 0
	v_mfma_f32_16x16x32_bf16 v[52:55], v[174:177], v[190:193], v[52:55]
	v_mfma_f32_16x16x32_bf16 v[44:47], v[182:185], v[190:193], v[44:47]
	v_mfma_f32_16x16x32_bf16 v[36:39], v[174:177], v[198:201], v[36:39]
	v_mfma_f32_16x16x32_bf16 v[28:31], v[182:185], v[198:201], v[28:31]
	v_mfma_f32_16x16x32_bf16 v[20:23], v[174:177], v[206:209], v[20:23]
	v_mfma_f32_16x16x32_bf16 v[12:15], v[182:185], v[206:209], v[12:15]
	v_mfma_f32_16x16x32_bf16 v[4:7], v[174:177], v[214:217], v[4:7]
	v_mfma_f32_16x16x32_bf16 v[0:3], v[182:185], v[214:217], v[0:3]
	s_setprio 0
	s_barrier
	s_add_i32 s46, 0, 0x18000
	v_add_u32_e32 v161, s46, v156
	s_add_i32 s47, 0, 0x1c000
	ds_read_b128 v[144:147], v161
	ds_read_b128 v[148:151], v161 offset:1024
	ds_read_b128 v[162:165], v161 offset:2048
	ds_read_b128 v[166:169], v161 offset:3072
	v_add_u32_e32 v161, s47, v156
	ds_read_b128 v[170:173], v161
	ds_read_b128 v[174:177], v161 offset:1024
	ds_read_b128 v[178:181], v161 offset:2048
	ds_read_b128 v[182:185], v161 offset:3072
	s_add_u32 s18, s18, 0xb0000
	s_addc_u32 s19, s19, 0
	s_mov_b32 m0, s28
	v_lshl_add_u64 v[226:227], s[18:19], 0, v[128:129]
	ds_read_b128 v[186:189], v160 offset:32768
	ds_read_b128 v[190:193], v160 offset:33792
	ds_read_b128 v[194:197], v160 offset:34816
	ds_read_b128 v[198:201], v160 offset:35840
	ds_read_b128 v[202:205], v160 offset:36864
	ds_read_b128 v[206:209], v160 offset:37888
	ds_read_b128 v[210:213], v160 offset:38912
	ds_read_b128 v[214:217], v160 offset:39936
	global_load_lds_dwordx4 v[226:227], off
	v_lshl_add_u64 v[226:227], s[18:19], 0, v[132:133]
	s_mov_b32 m0, s29
	s_nop 0
	global_load_lds_dwordx4 v[226:227], off
	s_waitcnt vmcnt(8)
	s_waitcnt lgkmcnt(0)
	s_barrier
	s_setprio 3
	s_waitcnt lgkmcnt(0)
	v_mfma_f32_16x16x32_bf16 v[124:127], v[144:147], v[186:189], v[124:127]
	v_mfma_f32_16x16x32_bf16 v[120:123], v[162:165], v[186:189], v[120:123]
	v_mfma_f32_16x16x32_bf16 v[108:111], v[144:147], v[194:197], v[108:111]
	v_mfma_f32_16x16x32_bf16 v[104:107], v[162:165], v[194:197], v[104:107]
	v_mfma_f32_16x16x32_bf16 v[96:99], v[144:147], v[202:205], v[96:99]
	v_mfma_f32_16x16x32_bf16 v[88:91], v[162:165], v[202:205], v[88:91]
	v_mfma_f32_16x16x32_bf16 v[80:83], v[144:147], v[210:213], v[80:83]
	v_mfma_f32_16x16x32_bf16 v[72:75], v[162:165], v[210:213], v[72:75]
	v_mfma_f32_16x16x32_bf16 v[124:127], v[148:151], v[190:193], v[124:127]
	v_mfma_f32_16x16x32_bf16 v[120:123], v[166:169], v[190:193], v[120:123]
	v_mfma_f32_16x16x32_bf16 v[108:111], v[148:151], v[198:201], v[108:111]
	v_mfma_f32_16x16x32_bf16 v[104:107], v[166:169], v[198:201], v[104:107]
	v_mfma_f32_16x16x32_bf16 v[96:99], v[148:151], v[206:209], v[96:99]
	v_mfma_f32_16x16x32_bf16 v[88:91], v[166:169], v[206:209], v[88:91]
	v_mfma_f32_16x16x32_bf16 v[80:83], v[148:151], v[214:217], v[80:83]
	v_mfma_f32_16x16x32_bf16 v[72:75], v[166:169], v[214:217], v[72:75]
	v_mfma_f32_16x16x32_bf16 v[116:119], v[170:173], v[186:189], v[116:119]
	v_mfma_f32_16x16x32_bf16 v[112:115], v[178:181], v[186:189], v[112:115]
	v_mfma_f32_16x16x32_bf16 v[100:103], v[170:173], v[194:197], v[100:103]
	v_mfma_f32_16x16x32_bf16 v[92:95], v[178:181], v[194:197], v[92:95]
	v_mfma_f32_16x16x32_bf16 v[84:87], v[170:173], v[202:205], v[84:87]
	v_mfma_f32_16x16x32_bf16 v[76:79], v[178:181], v[202:205], v[76:79]
	v_mfma_f32_16x16x32_bf16 v[68:71], v[170:173], v[210:213], v[68:71]
	v_mfma_f32_16x16x32_bf16 v[64:67], v[178:181], v[210:213], v[64:67]
	v_mfma_f32_16x16x32_bf16 v[116:119], v[174:177], v[190:193], v[116:119]
	v_mfma_f32_16x16x32_bf16 v[112:115], v[182:185], v[190:193], v[112:115]
	v_mfma_f32_16x16x32_bf16 v[100:103], v[174:177], v[198:201], v[100:103]
	v_mfma_f32_16x16x32_bf16 v[92:95], v[182:185], v[198:201], v[92:95]
	v_mfma_f32_16x16x32_bf16 v[84:87], v[174:177], v[206:209], v[84:87]
	v_mfma_f32_16x16x32_bf16 v[76:79], v[182:185], v[206:209], v[76:79]
	v_mfma_f32_16x16x32_bf16 v[68:71], v[174:177], v[214:217], v[68:71]
	v_mfma_f32_16x16x32_bf16 v[64:67], v[182:185], v[214:217], v[64:67]
	s_setprio 0
	s_barrier
; #define PG8_STAGE(bufoff, gbase, voff) do { _Pragma("unroll") for (int _i = 0; _i < 2; ++_i) \
;         __builtin_amdgcn_global_load_lds((const unsigned*)((const char*)(gbase) + (voff)[_i]), (LAS unsigned*)(lds + (bufoff) + ldsw + _i * 8192), 16, 0, 0); } while (0)
; #define PG8_LDA(dst, b, h) do { _Pragma("unroll") for (int m = 0; m < 4; ++m) _Pragma("unroll") for (int k = 0; k < 2; ++k) dst[m][k] = *(const LAS bf16x8*)(lds + PG8_SA(b, h) + aoff + m * 2048 + k * 1024); } while (0)
; #define PG8_LDB(dst, b, h) do { _Pragma("unroll") for (int n = 0; n < 2; ++n) _Pragma("unroll") for (int k = 0; k < 2; ++k) dst[n][k] = *(const LAS bf16x8*)(lds + PG8_SB(b, h) + boff + n * 2048 + k * 1024); } while (0)
; #define PG8_MMA(ai, bj, At, Bt) do { __builtin_amdgcn_s_setprio(3); _Pragma("unroll") for (int m = 0; m < 4; ++m) _Pragma("unroll") for (int n = 0; n < 2; ++n) _Pragma("unroll") for (int k = 0; k < 2; ++k) \
;         acc[ai][bj][m][n] = __builtin_amdgcn_mfma_f32_16x16x32_bf16(Bt[n][k], At[m][k], acc[ai][bj][m][n], 0, 0, 0); __builtin_amdgcn_s_setprio(0); } while (0)
; #define PG8_WAIT_V(n) asm volatile("s_waitcnt vmcnt(" #n ")" ::: "memory")
; #define PG8_WAIT_L(n) asm volatile("s_waitcnt lgkmcnt(" #n ")" ::: "memory")
; #define PG8_BAR __builtin_amdgcn_s_barrier()
; #define PG8_SCHED __builtin_amdgcn_sched_barrier(0)
; template <class Epi, bool ALIGN_EPI>
; __device__ __forceinline__ void gemm_phase(LAS unsigned char* lds, const Gemm g, const StaticOrder& S, const Epi& E) {
;     ...
;             PG8_LDB(B0, 0, 0); PG8_LDB(B1, 0, 1); PG8_SCHED; PG8_LDA(At, 0, 0); PG8_STAGE(PG8_SA(1, 1), a1 + hstep, voffA);
;             PG8_WAIT_V(8); PG8_WAIT_L(0); PG8_BAR; PG8_MMA(0, 0, At, B0); PG8_MMA(0, 1, At, B1); PG8_BAR; PG8_SCHED;
;     ...
;             PG8_LDA(At, 1, 1); PG8_STAGE(PG8_SB(1, 0), b3, voffB); PG8_STAGE(PG8_SB(1, 1), b3 + hstep, voffB); PG8_STAGE(PG8_SA(1, 0), a3, voffA);
;             PG8_WAIT_V(8); PG8_WAIT_L(0); PG8_BAR; PG8_MMA(1, 0, At, B0); PG8_MMA(1, 1, At, B1); PG8_BAR; PG8_SCHED;
	s_add_i32 s18, s46, s23
	v_lshl_add_u64 v[218:219], v[218:219], 0, s[8:9]
	s_mov_b32 m0, s18
	ds_read_b128 v[186:189], v160 offset:49152
	ds_read_b128 v[190:193], v160 offset:50176
	ds_read_b128 v[194:197], v160 offset:51200
	ds_read_b128 v[198:201], v160 offset:52224
	ds_read_b128 v[202:205], v160 offset:53248
	ds_read_b128 v[206:209], v160 offset:54272
	ds_read_b128 v[210:213], v160 offset:55296
	ds_read_b128 v[214:217], v160 offset:56320
	global_load_lds_dwordx4 v[218:219], off
	s_add_i32 m0, s18, 0x2000
	s_add_u32 s16, s16, 0xb0080
	v_lshl_add_u64 v[218:219], v[220:221], 0, s[8:9]
	s_addc_u32 s17, s17, 0
	s_add_i32 s18, s47, s23
	global_load_lds_dwordx4 v[218:219], off
	v_lshl_add_u64 v[218:219], s[16:17], 0, v[130:131]
	s_mov_b32 m0, s18
	s_nop 0
	global_load_lds_dwordx4 v[218:219], off
	v_lshl_add_u64 v[218:219], s[16:17], 0, v[134:135]
	s_add_i32 m0, s18, 0x2000
	s_nop 0
	global_load_lds_dwordx4 v[218:219], off
	v_lshl_add_u64 v[218:219], v[222:223], 0, s[8:9]
	s_mov_b32 m0, s31
	s_nop 0
	global_load_lds_dwordx4 v[218:219], off
	v_lshl_add_u64 v[218:219], v[224:225], 0, s[8:9]
	s_mov_b32 m0, s33
	s_nop 0
	global_load_lds_dwordx4 v[218:219], off
	s_waitcnt vmcnt(8)
	s_waitcnt lgkmcnt(0)
	s_barrier
	s_setprio 3
	s_waitcnt lgkmcnt(0)
	v_mfma_f32_16x16x32_bf16 v[60:63], v[144:147], v[186:189], v[60:63]
	v_mfma_f32_16x16x32_bf16 v[56:59], v[162:165], v[186:189], v[56:59]
	v_mfma_f32_16x16x32_bf16 v[48:51], v[144:147], v[194:197], v[48:51]
	v_mfma_f32_16x16x32_bf16 v[40:43], v[162:165], v[194:197], v[40:43]
	v_mfma_f32_16x16x32_bf16 v[32:35], v[144:147], v[202:205], v[32:35]
	v_mfma_f32_16x16x32_bf16 v[24:27], v[162:165], v[202:205], v[24:27]
	v_mfma_f32_16x16x32_bf16 v[16:19], v[144:147], v[210:213], v[16:19]
	v_mfma_f32_16x16x32_bf16 v[8:11], v[162:165], v[210:213], v[8:11]
	v_mfma_f32_16x16x32_bf16 v[60:63], v[148:151], v[190:193], v[60:63]
	v_mfma_f32_16x16x32_bf16 v[56:59], v[166:169], v[190:193], v[56:59]
	v_mfma_f32_16x16x32_bf16 v[48:51], v[148:151], v[198:201], v[48:51]
	v_mfma_f32_16x16x32_bf16 v[40:43], v[166:169], v[198:201], v[40:43]
	v_mfma_f32_16x16x32_bf16 v[32:35], v[148:151], v[206:209], v[32:35]
	v_mfma_f32_16x16x32_bf16 v[24:27], v[166:169], v[206:209], v[24:27]
	v_mfma_f32_16x16x32_bf16 v[16:19], v[148:151], v[214:217], v[16:19]
	v_mfma_f32_16x16x32_bf16 v[8:11], v[166:169], v[214:217], v[8:11]
	v_mfma_f32_16x16x32_bf16 v[52:55], v[170:173], v[186:189], v[52:55]
	v_mfma_f32_16x16x32_bf16 v[44:47], v[178:181], v[186:189], v[44:47]
	v_mfma_f32_16x16x32_bf16 v[36:39], v[170:173], v[194:197], v[36:39]
	v_mfma_f32_16x16x32_bf16 v[28:31], v[178:181], v[194:197], v[28:31]
	v_mfma_f32_16x16x32_bf16 v[20:23], v[170:173], v[202:205], v[20:23]
	v_mfma_f32_16x16x32_bf16 v[12:15], v[178:181], v[202:205], v[12:15]
	v_mfma_f32_16x16x32_bf16 v[4:7], v[170:173], v[210:213], v[4:7]
	v_mfma_f32_16x16x32_bf16 v[0:3], v[178:181], v[210:213], v[0:3]
	v_mfma_f32_16x16x32_bf16 v[52:55], v[174:177], v[190:193], v[52:55]
	v_mfma_f32_16x16x32_bf16 v[44:47], v[182:185], v[190:193], v[44:47]
	v_mfma_f32_16x16x32_bf16 v[36:39], v[174:177], v[198:201], v[36:39]
	v_mfma_f32_16x16x32_bf16 v[28:31], v[182:185], v[198:201], v[28:31]
	v_mfma_f32_16x16x32_bf16 v[20:23], v[174:177], v[206:209], v[20:23]
	v_mfma_f32_16x16x32_bf16 v[12:15], v[182:185], v[206:209], v[12:15]
	v_mfma_f32_16x16x32_bf16 v[4:7], v[174:177], v[214:217], v[4:7]
	v_mfma_f32_16x16x32_bf16 v[0:3], v[182:185], v[214:217], v[0:3]
	s_setprio 0
	s_barrier
	s_add_i32 s45, s45, 2
	s_add_u32 s14, s14, 0x100
	s_addc_u32 s15, s15, 0
	s_add_u32 s43, s43, 0x100
	s_addc_u32 s44, s44, 0
.LBB0_1513:
	ds_read_b128 v[144:147], v158
	ds_read_b128 v[148:151], v158 offset:1024
	ds_read_b128 v[162:165], v158 offset:2048
	ds_read_b128 v[166:169], v158 offset:3072
	ds_read_b128 v[170:173], v159
	ds_read_b128 v[174:177], v159 offset:1024
	ds_read_b128 v[178:181], v159 offset:2048
	ds_read_b128 v[182:185], v159 offset:3072
	s_add_u32 s16, s14, 0xfff50080
	s_addc_u32 s17, s15, -1
	s_cmp_eq_u32 s45, 40
	s_cselect_b32 s19, s5, s17
	s_cselect_b32 s18, s4, s16
	s_cselect_b32 s17, s13, s44
	s_cselect_b32 s16, s12, s43
	v_lshl_add_u64 v[218:219], s[14:15], 0, v[136:137]
	s_add_i32 m0, s26, 0xc000
	ds_read_b128 v[186:189], v160
	ds_read_b128 v[190:193], v160 offset:1024
	ds_read_b128 v[194:197], v160 offset:2048
	ds_read_b128 v[198:201], v160 offset:3072
	ds_read_b128 v[202:205], v160 offset:4096
	ds_read_b128 v[206:209], v160 offset:5120
	ds_read_b128 v[210:213], v160 offset:6144
	ds_read_b128 v[214:217], v160 offset:7168
	global_load_lds_dwordx4 v[218:219], off
	v_lshl_add_u64 v[218:219], s[14:15], 0, v[138:139]
	s_add_i32 m0, s26, 0xe000
	s_nop 0
	global_load_lds_dwordx4 v[218:219], off
	s_waitcnt vmcnt(8)
	s_waitcnt lgkmcnt(0)
	s_barrier
; #define PG8_STAGE(bufoff, gbase, voff) do { _Pragma("unroll") for (int _i = 0; _i < 2; ++_i) \
;         __builtin_amdgcn_global_load_lds((const unsigned*)((const char*)(gbase) + (voff)[_i]), (LAS unsigned*)(lds + (bufoff) + ldsw + _i * 8192), 16, 0, 0); } while (0)
; #define PG8_LDA(dst, b, h) do { _Pragma("unroll") for (int m = 0; m < 4; ++m) _Pragma("unroll") for (int k = 0; k < 2; ++k) dst[m][k] = *(const LAS bf16x8*)(lds + PG8_SA(b, h) + aoff + m * 2048 + k * 1024); } while (0)
; #define PG8_MMA(ai, bj, At, Bt) do { __builtin_amdgcn_s_setprio(3); _Pragma("unroll") for (int m = 0; m < 4; ++m) _Pragma("unroll") for (int n = 0; n < 2; ++n) _Pragma("unroll") for (int k = 0; k < 2; ++k) \
;         acc[ai][bj][m][n] = __builtin_amdgcn_mfma_f32_16x16x32_bf16(Bt[n][k], At[m][k], acc[ai][bj][m][n], 0, 0, 0); __builtin_amdgcn_s_setprio(0); } while (0)
; #define PG8_WAIT_V(n) asm volatile("s_waitcnt vmcnt(" #n ")" ::: "memory")
; #define PG8_WAIT_L(n) asm volatile("s_waitcnt lgkmcnt(" #n ")" ::: "memory")
; #define PG8_BAR __builtin_amdgcn_s_barrier()
; #define PG8_SCHED __builtin_amdgcn_sched_barrier(0)
; template <class Epi, bool ALIGN_EPI>
; __device__ __forceinline__ void gemm_phase(LAS unsigned char* lds, const Gemm g, const StaticOrder& S, const Epi& E) {
;     ...
;             PG8_WAIT_V(8); PG8_WAIT_L(0); PG8_BAR; PG8_MMA(0, 0, At, B0); PG8_MMA(0, 1, At, B1); PG8_BAR; PG8_SCHED;
;             PG8_LDA(At, 0, 1); PG8_STAGE(PG8_SB(0, 0), b2, voffB); PG8_STAGE(PG8_SB(0, 1), b2 + hstep, voffB); PG8_STAGE(PG8_SA(0, 0), a2, voffA);
;             PG8_WAIT_V(8); PG8_WAIT_L(0); PG8_BAR; PG8_MMA(1, 0, At, B0); PG8_MMA(1, 1, At, B1); PG8_BAR; PG8_SCHED;
	s_setprio 3
	s_waitcnt lgkmcnt(0)
	v_mfma_f32_16x16x32_bf16 v[124:127], v[144:147], v[186:189], v[124:127]
	v_mfma_f32_16x16x32_bf16 v[120:123], v[162:165], v[186:189], v[120:123]
	v_mfma_f32_16x16x32_bf16 v[108:111], v[144:147], v[194:197], v[108:111]
	v_mfma_f32_16x16x32_bf16 v[104:107], v[162:165], v[194:197], v[104:107]
	v_mfma_f32_16x16x32_bf16 v[96:99], v[144:147], v[202:205], v[96:99]
	v_mfma_f32_16x16x32_bf16 v[88:91], v[162:165], v[202:205], v[88:91]
	v_mfma_f32_16x16x32_bf16 v[80:83], v[144:147], v[210:213], v[80:83]
	v_mfma_f32_16x16x32_bf16 v[72:75], v[162:165], v[210:213], v[72:75]
	v_mfma_f32_16x16x32_bf16 v[124:127], v[148:151], v[190:193], v[124:127]
	v_mfma_f32_16x16x32_bf16 v[120:123], v[166:169], v[190:193], v[120:123]
	v_mfma_f32_16x16x32_bf16 v[108:111], v[148:151], v[198:201], v[108:111]
	v_mfma_f32_16x16x32_bf16 v[104:107], v[166:169], v[198:201], v[104:107]
	v_mfma_f32_16x16x32_bf16 v[96:99], v[148:151], v[206:209], v[96:99]
	v_mfma_f32_16x16x32_bf16 v[88:91], v[166:169], v[206:209], v[88:91]
	v_mfma_f32_16x16x32_bf16 v[80:83], v[148:151], v[214:217], v[80:83]
	v_mfma_f32_16x16x32_bf16 v[72:75], v[166:169], v[214:217], v[72:75]
	v_mfma_f32_16x16x32_bf16 v[116:119], v[170:173], v[186:189], v[116:119]
	v_mfma_f32_16x16x32_bf16 v[112:115], v[178:181], v[186:189], v[112:115]
	v_mfma_f32_16x16x32_bf16 v[100:103], v[170:173], v[194:197], v[100:103]
	v_mfma_f32_16x16x32_bf16 v[92:95], v[178:181], v[194:197], v[92:95]
	v_mfma_f32_16x16x32_bf16 v[84:87], v[170:173], v[202:205], v[84:87]
	v_mfma_f32_16x16x32_bf16 v[76:79], v[178:181], v[202:205], v[76:79]
	v_mfma_f32_16x16x32_bf16 v[68:71], v[170:173], v[210:213], v[68:71]
	v_mfma_f32_16x16x32_bf16 v[64:67], v[178:181], v[210:213], v[64:67]
	v_mfma_f32_16x16x32_bf16 v[116:119], v[174:177], v[190:193], v[116:119]
	v_mfma_f32_16x16x32_bf16 v[112:115], v[182:185], v[190:193], v[112:115]
	v_mfma_f32_16x16x32_bf16 v[100:103], v[174:177], v[198:201], v[100:103]
	v_mfma_f32_16x16x32_bf16 v[92:95], v[182:185], v[198:201], v[92:95]
	v_mfma_f32_16x16x32_bf16 v[84:87], v[174:177], v[206:209], v[84:87]
	v_mfma_f32_16x16x32_bf16 v[76:79], v[182:185], v[206:209], v[76:79]
	v_mfma_f32_16x16x32_bf16 v[68:71], v[174:177], v[214:217], v[68:71]
	v_mfma_f32_16x16x32_bf16 v[64:67], v[182:185], v[214:217], v[64:67]
	s_setprio 0
	s_barrier
	s_add_i32 s46, s37, s23
	v_lshl_add_u64 v[218:219], s[16:17], 0, v[130:131]
	s_mov_b32 m0, s46
	ds_read_b128 v[186:189], v160 offset:16384
	ds_read_b128 v[190:193], v160 offset:17408
	ds_read_b128 v[194:197], v160 offset:18432
	ds_read_b128 v[198:201], v160 offset:19456
	ds_read_b128 v[202:205], v160 offset:20480
	ds_read_b128 v[206:209], v160 offset:21504
	ds_read_b128 v[210:213], v160 offset:22528
	ds_read_b128 v[214:217], v160 offset:23552
	global_load_lds_dwordx4 v[218:219], off
	s_add_i32 m0, s46, 0x2000
	s_add_u32 s46, s16, 0xb0000
	v_lshl_add_u64 v[220:221], s[16:17], 0, v[134:135]
	s_addc_u32 s47, s17, 0
	s_add_i32 s48, s38, s23
	global_load_lds_dwordx4 v[220:221], off
	v_lshl_add_u64 v[222:223], s[46:47], 0, v[130:131]
	s_mov_b32 m0, s48
	v_lshl_add_u64 v[224:225], s[18:19], 0, v[132:133]
	global_load_lds_dwordx4 v[222:223], off
	v_lshl_add_u64 v[222:223], s[46:47], 0, v[134:135]
	s_add_i32 m0, s48, 0x2000
	s_nop 0
	global_load_lds_dwordx4 v[222:223], off
	v_lshl_add_u64 v[222:223], s[18:19], 0, v[128:129]
	s_mov_b32 m0, s26
	s_nop 0
	global_load_lds_dwordx4 v[222:223], off
	s_mov_b32 m0, s27
	s_nop 0
	global_load_lds_dwordx4 v[224:225], off
	s_waitcnt vmcnt(8)
	s_waitcnt lgkmcnt(0)
	s_barrier
	s_setprio 3
	s_waitcnt lgkmcnt(0)
	v_mfma_f32_16x16x32_bf16 v[60:63], v[144:147], v[186:189], v[60:63]
	v_mfma_f32_16x16x32_bf16 v[56:59], v[162:165], v[186:189], v[56:59]
	v_mfma_f32_16x16x32_bf16 v[48:51], v[144:147], v[194:197], v[48:51]
	v_mfma_f32_16x16x32_bf16 v[40:43], v[162:165], v[194:197], v[40:43]
	v_mfma_f32_16x16x32_bf16 v[32:35], v[144:147], v[202:205], v[32:35]
	v_mfma_f32_16x16x32_bf16 v[24:27], v[162:165], v[202:205], v[24:27]
	v_mfma_f32_16x16x32_bf16 v[16:19], v[144:147], v[210:213], v[16:19]
	v_mfma_f32_16x16x32_bf16 v[8:11], v[162:165], v[210:213], v[8:11]
	v_mfma_f32_16x16x32_bf16 v[60:63], v[148:151], v[190:193], v[60:63]
	v_mfma_f32_16x16x32_bf16 v[56:59], v[166:169], v[190:193], v[56:59]
	v_mfma_f32_16x16x32_bf16 v[48:51], v[148:151], v[198:201], v[48:51]
	v_mfma_f32_16x16x32_bf16 v[40:43], v[166:169], v[198:201], v[40:43]
	v_mfma_f32_16x16x32_bf16 v[32:35], v[148:151], v[206:209], v[32:35]
	v_mfma_f32_16x16x32_bf16 v[24:27], v[166:169], v[206:209], v[24:27]
	v_mfma_f32_16x16x32_bf16 v[16:19], v[148:151], v[214:217], v[16:19]
	v_mfma_f32_16x16x32_bf16 v[8:11], v[166:169], v[214:217], v[8:11]
	v_mfma_f32_16x16x32_bf16 v[52:55], v[170:173], v[186:189], v[52:55]
	v_mfma_f32_16x16x32_bf16 v[44:47], v[178:181], v[186:189], v[44:47]
	v_mfma_f32_16x16x32_bf16 v[36:39], v[170:173], v[194:197], v[36:39]
	v_mfma_f32_16x16x32_bf16 v[28:31], v[178:181], v[194:197], v[28:31]
	v_mfma_f32_16x16x32_bf16 v[20:23], v[170:173], v[202:205], v[20:23]
	v_mfma_f32_16x16x32_bf16 v[12:15], v[178:181], v[202:205], v[12:15]
	v_mfma_f32_16x16x32_bf16 v[4:7], v[170:173], v[210:213], v[4:7]
	v_mfma_f32_16x16x32_bf16 v[0:3], v[178:181], v[210:213], v[0:3]
	v_mfma_f32_16x16x32_bf16 v[52:55], v[174:177], v[190:193], v[52:55]
	v_mfma_f32_16x16x32_bf16 v[44:47], v[182:185], v[190:193], v[44:47]
	v_mfma_f32_16x16x32_bf16 v[36:39], v[174:177], v[198:201], v[36:39]
	v_mfma_f32_16x16x32_bf16 v[28:31], v[182:185], v[198:201], v[28:31]
	v_mfma_f32_16x16x32_bf16 v[20:23], v[174:177], v[206:209], v[20:23]
	v_mfma_f32_16x16x32_bf16 v[12:15], v[182:185], v[206:209], v[12:15]
	v_mfma_f32_16x16x32_bf16 v[4:7], v[174:177], v[214:217], v[4:7]
	v_mfma_f32_16x16x32_bf16 v[0:3], v[182:185], v[214:217], v[0:3]
	s_setprio 0
	s_barrier
; #define PG8_STAGE(bufoff, gbase, voff) do { _Pragma("unroll") for (int _i = 0; _i < 2; ++_i) \
;         __builtin_amdgcn_global_load_lds((const unsigned*)((const char*)(gbase) + (voff)[_i]), (LAS unsigned*)(lds + (bufoff) + ldsw + _i * 8192), 16, 0, 0); } while (0)
; #define PG8_LDA(dst, b, h) do { _Pragma("unroll") for (int m = 0; m < 4; ++m) _Pragma("unroll") for (int k = 0; k < 2; ++k) dst[m][k] = *(const LAS bf16x8*)(lds + PG8_SA(b, h) + aoff + m * 2048 + k * 1024); } while (0)
; #define PG8_LDB(dst, b, h) do { _Pragma("unroll") for (int n = 0; n < 2; ++n) _Pragma("unroll") for (int k = 0; k < 2; ++k) dst[n][k] = *(const LAS bf16x8*)(lds + PG8_SB(b, h) + boff + n * 2048 + k * 1024); } while (0)
; #define PG8_MMA(ai, bj, At, Bt) do { __builtin_amdgcn_s_setprio(3); _Pragma("unroll") for (int m = 0; m < 4; ++m) _Pragma("unroll") for (int n = 0; n < 2; ++n) _Pragma("unroll") for (int k = 0; k < 2; ++k) \
;         acc[ai][bj][m][n] = __builtin_amdgcn_mfma_f32_16x16x32_bf16(Bt[n][k], At[m][k], acc[ai][bj][m][n], 0, 0, 0); __builtin_amdgcn_s_setprio(0); } while (0)
; #define PG8_WAIT_V(n) asm volatile("s_waitcnt vmcnt(" #n ")" ::: "memory")
; #define PG8_WAIT_L(n) asm volatile("s_waitcnt lgkmcnt(" #n ")" ::: "memory")
; #define PG8_BAR __builtin_amdgcn_s_barrier()
; #define PG8_SCHED __builtin_amdgcn_sched_barrier(0)
; template <class Epi, bool ALIGN_EPI>
; __device__ __forceinline__ void gemm_phase(LAS unsigned char* lds, const Gemm g, const StaticOrder& S, const Epi& E) {
;     ...
;             PG8_LDB(B0, 1, 0); PG8_LDB(B1, 1, 1); PG8_SCHED; PG8_LDA(At, 1, 0); PG8_STAGE(PG8_SA(0, 1), a2 + hstep, voffA);
;             PG8_WAIT_V(8); PG8_WAIT_L(0); PG8_BAR; PG8_MMA(0, 0, At, B0); PG8_MMA(0, 1, At, B1); PG8_BAR; PG8_SCHED;
	s_add_i32 s46, 0, 0x18000
	v_add_u32_e32 v161, s46, v156
	s_add_i32 s47, 0, 0x1c000
	ds_read_b128 v[144:147], v161
	ds_read_b128 v[148:151], v161 offset:1024
	ds_read_b128 v[162:165], v161 offset:2048
	ds_read_b128 v[166:169], v161 offset:3072
	v_add_u32_e32 v161, s47, v156
	ds_read_b128 v[170:173], v161
	ds_read_b128 v[174:177], v161 offset:1024
	ds_read_b128 v[178:181], v161 offset:2048
	ds_read_b128 v[182:185], v161 offset:3072
	s_add_u32 s18, s18, 0xb0000
	s_addc_u32 s19, s19, 0
	s_mov_b32 m0, s28
	v_lshl_add_u64 v[226:227], s[18:19], 0, v[128:129]
	ds_read_b128 v[186:189], v160 offset:32768
	ds_read_b128 v[190:193], v160 offset:33792
	ds_read_b128 v[194:197], v160 offset:34816
	ds_read_b128 v[198:201], v160 offset:35840
	ds_read_b128 v[202:205], v160 offset:36864
	ds_read_b128 v[206:209], v160 offset:37888
	ds_read_b128 v[210:213], v160 offset:38912
	ds_read_b128 v[214:217], v160 offset:39936
	global_load_lds_dwordx4 v[226:227], off
	v_lshl_add_u64 v[226:227], s[18:19], 0, v[132:133]
	s_mov_b32 m0, s29
	s_nop 0
	global_load_lds_dwordx4 v[226:227], off
	s_waitcnt vmcnt(8)
	s_waitcnt lgkmcnt(0)
	s_barrier
	s_setprio 3
	s_waitcnt lgkmcnt(0)
	v_mfma_f32_16x16x32_bf16 v[124:127], v[144:147], v[186:189], v[124:127]
	v_mfma_f32_16x16x32_bf16 v[120:123], v[162:165], v[186:189], v[120:123]
	v_mfma_f32_16x16x32_bf16 v[108:111], v[144:147], v[194:197], v[108:111]
	v_mfma_f32_16x16x32_bf16 v[104:107], v[162:165], v[194:197], v[104:107]
	v_mfma_f32_16x16x32_bf16 v[96:99], v[144:147], v[202:205], v[96:99]
	v_mfma_f32_16x16x32_bf16 v[88:91], v[162:165], v[202:205], v[88:91]
	v_mfma_f32_16x16x32_bf16 v[80:83], v[144:147], v[210:213], v[80:83]
	v_mfma_f32_16x16x32_bf16 v[72:75], v[162:165], v[210:213], v[72:75]
	v_mfma_f32_16x16x32_bf16 v[124:127], v[148:151], v[190:193], v[124:127]
	v_mfma_f32_16x16x32_bf16 v[120:123], v[166:169], v[190:193], v[120:123]
	v_mfma_f32_16x16x32_bf16 v[108:111], v[148:151], v[198:201], v[108:111]
	v_mfma_f32_16x16x32_bf16 v[104:107], v[166:169], v[198:201], v[104:107]
	v_mfma_f32_16x16x32_bf16 v[96:99], v[148:151], v[206:209], v[96:99]
	v_mfma_f32_16x16x32_bf16 v[88:91], v[166:169], v[206:209], v[88:91]
	v_mfma_f32_16x16x32_bf16 v[80:83], v[148:151], v[214:217], v[80:83]
	v_mfma_f32_16x16x32_bf16 v[72:75], v[166:169], v[214:217], v[72:75]
	v_mfma_f32_16x16x32_bf16 v[116:119], v[170:173], v[186:189], v[116:119]
	v_mfma_f32_16x16x32_bf16 v[112:115], v[178:181], v[186:189], v[112:115]
	v_mfma_f32_16x16x32_bf16 v[100:103], v[170:173], v[194:197], v[100:103]
	v_mfma_f32_16x16x32_bf16 v[92:95], v[178:181], v[194:197], v[92:95]
	v_mfma_f32_16x16x32_bf16 v[84:87], v[170:173], v[202:205], v[84:87]
	v_mfma_f32_16x16x32_bf16 v[76:79], v[178:181], v[202:205], v[76:79]
	v_mfma_f32_16x16x32_bf16 v[68:71], v[170:173], v[210:213], v[68:71]
	v_mfma_f32_16x16x32_bf16 v[64:67], v[178:181], v[210:213], v[64:67]
	v_mfma_f32_16x16x32_bf16 v[116:119], v[174:177], v[190:193], v[116:119]
	v_mfma_f32_16x16x32_bf16 v[112:115], v[182:185], v[190:193], v[112:115]
	v_mfma_f32_16x16x32_bf16 v[100:103], v[174:177], v[198:201], v[100:103]
	v_mfma_f32_16x16x32_bf16 v[92:95], v[182:185], v[198:201], v[92:95]
	v_mfma_f32_16x16x32_bf16 v[84:87], v[174:177], v[206:209], v[84:87]
	v_mfma_f32_16x16x32_bf16 v[76:79], v[182:185], v[206:209], v[76:79]
	v_mfma_f32_16x16x32_bf16 v[68:71], v[174:177], v[214:217], v[68:71]
	v_mfma_f32_16x16x32_bf16 v[64:67], v[182:185], v[214:217], v[64:67]
	s_setprio 0
	s_barrier
; #define PG8_STAGE(bufoff, gbase, voff) do { _Pragma("unroll") for (int _i = 0; _i < 2; ++_i) \
;         __builtin_amdgcn_global_load_lds((const unsigned*)((const char*)(gbase) + (voff)[_i]), (LAS unsigned*)(lds + (bufoff) + ldsw + _i * 8192), 16, 0, 0); } while (0)
; #define PG8_LDA(dst, b, h) do { _Pragma("unroll") for (int m = 0; m < 4; ++m) _Pragma("unroll") for (int k = 0; k < 2; ++k) dst[m][k] = *(const LAS bf16x8*)(lds + PG8_SA(b, h) + aoff + m * 2048 + k * 1024); } while (0)
; #define PG8_MMA(ai, bj, At, Bt) do { __builtin_amdgcn_s_setprio(3); _Pragma("unroll") for (int m = 0; m < 4; ++m) _Pragma("unroll") for (int n = 0; n < 2; ++n) _Pragma("unroll") for (int k = 0; k < 2; ++k) \
;         acc[ai][bj][m][n] = __builtin_amdgcn_mfma_f32_16x16x32_bf16(Bt[n][k], At[m][k], acc[ai][bj][m][n], 0, 0, 0); __builtin_amdgcn_s_setprio(0); } while (0)
; #define PG8_WAIT_V(n) asm volatile("s_waitcnt vmcnt(" #n ")" ::: "memory")
; #define PG8_WAIT_L(n) asm volatile("s_waitcnt lgkmcnt(" #n ")" ::: "memory")
; #define PG8_BAR __builtin_amdgcn_s_barrier()
; #define PG8_SCHED __builtin_amdgcn_sched_barrier(0)
; template <class Epi, bool ALIGN_EPI>
; __device__ __forceinline__ void gemm_phase(LAS unsigned char* lds, const Gemm g, const StaticOrder& S, const Epi& E) {
;     ...
;             PG8_LDA(At, 1, 1); PG8_STAGE(PG8_SB(1, 0), b3, voffB); PG8_STAGE(PG8_SB(1, 1), b3 + hstep, voffB); PG8_STAGE(PG8_SA(1, 0), a3, voffA);
;             PG8_WAIT_V(8); PG8_WAIT_L(0); PG8_BAR; PG8_MMA(1, 0, At, B0); PG8_MMA(1, 1, At, B1); PG8_BAR; PG8_SCHED;
;         }
;         if constexpr (ALIGN_EPI) { if (wr == 0) PG8_BAR; }
	s_add_i32 s18, s46, s23
	v_lshl_add_u64 v[218:219], v[218:219], 0, s[8:9]
	s_mov_b32 m0, s18
	ds_read_b128 v[186:189], v160 offset:49152
	ds_read_b128 v[190:193], v160 offset:50176
	ds_read_b128 v[194:197], v160 offset:51200
	ds_read_b128 v[198:201], v160 offset:52224
	ds_read_b128 v[202:205], v160 offset:53248
	ds_read_b128 v[206:209], v160 offset:54272
	ds_read_b128 v[210:213], v160 offset:55296
	ds_read_b128 v[214:217], v160 offset:56320
	global_load_lds_dwordx4 v[218:219], off
	s_add_i32 m0, s18, 0x2000
	s_add_u32 s16, s16, 0xb0080
	v_lshl_add_u64 v[218:219], v[220:221], 0, s[8:9]
	s_addc_u32 s17, s17, 0
	s_add_i32 s18, s47, s23
	global_load_lds_dwordx4 v[218:219], off
	v_lshl_add_u64 v[218:219], s[16:17], 0, v[130:131]
	s_mov_b32 m0, s18
	s_nop 0
	global_load_lds_dwordx4 v[218:219], off
	v_lshl_add_u64 v[218:219], s[16:17], 0, v[134:135]
	s_add_i32 m0, s18, 0x2000
	s_nop 0
	global_load_lds_dwordx4 v[218:219], off
	v_lshl_add_u64 v[218:219], v[222:223], 0, s[8:9]
	s_mov_b32 m0, s31
	s_nop 0
	global_load_lds_dwordx4 v[218:219], off
	v_lshl_add_u64 v[218:219], v[224:225], 0, s[8:9]
	s_mov_b32 m0, s33
	s_nop 0
	global_load_lds_dwordx4 v[218:219], off
	s_waitcnt vmcnt(8)
	s_waitcnt lgkmcnt(0)
	s_barrier
	s_setprio 3
	s_waitcnt lgkmcnt(0)
	v_mfma_f32_16x16x32_bf16 v[60:63], v[144:147], v[186:189], v[60:63]
	v_mfma_f32_16x16x32_bf16 v[56:59], v[162:165], v[186:189], v[56:59]
	v_mfma_f32_16x16x32_bf16 v[48:51], v[144:147], v[194:197], v[48:51]
	v_mfma_f32_16x16x32_bf16 v[40:43], v[162:165], v[194:197], v[40:43]
	v_mfma_f32_16x16x32_bf16 v[32:35], v[144:147], v[202:205], v[32:35]
	v_mfma_f32_16x16x32_bf16 v[24:27], v[162:165], v[202:205], v[24:27]
	v_mfma_f32_16x16x32_bf16 v[16:19], v[144:147], v[210:213], v[16:19]
	v_mfma_f32_16x16x32_bf16 v[8:11], v[162:165], v[210:213], v[8:11]
	v_mfma_f32_16x16x32_bf16 v[60:63], v[148:151], v[190:193], v[60:63]
	v_mfma_f32_16x16x32_bf16 v[56:59], v[166:169], v[190:193], v[56:59]
	v_mfma_f32_16x16x32_bf16 v[48:51], v[148:151], v[198:201], v[48:51]
	v_mfma_f32_16x16x32_bf16 v[40:43], v[166:169], v[198:201], v[40:43]
	v_mfma_f32_16x16x32_bf16 v[32:35], v[148:151], v[206:209], v[32:35]
	v_mfma_f32_16x16x32_bf16 v[24:27], v[166:169], v[206:209], v[24:27]
	v_mfma_f32_16x16x32_bf16 v[16:19], v[148:151], v[214:217], v[16:19]
	v_mfma_f32_16x16x32_bf16 v[8:11], v[166:169], v[214:217], v[8:11]
	v_mfma_f32_16x16x32_bf16 v[52:55], v[170:173], v[186:189], v[52:55]
	v_mfma_f32_16x16x32_bf16 v[44:47], v[178:181], v[186:189], v[44:47]
	v_mfma_f32_16x16x32_bf16 v[36:39], v[170:173], v[194:197], v[36:39]
	v_mfma_f32_16x16x32_bf16 v[28:31], v[178:181], v[194:197], v[28:31]
	v_mfma_f32_16x16x32_bf16 v[20:23], v[170:173], v[202:205], v[20:23]
	v_mfma_f32_16x16x32_bf16 v[12:15], v[178:181], v[202:205], v[12:15]
	v_mfma_f32_16x16x32_bf16 v[4:7], v[170:173], v[210:213], v[4:7]
	v_mfma_f32_16x16x32_bf16 v[0:3], v[178:181], v[210:213], v[0:3]
	v_mfma_f32_16x16x32_bf16 v[52:55], v[174:177], v[190:193], v[52:55]
	v_mfma_f32_16x16x32_bf16 v[44:47], v[182:185], v[190:193], v[44:47]
	v_mfma_f32_16x16x32_bf16 v[36:39], v[174:177], v[198:201], v[36:39]
	v_mfma_f32_16x16x32_bf16 v[28:31], v[182:185], v[198:201], v[28:31]
	v_mfma_f32_16x16x32_bf16 v[20:23], v[174:177], v[206:209], v[20:23]
	v_mfma_f32_16x16x32_bf16 v[12:15], v[182:185], v[206:209], v[12:15]
	v_mfma_f32_16x16x32_bf16 v[4:7], v[174:177], v[214:217], v[4:7]
	v_mfma_f32_16x16x32_bf16 v[0:3], v[182:185], v[214:217], v[0:3]
	s_setprio 0
	s_barrier
	s_add_i32 s45, s45, 2
	s_add_u32 s14, s14, 0x100
	s_addc_u32 s15, s15, 0
	s_add_u32 s43, s43, 0x100
	s_addc_u32 s44, s44, 0
	s_cmp_gt_u32 s45, 41
	s_cbranch_scc0 .LBB0_1513
	s_and_b64 vcc, exec, s[10:11]
	s_cbranch_vccz .LBB0_1516
	s_barrier
